# attention: row sums on VALU (ones-MFMA block removed), LDS waits moved to first consumers with counted lgkmcnt; K-loop mid-segment setprio flips removed
# speedup vs baseline: 1.0194x; 1.0080x over previous
; #define PG8_STAGE(bufoff, gbase, voff) do { _Pragma("unroll") for (int _i = 0; _i < 2; ++_i) \
;         __builtin_amdgcn_global_load_lds((const unsigned*)((const char*)(gbase) + (voff)[_i]), (LAS unsigned*)(lds + (bufoff) + ldsw + _i * 8192), 16, 0, 0); } while (0)
; #define PG8_LDA(dst, b, h) do { _Pragma("unroll") for (int m = 0; m < 4; ++m) _Pragma("unroll") for (int k = 0; k < 2; ++k) dst[m][k] = *(const LAS bf16x8*)(lds + PG8_SA(b, h) + aoff + m * 2048 + k * 1024); } while (0)
; #define PG8_LDB(dst, b, h) do { _Pragma("unroll") for (int n = 0; n < 2; ++n) _Pragma("unroll") for (int k = 0; k < 2; ++k) dst[n][k] = *(const LAS bf16x8*)(lds + PG8_SB(b, h) + boff + n * 2048 + k * 1024); } while (0)
; #define PG8_WAIT_V(n) asm volatile("s_waitcnt vmcnt(" #n ")" ::: "memory")
; #define PG8_WAIT_L(n) asm volatile("s_waitcnt lgkmcnt(" #n ")" ::: "memory")
; #define PG8_BAR __builtin_amdgcn_s_barrier()
; #define PG8_SCHED __builtin_amdgcn_sched_barrier(0)
; template <class Epi, class Sched>
; __device__ __forceinline__ void gemm_phase(LAS unsigned char* lds, const Gemm g, const Sched& S, const Epi& E) {
;     ...
;         for (int t = 0; t < nt; t += 2) {
;             if constexpr (Epi::HOOKS) { if (cur.kind == 3 && (t == 4 || t == 12)) { int fr_ = fr, fq_ = fq; asm volatile("" : "+v"(fr_), "+v"(fq_)); E.hook(acc, cur, t == 4 ? 0 : 1, wr, wc, fr_, fq_); } }
;             const bool last = (t == nt - 2);
;             const char* a1 = cA + (size_t)(t + 1) * kstep;
;             const char* a2 = last ? nA : cA + (size_t)(t + 2) * kstep; const char* b2 = last ? nB : cB + (size_t)(t + 2) * kstep;
;             const char* a3 = a2 + kstep; const char* b3 = b2 + kstep;
;             PG8_LDB(B0, 0, 0); PG8_LDB(B1, 0, 1); PG8_SCHED; PG8_LDA(At, 0, 0); PG8_STAGE(PG8_SA(1, 1), a1 + hstepA, voffA);
;             PG8_WAIT_V(8); PG8_WAIT_L(0); PG8_BAR; PG8_MMA(0, 0, At, B0); PG8_MMA(0, 1, At, B1); PG8_BAR; PG8_SCHED;
;             PG8_LDA(At, 0, 1); PG8_STAGE(PG8_SB(0, 0), b2, voffB); PG8_STAGE(PG8_SB(0, 1), b2 + hstepB, voffB); PG8_STAGE(PG8_SA(0, 0), a2, voffA);
;             PG8_WAIT_V(8); PG8_WAIT_L(0); PG8_BAR; PG8_MMA(1, 0, At, B0); PG8_MMA(1, 1, At, B1); PG8_BAR; PG8_SCHED;
;             PG8_LDB(B0, 1, 0); PG8_LDB(B1, 1, 1); PG8_SCHED; PG8_LDA(At, 1, 0); PG8_STAGE(PG8_SA(0, 1), a2 + hstepA, voffA);
.LBB0_101:
	s_add_i32 s68, s0, 2
	s_add_u32 s1, s20, 0xfff00080
	s_addc_u32 s42, s21, -1
	s_add_i32 s52, 0, 0x10000
	s_cmp_eq_u32 s72, s0
	s_cselect_b32 s43, s41, s42
	s_cselect_b32 s42, s48, s1
	s_cselect_b32 s1, s85, s94
	s_cselect_b32 s0, s87, s93
	s_add_i32 s53, 0, 0x14000
	v_add_u32_e32 v152, s52, v166
	v_add_u32_e32 v172, s53, v166
	ds_read_b128 v[130:133], v152
	ds_read_b128 v[134:137], v152 offset:1024
	ds_read_b128 v[138:141], v152 offset:2048
	ds_read_b128 v[152:155], v152 offset:3072
	ds_read_b128 v[156:159], v172
	ds_read_b128 v[160:163], v172 offset:1024
	ds_read_b128 v[168:171], v172 offset:2048
	ds_read_b128 v[172:175], v172 offset:3072
	v_lshl_add_u64 v[184:185], s[20:21], 0, v[150:151]
	s_add_i32 m0, s15, 0xc000
	ds_read_b128 v[176:179], v167
	ds_read_b128 v[180:183], v167 offset:1024
	ds_read_b128 v[196:199], v167 offset:2048
	ds_read_b128 v[200:203], v167 offset:3072
	ds_read_b128 v[204:207], v167 offset:4096
	ds_read_b128 v[208:211], v167 offset:5120
	ds_read_b128 v[212:215], v167 offset:6144
	ds_read_b128 v[216:219], v167 offset:7168
	global_load_lds_dwordx4 v[184:185], off
	v_lshl_add_u64 v[184:185], s[20:21], 0, v[148:149]
	s_add_i32 m0, s15, 0xe000
	s_nop 0
	global_load_lds_dwordx4 v[184:185], off
	s_waitcnt vmcnt(8)
	s_waitcnt lgkmcnt(0)
	s_barrier
	s_setprio 1
	s_waitcnt lgkmcnt(0)
	v_mfma_f32_16x16x32_bf16 v[126:129], v[130:133], v[176:179], v[126:129]
	v_mfma_f32_16x16x32_bf16 v[122:125], v[138:141], v[176:179], v[122:125]
	v_mfma_f32_16x16x32_bf16 v[110:113], v[130:133], v[196:199], v[110:113]
	v_mfma_f32_16x16x32_bf16 v[106:109], v[138:141], v[196:199], v[106:109]
	v_mfma_f32_16x16x32_bf16 v[94:97], v[130:133], v[204:207], v[94:97]
	v_mfma_f32_16x16x32_bf16 v[90:93], v[138:141], v[204:207], v[90:93]
	v_mfma_f32_16x16x32_bf16 v[78:81], v[130:133], v[212:215], v[78:81]
	v_mfma_f32_16x16x32_bf16 v[74:77], v[138:141], v[212:215], v[74:77]
	v_mfma_f32_16x16x32_bf16 v[126:129], v[134:137], v[180:183], v[126:129]
	v_mfma_f32_16x16x32_bf16 v[122:125], v[152:155], v[180:183], v[122:125]
	v_mfma_f32_16x16x32_bf16 v[110:113], v[134:137], v[200:203], v[110:113]
	v_mfma_f32_16x16x32_bf16 v[106:109], v[152:155], v[200:203], v[106:109]
	v_mfma_f32_16x16x32_bf16 v[94:97], v[134:137], v[208:211], v[94:97]
	v_mfma_f32_16x16x32_bf16 v[90:93], v[152:155], v[208:211], v[90:93]
	v_mfma_f32_16x16x32_bf16 v[78:81], v[134:137], v[216:219], v[78:81]
	v_mfma_f32_16x16x32_bf16 v[74:77], v[152:155], v[216:219], v[74:77]
	v_mfma_f32_16x16x32_bf16 v[118:121], v[156:159], v[176:179], v[118:121]
	v_mfma_f32_16x16x32_bf16 v[114:117], v[168:171], v[176:179], v[114:117]
	v_mfma_f32_16x16x32_bf16 v[102:105], v[156:159], v[196:199], v[102:105]
	v_mfma_f32_16x16x32_bf16 v[98:101], v[168:171], v[196:199], v[98:101]
	v_mfma_f32_16x16x32_bf16 v[86:89], v[156:159], v[204:207], v[86:89]
	v_mfma_f32_16x16x32_bf16 v[82:85], v[168:171], v[204:207], v[82:85]
	v_mfma_f32_16x16x32_bf16 v[70:73], v[156:159], v[212:215], v[70:73]
	v_mfma_f32_16x16x32_bf16 v[66:69], v[168:171], v[212:215], v[66:69]
	v_mfma_f32_16x16x32_bf16 v[118:121], v[160:163], v[180:183], v[118:121]
	v_mfma_f32_16x16x32_bf16 v[114:117], v[172:175], v[180:183], v[114:117]
	v_mfma_f32_16x16x32_bf16 v[102:105], v[160:163], v[200:203], v[102:105]
	v_mfma_f32_16x16x32_bf16 v[98:101], v[172:175], v[200:203], v[98:101]
	v_mfma_f32_16x16x32_bf16 v[86:89], v[160:163], v[208:211], v[86:89]
	v_mfma_f32_16x16x32_bf16 v[82:85], v[172:175], v[208:211], v[82:85]
	v_mfma_f32_16x16x32_bf16 v[70:73], v[160:163], v[216:219], v[70:73]
	v_mfma_f32_16x16x32_bf16 v[66:69], v[172:175], v[216:219], v[66:69]
	s_setprio 0
	s_barrier
	s_add_i32 s52, s52, s14
	v_lshl_add_u64 v[184:185], s[0:1], 0, v[0:1]
	s_mov_b32 m0, s52
	ds_read_b128 v[176:179], v167 offset:16384
	ds_read_b128 v[180:183], v167 offset:17408
	ds_read_b128 v[196:199], v167 offset:18432
	ds_read_b128 v[200:203], v167 offset:19456
	ds_read_b128 v[204:207], v167 offset:20480
	ds_read_b128 v[208:211], v167 offset:21504
	ds_read_b128 v[212:215], v167 offset:22528
	ds_read_b128 v[216:219], v167 offset:23552
	global_load_lds_dwordx4 v[184:185], off
	s_add_i32 m0, s52, 0x2000
	s_add_u32 s96, s0, 0x100000
	v_lshl_add_u64 v[220:221], s[0:1], 0, v[146:147]
	s_addc_u32 s97, s1, 0
	s_add_i32 s52, s53, s14
	global_load_lds_dwordx4 v[220:221], off
	v_lshl_add_u64 v[232:233], s[96:97], 0, v[0:1]
	s_mov_b32 m0, s52
	v_lshl_add_u64 v[234:235], s[42:43], 0, v[144:145]
	global_load_lds_dwordx4 v[232:233], off
	v_lshl_add_u64 v[232:233], s[96:97], 0, v[146:147]
	s_add_i32 m0, s52, 0x2000
	s_nop 0
	global_load_lds_dwordx4 v[232:233], off
	v_lshl_add_u64 v[232:233], s[42:43], 0, v[142:143]
	s_mov_b32 m0, s15
	s_nop 0
	global_load_lds_dwordx4 v[232:233], off
	s_mov_b32 m0, s16
	s_nop 0
	global_load_lds_dwordx4 v[234:235], off
	s_waitcnt vmcnt(8)
	s_waitcnt lgkmcnt(0)
	s_barrier
; #define PG8_STAGE(bufoff, gbase, voff) do { _Pragma("unroll") for (int _i = 0; _i < 2; ++_i) \
;         __builtin_amdgcn_global_load_lds((const unsigned*)((const char*)(gbase) + (voff)[_i]), (LAS unsigned*)(lds + (bufoff) + ldsw + _i * 8192), 16, 0, 0); } while (0)
; #define PG8_LDA(dst, b, h) do { _Pragma("unroll") for (int m = 0; m < 4; ++m) _Pragma("unroll") for (int k = 0; k < 2; ++k) dst[m][k] = *(const LAS bf16x8*)(lds + PG8_SA(b, h) + aoff + m * 2048 + k * 1024); } while (0)
; #define PG8_LDB(dst, b, h) do { _Pragma("unroll") for (int n = 0; n < 2; ++n) _Pragma("unroll") for (int k = 0; k < 2; ++k) dst[n][k] = *(const LAS bf16x8*)(lds + PG8_SB(b, h) + boff + n * 2048 + k * 1024); } while (0)
; #define PG8_MMA(ai, bj, At, Bt) do { __builtin_amdgcn_s_setprio(1); _Pragma("unroll") for (int m = 0; m < 4; ++m) _Pragma("unroll") for (int n = 0; n < 2; ++n) _Pragma("unroll") for (int k = 0; k < 2; ++k) \
;         acc[ai][bj][m][n] = __builtin_amdgcn_mfma_f32_16x16x32_bf16(Bt[n][k], At[m][k], acc[ai][bj][m][n], 0, 0, 0); __builtin_amdgcn_s_setprio(0); } while (0)
; #define PG8_WAIT_V(n) asm volatile("s_waitcnt vmcnt(" #n ")" ::: "memory")
; #define PG8_WAIT_L(n) asm volatile("s_waitcnt lgkmcnt(" #n ")" ::: "memory")
; #define PG8_BAR __builtin_amdgcn_s_barrier()
; #define PG8_SCHED __builtin_amdgcn_sched_barrier(0)
; template <class Epi, class Sched>
; __device__ __forceinline__ void gemm_phase(LAS unsigned char* lds, const Gemm g, const Sched& S, const Epi& E) {
;     ...
;             PG8_WAIT_V(8); PG8_WAIT_L(0); PG8_BAR; PG8_MMA(0, 0, At, B0); PG8_MMA(0, 1, At, B1); PG8_BAR; PG8_SCHED;
;             PG8_LDA(At, 0, 1); PG8_STAGE(PG8_SB(0, 0), b2, voffB); PG8_STAGE(PG8_SB(0, 1), b2 + hstepB, voffB); PG8_STAGE(PG8_SA(0, 0), a2, voffA);
;             PG8_WAIT_V(8); PG8_WAIT_L(0); PG8_BAR; PG8_MMA(1, 0, At, B0); PG8_MMA(1, 1, At, B1); PG8_BAR; PG8_SCHED;
;             PG8_LDB(B0, 1, 0); PG8_LDB(B1, 1, 1); PG8_SCHED; PG8_LDA(At, 1, 0); PG8_STAGE(PG8_SA(0, 1), a2 + hstepA, voffA);
;             PG8_WAIT_V(8); PG8_WAIT_L(0); PG8_BAR; PG8_MMA(0, 0, At, B0); PG8_MMA(0, 1, At, B1); PG8_BAR; PG8_SCHED;
;             PG8_LDA(At, 1, 1); PG8_STAGE(PG8_SB(1, 0), b3, voffB); PG8_STAGE(PG8_SB(1, 1), b3 + hstepB, voffB); PG8_STAGE(PG8_SA(1, 0), a3, voffA);
	s_setprio 1
	s_waitcnt lgkmcnt(0)
	v_mfma_f32_16x16x32_bf16 v[62:65], v[130:133], v[176:179], v[62:65]
	v_mfma_f32_16x16x32_bf16 v[58:61], v[138:141], v[176:179], v[58:61]
	v_mfma_f32_16x16x32_bf16 v[46:49], v[130:133], v[196:199], v[46:49]
	v_mfma_f32_16x16x32_bf16 v[42:45], v[138:141], v[196:199], v[42:45]
	v_mfma_f32_16x16x32_bf16 v[30:33], v[130:133], v[204:207], v[30:33]
	v_mfma_f32_16x16x32_bf16 v[26:29], v[138:141], v[204:207], v[26:29]
	v_mfma_f32_16x16x32_bf16 v[14:17], v[130:133], v[212:215], v[14:17]
	v_mfma_f32_16x16x32_bf16 v[10:13], v[138:141], v[212:215], v[10:13]
	v_mfma_f32_16x16x32_bf16 v[62:65], v[134:137], v[180:183], v[62:65]
	v_mfma_f32_16x16x32_bf16 v[58:61], v[152:155], v[180:183], v[58:61]
	v_mfma_f32_16x16x32_bf16 v[46:49], v[134:137], v[200:203], v[46:49]
	v_mfma_f32_16x16x32_bf16 v[42:45], v[152:155], v[200:203], v[42:45]
	v_mfma_f32_16x16x32_bf16 v[30:33], v[134:137], v[208:211], v[30:33]
	v_mfma_f32_16x16x32_bf16 v[26:29], v[152:155], v[208:211], v[26:29]
	v_mfma_f32_16x16x32_bf16 v[14:17], v[134:137], v[216:219], v[14:17]
	v_mfma_f32_16x16x32_bf16 v[10:13], v[152:155], v[216:219], v[10:13]
	v_mfma_f32_16x16x32_bf16 v[54:57], v[156:159], v[176:179], v[54:57]
	v_mfma_f32_16x16x32_bf16 v[50:53], v[168:171], v[176:179], v[50:53]
	v_mfma_f32_16x16x32_bf16 v[38:41], v[156:159], v[196:199], v[38:41]
	v_mfma_f32_16x16x32_bf16 v[34:37], v[168:171], v[196:199], v[34:37]
	v_mfma_f32_16x16x32_bf16 v[22:25], v[156:159], v[204:207], v[22:25]
	v_mfma_f32_16x16x32_bf16 v[18:21], v[168:171], v[204:207], v[18:21]
	v_mfma_f32_16x16x32_bf16 v[6:9], v[156:159], v[212:215], v[6:9]
	v_mfma_f32_16x16x32_bf16 v[2:5], v[168:171], v[212:215], v[2:5]
	v_mfma_f32_16x16x32_bf16 v[54:57], v[160:163], v[180:183], v[54:57]
	v_mfma_f32_16x16x32_bf16 v[50:53], v[172:175], v[180:183], v[50:53]
	v_mfma_f32_16x16x32_bf16 v[38:41], v[160:163], v[200:203], v[38:41]
	v_mfma_f32_16x16x32_bf16 v[34:37], v[172:175], v[200:203], v[34:37]
	v_mfma_f32_16x16x32_bf16 v[22:25], v[160:163], v[208:211], v[22:25]
	v_mfma_f32_16x16x32_bf16 v[18:21], v[172:175], v[208:211], v[18:21]
	v_mfma_f32_16x16x32_bf16 v[6:9], v[160:163], v[216:219], v[6:9]
	v_mfma_f32_16x16x32_bf16 v[2:5], v[172:175], v[216:219], v[2:5]
	s_setprio 0
	s_barrier
	s_add_i32 s52, 0, 0x18000
	s_add_i32 s53, 0, 0x1c000
	v_add_u32_e32 v152, s52, v166
	v_add_u32_e32 v172, s53, v166
	ds_read_b128 v[130:133], v152
	ds_read_b128 v[134:137], v152 offset:1024
	ds_read_b128 v[138:141], v152 offset:2048
	ds_read_b128 v[152:155], v152 offset:3072
	ds_read_b128 v[156:159], v172
	ds_read_b128 v[160:163], v172 offset:1024
	ds_read_b128 v[168:171], v172 offset:2048
	ds_read_b128 v[172:175], v172 offset:3072
	s_add_u32 s42, s42, 0x100000
	s_addc_u32 s43, s43, 0
	s_mov_b32 m0, s17
	v_lshl_add_u64 v[236:237], s[42:43], 0, v[142:143]
	ds_read_b128 v[176:179], v167 offset:32768
	ds_read_b128 v[180:183], v167 offset:33792
	ds_read_b128 v[196:199], v167 offset:34816
	ds_read_b128 v[200:203], v167 offset:35840
	ds_read_b128 v[204:207], v167 offset:36864
	ds_read_b128 v[208:211], v167 offset:37888
	ds_read_b128 v[212:215], v167 offset:38912
	ds_read_b128 v[216:219], v167 offset:39936
	global_load_lds_dwordx4 v[236:237], off
	v_lshl_add_u64 v[236:237], s[42:43], 0, v[144:145]
	s_mov_b32 m0, s19
	s_nop 0
	global_load_lds_dwordx4 v[236:237], off
	s_waitcnt vmcnt(8)
	s_waitcnt lgkmcnt(0)
	s_barrier
	s_setprio 1
	s_waitcnt lgkmcnt(0)
	v_mfma_f32_16x16x32_bf16 v[126:129], v[130:133], v[176:179], v[126:129]
	v_mfma_f32_16x16x32_bf16 v[122:125], v[138:141], v[176:179], v[122:125]
	v_mfma_f32_16x16x32_bf16 v[110:113], v[130:133], v[196:199], v[110:113]
	v_mfma_f32_16x16x32_bf16 v[106:109], v[138:141], v[196:199], v[106:109]
	v_mfma_f32_16x16x32_bf16 v[94:97], v[130:133], v[204:207], v[94:97]
	v_mfma_f32_16x16x32_bf16 v[90:93], v[138:141], v[204:207], v[90:93]
	v_mfma_f32_16x16x32_bf16 v[78:81], v[130:133], v[212:215], v[78:81]
	v_mfma_f32_16x16x32_bf16 v[74:77], v[138:141], v[212:215], v[74:77]
	v_mfma_f32_16x16x32_bf16 v[126:129], v[134:137], v[180:183], v[126:129]
	v_mfma_f32_16x16x32_bf16 v[122:125], v[152:155], v[180:183], v[122:125]
	v_mfma_f32_16x16x32_bf16 v[110:113], v[134:137], v[200:203], v[110:113]
	v_mfma_f32_16x16x32_bf16 v[106:109], v[152:155], v[200:203], v[106:109]
	v_mfma_f32_16x16x32_bf16 v[94:97], v[134:137], v[208:211], v[94:97]
	v_mfma_f32_16x16x32_bf16 v[90:93], v[152:155], v[208:211], v[90:93]
	v_mfma_f32_16x16x32_bf16 v[78:81], v[134:137], v[216:219], v[78:81]
	v_mfma_f32_16x16x32_bf16 v[74:77], v[152:155], v[216:219], v[74:77]
	v_mfma_f32_16x16x32_bf16 v[118:121], v[156:159], v[176:179], v[118:121]
	v_mfma_f32_16x16x32_bf16 v[114:117], v[168:171], v[176:179], v[114:117]
	v_mfma_f32_16x16x32_bf16 v[102:105], v[156:159], v[196:199], v[102:105]
	v_mfma_f32_16x16x32_bf16 v[98:101], v[168:171], v[196:199], v[98:101]
	v_mfma_f32_16x16x32_bf16 v[86:89], v[156:159], v[204:207], v[86:89]
	v_mfma_f32_16x16x32_bf16 v[82:85], v[168:171], v[204:207], v[82:85]
	v_mfma_f32_16x16x32_bf16 v[70:73], v[156:159], v[212:215], v[70:73]
	v_mfma_f32_16x16x32_bf16 v[66:69], v[168:171], v[212:215], v[66:69]
	v_mfma_f32_16x16x32_bf16 v[118:121], v[160:163], v[180:183], v[118:121]
	v_mfma_f32_16x16x32_bf16 v[114:117], v[172:175], v[180:183], v[114:117]
	v_mfma_f32_16x16x32_bf16 v[102:105], v[160:163], v[200:203], v[102:105]
	v_mfma_f32_16x16x32_bf16 v[98:101], v[172:175], v[200:203], v[98:101]
	v_mfma_f32_16x16x32_bf16 v[86:89], v[160:163], v[208:211], v[86:89]
	v_mfma_f32_16x16x32_bf16 v[82:85], v[172:175], v[208:211], v[82:85]
	v_mfma_f32_16x16x32_bf16 v[70:73], v[160:163], v[216:219], v[70:73]
	v_mfma_f32_16x16x32_bf16 v[66:69], v[172:175], v[216:219], v[66:69]
	s_setprio 0
	s_barrier
; #define PG8_STAGE(bufoff, gbase, voff) do { _Pragma("unroll") for (int _i = 0; _i < 2; ++_i) \
;         __builtin_amdgcn_global_load_lds((const unsigned*)((const char*)(gbase) + (voff)[_i]), (LAS unsigned*)(lds + (bufoff) + ldsw + _i * 8192), 16, 0, 0); } while (0)
; #define PG8_LDA(dst, b, h) do { _Pragma("unroll") for (int m = 0; m < 4; ++m) _Pragma("unroll") for (int k = 0; k < 2; ++k) dst[m][k] = *(const LAS bf16x8*)(lds + PG8_SA(b, h) + aoff + m * 2048 + k * 1024); } while (0)
; #define PG8_MMA(ai, bj, At, Bt) do { __builtin_amdgcn_s_setprio(1); _Pragma("unroll") for (int m = 0; m < 4; ++m) _Pragma("unroll") for (int n = 0; n < 2; ++n) _Pragma("unroll") for (int k = 0; k < 2; ++k) \
;         acc[ai][bj][m][n] = __builtin_amdgcn_mfma_f32_16x16x32_bf16(Bt[n][k], At[m][k], acc[ai][bj][m][n], 0, 0, 0); __builtin_amdgcn_s_setprio(0); } while (0)
; #define PG8_WAIT_V(n) asm volatile("s_waitcnt vmcnt(" #n ")" ::: "memory")
; #define PG8_WAIT_L(n) asm volatile("s_waitcnt lgkmcnt(" #n ")" ::: "memory")
; #define PG8_BAR __builtin_amdgcn_s_barrier()
; #define PG8_SCHED __builtin_amdgcn_sched_barrier(0)
; template <class Epi, class Sched>
; __device__ __forceinline__ void gemm_phase(LAS unsigned char* lds, const Gemm g, const Sched& S, const Epi& E) {
;     ...
;             PG8_WAIT_V(8); PG8_WAIT_L(0); PG8_BAR; PG8_MMA(0, 0, At, B0); PG8_MMA(0, 1, At, B1); PG8_BAR; PG8_SCHED;
;             PG8_LDA(At, 1, 1); PG8_STAGE(PG8_SB(1, 0), b3, voffB); PG8_STAGE(PG8_SB(1, 1), b3 + hstepB, voffB); PG8_STAGE(PG8_SA(1, 0), a3, voffA);
;             PG8_WAIT_V(8); PG8_WAIT_L(0); PG8_BAR; PG8_MMA(1, 0, At, B0); PG8_MMA(1, 1, At, B1); PG8_BAR; PG8_SCHED;
;         }
	s_add_i32 s42, s52, s14
	v_lshl_add_u64 v[184:185], v[184:185], 0, s[26:27]
	s_mov_b32 m0, s42
	ds_read_b128 v[176:179], v167 offset:49152
	ds_read_b128 v[180:183], v167 offset:50176
	ds_read_b128 v[196:199], v167 offset:51200
	ds_read_b128 v[200:203], v167 offset:52224
	ds_read_b128 v[204:207], v167 offset:53248
	ds_read_b128 v[208:211], v167 offset:54272
	ds_read_b128 v[212:215], v167 offset:55296
	ds_read_b128 v[216:219], v167 offset:56320
	global_load_lds_dwordx4 v[184:185], off
	s_add_i32 m0, s42, 0x2000
	s_add_u32 s0, s0, 0x100080
	v_lshl_add_u64 v[184:185], v[220:221], 0, s[26:27]
	s_addc_u32 s1, s1, 0
	s_add_i32 s42, s53, s14
	global_load_lds_dwordx4 v[184:185], off
	v_lshl_add_u64 v[184:185], s[0:1], 0, v[0:1]
	s_mov_b32 m0, s42
	s_nop 0
	global_load_lds_dwordx4 v[184:185], off
	v_lshl_add_u64 v[184:185], s[0:1], 0, v[146:147]
	s_add_i32 m0, s42, 0x2000
	s_nop 0
	global_load_lds_dwordx4 v[184:185], off
	v_lshl_add_u64 v[184:185], v[232:233], 0, s[26:27]
	s_mov_b32 m0, s67
	s_nop 0
	global_load_lds_dwordx4 v[184:185], off
	v_lshl_add_u64 v[184:185], v[234:235], 0, s[26:27]
	s_mov_b32 m0, s69
	s_nop 0
	global_load_lds_dwordx4 v[184:185], off
	s_waitcnt vmcnt(8)
	s_waitcnt lgkmcnt(0)
	s_barrier
	s_setprio 1
	s_waitcnt lgkmcnt(0)
	v_mfma_f32_16x16x32_bf16 v[62:65], v[130:133], v[176:179], v[62:65]
	v_mfma_f32_16x16x32_bf16 v[58:61], v[138:141], v[176:179], v[58:61]
	v_mfma_f32_16x16x32_bf16 v[46:49], v[130:133], v[196:199], v[46:49]
	v_mfma_f32_16x16x32_bf16 v[42:45], v[138:141], v[196:199], v[42:45]
	v_mfma_f32_16x16x32_bf16 v[30:33], v[130:133], v[204:207], v[30:33]
	v_mfma_f32_16x16x32_bf16 v[26:29], v[138:141], v[204:207], v[26:29]
	v_mfma_f32_16x16x32_bf16 v[14:17], v[130:133], v[212:215], v[14:17]
	v_mfma_f32_16x16x32_bf16 v[10:13], v[138:141], v[212:215], v[10:13]
	v_mfma_f32_16x16x32_bf16 v[62:65], v[134:137], v[180:183], v[62:65]
	v_mfma_f32_16x16x32_bf16 v[58:61], v[152:155], v[180:183], v[58:61]
	v_mfma_f32_16x16x32_bf16 v[46:49], v[134:137], v[200:203], v[46:49]
	v_mfma_f32_16x16x32_bf16 v[42:45], v[152:155], v[200:203], v[42:45]
	v_mfma_f32_16x16x32_bf16 v[30:33], v[134:137], v[208:211], v[30:33]
	v_mfma_f32_16x16x32_bf16 v[26:29], v[152:155], v[208:211], v[26:29]
	v_mfma_f32_16x16x32_bf16 v[14:17], v[134:137], v[216:219], v[14:17]
	v_mfma_f32_16x16x32_bf16 v[10:13], v[152:155], v[216:219], v[10:13]
	v_mfma_f32_16x16x32_bf16 v[54:57], v[156:159], v[176:179], v[54:57]
	v_mfma_f32_16x16x32_bf16 v[50:53], v[168:171], v[176:179], v[50:53]
	v_mfma_f32_16x16x32_bf16 v[38:41], v[156:159], v[196:199], v[38:41]
	v_mfma_f32_16x16x32_bf16 v[34:37], v[168:171], v[196:199], v[34:37]
	v_mfma_f32_16x16x32_bf16 v[22:25], v[156:159], v[204:207], v[22:25]
	v_mfma_f32_16x16x32_bf16 v[18:21], v[168:171], v[204:207], v[18:21]
	v_mfma_f32_16x16x32_bf16 v[6:9], v[156:159], v[212:215], v[6:9]
	v_mfma_f32_16x16x32_bf16 v[2:5], v[168:171], v[212:215], v[2:5]
	v_mfma_f32_16x16x32_bf16 v[54:57], v[160:163], v[180:183], v[54:57]
	v_mfma_f32_16x16x32_bf16 v[50:53], v[172:175], v[180:183], v[50:53]
	v_mfma_f32_16x16x32_bf16 v[38:41], v[160:163], v[200:203], v[38:41]
	v_mfma_f32_16x16x32_bf16 v[34:37], v[172:175], v[200:203], v[34:37]
	v_mfma_f32_16x16x32_bf16 v[22:25], v[160:163], v[208:211], v[22:25]
	v_mfma_f32_16x16x32_bf16 v[18:21], v[172:175], v[208:211], v[18:21]
	v_mfma_f32_16x16x32_bf16 v[6:9], v[160:163], v[216:219], v[6:9]
	v_mfma_f32_16x16x32_bf16 v[2:5], v[172:175], v[216:219], v[2:5]
	s_setprio 0
	s_barrier
	s_add_u32 s93, s93, 0x100
	s_addc_u32 s94, s94, 0
	s_add_u32 s20, s20, 0x100
	s_addc_u32 s21, s21, 0
	s_cmp_ge_i32 s68, s46
	s_mov_b32 s0, s68
	s_cbranch_scc0 .LBB0_101
	v_readlane_b32 s94, v255, 0
	v_readlane_b32 s95, v255, 1

; #define PG8_STAGE(bufoff, gbase, voff) do { _Pragma("unroll") for (int _i = 0; _i < 2; ++_i) \
;         __builtin_amdgcn_global_load_lds((const unsigned*)((const char*)(gbase) + (voff)[_i]), (LAS unsigned*)(lds + (bufoff) + ldsw + _i * 8192), 16, 0, 0); } while (0)
; #define PG8_LDA(dst, b, h) do { _Pragma("unroll") for (int m = 0; m < 4; ++m) _Pragma("unroll") for (int k = 0; k < 2; ++k) dst[m][k] = *(const LAS bf16x8*)(lds + PG8_SA(b, h) + aoff + m * 2048 + k * 1024); } while (0)
; #define PG8_LDB(dst, b, h) do { _Pragma("unroll") for (int n = 0; n < 2; ++n) _Pragma("unroll") for (int k = 0; k < 2; ++k) dst[n][k] = *(const LAS bf16x8*)(lds + PG8_SB(b, h) + boff + n * 2048 + k * 1024); } while (0)
; #define PG8_MMA(ai, bj, At, Bt) do { __builtin_amdgcn_s_setprio(1); _Pragma("unroll") for (int m = 0; m < 4; ++m) _Pragma("unroll") for (int n = 0; n < 2; ++n) _Pragma("unroll") for (int k = 0; k < 2; ++k) \
;         acc[ai][bj][m][n] = __builtin_amdgcn_mfma_f32_16x16x32_bf16(Bt[n][k], At[m][k], acc[ai][bj][m][n], 0, 0, 0); __builtin_amdgcn_s_setprio(0); } while (0)
; #define PG8_WAIT_V(n) asm volatile("s_waitcnt vmcnt(" #n ")" ::: "memory")
; #define PG8_WAIT_L(n) asm volatile("s_waitcnt lgkmcnt(" #n ")" ::: "memory")
; #define PG8_BAR __builtin_amdgcn_s_barrier()
; template <class Epi, class Sched>
; __device__ __forceinline__ void gemm_phase(LAS unsigned char* lds, const Gemm g, const Sched& S, const Epi& E) {
;     ...
;         for (int t = 0; t < nt; t += 2) {
;             if constexpr (Epi::HOOKS) { if (cur.kind == 3 && (t == 4 || t == 12)) { int fr_ = fr, fq_ = fq; asm volatile("" : "+v"(fr_), "+v"(fq_)); E.hook(acc, cur, t == 4 ? 0 : 1, wr, wc, fr_, fq_); } }
;             const bool last = (t == nt - 2);
;             const char* a1 = cA + (size_t)(t + 1) * kstep;
;             const char* a2 = last ? nA : cA + (size_t)(t + 2) * kstep; const char* b2 = last ? nB : cB + (size_t)(t + 2) * kstep;
;             const char* a3 = a2 + kstep; const char* b3 = b2 + kstep;
;             PG8_LDB(B0, 0, 0); PG8_LDB(B1, 0, 1); PG8_SCHED; PG8_LDA(At, 0, 0); PG8_STAGE(PG8_SA(1, 1), a1 + hstepA, voffA);
;             PG8_WAIT_V(8); PG8_WAIT_L(0); PG8_BAR; PG8_MMA(0, 0, At, B0); PG8_MMA(0, 1, At, B1); PG8_BAR; PG8_SCHED;
;             PG8_LDA(At, 0, 1); PG8_STAGE(PG8_SB(0, 0), b2, voffB); PG8_STAGE(PG8_SB(0, 1), b2 + hstepB, voffB); PG8_STAGE(PG8_SA(0, 0), a2, voffA);
.LBB0_209:
	s_add_i32 s68, s0, 2
	s_add_u32 s1, s20, 0xfffc0080
	s_addc_u32 s52, s21, -1
	s_add_i32 s53, 0, 0x10000
	s_cmp_eq_u32 s72, s0
	s_cselect_b32 s85, s43, s52
	s_cselect_b32 s84, s59, s1
	s_cselect_b32 s1, s86, s89
	s_cselect_b32 s0, s87, s88
	s_add_i32 s52, 0, 0x14000
	v_add_u32_e32 v142, s53, v177
	v_add_u32_e32 v168, s52, v177
	ds_read_b128 v[130:133], v142
	ds_read_b128 v[134:137], v142 offset:1024
	ds_read_b128 v[138:141], v142 offset:2048
	ds_read_b128 v[142:145], v142 offset:3072
	ds_read_b128 v[156:159], v168
	ds_read_b128 v[160:163], v168 offset:1024
	ds_read_b128 v[164:167], v168 offset:2048
	ds_read_b128 v[180:183], v168 offset:3072
	v_lshl_add_u64 v[168:169], s[20:21], 0, v[154:155]
	s_add_i32 m0, s19, 0xc000
	ds_read_b128 v[196:199], v179
	ds_read_b128 v[200:203], v179 offset:1024
	ds_read_b128 v[204:207], v179 offset:2048
	ds_read_b128 v[208:211], v179 offset:3072
	ds_read_b128 v[212:215], v179 offset:4096
	ds_read_b128 v[216:219], v179 offset:5120
	ds_read_b128 v[232:235], v179 offset:6144
	ds_read_b128 v[248:251], v179 offset:7168
	global_load_lds_dwordx4 v[168:169], off
	v_lshl_add_u64 v[168:169], s[20:21], 0, v[152:153]
	s_add_i32 m0, s19, 0xe000
	s_nop 0
	global_load_lds_dwordx4 v[168:169], off
	s_waitcnt vmcnt(8)
	s_waitcnt lgkmcnt(0)
	s_barrier
	s_setprio 1
	s_waitcnt lgkmcnt(0)
	v_mfma_f32_16x16x32_bf16 v[126:129], v[130:133], v[196:199], v[126:129]
	v_mfma_f32_16x16x32_bf16 v[122:125], v[138:141], v[196:199], v[122:125]
	v_mfma_f32_16x16x32_bf16 v[110:113], v[130:133], v[204:207], v[110:113]
	v_mfma_f32_16x16x32_bf16 v[106:109], v[138:141], v[204:207], v[106:109]
	v_mfma_f32_16x16x32_bf16 v[94:97], v[130:133], v[212:215], v[94:97]
	v_mfma_f32_16x16x32_bf16 v[90:93], v[138:141], v[212:215], v[90:93]
	v_mfma_f32_16x16x32_bf16 v[78:81], v[130:133], v[232:235], v[78:81]
	v_mfma_f32_16x16x32_bf16 v[74:77], v[138:141], v[232:235], v[74:77]
	v_mfma_f32_16x16x32_bf16 v[126:129], v[134:137], v[200:203], v[126:129]
	v_mfma_f32_16x16x32_bf16 v[122:125], v[142:145], v[200:203], v[122:125]
	v_mfma_f32_16x16x32_bf16 v[110:113], v[134:137], v[208:211], v[110:113]
	v_mfma_f32_16x16x32_bf16 v[106:109], v[142:145], v[208:211], v[106:109]
	v_mfma_f32_16x16x32_bf16 v[94:97], v[134:137], v[216:219], v[94:97]
	v_mfma_f32_16x16x32_bf16 v[90:93], v[142:145], v[216:219], v[90:93]
	v_mfma_f32_16x16x32_bf16 v[78:81], v[134:137], v[248:251], v[78:81]
	v_mfma_f32_16x16x32_bf16 v[74:77], v[142:145], v[248:251], v[74:77]
	v_mfma_f32_16x16x32_bf16 v[118:121], v[156:159], v[196:199], v[118:121]
	v_mfma_f32_16x16x32_bf16 v[114:117], v[164:167], v[196:199], v[114:117]
	v_mfma_f32_16x16x32_bf16 v[102:105], v[156:159], v[204:207], v[102:105]
	v_mfma_f32_16x16x32_bf16 v[98:101], v[164:167], v[204:207], v[98:101]
	v_mfma_f32_16x16x32_bf16 v[86:89], v[156:159], v[212:215], v[86:89]
	v_mfma_f32_16x16x32_bf16 v[82:85], v[164:167], v[212:215], v[82:85]
	v_mfma_f32_16x16x32_bf16 v[70:73], v[156:159], v[232:235], v[70:73]
	v_mfma_f32_16x16x32_bf16 v[66:69], v[164:167], v[232:235], v[66:69]
	v_mfma_f32_16x16x32_bf16 v[118:121], v[160:163], v[200:203], v[118:121]
	v_mfma_f32_16x16x32_bf16 v[114:117], v[180:183], v[200:203], v[114:117]
	v_mfma_f32_16x16x32_bf16 v[102:105], v[160:163], v[208:211], v[102:105]
	v_mfma_f32_16x16x32_bf16 v[98:101], v[180:183], v[208:211], v[98:101]
	v_mfma_f32_16x16x32_bf16 v[86:89], v[160:163], v[216:219], v[86:89]
	v_mfma_f32_16x16x32_bf16 v[82:85], v[180:183], v[216:219], v[82:85]
	v_mfma_f32_16x16x32_bf16 v[70:73], v[160:163], v[248:251], v[70:73]
	v_mfma_f32_16x16x32_bf16 v[66:69], v[180:183], v[248:251], v[66:69]
	s_setprio 0
	s_barrier
	s_add_i32 s53, s53, s17
	v_lshl_add_u64 v[168:169], s[0:1], 0, v[0:1]
	s_mov_b32 m0, s53
	ds_read_b128 v[196:199], v179 offset:16384
	ds_read_b128 v[200:203], v179 offset:17408
	ds_read_b128 v[204:207], v179 offset:18432
	ds_read_b128 v[208:211], v179 offset:19456
	ds_read_b128 v[212:215], v179 offset:20480
	ds_read_b128 v[216:219], v179 offset:21504
	ds_read_b128 v[232:235], v179 offset:22528
	ds_read_b128 v[248:251], v179 offset:23552
	global_load_lds_dwordx4 v[168:169], off
	s_add_i32 m0, s53, 0x2000
	s_add_u32 s90, s0, 0x40000
	v_lshl_add_u64 v[174:175], s[0:1], 0, v[150:151]
	s_addc_u32 s91, s1, 0
	s_add_i32 s52, s52, s17
	global_load_lds_dwordx4 v[174:175], off
	v_lshl_add_u64 v[184:185], s[90:91], 0, v[0:1]
	s_mov_b32 m0, s52
	v_lshl_add_u64 v[220:221], s[84:85], 0, v[148:149]
	global_load_lds_dwordx4 v[184:185], off
	v_lshl_add_u64 v[184:185], s[90:91], 0, v[150:151]
	s_add_i32 m0, s52, 0x2000
	s_nop 0
	global_load_lds_dwordx4 v[184:185], off
	v_lshl_add_u64 v[184:185], s[84:85], 0, v[146:147]
	s_mov_b32 m0, s19
	s_nop 0
	global_load_lds_dwordx4 v[184:185], off
	s_mov_b32 m0, s44
	s_nop 0
	global_load_lds_dwordx4 v[220:221], off
	s_waitcnt vmcnt(8)
	s_waitcnt lgkmcnt(0)
	s_barrier
; #define PG8_STAGE(bufoff, gbase, voff) do { _Pragma("unroll") for (int _i = 0; _i < 2; ++_i) \
;         __builtin_amdgcn_global_load_lds((const unsigned*)((const char*)(gbase) + (voff)[_i]), (LAS unsigned*)(lds + (bufoff) + ldsw + _i * 8192), 16, 0, 0); } while (0)
; #define PG8_LDA(dst, b, h) do { _Pragma("unroll") for (int m = 0; m < 4; ++m) _Pragma("unroll") for (int k = 0; k < 2; ++k) dst[m][k] = *(const LAS bf16x8*)(lds + PG8_SA(b, h) + aoff + m * 2048 + k * 1024); } while (0)
; #define PG8_LDB(dst, b, h) do { _Pragma("unroll") for (int n = 0; n < 2; ++n) _Pragma("unroll") for (int k = 0; k < 2; ++k) dst[n][k] = *(const LAS bf16x8*)(lds + PG8_SB(b, h) + boff + n * 2048 + k * 1024); } while (0)
; #define PG8_MMA(ai, bj, At, Bt) do { __builtin_amdgcn_s_setprio(1); _Pragma("unroll") for (int m = 0; m < 4; ++m) _Pragma("unroll") for (int n = 0; n < 2; ++n) _Pragma("unroll") for (int k = 0; k < 2; ++k) \
;         acc[ai][bj][m][n] = __builtin_amdgcn_mfma_f32_16x16x32_bf16(Bt[n][k], At[m][k], acc[ai][bj][m][n], 0, 0, 0); __builtin_amdgcn_s_setprio(0); } while (0)
; #define PG8_WAIT_V(n) asm volatile("s_waitcnt vmcnt(" #n ")" ::: "memory")
; #define PG8_BAR __builtin_amdgcn_s_barrier()
; template <class Epi, class Sched>
; __device__ __forceinline__ void gemm_phase(LAS unsigned char* lds, const Gemm g, const Sched& S, const Epi& E) {
;     ...
;             PG8_LDB(B0, 0, 0); PG8_LDB(B1, 0, 1); PG8_SCHED; PG8_LDA(At, 0, 0); PG8_STAGE(PG8_SA(1, 1), a1 + hstepA, voffA);
;             PG8_WAIT_V(8); PG8_WAIT_L(0); PG8_BAR; PG8_MMA(0, 0, At, B0); PG8_MMA(0, 1, At, B1); PG8_BAR; PG8_SCHED;
;             PG8_LDA(At, 0, 1); PG8_STAGE(PG8_SB(0, 0), b2, voffB); PG8_STAGE(PG8_SB(0, 1), b2 + hstepB, voffB); PG8_STAGE(PG8_SA(0, 0), a2, voffA);
;             PG8_WAIT_V(8); PG8_WAIT_L(0); PG8_BAR; PG8_MMA(1, 0, At, B0); PG8_MMA(1, 1, At, B1); PG8_BAR; PG8_SCHED;
;             PG8_LDB(B0, 1, 0); PG8_LDB(B1, 1, 1); PG8_SCHED; PG8_LDA(At, 1, 0); PG8_STAGE(PG8_SA(0, 1), a2 + hstepA, voffA);
;             PG8_WAIT_V(8); PG8_WAIT_L(0); PG8_BAR; PG8_MMA(0, 0, At, B0); PG8_MMA(0, 1, At, B1); PG8_BAR; PG8_SCHED;
;             PG8_LDA(At, 1, 1); PG8_STAGE(PG8_SB(1, 0), b3, voffB); PG8_STAGE(PG8_SB(1, 1), b3 + hstepB, voffB); PG8_STAGE(PG8_SA(1, 0), a3, voffA);
;             PG8_WAIT_V(8); PG8_WAIT_L(0); PG8_BAR; PG8_MMA(1, 0, At, B0); PG8_MMA(1, 1, At, B1); PG8_BAR; PG8_SCHED;
	s_setprio 1
	s_waitcnt lgkmcnt(0)
	v_mfma_f32_16x16x32_bf16 v[62:65], v[130:133], v[196:199], v[62:65]
	v_mfma_f32_16x16x32_bf16 v[58:61], v[138:141], v[196:199], v[58:61]
	v_mfma_f32_16x16x32_bf16 v[46:49], v[130:133], v[204:207], v[46:49]
	v_mfma_f32_16x16x32_bf16 v[42:45], v[138:141], v[204:207], v[42:45]
	v_mfma_f32_16x16x32_bf16 v[30:33], v[130:133], v[212:215], v[30:33]
	v_mfma_f32_16x16x32_bf16 v[26:29], v[138:141], v[212:215], v[26:29]
	v_mfma_f32_16x16x32_bf16 v[14:17], v[130:133], v[232:235], v[14:17]
	v_mfma_f32_16x16x32_bf16 v[10:13], v[138:141], v[232:235], v[10:13]
	v_mfma_f32_16x16x32_bf16 v[62:65], v[134:137], v[200:203], v[62:65]
	v_mfma_f32_16x16x32_bf16 v[58:61], v[142:145], v[200:203], v[58:61]
	v_mfma_f32_16x16x32_bf16 v[46:49], v[134:137], v[208:211], v[46:49]
	v_mfma_f32_16x16x32_bf16 v[42:45], v[142:145], v[208:211], v[42:45]
	v_mfma_f32_16x16x32_bf16 v[30:33], v[134:137], v[216:219], v[30:33]
	v_mfma_f32_16x16x32_bf16 v[26:29], v[142:145], v[216:219], v[26:29]
	v_mfma_f32_16x16x32_bf16 v[14:17], v[134:137], v[248:251], v[14:17]
	v_mfma_f32_16x16x32_bf16 v[10:13], v[142:145], v[248:251], v[10:13]
	v_mfma_f32_16x16x32_bf16 v[54:57], v[156:159], v[196:199], v[54:57]
	v_mfma_f32_16x16x32_bf16 v[50:53], v[164:167], v[196:199], v[50:53]
	v_mfma_f32_16x16x32_bf16 v[38:41], v[156:159], v[204:207], v[38:41]
	v_mfma_f32_16x16x32_bf16 v[34:37], v[164:167], v[204:207], v[34:37]
	v_mfma_f32_16x16x32_bf16 v[22:25], v[156:159], v[212:215], v[22:25]
	v_mfma_f32_16x16x32_bf16 v[18:21], v[164:167], v[212:215], v[18:21]
	v_mfma_f32_16x16x32_bf16 v[6:9], v[156:159], v[232:235], v[6:9]
	v_mfma_f32_16x16x32_bf16 v[2:5], v[164:167], v[232:235], v[2:5]
	v_mfma_f32_16x16x32_bf16 v[54:57], v[160:163], v[200:203], v[54:57]
	v_mfma_f32_16x16x32_bf16 v[50:53], v[180:183], v[200:203], v[50:53]
	v_mfma_f32_16x16x32_bf16 v[38:41], v[160:163], v[208:211], v[38:41]
	v_mfma_f32_16x16x32_bf16 v[34:37], v[180:183], v[208:211], v[34:37]
	v_mfma_f32_16x16x32_bf16 v[22:25], v[160:163], v[216:219], v[22:25]
	v_mfma_f32_16x16x32_bf16 v[18:21], v[180:183], v[216:219], v[18:21]
	v_mfma_f32_16x16x32_bf16 v[6:9], v[160:163], v[248:251], v[6:9]
	v_mfma_f32_16x16x32_bf16 v[2:5], v[180:183], v[248:251], v[2:5]
	s_setprio 0
	s_barrier
	s_add_i32 s52, 0, 0x18000
	s_add_i32 s53, 0, 0x1c000
	v_add_u32_e32 v142, s52, v177
	v_add_u32_e32 v170, s53, v177
	ds_read_b128 v[130:133], v142
	ds_read_b128 v[134:137], v142 offset:1024
	ds_read_b128 v[138:141], v142 offset:2048
	ds_read_b128 v[142:145], v142 offset:3072
	ds_read_b128 v[156:159], v170
	ds_read_b128 v[160:163], v170 offset:1024
	ds_read_b128 v[164:167], v170 offset:2048
	ds_read_b128 v[180:183], v170 offset:3072
	s_add_u32 s84, s84, 0x40000
	s_addc_u32 s85, s85, 0
	s_mov_b32 m0, s46
	v_lshl_add_u64 v[236:237], s[84:85], 0, v[146:147]
	ds_read_b128 v[196:199], v179 offset:32768
	ds_read_b128 v[200:203], v179 offset:33792
	ds_read_b128 v[204:207], v179 offset:34816
	ds_read_b128 v[208:211], v179 offset:35840
	ds_read_b128 v[212:215], v179 offset:36864
	ds_read_b128 v[216:219], v179 offset:37888
	ds_read_b128 v[232:235], v179 offset:38912
	ds_read_b128 v[248:251], v179 offset:39936
	global_load_lds_dwordx4 v[236:237], off
	v_lshl_add_u64 v[236:237], s[84:85], 0, v[148:149]
	s_mov_b32 m0, s47
	s_nop 0
	global_load_lds_dwordx4 v[236:237], off
	s_waitcnt vmcnt(8)
	s_waitcnt lgkmcnt(0)
	s_barrier
	s_setprio 1
	s_waitcnt lgkmcnt(0)
	v_mfma_f32_16x16x32_bf16 v[126:129], v[130:133], v[196:199], v[126:129]
	v_mfma_f32_16x16x32_bf16 v[122:125], v[138:141], v[196:199], v[122:125]
	v_mfma_f32_16x16x32_bf16 v[110:113], v[130:133], v[204:207], v[110:113]
	v_mfma_f32_16x16x32_bf16 v[106:109], v[138:141], v[204:207], v[106:109]
	v_mfma_f32_16x16x32_bf16 v[94:97], v[130:133], v[212:215], v[94:97]
	v_mfma_f32_16x16x32_bf16 v[90:93], v[138:141], v[212:215], v[90:93]
	v_mfma_f32_16x16x32_bf16 v[78:81], v[130:133], v[232:235], v[78:81]
	v_mfma_f32_16x16x32_bf16 v[74:77], v[138:141], v[232:235], v[74:77]
	v_mfma_f32_16x16x32_bf16 v[126:129], v[134:137], v[200:203], v[126:129]
	v_mfma_f32_16x16x32_bf16 v[122:125], v[142:145], v[200:203], v[122:125]
	v_mfma_f32_16x16x32_bf16 v[110:113], v[134:137], v[208:211], v[110:113]
	v_mfma_f32_16x16x32_bf16 v[106:109], v[142:145], v[208:211], v[106:109]
	v_mfma_f32_16x16x32_bf16 v[94:97], v[134:137], v[216:219], v[94:97]
	v_mfma_f32_16x16x32_bf16 v[90:93], v[142:145], v[216:219], v[90:93]
	v_mfma_f32_16x16x32_bf16 v[78:81], v[134:137], v[248:251], v[78:81]
	v_mfma_f32_16x16x32_bf16 v[74:77], v[142:145], v[248:251], v[74:77]
	v_mfma_f32_16x16x32_bf16 v[118:121], v[156:159], v[196:199], v[118:121]
	v_mfma_f32_16x16x32_bf16 v[114:117], v[164:167], v[196:199], v[114:117]
	v_mfma_f32_16x16x32_bf16 v[102:105], v[156:159], v[204:207], v[102:105]
	v_mfma_f32_16x16x32_bf16 v[98:101], v[164:167], v[204:207], v[98:101]
	v_mfma_f32_16x16x32_bf16 v[86:89], v[156:159], v[212:215], v[86:89]
	v_mfma_f32_16x16x32_bf16 v[82:85], v[164:167], v[212:215], v[82:85]
	v_mfma_f32_16x16x32_bf16 v[70:73], v[156:159], v[232:235], v[70:73]
	v_mfma_f32_16x16x32_bf16 v[66:69], v[164:167], v[232:235], v[66:69]
	v_mfma_f32_16x16x32_bf16 v[118:121], v[160:163], v[200:203], v[118:121]
	v_mfma_f32_16x16x32_bf16 v[114:117], v[180:183], v[200:203], v[114:117]
	v_mfma_f32_16x16x32_bf16 v[102:105], v[160:163], v[208:211], v[102:105]
	v_mfma_f32_16x16x32_bf16 v[98:101], v[180:183], v[208:211], v[98:101]
	v_mfma_f32_16x16x32_bf16 v[86:89], v[160:163], v[216:219], v[86:89]
	v_mfma_f32_16x16x32_bf16 v[82:85], v[180:183], v[216:219], v[82:85]
	v_mfma_f32_16x16x32_bf16 v[70:73], v[160:163], v[248:251], v[70:73]
	v_mfma_f32_16x16x32_bf16 v[66:69], v[180:183], v[248:251], v[66:69]
	s_setprio 0
	s_barrier
; #define PG8_STAGE(bufoff, gbase, voff) do { _Pragma("unroll") for (int _i = 0; _i < 2; ++_i) \
;         __builtin_amdgcn_global_load_lds((const unsigned*)((const char*)(gbase) + (voff)[_i]), (LAS unsigned*)(lds + (bufoff) + ldsw + _i * 8192), 16, 0, 0); } while (0)
; #define PG8_LDA(dst, b, h) do { _Pragma("unroll") for (int m = 0; m < 4; ++m) _Pragma("unroll") for (int k = 0; k < 2; ++k) dst[m][k] = *(const LAS bf16x8*)(lds + PG8_SA(b, h) + aoff + m * 2048 + k * 1024); } while (0)
; #define PG8_LDB(dst, b, h) do { _Pragma("unroll") for (int n = 0; n < 2; ++n) _Pragma("unroll") for (int k = 0; k < 2; ++k) dst[n][k] = *(const LAS bf16x8*)(lds + PG8_SB(b, h) + boff + n * 2048 + k * 1024); } while (0)
; #define PG8_MMA(ai, bj, At, Bt) do { __builtin_amdgcn_s_setprio(1); _Pragma("unroll") for (int m = 0; m < 4; ++m) _Pragma("unroll") for (int n = 0; n < 2; ++n) _Pragma("unroll") for (int k = 0; k < 2; ++k) \
;         acc[ai][bj][m][n] = __builtin_amdgcn_mfma_f32_16x16x32_bf16(Bt[n][k], At[m][k], acc[ai][bj][m][n], 0, 0, 0); __builtin_amdgcn_s_setprio(0); } while (0)
; #define PG8_WAIT_V(n) asm volatile("s_waitcnt vmcnt(" #n ")" ::: "memory")
; #define PG8_BAR __builtin_amdgcn_s_barrier()
; template <class Epi, class Sched>
; __device__ __forceinline__ void gemm_phase(LAS unsigned char* lds, const Gemm g, const Sched& S, const Epi& E) {
;     ...
;             PG8_LDB(B0, 0, 0); PG8_LDB(B1, 0, 1); PG8_SCHED; PG8_LDA(At, 0, 0); PG8_STAGE(PG8_SA(1, 1), a1 + hstepA, voffA);
;             PG8_WAIT_V(8); PG8_WAIT_L(0); PG8_BAR; PG8_MMA(0, 0, At, B0); PG8_MMA(0, 1, At, B1); PG8_BAR; PG8_SCHED;
;             PG8_LDA(At, 0, 1); PG8_STAGE(PG8_SB(0, 0), b2, voffB); PG8_STAGE(PG8_SB(0, 1), b2 + hstepB, voffB); PG8_STAGE(PG8_SA(0, 0), a2, voffA);
;             PG8_WAIT_V(8); PG8_WAIT_L(0); PG8_BAR; PG8_MMA(1, 0, At, B0); PG8_MMA(1, 1, At, B1); PG8_BAR; PG8_SCHED;
;             PG8_LDB(B0, 1, 0); PG8_LDB(B1, 1, 1); PG8_SCHED; PG8_LDA(At, 1, 0); PG8_STAGE(PG8_SA(0, 1), a2 + hstepA, voffA);
;             PG8_WAIT_V(8); PG8_WAIT_L(0); PG8_BAR; PG8_MMA(0, 0, At, B0); PG8_MMA(0, 1, At, B1); PG8_BAR; PG8_SCHED;
;             PG8_LDA(At, 1, 1); PG8_STAGE(PG8_SB(1, 0), b3, voffB); PG8_STAGE(PG8_SB(1, 1), b3 + hstepB, voffB); PG8_STAGE(PG8_SA(1, 0), a3, voffA);
;             PG8_WAIT_V(8); PG8_WAIT_L(0); PG8_BAR; PG8_MMA(1, 0, At, B0); PG8_MMA(1, 1, At, B1); PG8_BAR; PG8_SCHED;
;         }
	s_add_i32 s52, s52, s17
	v_lshl_add_u64 v[168:169], v[168:169], 0, s[26:27]
	s_mov_b32 m0, s52
	ds_read_b128 v[196:199], v179 offset:49152
	ds_read_b128 v[200:203], v179 offset:50176
	ds_read_b128 v[204:207], v179 offset:51200
	ds_read_b128 v[208:211], v179 offset:52224
	ds_read_b128 v[212:215], v179 offset:53248
	ds_read_b128 v[216:219], v179 offset:54272
	ds_read_b128 v[232:235], v179 offset:55296
	ds_read_b128 v[248:251], v179 offset:56320
	global_load_lds_dwordx4 v[168:169], off
	s_add_i32 m0, s52, 0x2000
	s_add_u32 s0, s0, 0x40080
	v_lshl_add_u64 v[168:169], v[174:175], 0, s[26:27]
	s_addc_u32 s1, s1, 0
	s_add_i32 s52, s53, s17
	global_load_lds_dwordx4 v[168:169], off
	v_lshl_add_u64 v[168:169], s[0:1], 0, v[0:1]
	s_mov_b32 m0, s52
	s_nop 0
	global_load_lds_dwordx4 v[168:169], off
	v_lshl_add_u64 v[168:169], s[0:1], 0, v[150:151]
	s_add_i32 m0, s52, 0x2000
	s_nop 0
	global_load_lds_dwordx4 v[168:169], off
	v_lshl_add_u64 v[168:169], v[184:185], 0, s[26:27]
	s_mov_b32 m0, s69
	s_nop 0
	global_load_lds_dwordx4 v[168:169], off
	v_lshl_add_u64 v[168:169], v[220:221], 0, s[26:27]
	s_mov_b32 m0, s71
	s_nop 0
	global_load_lds_dwordx4 v[168:169], off
	s_waitcnt vmcnt(8)
	s_waitcnt lgkmcnt(0)
	s_barrier
	s_setprio 1
	s_waitcnt lgkmcnt(0)
	v_mfma_f32_16x16x32_bf16 v[62:65], v[130:133], v[196:199], v[62:65]
	v_mfma_f32_16x16x32_bf16 v[58:61], v[138:141], v[196:199], v[58:61]
	v_mfma_f32_16x16x32_bf16 v[46:49], v[130:133], v[204:207], v[46:49]
	v_mfma_f32_16x16x32_bf16 v[42:45], v[138:141], v[204:207], v[42:45]
	v_mfma_f32_16x16x32_bf16 v[30:33], v[130:133], v[212:215], v[30:33]
	v_mfma_f32_16x16x32_bf16 v[26:29], v[138:141], v[212:215], v[26:29]
	v_mfma_f32_16x16x32_bf16 v[14:17], v[130:133], v[232:235], v[14:17]
	v_mfma_f32_16x16x32_bf16 v[10:13], v[138:141], v[232:235], v[10:13]
	v_mfma_f32_16x16x32_bf16 v[62:65], v[134:137], v[200:203], v[62:65]
	v_mfma_f32_16x16x32_bf16 v[58:61], v[142:145], v[200:203], v[58:61]
	v_mfma_f32_16x16x32_bf16 v[46:49], v[134:137], v[208:211], v[46:49]
	v_mfma_f32_16x16x32_bf16 v[42:45], v[142:145], v[208:211], v[42:45]
	v_mfma_f32_16x16x32_bf16 v[30:33], v[134:137], v[216:219], v[30:33]
	v_mfma_f32_16x16x32_bf16 v[26:29], v[142:145], v[216:219], v[26:29]
	v_mfma_f32_16x16x32_bf16 v[14:17], v[134:137], v[248:251], v[14:17]
	v_mfma_f32_16x16x32_bf16 v[10:13], v[142:145], v[248:251], v[10:13]
	v_mfma_f32_16x16x32_bf16 v[54:57], v[156:159], v[196:199], v[54:57]
	v_mfma_f32_16x16x32_bf16 v[50:53], v[164:167], v[196:199], v[50:53]
	v_mfma_f32_16x16x32_bf16 v[38:41], v[156:159], v[204:207], v[38:41]
	v_mfma_f32_16x16x32_bf16 v[34:37], v[164:167], v[204:207], v[34:37]
	v_mfma_f32_16x16x32_bf16 v[22:25], v[156:159], v[212:215], v[22:25]
	v_mfma_f32_16x16x32_bf16 v[18:21], v[164:167], v[212:215], v[18:21]
	v_mfma_f32_16x16x32_bf16 v[6:9], v[156:159], v[232:235], v[6:9]
	v_mfma_f32_16x16x32_bf16 v[2:5], v[164:167], v[232:235], v[2:5]
	v_mfma_f32_16x16x32_bf16 v[54:57], v[160:163], v[200:203], v[54:57]
	v_mfma_f32_16x16x32_bf16 v[50:53], v[180:183], v[200:203], v[50:53]
	v_mfma_f32_16x16x32_bf16 v[38:41], v[160:163], v[208:211], v[38:41]
	v_mfma_f32_16x16x32_bf16 v[34:37], v[180:183], v[208:211], v[34:37]
	v_mfma_f32_16x16x32_bf16 v[22:25], v[160:163], v[216:219], v[22:25]
	v_mfma_f32_16x16x32_bf16 v[18:21], v[180:183], v[216:219], v[18:21]
	v_mfma_f32_16x16x32_bf16 v[6:9], v[160:163], v[248:251], v[6:9]
	v_mfma_f32_16x16x32_bf16 v[2:5], v[180:183], v[248:251], v[2:5]
	s_setprio 0
	s_barrier
	s_add_u32 s88, s88, 0x100
	s_addc_u32 s89, s89, 0
	s_add_u32 s20, s20, 0x100
	s_addc_u32 s21, s21, 0
	s_cmp_ge_i32 s68, s48
	s_mov_b32 s0, s68
	s_cbranch_scc0 .LBB0_209

; #define PG8_STAGE(bufoff, gbase, voff) do { _Pragma("unroll") for (int _i = 0; _i < 2; ++_i) \
;         __builtin_amdgcn_global_load_lds((const unsigned*)((const char*)(gbase) + (voff)[_i]), (LAS unsigned*)(lds + (bufoff) + ldsw + _i * 8192), 16, 0, 0); } while (0)
; #define PG8_LDA(dst, b, h) do { _Pragma("unroll") for (int m = 0; m < 4; ++m) _Pragma("unroll") for (int k = 0; k < 2; ++k) dst[m][k] = *(const LAS bf16x8*)(lds + PG8_SA(b, h) + aoff + m * 2048 + k * 1024); } while (0)
; #define PG8_LDB(dst, b, h) do { _Pragma("unroll") for (int n = 0; n < 2; ++n) _Pragma("unroll") for (int k = 0; k < 2; ++k) dst[n][k] = *(const LAS bf16x8*)(lds + PG8_SB(b, h) + boff + n * 2048 + k * 1024); } while (0)
; #define PG8_MMA(ai, bj, At, Bt) do { __builtin_amdgcn_s_setprio(1); _Pragma("unroll") for (int m = 0; m < 4; ++m) _Pragma("unroll") for (int n = 0; n < 2; ++n) _Pragma("unroll") for (int k = 0; k < 2; ++k) \
;         acc[ai][bj][m][n] = __builtin_amdgcn_mfma_f32_16x16x32_bf16(Bt[n][k], At[m][k], acc[ai][bj][m][n], 0, 0, 0); __builtin_amdgcn_s_setprio(0); } while (0)
; #define PG8_WAIT_V(n) asm volatile("s_waitcnt vmcnt(" #n ")" ::: "memory")
; #define PG8_WAIT_L(n) asm volatile("s_waitcnt lgkmcnt(" #n ")" ::: "memory")
; #define PG8_BAR __builtin_amdgcn_s_barrier()
; #define PG8_SCHED __builtin_amdgcn_sched_barrier(0)
; template <class Epi, class Sched>
; __device__ __forceinline__ void gemm_phase(LAS unsigned char* lds, const Gemm g, const Sched& S, const Epi& E) {
;     ...
;             const char* a1 = cA + (size_t)(t + 1) * kstep;
;             const char* a2 = last ? nA : cA + (size_t)(t + 2) * kstep; const char* b2 = last ? nB : cB + (size_t)(t + 2) * kstep;
;             const char* a3 = a2 + kstep; const char* b3 = b2 + kstep;
;             PG8_LDB(B0, 0, 0); PG8_LDB(B1, 0, 1); PG8_SCHED; PG8_LDA(At, 0, 0); PG8_STAGE(PG8_SA(1, 1), a1 + hstepA, voffA);
;             PG8_WAIT_V(8); PG8_WAIT_L(0); PG8_BAR; PG8_MMA(0, 0, At, B0); PG8_MMA(0, 1, At, B1); PG8_BAR; PG8_SCHED;
;             PG8_LDA(At, 0, 1); PG8_STAGE(PG8_SB(0, 0), b2, voffB); PG8_STAGE(PG8_SB(0, 1), b2 + hstepB, voffB); PG8_STAGE(PG8_SA(0, 0), a2, voffA);
;             PG8_WAIT_V(8); PG8_WAIT_L(0); PG8_BAR; PG8_MMA(1, 0, At, B0); PG8_MMA(1, 1, At, B1); PG8_BAR; PG8_SCHED;
.LBB0_238:
	s_add_i32 s68, s0, 2
	s_add_u32 s1, s20, 0xfffc0080
	s_addc_u32 s52, s21, -1
	s_add_i32 s53, 0, 0x10000
	s_cmp_eq_u32 s71, s0
	s_cselect_b32 s89, s48, s52
	s_cselect_b32 s88, s59, s1
	s_cselect_b32 s1, s63, s90
	s_cselect_b32 s0, s85, s87
	s_add_i32 s52, 0, 0x14000
	v_add_u32_e32 v152, s53, v164
	v_add_u32_e32 v160, s52, v164
	ds_read_b128 v[130:133], v152
	ds_read_b128 v[134:137], v152 offset:1024
	ds_read_b128 v[138:141], v152 offset:2048
	ds_read_b128 v[152:155], v152 offset:3072
	ds_read_b128 v[156:159], v160
	ds_read_b128 v[166:169], v160 offset:1024
	ds_read_b128 v[170:173], v160 offset:2048
	ds_read_b128 v[174:177], v160 offset:3072
	v_lshl_add_u64 v[160:161], s[20:21], 0, v[150:151]
	s_add_i32 m0, s15, 0xc000
	ds_read_b128 v[178:181], v165
	ds_read_b128 v[182:185], v165 offset:1024
	ds_read_b128 v[196:199], v165 offset:2048
	ds_read_b128 v[200:203], v165 offset:3072
	ds_read_b128 v[204:207], v165 offset:4096
	ds_read_b128 v[208:211], v165 offset:5120
	ds_read_b128 v[212:215], v165 offset:6144
	ds_read_b128 v[216:219], v165 offset:7168
	global_load_lds_dwordx4 v[160:161], off
	v_lshl_add_u64 v[160:161], s[20:21], 0, v[148:149]
	s_add_i32 m0, s15, 0xe000
	s_nop 0
	global_load_lds_dwordx4 v[160:161], off
	s_waitcnt vmcnt(8)
	s_waitcnt lgkmcnt(0)
	s_barrier
	s_setprio 1
	s_waitcnt lgkmcnt(0)
	v_mfma_f32_16x16x32_bf16 v[126:129], v[130:133], v[178:181], v[126:129]
	v_mfma_f32_16x16x32_bf16 v[122:125], v[138:141], v[178:181], v[122:125]
	v_mfma_f32_16x16x32_bf16 v[110:113], v[130:133], v[196:199], v[110:113]
	v_mfma_f32_16x16x32_bf16 v[106:109], v[138:141], v[196:199], v[106:109]
	v_mfma_f32_16x16x32_bf16 v[94:97], v[130:133], v[204:207], v[94:97]
	v_mfma_f32_16x16x32_bf16 v[90:93], v[138:141], v[204:207], v[90:93]
	v_mfma_f32_16x16x32_bf16 v[78:81], v[130:133], v[212:215], v[78:81]
	v_mfma_f32_16x16x32_bf16 v[74:77], v[138:141], v[212:215], v[74:77]
	v_mfma_f32_16x16x32_bf16 v[126:129], v[134:137], v[182:185], v[126:129]
	v_mfma_f32_16x16x32_bf16 v[122:125], v[152:155], v[182:185], v[122:125]
	v_mfma_f32_16x16x32_bf16 v[110:113], v[134:137], v[200:203], v[110:113]
	v_mfma_f32_16x16x32_bf16 v[106:109], v[152:155], v[200:203], v[106:109]
	v_mfma_f32_16x16x32_bf16 v[94:97], v[134:137], v[208:211], v[94:97]
	v_mfma_f32_16x16x32_bf16 v[90:93], v[152:155], v[208:211], v[90:93]
	v_mfma_f32_16x16x32_bf16 v[78:81], v[134:137], v[216:219], v[78:81]
	v_mfma_f32_16x16x32_bf16 v[74:77], v[152:155], v[216:219], v[74:77]
	v_mfma_f32_16x16x32_bf16 v[118:121], v[156:159], v[178:181], v[118:121]
	v_mfma_f32_16x16x32_bf16 v[114:117], v[170:173], v[178:181], v[114:117]
	v_mfma_f32_16x16x32_bf16 v[102:105], v[156:159], v[196:199], v[102:105]
	v_mfma_f32_16x16x32_bf16 v[98:101], v[170:173], v[196:199], v[98:101]
	v_mfma_f32_16x16x32_bf16 v[86:89], v[156:159], v[204:207], v[86:89]
	v_mfma_f32_16x16x32_bf16 v[82:85], v[170:173], v[204:207], v[82:85]
	v_mfma_f32_16x16x32_bf16 v[70:73], v[156:159], v[212:215], v[70:73]
	v_mfma_f32_16x16x32_bf16 v[66:69], v[170:173], v[212:215], v[66:69]
	v_mfma_f32_16x16x32_bf16 v[118:121], v[166:169], v[182:185], v[118:121]
	v_mfma_f32_16x16x32_bf16 v[114:117], v[174:177], v[182:185], v[114:117]
	v_mfma_f32_16x16x32_bf16 v[102:105], v[166:169], v[200:203], v[102:105]
	v_mfma_f32_16x16x32_bf16 v[98:101], v[174:177], v[200:203], v[98:101]
	v_mfma_f32_16x16x32_bf16 v[86:89], v[166:169], v[208:211], v[86:89]
	v_mfma_f32_16x16x32_bf16 v[82:85], v[174:177], v[208:211], v[82:85]
	v_mfma_f32_16x16x32_bf16 v[70:73], v[166:169], v[216:219], v[70:73]
	v_mfma_f32_16x16x32_bf16 v[66:69], v[174:177], v[216:219], v[66:69]
	s_setprio 0
	s_barrier
	s_add_i32 s53, s53, s14
	v_lshl_add_u64 v[160:161], s[0:1], 0, v[0:1]
	s_mov_b32 m0, s53
	ds_read_b128 v[178:181], v165 offset:16384
	ds_read_b128 v[182:185], v165 offset:17408
	ds_read_b128 v[196:199], v165 offset:18432
	ds_read_b128 v[200:203], v165 offset:19456
	ds_read_b128 v[204:207], v165 offset:20480
	ds_read_b128 v[208:211], v165 offset:21504
	ds_read_b128 v[212:215], v165 offset:22528
	ds_read_b128 v[216:219], v165 offset:23552
	global_load_lds_dwordx4 v[160:161], off
	s_add_i32 m0, s53, 0x2000
	s_add_u32 s92, s0, 0x40000
	v_lshl_add_u64 v[220:221], s[0:1], 0, v[146:147]
	s_addc_u32 s93, s1, 0
	s_add_i32 s52, s52, s14
	global_load_lds_dwordx4 v[220:221], off
	v_lshl_add_u64 v[232:233], s[92:93], 0, v[0:1]
	s_mov_b32 m0, s52
	v_lshl_add_u64 v[234:235], s[88:89], 0, v[144:145]
	global_load_lds_dwordx4 v[232:233], off
	v_lshl_add_u64 v[232:233], s[92:93], 0, v[146:147]
	s_add_i32 m0, s52, 0x2000
	s_nop 0
	global_load_lds_dwordx4 v[232:233], off
	v_lshl_add_u64 v[232:233], s[88:89], 0, v[142:143]
	s_mov_b32 m0, s15
	s_nop 0
	global_load_lds_dwordx4 v[232:233], off
	s_mov_b32 m0, s16
	s_nop 0
	global_load_lds_dwordx4 v[234:235], off
	s_waitcnt vmcnt(8)
	s_waitcnt lgkmcnt(0)
	s_barrier
; #define PG8_STAGE(bufoff, gbase, voff) do { _Pragma("unroll") for (int _i = 0; _i < 2; ++_i) \
;         __builtin_amdgcn_global_load_lds((const unsigned*)((const char*)(gbase) + (voff)[_i]), (LAS unsigned*)(lds + (bufoff) + ldsw + _i * 8192), 16, 0, 0); } while (0)
; #define PG8_LDA(dst, b, h) do { _Pragma("unroll") for (int m = 0; m < 4; ++m) _Pragma("unroll") for (int k = 0; k < 2; ++k) dst[m][k] = *(const LAS bf16x8*)(lds + PG8_SA(b, h) + aoff + m * 2048 + k * 1024); } while (0)
; #define PG8_LDB(dst, b, h) do { _Pragma("unroll") for (int n = 0; n < 2; ++n) _Pragma("unroll") for (int k = 0; k < 2; ++k) dst[n][k] = *(const LAS bf16x8*)(lds + PG8_SB(b, h) + boff + n * 2048 + k * 1024); } while (0)
; #define PG8_MMA(ai, bj, At, Bt) do { __builtin_amdgcn_s_setprio(1); _Pragma("unroll") for (int m = 0; m < 4; ++m) _Pragma("unroll") for (int n = 0; n < 2; ++n) _Pragma("unroll") for (int k = 0; k < 2; ++k) \
;         acc[ai][bj][m][n] = __builtin_amdgcn_mfma_f32_16x16x32_bf16(Bt[n][k], At[m][k], acc[ai][bj][m][n], 0, 0, 0); __builtin_amdgcn_s_setprio(0); } while (0)
; #define PG8_WAIT_V(n) asm volatile("s_waitcnt vmcnt(" #n ")" ::: "memory")
; #define PG8_WAIT_L(n) asm volatile("s_waitcnt lgkmcnt(" #n ")" ::: "memory")
; #define PG8_BAR __builtin_amdgcn_s_barrier()
; #define PG8_SCHED __builtin_amdgcn_sched_barrier(0)
; template <class Epi, class Sched>
; __device__ __forceinline__ void gemm_phase(LAS unsigned char* lds, const Gemm g, const Sched& S, const Epi& E) {
;     ...
;             PG8_WAIT_V(8); PG8_WAIT_L(0); PG8_BAR; PG8_MMA(1, 0, At, B0); PG8_MMA(1, 1, At, B1); PG8_BAR; PG8_SCHED;
;             PG8_LDB(B0, 1, 0); PG8_LDB(B1, 1, 1); PG8_SCHED; PG8_LDA(At, 1, 0); PG8_STAGE(PG8_SA(0, 1), a2 + hstepA, voffA);
;             PG8_WAIT_V(8); PG8_WAIT_L(0); PG8_BAR; PG8_MMA(0, 0, At, B0); PG8_MMA(0, 1, At, B1); PG8_BAR; PG8_SCHED;
	s_setprio 1
	s_waitcnt lgkmcnt(0)
	v_mfma_f32_16x16x32_bf16 v[62:65], v[130:133], v[178:181], v[62:65]
	v_mfma_f32_16x16x32_bf16 v[58:61], v[138:141], v[178:181], v[58:61]
	v_mfma_f32_16x16x32_bf16 v[46:49], v[130:133], v[196:199], v[46:49]
	v_mfma_f32_16x16x32_bf16 v[42:45], v[138:141], v[196:199], v[42:45]
	v_mfma_f32_16x16x32_bf16 v[30:33], v[130:133], v[204:207], v[30:33]
	v_mfma_f32_16x16x32_bf16 v[26:29], v[138:141], v[204:207], v[26:29]
	v_mfma_f32_16x16x32_bf16 v[14:17], v[130:133], v[212:215], v[14:17]
	v_mfma_f32_16x16x32_bf16 v[10:13], v[138:141], v[212:215], v[10:13]
	v_mfma_f32_16x16x32_bf16 v[62:65], v[134:137], v[182:185], v[62:65]
	v_mfma_f32_16x16x32_bf16 v[58:61], v[152:155], v[182:185], v[58:61]
	v_mfma_f32_16x16x32_bf16 v[46:49], v[134:137], v[200:203], v[46:49]
	v_mfma_f32_16x16x32_bf16 v[42:45], v[152:155], v[200:203], v[42:45]
	v_mfma_f32_16x16x32_bf16 v[30:33], v[134:137], v[208:211], v[30:33]
	v_mfma_f32_16x16x32_bf16 v[26:29], v[152:155], v[208:211], v[26:29]
	v_mfma_f32_16x16x32_bf16 v[14:17], v[134:137], v[216:219], v[14:17]
	v_mfma_f32_16x16x32_bf16 v[10:13], v[152:155], v[216:219], v[10:13]
	v_mfma_f32_16x16x32_bf16 v[54:57], v[156:159], v[178:181], v[54:57]
	v_mfma_f32_16x16x32_bf16 v[50:53], v[170:173], v[178:181], v[50:53]
	v_mfma_f32_16x16x32_bf16 v[38:41], v[156:159], v[196:199], v[38:41]
	v_mfma_f32_16x16x32_bf16 v[34:37], v[170:173], v[196:199], v[34:37]
	v_mfma_f32_16x16x32_bf16 v[22:25], v[156:159], v[204:207], v[22:25]
	v_mfma_f32_16x16x32_bf16 v[18:21], v[170:173], v[204:207], v[18:21]
	v_mfma_f32_16x16x32_bf16 v[6:9], v[156:159], v[212:215], v[6:9]
	v_mfma_f32_16x16x32_bf16 v[2:5], v[170:173], v[212:215], v[2:5]
	v_mfma_f32_16x16x32_bf16 v[54:57], v[166:169], v[182:185], v[54:57]
	v_mfma_f32_16x16x32_bf16 v[50:53], v[174:177], v[182:185], v[50:53]
	v_mfma_f32_16x16x32_bf16 v[38:41], v[166:169], v[200:203], v[38:41]
	v_mfma_f32_16x16x32_bf16 v[34:37], v[174:177], v[200:203], v[34:37]
	v_mfma_f32_16x16x32_bf16 v[22:25], v[166:169], v[208:211], v[22:25]
	v_mfma_f32_16x16x32_bf16 v[18:21], v[174:177], v[208:211], v[18:21]
	v_mfma_f32_16x16x32_bf16 v[6:9], v[166:169], v[216:219], v[6:9]
	v_mfma_f32_16x16x32_bf16 v[2:5], v[174:177], v[216:219], v[2:5]
	s_setprio 0
	s_barrier
	s_add_i32 s52, 0, 0x18000
	s_add_i32 s53, 0, 0x1c000
	v_add_u32_e32 v152, s52, v164
	v_add_u32_e32 v174, s53, v164
	ds_read_b128 v[130:133], v152
	ds_read_b128 v[134:137], v152 offset:1024
	ds_read_b128 v[138:141], v152 offset:2048
	ds_read_b128 v[152:155], v152 offset:3072
	ds_read_b128 v[156:159], v174
	ds_read_b128 v[166:169], v174 offset:1024
	ds_read_b128 v[170:173], v174 offset:2048
	ds_read_b128 v[174:177], v174 offset:3072
	s_add_u32 s88, s88, 0x40000
	s_addc_u32 s89, s89, 0
	s_mov_b32 m0, s17
	v_lshl_add_u64 v[236:237], s[88:89], 0, v[142:143]
	ds_read_b128 v[178:181], v165 offset:32768
	ds_read_b128 v[182:185], v165 offset:33792
	ds_read_b128 v[196:199], v165 offset:34816
	ds_read_b128 v[200:203], v165 offset:35840
	ds_read_b128 v[204:207], v165 offset:36864
	ds_read_b128 v[208:211], v165 offset:37888
	ds_read_b128 v[212:215], v165 offset:38912
	ds_read_b128 v[216:219], v165 offset:39936
	global_load_lds_dwordx4 v[236:237], off
	v_lshl_add_u64 v[236:237], s[88:89], 0, v[144:145]
	s_mov_b32 m0, s19
	s_nop 0
	global_load_lds_dwordx4 v[236:237], off
	s_waitcnt vmcnt(8)
	s_waitcnt lgkmcnt(0)
	s_barrier
	s_setprio 1
	s_waitcnt lgkmcnt(0)
	v_mfma_f32_16x16x32_bf16 v[126:129], v[130:133], v[178:181], v[126:129]
	v_mfma_f32_16x16x32_bf16 v[122:125], v[138:141], v[178:181], v[122:125]
	v_mfma_f32_16x16x32_bf16 v[110:113], v[130:133], v[196:199], v[110:113]
	v_mfma_f32_16x16x32_bf16 v[106:109], v[138:141], v[196:199], v[106:109]
	v_mfma_f32_16x16x32_bf16 v[94:97], v[130:133], v[204:207], v[94:97]
	v_mfma_f32_16x16x32_bf16 v[90:93], v[138:141], v[204:207], v[90:93]
	v_mfma_f32_16x16x32_bf16 v[78:81], v[130:133], v[212:215], v[78:81]
	v_mfma_f32_16x16x32_bf16 v[74:77], v[138:141], v[212:215], v[74:77]
	v_mfma_f32_16x16x32_bf16 v[126:129], v[134:137], v[182:185], v[126:129]
	v_mfma_f32_16x16x32_bf16 v[122:125], v[152:155], v[182:185], v[122:125]
	v_mfma_f32_16x16x32_bf16 v[110:113], v[134:137], v[200:203], v[110:113]
	v_mfma_f32_16x16x32_bf16 v[106:109], v[152:155], v[200:203], v[106:109]
	v_mfma_f32_16x16x32_bf16 v[94:97], v[134:137], v[208:211], v[94:97]
	v_mfma_f32_16x16x32_bf16 v[90:93], v[152:155], v[208:211], v[90:93]
	v_mfma_f32_16x16x32_bf16 v[78:81], v[134:137], v[216:219], v[78:81]
	v_mfma_f32_16x16x32_bf16 v[74:77], v[152:155], v[216:219], v[74:77]
	v_mfma_f32_16x16x32_bf16 v[118:121], v[156:159], v[178:181], v[118:121]
	v_mfma_f32_16x16x32_bf16 v[114:117], v[170:173], v[178:181], v[114:117]
	v_mfma_f32_16x16x32_bf16 v[102:105], v[156:159], v[196:199], v[102:105]
	v_mfma_f32_16x16x32_bf16 v[98:101], v[170:173], v[196:199], v[98:101]
	v_mfma_f32_16x16x32_bf16 v[86:89], v[156:159], v[204:207], v[86:89]
	v_mfma_f32_16x16x32_bf16 v[82:85], v[170:173], v[204:207], v[82:85]
	v_mfma_f32_16x16x32_bf16 v[70:73], v[156:159], v[212:215], v[70:73]
	v_mfma_f32_16x16x32_bf16 v[66:69], v[170:173], v[212:215], v[66:69]
	v_mfma_f32_16x16x32_bf16 v[118:121], v[166:169], v[182:185], v[118:121]
	v_mfma_f32_16x16x32_bf16 v[114:117], v[174:177], v[182:185], v[114:117]
	v_mfma_f32_16x16x32_bf16 v[102:105], v[166:169], v[200:203], v[102:105]
	v_mfma_f32_16x16x32_bf16 v[98:101], v[174:177], v[200:203], v[98:101]
	v_mfma_f32_16x16x32_bf16 v[86:89], v[166:169], v[208:211], v[86:89]
	v_mfma_f32_16x16x32_bf16 v[82:85], v[174:177], v[208:211], v[82:85]
	v_mfma_f32_16x16x32_bf16 v[70:73], v[166:169], v[216:219], v[70:73]
	v_mfma_f32_16x16x32_bf16 v[66:69], v[174:177], v[216:219], v[66:69]
	s_setprio 0
	s_barrier
; #define PG8_STAGE(bufoff, gbase, voff) do { _Pragma("unroll") for (int _i = 0; _i < 2; ++_i) \
;         __builtin_amdgcn_global_load_lds((const unsigned*)((const char*)(gbase) + (voff)[_i]), (LAS unsigned*)(lds + (bufoff) + ldsw + _i * 8192), 16, 0, 0); } while (0)
; #define PG8_LDA(dst, b, h) do { _Pragma("unroll") for (int m = 0; m < 4; ++m) _Pragma("unroll") for (int k = 0; k < 2; ++k) dst[m][k] = *(const LAS bf16x8*)(lds + PG8_SA(b, h) + aoff + m * 2048 + k * 1024); } while (0)
; #define PG8_MMA(ai, bj, At, Bt) do { __builtin_amdgcn_s_setprio(1); _Pragma("unroll") for (int m = 0; m < 4; ++m) _Pragma("unroll") for (int n = 0; n < 2; ++n) _Pragma("unroll") for (int k = 0; k < 2; ++k) \
;         acc[ai][bj][m][n] = __builtin_amdgcn_mfma_f32_16x16x32_bf16(Bt[n][k], At[m][k], acc[ai][bj][m][n], 0, 0, 0); __builtin_amdgcn_s_setprio(0); } while (0)
; #define PG8_WAIT_V(n) asm volatile("s_waitcnt vmcnt(" #n ")" ::: "memory")
; #define PG8_WAIT_L(n) asm volatile("s_waitcnt lgkmcnt(" #n ")" ::: "memory")
; #define PG8_BAR __builtin_amdgcn_s_barrier()
; #define PG8_SCHED __builtin_amdgcn_sched_barrier(0)
; template <class Epi, class Sched>
; __device__ __forceinline__ void gemm_phase(LAS unsigned char* lds, const Gemm g, const Sched& S, const Epi& E) {
;     ...
;             PG8_LDA(At, 1, 1); PG8_STAGE(PG8_SB(1, 0), b3, voffB); PG8_STAGE(PG8_SB(1, 1), b3 + hstepB, voffB); PG8_STAGE(PG8_SA(1, 0), a3, voffA);
;             PG8_WAIT_V(8); PG8_WAIT_L(0); PG8_BAR; PG8_MMA(1, 0, At, B0); PG8_MMA(1, 1, At, B1); PG8_BAR; PG8_SCHED;
;         }
	s_add_i32 s52, s52, s14
	v_lshl_add_u64 v[160:161], v[160:161], 0, s[26:27]
	s_mov_b32 m0, s52
	ds_read_b128 v[178:181], v165 offset:49152
	ds_read_b128 v[182:185], v165 offset:50176
	ds_read_b128 v[196:199], v165 offset:51200
	ds_read_b128 v[200:203], v165 offset:52224
	ds_read_b128 v[204:207], v165 offset:53248
	ds_read_b128 v[208:211], v165 offset:54272
	ds_read_b128 v[212:215], v165 offset:55296
	ds_read_b128 v[216:219], v165 offset:56320
	global_load_lds_dwordx4 v[160:161], off
	s_add_i32 m0, s52, 0x2000
	s_add_u32 s0, s0, 0x40080
	v_lshl_add_u64 v[160:161], v[220:221], 0, s[26:27]
	s_addc_u32 s1, s1, 0
	s_add_i32 s52, s53, s14
	global_load_lds_dwordx4 v[160:161], off
	v_lshl_add_u64 v[160:161], s[0:1], 0, v[0:1]
	s_mov_b32 m0, s52
	s_nop 0
	global_load_lds_dwordx4 v[160:161], off
	v_lshl_add_u64 v[160:161], s[0:1], 0, v[146:147]
	s_add_i32 m0, s52, 0x2000
	s_nop 0
	global_load_lds_dwordx4 v[160:161], off
	v_lshl_add_u64 v[160:161], v[232:233], 0, s[26:27]
	s_mov_b32 m0, s67
	s_nop 0
	global_load_lds_dwordx4 v[160:161], off
	v_lshl_add_u64 v[160:161], v[234:235], 0, s[26:27]
	s_mov_b32 m0, s69
	s_nop 0
	global_load_lds_dwordx4 v[160:161], off
	s_waitcnt vmcnt(8)
	s_waitcnt lgkmcnt(0)
	s_barrier
	s_setprio 1
	s_waitcnt lgkmcnt(0)
	v_mfma_f32_16x16x32_bf16 v[62:65], v[130:133], v[178:181], v[62:65]
	v_mfma_f32_16x16x32_bf16 v[58:61], v[138:141], v[178:181], v[58:61]
	v_mfma_f32_16x16x32_bf16 v[46:49], v[130:133], v[196:199], v[46:49]
	v_mfma_f32_16x16x32_bf16 v[42:45], v[138:141], v[196:199], v[42:45]
	v_mfma_f32_16x16x32_bf16 v[30:33], v[130:133], v[204:207], v[30:33]
	v_mfma_f32_16x16x32_bf16 v[26:29], v[138:141], v[204:207], v[26:29]
	v_mfma_f32_16x16x32_bf16 v[14:17], v[130:133], v[212:215], v[14:17]
	v_mfma_f32_16x16x32_bf16 v[10:13], v[138:141], v[212:215], v[10:13]
	v_mfma_f32_16x16x32_bf16 v[62:65], v[134:137], v[182:185], v[62:65]
	v_mfma_f32_16x16x32_bf16 v[58:61], v[152:155], v[182:185], v[58:61]
	v_mfma_f32_16x16x32_bf16 v[46:49], v[134:137], v[200:203], v[46:49]
	v_mfma_f32_16x16x32_bf16 v[42:45], v[152:155], v[200:203], v[42:45]
	v_mfma_f32_16x16x32_bf16 v[30:33], v[134:137], v[208:211], v[30:33]
	v_mfma_f32_16x16x32_bf16 v[26:29], v[152:155], v[208:211], v[26:29]
	v_mfma_f32_16x16x32_bf16 v[14:17], v[134:137], v[216:219], v[14:17]
	v_mfma_f32_16x16x32_bf16 v[10:13], v[152:155], v[216:219], v[10:13]
	v_mfma_f32_16x16x32_bf16 v[54:57], v[156:159], v[178:181], v[54:57]
	v_mfma_f32_16x16x32_bf16 v[50:53], v[170:173], v[178:181], v[50:53]
	v_mfma_f32_16x16x32_bf16 v[38:41], v[156:159], v[196:199], v[38:41]
	v_mfma_f32_16x16x32_bf16 v[34:37], v[170:173], v[196:199], v[34:37]
	v_mfma_f32_16x16x32_bf16 v[22:25], v[156:159], v[204:207], v[22:25]
	v_mfma_f32_16x16x32_bf16 v[18:21], v[170:173], v[204:207], v[18:21]
	v_mfma_f32_16x16x32_bf16 v[6:9], v[156:159], v[212:215], v[6:9]
	v_mfma_f32_16x16x32_bf16 v[2:5], v[170:173], v[212:215], v[2:5]
	v_mfma_f32_16x16x32_bf16 v[54:57], v[166:169], v[182:185], v[54:57]
	v_mfma_f32_16x16x32_bf16 v[50:53], v[174:177], v[182:185], v[50:53]
	v_mfma_f32_16x16x32_bf16 v[38:41], v[166:169], v[200:203], v[38:41]
	v_mfma_f32_16x16x32_bf16 v[34:37], v[174:177], v[200:203], v[34:37]
	v_mfma_f32_16x16x32_bf16 v[22:25], v[166:169], v[208:211], v[22:25]
	v_mfma_f32_16x16x32_bf16 v[18:21], v[174:177], v[208:211], v[18:21]
	v_mfma_f32_16x16x32_bf16 v[6:9], v[166:169], v[216:219], v[6:9]
	v_mfma_f32_16x16x32_bf16 v[2:5], v[174:177], v[216:219], v[2:5]
	s_setprio 0
	s_barrier
	s_add_u32 s87, s87, 0x100
	s_addc_u32 s90, s90, 0
	s_add_u32 s20, s20, 0x100
	s_addc_u32 s21, s21, 0
	s_cmp_ge_i32 s68, s46
	s_mov_b32 s0, s68
	s_cbranch_scc0 .LBB0_238

; #define PG8_STAGE(bufoff, gbase, voff) do { _Pragma("unroll") for (int _i = 0; _i < 2; ++_i) \
;         __builtin_amdgcn_global_load_lds((const unsigned*)((const char*)(gbase) + (voff)[_i]), (LAS unsigned*)(lds + (bufoff) + ldsw + _i * 8192), 16, 0, 0); } while (0)
; #define PG8_LDA(dst, b, h) do { _Pragma("unroll") for (int m = 0; m < 4; ++m) _Pragma("unroll") for (int k = 0; k < 2; ++k) dst[m][k] = *(const LAS bf16x8*)(lds + PG8_SA(b, h) + aoff + m * 2048 + k * 1024); } while (0)
; #define PG8_LDB(dst, b, h) do { _Pragma("unroll") for (int n = 0; n < 2; ++n) _Pragma("unroll") for (int k = 0; k < 2; ++k) dst[n][k] = *(const LAS bf16x8*)(lds + PG8_SB(b, h) + boff + n * 2048 + k * 1024); } while (0)
; #define PG8_MMA(ai, bj, At, Bt) do { __builtin_amdgcn_s_setprio(1); _Pragma("unroll") for (int m = 0; m < 4; ++m) _Pragma("unroll") for (int n = 0; n < 2; ++n) _Pragma("unroll") for (int k = 0; k < 2; ++k) \
;         acc[ai][bj][m][n] = __builtin_amdgcn_mfma_f32_16x16x32_bf16(Bt[n][k], At[m][k], acc[ai][bj][m][n], 0, 0, 0); __builtin_amdgcn_s_setprio(0); } while (0)
; #define PG8_WAIT_V(n) asm volatile("s_waitcnt vmcnt(" #n ")" ::: "memory")
; #define PG8_WAIT_L(n) asm volatile("s_waitcnt lgkmcnt(" #n ")" ::: "memory")
; #define PG8_BAR __builtin_amdgcn_s_barrier()
; #define PG8_SCHED __builtin_amdgcn_sched_barrier(0)
; template <class Epi, class Sched>
; __device__ __forceinline__ void gemm_phase(LAS unsigned char* lds, const Gemm g, const Sched& S, const Epi& E) {
;     ...
;             const char* a1 = cA + (size_t)(t + 1) * kstep;
;             const char* a2 = last ? nA : cA + (size_t)(t + 2) * kstep; const char* b2 = last ? nB : cB + (size_t)(t + 2) * kstep;
;             const char* a3 = a2 + kstep; const char* b3 = b2 + kstep;
;             PG8_LDB(B0, 0, 0); PG8_LDB(B1, 0, 1); PG8_SCHED; PG8_LDA(At, 0, 0); PG8_STAGE(PG8_SA(1, 1), a1 + hstepA, voffA);
;             PG8_WAIT_V(8); PG8_WAIT_L(0); PG8_BAR; PG8_MMA(0, 0, At, B0); PG8_MMA(0, 1, At, B1); PG8_BAR; PG8_SCHED;
;             PG8_LDA(At, 0, 1); PG8_STAGE(PG8_SB(0, 0), b2, voffB); PG8_STAGE(PG8_SB(0, 1), b2 + hstepB, voffB); PG8_STAGE(PG8_SA(0, 0), a2, voffA);
;             PG8_WAIT_V(8); PG8_WAIT_L(0); PG8_BAR; PG8_MMA(1, 0, At, B0); PG8_MMA(1, 1, At, B1); PG8_BAR; PG8_SCHED;
.LBB0_291:
	s_add_i32 s68, s19, 2
	s_add_u32 s0, s30, s40
	s_addc_u32 s1, s31, s41
	s_add_u32 s0, s0, 0x100
	s_addc_u32 s1, s1, 0
	s_add_u32 s52, s69, s40
	s_addc_u32 s53, s72, s41
	s_add_i32 s76, 0, 0x10000
	s_cmp_eq_u32 s71, s19
	s_cselect_b32 s21, s16, s1
	s_cselect_b32 s20, s17, s0
	s_cselect_b32 s1, s87, s53
	s_cselect_b32 s0, s86, s52
	s_add_i32 s19, 0, 0x14000
	v_add_u32_e32 v142, s76, v195
	v_add_u32_e32 v172, s19, v195
	ds_read_b128 v[130:133], v142
	ds_read_b128 v[134:137], v142 offset:1024
	ds_read_b128 v[138:141], v142 offset:2048
	ds_read_b128 v[142:145], v142 offset:3072
	ds_read_b128 v[146:149], v172
	ds_read_b128 v[164:167], v172 offset:1024
	ds_read_b128 v[168:171], v172 offset:2048
	ds_read_b128 v[172:175], v172 offset:3072
	v_lshl_add_u64 v[182:183], v[162:163], 0, s[40:41]
	s_add_i32 m0, s25, 0xc000
	ds_read_b128 v[176:179], v199
	ds_read_b128 v[200:203], v199 offset:1024
	ds_read_b128 v[204:207], v199 offset:2048
	ds_read_b128 v[208:211], v199 offset:3072
	ds_read_b128 v[212:215], v199 offset:4096
	ds_read_b128 v[216:219], v199 offset:5120
	ds_read_b128 v[232:235], v199 offset:6144
	ds_read_b128 v[248:251], v199 offset:7168
	global_load_lds_dwordx4 v[182:183], off
	v_lshl_add_u64 v[182:183], v[160:161], 0, s[40:41]
	s_add_i32 m0, s25, 0xe000
	s_nop 0
	global_load_lds_dwordx4 v[182:183], off
	s_waitcnt vmcnt(8)
	s_waitcnt lgkmcnt(0)
	s_barrier
	s_setprio 1
	s_waitcnt lgkmcnt(0)
	v_mfma_f32_16x16x32_bf16 v[126:129], v[130:133], v[176:179], v[126:129]
	v_mfma_f32_16x16x32_bf16 v[122:125], v[138:141], v[176:179], v[122:125]
	v_mfma_f32_16x16x32_bf16 v[118:121], v[130:133], v[204:207], v[118:121]
	v_mfma_f32_16x16x32_bf16 v[114:117], v[138:141], v[204:207], v[114:117]
	v_mfma_f32_16x16x32_bf16 v[110:113], v[130:133], v[212:215], v[110:113]
	v_mfma_f32_16x16x32_bf16 v[106:109], v[138:141], v[212:215], v[106:109]
	v_mfma_f32_16x16x32_bf16 v[102:105], v[130:133], v[232:235], v[102:105]
	v_mfma_f32_16x16x32_bf16 v[98:101], v[138:141], v[232:235], v[98:101]
	v_mfma_f32_16x16x32_bf16 v[126:129], v[134:137], v[200:203], v[126:129]
	v_mfma_f32_16x16x32_bf16 v[122:125], v[142:145], v[200:203], v[122:125]
	v_mfma_f32_16x16x32_bf16 v[118:121], v[134:137], v[208:211], v[118:121]
	v_mfma_f32_16x16x32_bf16 v[114:117], v[142:145], v[208:211], v[114:117]
	v_mfma_f32_16x16x32_bf16 v[110:113], v[134:137], v[216:219], v[110:113]
	v_mfma_f32_16x16x32_bf16 v[106:109], v[142:145], v[216:219], v[106:109]
	v_mfma_f32_16x16x32_bf16 v[102:105], v[134:137], v[248:251], v[102:105]
	v_mfma_f32_16x16x32_bf16 v[98:101], v[142:145], v[248:251], v[98:101]
	v_mfma_f32_16x16x32_bf16 v[62:65], v[146:149], v[176:179], v[62:65]
	v_mfma_f32_16x16x32_bf16 v[58:61], v[168:171], v[176:179], v[58:61]
	v_mfma_f32_16x16x32_bf16 v[54:57], v[146:149], v[204:207], v[54:57]
	v_mfma_f32_16x16x32_bf16 v[50:53], v[168:171], v[204:207], v[50:53]
	v_mfma_f32_16x16x32_bf16 v[46:49], v[146:149], v[212:215], v[46:49]
	v_mfma_f32_16x16x32_bf16 v[42:45], v[168:171], v[212:215], v[42:45]
	v_mfma_f32_16x16x32_bf16 v[38:41], v[146:149], v[232:235], v[38:41]
	v_mfma_f32_16x16x32_bf16 v[34:37], v[168:171], v[232:235], v[34:37]
	v_mfma_f32_16x16x32_bf16 v[62:65], v[164:167], v[200:203], v[62:65]
	v_mfma_f32_16x16x32_bf16 v[58:61], v[172:175], v[200:203], v[58:61]
	v_mfma_f32_16x16x32_bf16 v[54:57], v[164:167], v[208:211], v[54:57]
	v_mfma_f32_16x16x32_bf16 v[50:53], v[172:175], v[208:211], v[50:53]
	v_mfma_f32_16x16x32_bf16 v[46:49], v[164:167], v[216:219], v[46:49]
	v_mfma_f32_16x16x32_bf16 v[42:45], v[172:175], v[216:219], v[42:45]
	v_mfma_f32_16x16x32_bf16 v[38:41], v[164:167], v[248:251], v[38:41]
	v_mfma_f32_16x16x32_bf16 v[34:37], v[172:175], v[248:251], v[34:37]
	s_setprio 0
	s_barrier
	s_add_i32 s52, s76, s92
	v_lshl_add_u64 v[182:183], s[0:1], 0, v[0:1]
	s_mov_b32 m0, s52
	ds_read_b128 v[176:179], v199 offset:16384
	ds_read_b128 v[200:203], v199 offset:17408
	ds_read_b128 v[204:207], v199 offset:18432
	ds_read_b128 v[208:211], v199 offset:19456
	ds_read_b128 v[212:215], v199 offset:20480
	ds_read_b128 v[216:219], v199 offset:21504
	ds_read_b128 v[232:235], v199 offset:22528
	ds_read_b128 v[248:251], v199 offset:23552
	global_load_lds_dwordx4 v[182:183], off
	s_add_i32 m0, s52, 0x2000
	s_add_u32 vcc_lo, s0, 0x40000
	v_lshl_add_u64 v[196:197], s[0:1], 0, v[154:155]
	s_addc_u32 vcc_hi, s1, 0
	s_add_i32 s19, s19, s92
	global_load_lds_dwordx4 v[196:197], off
	v_lshl_add_u64 v[220:221], vcc, 0, v[0:1]
	s_mov_b32 m0, s19
	v_lshl_add_u64 v[236:237], s[20:21], 0, v[152:153]
	global_load_lds_dwordx4 v[220:221], off
	v_lshl_add_u64 v[220:221], vcc, 0, v[154:155]
	s_add_i32 m0, s19, 0x2000
	s_nop 0
	global_load_lds_dwordx4 v[220:221], off
	v_lshl_add_u64 v[220:221], s[20:21], 0, v[150:151]
	s_mov_b32 m0, s25
	s_nop 0
	global_load_lds_dwordx4 v[220:221], off
	s_mov_b32 m0, s93
	s_nop 0
	global_load_lds_dwordx4 v[236:237], off
	s_waitcnt vmcnt(8)
	s_waitcnt lgkmcnt(0)
	s_barrier
; #define PG8_STAGE(bufoff, gbase, voff) do { _Pragma("unroll") for (int _i = 0; _i < 2; ++_i) \
;         __builtin_amdgcn_global_load_lds((const unsigned*)((const char*)(gbase) + (voff)[_i]), (LAS unsigned*)(lds + (bufoff) + ldsw + _i * 8192), 16, 0, 0); } while (0)
; #define PG8_LDA(dst, b, h) do { _Pragma("unroll") for (int m = 0; m < 4; ++m) _Pragma("unroll") for (int k = 0; k < 2; ++k) dst[m][k] = *(const LAS bf16x8*)(lds + PG8_SA(b, h) + aoff + m * 2048 + k * 1024); } while (0)
; #define PG8_LDB(dst, b, h) do { _Pragma("unroll") for (int n = 0; n < 2; ++n) _Pragma("unroll") for (int k = 0; k < 2; ++k) dst[n][k] = *(const LAS bf16x8*)(lds + PG8_SB(b, h) + boff + n * 2048 + k * 1024); } while (0)
; #define PG8_MMA(ai, bj, At, Bt) do { __builtin_amdgcn_s_setprio(1); _Pragma("unroll") for (int m = 0; m < 4; ++m) _Pragma("unroll") for (int n = 0; n < 2; ++n) _Pragma("unroll") for (int k = 0; k < 2; ++k) \
;         acc[ai][bj][m][n] = __builtin_amdgcn_mfma_f32_16x16x32_bf16(Bt[n][k], At[m][k], acc[ai][bj][m][n], 0, 0, 0); __builtin_amdgcn_s_setprio(0); } while (0)
; #define PG8_WAIT_V(n) asm volatile("s_waitcnt vmcnt(" #n ")" ::: "memory")
; #define PG8_WAIT_L(n) asm volatile("s_waitcnt lgkmcnt(" #n ")" ::: "memory")
; #define PG8_BAR __builtin_amdgcn_s_barrier()
; #define PG8_SCHED __builtin_amdgcn_sched_barrier(0)
; template <class Epi, class Sched>
; __device__ __forceinline__ void gemm_phase(LAS unsigned char* lds, const Gemm g, const Sched& S, const Epi& E) {
;     ...
;             PG8_WAIT_V(8); PG8_WAIT_L(0); PG8_BAR; PG8_MMA(1, 0, At, B0); PG8_MMA(1, 1, At, B1); PG8_BAR; PG8_SCHED;
;             PG8_LDB(B0, 1, 0); PG8_LDB(B1, 1, 1); PG8_SCHED; PG8_LDA(At, 1, 0); PG8_STAGE(PG8_SA(0, 1), a2 + hstepA, voffA);
;             PG8_WAIT_V(8); PG8_WAIT_L(0); PG8_BAR; PG8_MMA(0, 0, At, B0); PG8_MMA(0, 1, At, B1); PG8_BAR; PG8_SCHED;
	s_setprio 1
	s_waitcnt lgkmcnt(0)
	v_mfma_f32_16x16x32_bf16 v[94:97], v[130:133], v[176:179], v[94:97]
	v_mfma_f32_16x16x32_bf16 v[90:93], v[138:141], v[176:179], v[90:93]
	v_mfma_f32_16x16x32_bf16 v[86:89], v[130:133], v[204:207], v[86:89]
	v_mfma_f32_16x16x32_bf16 v[82:85], v[138:141], v[204:207], v[82:85]
	v_mfma_f32_16x16x32_bf16 v[78:81], v[130:133], v[212:215], v[78:81]
	v_mfma_f32_16x16x32_bf16 v[74:77], v[138:141], v[212:215], v[74:77]
	v_mfma_f32_16x16x32_bf16 v[70:73], v[130:133], v[232:235], v[70:73]
	v_mfma_f32_16x16x32_bf16 v[66:69], v[138:141], v[232:235], v[66:69]
	v_mfma_f32_16x16x32_bf16 v[94:97], v[134:137], v[200:203], v[94:97]
	v_mfma_f32_16x16x32_bf16 v[90:93], v[142:145], v[200:203], v[90:93]
	v_mfma_f32_16x16x32_bf16 v[86:89], v[134:137], v[208:211], v[86:89]
	v_mfma_f32_16x16x32_bf16 v[82:85], v[142:145], v[208:211], v[82:85]
	v_mfma_f32_16x16x32_bf16 v[78:81], v[134:137], v[216:219], v[78:81]
	v_mfma_f32_16x16x32_bf16 v[74:77], v[142:145], v[216:219], v[74:77]
	v_mfma_f32_16x16x32_bf16 v[70:73], v[134:137], v[248:251], v[70:73]
	v_mfma_f32_16x16x32_bf16 v[66:69], v[142:145], v[248:251], v[66:69]
	v_mfma_f32_16x16x32_bf16 v[30:33], v[146:149], v[176:179], v[30:33]
	v_mfma_f32_16x16x32_bf16 v[26:29], v[168:171], v[176:179], v[26:29]
	v_mfma_f32_16x16x32_bf16 v[22:25], v[146:149], v[204:207], v[22:25]
	v_mfma_f32_16x16x32_bf16 v[18:21], v[168:171], v[204:207], v[18:21]
	v_mfma_f32_16x16x32_bf16 v[14:17], v[146:149], v[212:215], v[14:17]
	v_mfma_f32_16x16x32_bf16 v[10:13], v[168:171], v[212:215], v[10:13]
	v_mfma_f32_16x16x32_bf16 v[6:9], v[146:149], v[232:235], v[6:9]
	v_mfma_f32_16x16x32_bf16 v[2:5], v[168:171], v[232:235], v[2:5]
	v_mfma_f32_16x16x32_bf16 v[30:33], v[164:167], v[200:203], v[30:33]
	v_mfma_f32_16x16x32_bf16 v[26:29], v[172:175], v[200:203], v[26:29]
	v_mfma_f32_16x16x32_bf16 v[22:25], v[164:167], v[208:211], v[22:25]
	v_mfma_f32_16x16x32_bf16 v[18:21], v[172:175], v[208:211], v[18:21]
	v_mfma_f32_16x16x32_bf16 v[14:17], v[164:167], v[216:219], v[14:17]
	v_mfma_f32_16x16x32_bf16 v[10:13], v[172:175], v[216:219], v[10:13]
	v_mfma_f32_16x16x32_bf16 v[6:9], v[164:167], v[248:251], v[6:9]
	v_mfma_f32_16x16x32_bf16 v[2:5], v[172:175], v[248:251], v[2:5]
	s_setprio 0
	s_barrier
	s_add_i32 s19, 0, 0x18000
	s_add_i32 s52, 0, 0x1c000
	v_add_u32_e32 v142, s19, v195
	v_add_u32_e32 v172, s52, v195
	ds_read_b128 v[130:133], v142
	ds_read_b128 v[134:137], v142 offset:1024
	ds_read_b128 v[138:141], v142 offset:2048
	ds_read_b128 v[142:145], v142 offset:3072
	ds_read_b128 v[146:149], v172
	ds_read_b128 v[164:167], v172 offset:1024
	ds_read_b128 v[168:171], v172 offset:2048
	ds_read_b128 v[172:175], v172 offset:3072
	s_add_u32 s20, s20, 0x40000
	s_addc_u32 s21, s21, 0
	s_mov_b32 m0, s94
	v_lshl_add_u64 v[246:247], s[20:21], 0, v[150:151]
	ds_read_b128 v[176:179], v199 offset:32768
	ds_read_b128 v[200:203], v199 offset:33792
	ds_read_b128 v[204:207], v199 offset:34816
	ds_read_b128 v[208:211], v199 offset:35840
	ds_read_b128 v[212:215], v199 offset:36864
	ds_read_b128 v[216:219], v199 offset:37888
	ds_read_b128 v[232:235], v199 offset:38912
	ds_read_b128 v[248:251], v199 offset:39936
	global_load_lds_dwordx4 v[246:247], off
	v_lshl_add_u64 v[246:247], s[20:21], 0, v[152:153]
	s_mov_b32 m0, s95
	s_nop 0
	global_load_lds_dwordx4 v[246:247], off
	s_waitcnt vmcnt(8)
	s_waitcnt lgkmcnt(0)
	s_barrier
	s_setprio 1
	s_waitcnt lgkmcnt(0)
	v_mfma_f32_16x16x32_bf16 v[126:129], v[130:133], v[176:179], v[126:129]
	v_mfma_f32_16x16x32_bf16 v[122:125], v[138:141], v[176:179], v[122:125]
	v_mfma_f32_16x16x32_bf16 v[118:121], v[130:133], v[204:207], v[118:121]
	v_mfma_f32_16x16x32_bf16 v[114:117], v[138:141], v[204:207], v[114:117]
	v_mfma_f32_16x16x32_bf16 v[110:113], v[130:133], v[212:215], v[110:113]
	v_mfma_f32_16x16x32_bf16 v[106:109], v[138:141], v[212:215], v[106:109]
	v_mfma_f32_16x16x32_bf16 v[102:105], v[130:133], v[232:235], v[102:105]
	v_mfma_f32_16x16x32_bf16 v[98:101], v[138:141], v[232:235], v[98:101]
	v_mfma_f32_16x16x32_bf16 v[126:129], v[134:137], v[200:203], v[126:129]
	v_mfma_f32_16x16x32_bf16 v[122:125], v[142:145], v[200:203], v[122:125]
	v_mfma_f32_16x16x32_bf16 v[118:121], v[134:137], v[208:211], v[118:121]
	v_mfma_f32_16x16x32_bf16 v[114:117], v[142:145], v[208:211], v[114:117]
	v_mfma_f32_16x16x32_bf16 v[110:113], v[134:137], v[216:219], v[110:113]
	v_mfma_f32_16x16x32_bf16 v[106:109], v[142:145], v[216:219], v[106:109]
	v_mfma_f32_16x16x32_bf16 v[102:105], v[134:137], v[248:251], v[102:105]
	v_mfma_f32_16x16x32_bf16 v[98:101], v[142:145], v[248:251], v[98:101]
	v_mfma_f32_16x16x32_bf16 v[62:65], v[146:149], v[176:179], v[62:65]
	v_mfma_f32_16x16x32_bf16 v[58:61], v[168:171], v[176:179], v[58:61]
	v_mfma_f32_16x16x32_bf16 v[54:57], v[146:149], v[204:207], v[54:57]
	v_mfma_f32_16x16x32_bf16 v[50:53], v[168:171], v[204:207], v[50:53]
	v_mfma_f32_16x16x32_bf16 v[46:49], v[146:149], v[212:215], v[46:49]
	v_mfma_f32_16x16x32_bf16 v[42:45], v[168:171], v[212:215], v[42:45]
	v_mfma_f32_16x16x32_bf16 v[38:41], v[146:149], v[232:235], v[38:41]
	v_mfma_f32_16x16x32_bf16 v[34:37], v[168:171], v[232:235], v[34:37]
	v_mfma_f32_16x16x32_bf16 v[62:65], v[164:167], v[200:203], v[62:65]
	v_mfma_f32_16x16x32_bf16 v[58:61], v[172:175], v[200:203], v[58:61]
	v_mfma_f32_16x16x32_bf16 v[54:57], v[164:167], v[208:211], v[54:57]
	v_mfma_f32_16x16x32_bf16 v[50:53], v[172:175], v[208:211], v[50:53]
	v_mfma_f32_16x16x32_bf16 v[46:49], v[164:167], v[216:219], v[46:49]
	v_mfma_f32_16x16x32_bf16 v[42:45], v[172:175], v[216:219], v[42:45]
	v_mfma_f32_16x16x32_bf16 v[38:41], v[164:167], v[248:251], v[38:41]
	v_mfma_f32_16x16x32_bf16 v[34:37], v[172:175], v[248:251], v[34:37]
	s_setprio 0
	s_barrier
; #define PG8_STAGE(bufoff, gbase, voff) do { _Pragma("unroll") for (int _i = 0; _i < 2; ++_i) \
;         __builtin_amdgcn_global_load_lds((const unsigned*)((const char*)(gbase) + (voff)[_i]), (LAS unsigned*)(lds + (bufoff) + ldsw + _i * 8192), 16, 0, 0); } while (0)
; #define PG8_LDA(dst, b, h) do { _Pragma("unroll") for (int m = 0; m < 4; ++m) _Pragma("unroll") for (int k = 0; k < 2; ++k) dst[m][k] = *(const LAS bf16x8*)(lds + PG8_SA(b, h) + aoff + m * 2048 + k * 1024); } while (0)
; #define PG8_MMA(ai, bj, At, Bt) do { __builtin_amdgcn_s_setprio(1); _Pragma("unroll") for (int m = 0; m < 4; ++m) _Pragma("unroll") for (int n = 0; n < 2; ++n) _Pragma("unroll") for (int k = 0; k < 2; ++k) \
;         acc[ai][bj][m][n] = __builtin_amdgcn_mfma_f32_16x16x32_bf16(Bt[n][k], At[m][k], acc[ai][bj][m][n], 0, 0, 0); __builtin_amdgcn_s_setprio(0); } while (0)
; #define PG8_WAIT_V(n) asm volatile("s_waitcnt vmcnt(" #n ")" ::: "memory")
; #define PG8_WAIT_L(n) asm volatile("s_waitcnt lgkmcnt(" #n ")" ::: "memory")
; #define PG8_BAR __builtin_amdgcn_s_barrier()
; #define PG8_SCHED __builtin_amdgcn_sched_barrier(0)
; template <class Epi, class Sched>
; __device__ __forceinline__ void gemm_phase(LAS unsigned char* lds, const Gemm g, const Sched& S, const Epi& E) {
;     ...
;             PG8_LDA(At, 1, 1); PG8_STAGE(PG8_SB(1, 0), b3, voffB); PG8_STAGE(PG8_SB(1, 1), b3 + hstepB, voffB); PG8_STAGE(PG8_SA(1, 0), a3, voffA);
;             PG8_WAIT_V(8); PG8_WAIT_L(0); PG8_BAR; PG8_MMA(1, 0, At, B0); PG8_MMA(1, 1, At, B1); PG8_BAR; PG8_SCHED;
;         }
	s_add_i32 s19, s19, s92
	v_lshl_add_u64 v[182:183], v[182:183], 0, s[26:27]
	s_mov_b32 m0, s19
	ds_read_b128 v[176:179], v199 offset:49152
	ds_read_b128 v[200:203], v199 offset:50176
	ds_read_b128 v[204:207], v199 offset:51200
	ds_read_b128 v[208:211], v199 offset:52224
	ds_read_b128 v[212:215], v199 offset:53248
	ds_read_b128 v[216:219], v199 offset:54272
	ds_read_b128 v[232:235], v199 offset:55296
	ds_read_b128 v[248:251], v199 offset:56320
	global_load_lds_dwordx4 v[182:183], off
	s_add_i32 m0, s19, 0x2000
	s_add_u32 s0, s0, 0x40080
	v_lshl_add_u64 v[182:183], v[196:197], 0, s[26:27]
	s_addc_u32 s1, s1, 0
	s_add_i32 s19, s52, s92
	global_load_lds_dwordx4 v[182:183], off
	v_lshl_add_u64 v[182:183], s[0:1], 0, v[0:1]
	s_mov_b32 m0, s19
	s_nop 0
	global_load_lds_dwordx4 v[182:183], off
	v_lshl_add_u64 v[182:183], s[0:1], 0, v[154:155]
	s_add_i32 m0, s19, 0x2000
	s_nop 0
	global_load_lds_dwordx4 v[182:183], off
	v_lshl_add_u64 v[182:183], v[220:221], 0, s[26:27]
	s_mov_b32 m0, s97
	s_nop 0
	global_load_lds_dwordx4 v[182:183], off
	v_lshl_add_u64 v[182:183], v[236:237], 0, s[26:27]
	s_mov_b32 m0, s44
	s_nop 0
	global_load_lds_dwordx4 v[182:183], off
	s_waitcnt vmcnt(8)
	s_waitcnt lgkmcnt(0)
	s_barrier
	s_setprio 1
	s_waitcnt lgkmcnt(0)
	v_mfma_f32_16x16x32_bf16 v[94:97], v[130:133], v[176:179], v[94:97]
	v_mfma_f32_16x16x32_bf16 v[90:93], v[138:141], v[176:179], v[90:93]
	v_mfma_f32_16x16x32_bf16 v[86:89], v[130:133], v[204:207], v[86:89]
	v_mfma_f32_16x16x32_bf16 v[82:85], v[138:141], v[204:207], v[82:85]
	v_mfma_f32_16x16x32_bf16 v[78:81], v[130:133], v[212:215], v[78:81]
	v_mfma_f32_16x16x32_bf16 v[74:77], v[138:141], v[212:215], v[74:77]
	v_mfma_f32_16x16x32_bf16 v[70:73], v[130:133], v[232:235], v[70:73]
	v_mfma_f32_16x16x32_bf16 v[66:69], v[138:141], v[232:235], v[66:69]
	v_mfma_f32_16x16x32_bf16 v[94:97], v[134:137], v[200:203], v[94:97]
	v_mfma_f32_16x16x32_bf16 v[90:93], v[142:145], v[200:203], v[90:93]
	v_mfma_f32_16x16x32_bf16 v[86:89], v[134:137], v[208:211], v[86:89]
	v_mfma_f32_16x16x32_bf16 v[82:85], v[142:145], v[208:211], v[82:85]
	v_mfma_f32_16x16x32_bf16 v[78:81], v[134:137], v[216:219], v[78:81]
	v_mfma_f32_16x16x32_bf16 v[74:77], v[142:145], v[216:219], v[74:77]
	v_mfma_f32_16x16x32_bf16 v[70:73], v[134:137], v[248:251], v[70:73]
	v_mfma_f32_16x16x32_bf16 v[66:69], v[142:145], v[248:251], v[66:69]
	v_mfma_f32_16x16x32_bf16 v[30:33], v[146:149], v[176:179], v[30:33]
	v_mfma_f32_16x16x32_bf16 v[26:29], v[168:171], v[176:179], v[26:29]
	v_mfma_f32_16x16x32_bf16 v[22:25], v[146:149], v[204:207], v[22:25]
	v_mfma_f32_16x16x32_bf16 v[18:21], v[168:171], v[204:207], v[18:21]
	v_mfma_f32_16x16x32_bf16 v[14:17], v[146:149], v[212:215], v[14:17]
	v_mfma_f32_16x16x32_bf16 v[10:13], v[168:171], v[212:215], v[10:13]
	v_mfma_f32_16x16x32_bf16 v[6:9], v[146:149], v[232:235], v[6:9]
	v_mfma_f32_16x16x32_bf16 v[2:5], v[168:171], v[232:235], v[2:5]
	v_mfma_f32_16x16x32_bf16 v[30:33], v[164:167], v[200:203], v[30:33]
	v_mfma_f32_16x16x32_bf16 v[26:29], v[172:175], v[200:203], v[26:29]
	v_mfma_f32_16x16x32_bf16 v[22:25], v[164:167], v[208:211], v[22:25]
	v_mfma_f32_16x16x32_bf16 v[18:21], v[172:175], v[208:211], v[18:21]
	v_mfma_f32_16x16x32_bf16 v[14:17], v[164:167], v[216:219], v[14:17]
	v_mfma_f32_16x16x32_bf16 v[10:13], v[172:175], v[216:219], v[10:13]
	v_mfma_f32_16x16x32_bf16 v[6:9], v[164:167], v[248:251], v[6:9]
	v_mfma_f32_16x16x32_bf16 v[2:5], v[172:175], v[248:251], v[2:5]
	s_setprio 0
	s_barrier
	s_add_u32 s40, s40, 0x100
	s_addc_u32 s41, s41, 0
	s_cmp_ge_i32 s68, s46
	s_cbranch_scc0 .LBB0_284

; #define LAS __attribute__((address_space(3)))
; __device__ __forceinline__ unsigned pk2(float lo, float hi) { f32x2 v = {lo, hi}; bf16x2_t b = __builtin_convertvector(v, bf16x2_t); return __builtin_bit_cast(unsigned, b); }
; template <bool MASKED> ...
;     ...
; #pragma unroll
;     for (int r = 0; r < 16; ++r) { s0[r] = __builtin_amdgcn_exp2f(s0[r]); s1[r] = __builtin_amdgcn_exp2f(s1[r]); }
;     u32x4 pw[4];
;     pw[0] = (u32x4){pk2(s0[0], s0[1]), pk2(s0[2], s0[3]), pk2(s0[4], s0[5]), pk2(s0[6], s0[7])};
;     pw[1] = (u32x4){pk2(s0[8], s0[9]), pk2(s0[10], s0[11]), pk2(s0[12], s0[13]), pk2(s0[14], s0[15])};
;     pw[2] = (u32x4){pk2(s1[0], s1[1]), pk2(s1[2], s1[3]), pk2(s1[4], s1[5]), pk2(s1[6], s1[7])};
;     pw[3] = (u32x4){pk2(s1[8], s1[9]), pk2(s1[10], s1[11]), pk2(s1[12], s1[13]), pk2(s1[14], s1[15])};
; #pragma unroll
;     for (int ks = 0; ks < 4; ++ks) {
;         const s16x4 a0 = *(const LAS s16x4*)(vb + 32 * ks), a1 = *(const LAS s16x4*)(vb + 32 * ks + 16);
;         const s16x4 c0 = *(const LAS s16x4*)(vb + 32 * AV_PITCH + 32 * ks), c1 = *(const LAS s16x4*)(vb + 32 * AV_PITCH + 32 * ks + 16);
;         const bf16x8 vf0 = (bf16x8){a0[0], a0[1], a0[2], a0[3], a1[0], a1[1], a1[2], a1[3]}, vf1 = (bf16x8){c0[0], c0[1], c0[2], c0[3], c1[0], c1[1], c1[2], c1[3]};
;         const bf16x8 pf = __builtin_bit_cast(bf16x8, pw[ks]);
;         o0 = __builtin_amdgcn_mfma_f32_32x32x16_bf16(vf0, pf, o0, 0, 0, 0); o1 = __builtin_amdgcn_mfma_f32_32x32x16_bf16(vf1, pf, o1, 0, 0, 0);
;         o2 = __builtin_amdgcn_mfma_f32_32x32x16_bf16(ones, pf, o2, 0, 0, 0);
;     }
.LBB0_317:
	v_exp_f32_e32 v90, v98
	v_exp_f32_e32 v14, v14
	v_exp_f32_e32 v91, v99
	v_exp_f32_e32 v15, v15
	v_exp_f32_e32 v80, v80
	v_exp_f32_e32 v81, v81
	v_exp_f32_e32 v66, v66
	v_exp_f32_e32 v67, v67
	v_exp_f32_e32 v64, v64
	v_exp_f32_e32 v65, v65
	v_exp_f32_e32 v98, v73
	v_exp_f32_e32 v73, v84
	v_exp_f32_e32 v84, v74
	v_exp_f32_e32 v74, v85
	v_exp_f32_e32 v85, v75
	v_exp_f32_e32 v75, v86
	v_exp_f32_e32 v86, v76
	v_exp_f32_e32 v76, v87
	v_exp_f32_e32 v82, v82
	v_exp_f32_e32 v83, v83
	v_exp_f32_e32 v87, v77
	v_exp_f32_e32 v77, v88
	v_exp_f32_e32 v88, v78
	v_exp_f32_e32 v78, v89
	v_exp_f32_e32 v92, v96
	v_exp_f32_e32 v93, v97
	v_exp_f32_e32 v94, v68
	v_exp_f32_e32 v95, v69
	v_exp_f32_e32 v96, v70
	v_exp_f32_e32 v97, v72
	v_exp_f32_e32 v72, v71
	v_add_f32_e32 v250, v250, v90
	v_add_f32_e32 v250, v250, v91
	v_cvt_pk_bf16_f32 v68, v90, v91
	v_add_f32_e32 v250, v250, v80
	v_add_f32_e32 v251, v251, v81
	v_cvt_pk_bf16_f32 v69, v80, v81
	v_add_f32_e32 v250, v250, v66
	v_add_f32_e32 v251, v251, v67
	v_cvt_pk_bf16_f32 v70, v66, v67
	v_add_f32_e32 v250, v250, v64
	v_add_f32_e32 v251, v251, v65
	v_cvt_pk_bf16_f32 v71, v64, v65
	v_add_f32_e32 v251, v251, v73
	v_add_f32_e32 v251, v251, v74
	v_cvt_pk_bf16_f32 v73, v73, v74
	v_add_f32_e32 v251, v251, v75
	v_add_f32_e32 v251, v251, v76
	v_cvt_pk_bf16_f32 v74, v75, v76
	v_add_f32_e32 v251, v251, v14
	v_add_f32_e32 v251, v251, v15
	v_cvt_pk_bf16_f32 v76, v14, v15
	v_add_u32_e32 v14, 0x6000, v209
	v_add_u32_e32 v15, 0x4000, v209
	v_add_f32_e32 v251, v251, v77
	v_add_f32_e32 v251, v251, v78
	v_cvt_pk_bf16_f32 v75, v77, v78
	v_add_f32_e32 v250, v250, v82
	v_add_f32_e32 v251, v251, v83
	v_cvt_pk_bf16_f32 v78, v82, v83
	v_add_f32_e32 v250, v250, v84
	v_add_f32_e32 v250, v250, v85
	v_cvt_pk_bf16_f32 v65, v84, v85
	v_add_f32_e32 v250, v250, v86
	v_add_f32_e32 v250, v250, v87
	v_cvt_pk_bf16_f32 v66, v86, v87
	s_nop 0
	ds_read2_b64 v[80:83], v14 offset0:112 offset1:114
	ds_read2_b64 v[84:87], v15 offset0:80 offset1:82
	v_exp_f32_e32 v89, v79
	v_add_f32_e32 v250, v250, v96
	v_add_f32_e32 v250, v250, v72
	v_cvt_pk_bf16_f32 v72, v96, v72
	v_add_f32_e32 v250, v250, v92
	v_add_f32_e32 v251, v251, v93
	v_cvt_pk_bf16_f32 v77, v92, v93
	v_add_f32_e32 v250, v250, v94
	v_add_f32_e32 v251, v251, v95
	v_cvt_pk_bf16_f32 v79, v94, v95
	v_add_f32_e32 v250, v250, v88
	v_add_f32_e32 v251, v251, v89
	v_cvt_pk_bf16_f32 v67, v88, v89
	s_waitcnt lgkmcnt(0)
	v_mfma_f32_32x32x16_bf16 v[32:47], v[84:87], v[68:71], v[32:47]
	ds_read2_b64 v[88:91], v15 offset0:84 offset1:86
	v_add_f32_e32 v250, v250, v98
	v_add_f32_e32 v251, v251, v97
	v_cvt_pk_bf16_f32 v64, v97, v98
	v_mfma_f32_32x32x16_bf16 v[16:31], v[80:83], v[68:71], v[16:31]
	ds_read2_b64 v[68:71], v14 offset0:116 offset1:118
	s_waitcnt lgkmcnt(1)
	v_mfma_f32_32x32x16_bf16 v[32:47], v[88:91], v[72:75], v[32:47]
	s_waitcnt lgkmcnt(0)
	v_mfma_f32_32x32x16_bf16 v[16:31], v[68:71], v[72:75], v[16:31]
	ds_read2_b64 v[68:71], v15 offset0:88 offset1:90
	s_nop 0
	ds_read2_b64 v[72:75], v14 offset0:120 offset1:122
	s_waitcnt lgkmcnt(1)
	v_mfma_f32_32x32x16_bf16 v[32:47], v[68:71], v[76:79], v[32:47]
	ds_read2_b64 v[68:71], v15 offset0:92 offset1:94
	s_waitcnt lgkmcnt(1)
	v_mfma_f32_32x32x16_bf16 v[16:31], v[72:75], v[76:79], v[16:31]
	ds_read2_b64 v[72:75], v14 offset0:124 offset1:126
	s_nop 0
	s_waitcnt lgkmcnt(1)
	v_mfma_f32_32x32x16_bf16 v[32:47], v[68:71], v[64:67], v[32:47]
	s_waitcnt lgkmcnt(0)
	v_mfma_f32_32x32x16_bf16 v[16:31], v[72:75], v[64:67], v[16:31]
	s_nop 0
; #define LAS __attribute__((address_space(3)))
; __device__ __forceinline__ unsigned pk2(float lo, float hi) { f32x2 v = {lo, hi}; bf16x2_t b = __builtin_convertvector(v, bf16x2_t); return __builtin_bit_cast(unsigned, b); }
; __device__ __forceinline__ void attn_unit(int b, int h, int qb, const bf16_t* __restrict__ Q, const bf16_t* __restrict__ Kb, const bf16_t* __restrict__ Vt, bf16_t* __restrict__ O, LAS unsigned char* lds) {
;     ...
;     int J = 0;
;     for (; J < NT2 - 2; J += 2) { ATT_ITER(false, J, sA, sB, 0); ATT_ITER(false, J + 1, sB, sA, 1); }
;     { ATT_ITER(true, J, sA, sB, 0); ATT_ITER(true, J + 1, sB, sA, 1); }
;     ...
;     const float ltot = __shfl(o2[0], r32), inv = 1.0f / ltot;
;     LAS unsigned char* stg = lds + AV_OFF + 2 * AV_BYTES + wid * (32 * 136);
; #pragma unroll
;     for (int gI = 0; gI < 4; ++gI) {
;         u32x2 w0, w1; w0.x = pk2(o0[4 * gI] * inv, o0[4 * gI + 1] * inv); w0.y = pk2(o0[4 * gI + 2] * inv, o0[4 * gI + 3] * inv);
;         w1.x = pk2(o1[4 * gI] * inv, o1[4 * gI + 1] * inv); w1.y = pk2(o1[4 * gI + 2] * inv, o1[4 * gI + 3] * inv);
;         *(LAS u32x2*)(stg + r32 * 136 + 16 * gI + 8 * hi) = w0; *(LAS u32x2*)(stg + r32 * 136 + 64 + 16 * gI + 8 * hi) = w1;
;     }
;     asm volatile("s_waitcnt lgkmcnt(0)" ::: "memory");
;     bf16_t* ob = O + (rowbase + qw) * 1024 + h * 64;
; #pragma unroll
;     for (int i = 0; i < 4; ++i) { const int row = i * 8 + (lane >> 3), ch = lane & 7; const LAS unsigned char* p = stg + row * 136 + ch * 16;
;         const u32x2 x = *(const LAS u32x2*)p, y = *(const LAS u32x2*)(p + 8);
;         *(u32x4*)(ob + (size_t)row * 1024 + ch * 8) = (u32x4){x.x, x.y, y.x, y.y}; }
; __global__ void __launch_bounds__(512, 2) mk_fwd(Args args) {
;     ...
;             for (int u = bx; u < 256; u += G) scan_unit(u, LAb, LBb, CAT + 768, (LAS float*)lds);
;             { const int nu = (G == 256) ? 4 : (1024 - bx + G - 1) / G;
; #pragma unroll 1
;               for (int i = 0; i < nu; ++i) { int bh, qb;
;                   if (G == 256) { const int s = vcu & 3; bh = vcu >> 2; qb = (i == 0) ? 15 - s : (i == 1) ? 8 + s : (i == 2) ? 7 - s : s; }
;                   else { const int u = bx + i * G; bh = u >> 4; qb = 15 - (u & 15); }
;                   attn_unit(bh >> 3, bh & 7, qb, Qb, Kb, Vt, CAT + 256, lds); } }
.LBB0_318:
	ds_write_b128 v185, v[2:5]
	ds_write_b128 v205, v[6:9]
	ds_write_b128 v206, v[10:13]
	ds_write2_b64 v207, v[112:113], v[114:115] offset1:1
	ds_write2_b64 v208, v[116:117], v[118:119] offset1:1
	v_and_or_b32 v2, v224, 64, v195
	v_lshlrev_b32_e32 v2, 2, v2
	s_nop 4
	v_add_f32_e32 v250, v250, v251
	v_mov_b32_e32 v251, v250
	s_nop 1
	v_permlane32_swap_b32_e32 v250, v251
	v_add_f32_e32 v2, v250, v251
	s_mulk_i32 s43, 0x1100
	s_add_i32 s1, s43, 0
	s_add_i32 s19, s1, 0x15400
	s_waitcnt lgkmcnt(0)
	s_barrier
	v_div_scale_f32 v3, s[20:21], v2, v2, 1.0
	v_rcp_f32_e32 v4, v3
	s_lshl_b64 s[20:21], s[30:31], 11
	s_add_u32 s1, s36, s20
	s_addc_u32 s20, s37, s21
	v_fma_f32 v5, -v3, v4, 1.0
	v_fmac_f32_e32 v4, v5, v4
	v_div_scale_f32 v5, vcc, 1.0, v2, 1.0
	v_mul_f32_e32 v6, v5, v4
	v_fma_f32 v7, -v3, v6, v5
	v_fmac_f32_e32 v6, v7, v4
	v_fma_f32 v3, -v3, v6, v5
	v_div_fmas_f32 v3, v3, v4, v6
	v_div_fixup_f32 v2, v3, v2, 1.0
	v_mul_u32_u24_e32 v3, 0x88, v195
	v_pk_mul_f32 v[4:5], v[32:33], v[2:3] op_sel_hi:[1,0]
	v_pk_mul_f32 v[6:7], v[34:35], v[2:3] op_sel_hi:[1,0]
	v_cvt_pk_bf16_f32 v4, v4, v5
	v_cvt_pk_bf16_f32 v5, v6, v7
	v_pk_mul_f32 v[6:7], v[16:17], v[2:3] op_sel_hi:[1,0]
	v_pk_mul_f32 v[8:9], v[18:19], v[2:3] op_sel_hi:[1,0]
	v_cvt_pk_bf16_f32 v6, v6, v7
	v_cvt_pk_bf16_f32 v7, v8, v9
	v_pk_mul_f32 v[8:9], v[36:37], v[2:3] op_sel_hi:[1,0]
	v_pk_mul_f32 v[10:11], v[38:39], v[2:3] op_sel_hi:[1,0]
	v_add3_u32 v14, s19, v3, v204
	v_cvt_pk_bf16_f32 v8, v8, v9
	v_cvt_pk_bf16_f32 v9, v10, v11
	v_pk_mul_f32 v[10:11], v[20:21], v[2:3] op_sel_hi:[1,0]
	v_pk_mul_f32 v[12:13], v[22:23], v[2:3] op_sel_hi:[1,0]
	v_cvt_pk_bf16_f32 v10, v10, v11
	v_cvt_pk_bf16_f32 v11, v12, v13
	ds_write2_b64 v14, v[4:5], v[8:9] offset1:2
	ds_write2_b64 v14, v[6:7], v[10:11] offset0:8 offset1:10
	v_pk_mul_f32 v[4:5], v[40:41], v[2:3] op_sel_hi:[1,0]
	v_pk_mul_f32 v[6:7], v[42:43], v[2:3] op_sel_hi:[1,0]
	v_cvt_pk_bf16_f32 v4, v4, v5
	v_cvt_pk_bf16_f32 v5, v6, v7
	v_pk_mul_f32 v[6:7], v[24:25], v[2:3] op_sel_hi:[1,0]
	v_pk_mul_f32 v[8:9], v[26:27], v[2:3] op_sel_hi:[1,0]
	v_cvt_pk_bf16_f32 v6, v6, v7
	v_cvt_pk_bf16_f32 v7, v8, v9
	v_pk_mul_f32 v[8:9], v[44:45], v[2:3] op_sel_hi:[1,0]
	v_pk_mul_f32 v[10:11], v[46:47], v[2:3] op_sel_hi:[1,0]
	s_lshl_b32 s0, s0, 1
	v_cvt_pk_bf16_f32 v8, v8, v9
	v_cvt_pk_bf16_f32 v9, v10, v11
	v_pk_mul_f32 v[10:11], v[28:29], v[2:3] op_sel_hi:[1,0]
	v_pk_mul_f32 v[2:3], v[30:31], v[2:3] op_sel_hi:[1,0]
	s_add_u32 s0, s1, s0
	v_cvt_pk_bf16_f32 v10, v10, v11
	v_cvt_pk_bf16_f32 v11, v2, v3
	ds_write2_b64 v14, v[4:5], v[8:9] offset0:4 offset1:6
	ds_write2_b64 v14, v[6:7], v[10:11] offset0:12 offset1:14
	s_addc_u32 s1, s20, 0
	v_lshrrev_b32_e32 v8, 3, v0
	v_lshlrev_b32_e32 v0, 1, v124
	v_lshl_add_u64 v[6:7], s[0:1], 0, v[0:1]
	v_mul_u32_u24_e32 v0, 0x88, v8
	s_waitcnt lgkmcnt(0)
	v_add3_u32 v10, s19, v184, v0
	ds_read2_b64 v[2:5], v10 offset1:1
	v_lshlrev_b32_e32 v0, 11, v8
	v_lshl_add_u64 v[8:9], v[6:7], 0, v[0:1]
	s_add_i32 s42, s42, 1
	s_cmp_eq_u32 s42, s12
	s_waitcnt lgkmcnt(0)
	global_store_dwordx4 v[8:9], v[2:5], off
	ds_read2_b64 v[2:5], v10 offset0:136 offset1:137
	v_or_b32_e32 v8, 0x4000, v0
	v_mov_b32_e32 v9, v1
	v_lshl_add_u64 v[8:9], v[6:7], 0, v[8:9]
	v_mov_b32_e32 v195, v236
	s_waitcnt lgkmcnt(0)
	global_store_dwordx4 v[8:9], v[2:5], off
	v_or_b32_e32 v8, 0x8000, v0
	v_mov_b32_e32 v9, v1
	v_add_u32_e32 v2, 0x880, v10
	ds_read2_b64 v[2:5], v2 offset1:1
	v_lshl_add_u64 v[8:9], v[6:7], 0, v[8:9]
	v_or_b32_e32 v0, 0xc000, v0
	v_lshl_add_u64 v[6:7], v[6:7], 0, v[0:1]
	s_waitcnt lgkmcnt(0)
	global_store_dwordx4 v[8:9], v[2:5], off
	s_nop 1
	v_add_u32_e32 v2, 0xcc0, v10
	ds_read2_b64 v[2:5], v2 offset1:1
	s_waitcnt lgkmcnt(0)
	global_store_dwordx4 v[6:7], v[2:5], off
	s_cbranch_scc1 .LBB0_357
.LBB0_319:
	v_mov_b32_e32 v250, 0
	v_mov_b32_e32 v251, 0
	s_mov_b64 s[0:1], -1
	s_and_b64 vcc, exec, s[24:25]
	s_cbranch_vccz .LBB0_321
	s_mul_i32 s0, s42, s35
	s_add_i32 s0, s0, s2
	s_ashr_i32 s19, s0, 4
	s_andn2_b32 s38, 15, s0
	s_mov_b64 s[0:1], 0

; #define LAS __attribute__((address_space(3)))
; __device__ __forceinline__ int crow(int r, int hi) { return (r & 3) + 8 * (r >> 2) + 4 * hi; }
; template <bool MASKED> ...
;     if (MASKED) { if (64 * jl > __builtin_amdgcn_readfirstlane(qrel | 31)) return; }
;     f32x16 s0, s1;
;     { const bf16x8 ka = *(const LAS bf16x8*)(kb), kc = *(const LAS bf16x8*)(kb + 32 * AK_PITCH);
;       s0 = __builtin_amdgcn_mfma_f32_32x32x16_bf16(ka, qf[0], negm, 0, 0, 0); s1 = __builtin_amdgcn_mfma_f32_32x32x16_bf16(kc, qf[0], negm, 0, 0, 0); }
; #pragma unroll
;     for (int s = 1; s < 6; ++s) { const bf16x8 ka = *(const LAS bf16x8*)(kb + s * 32), kc = *(const LAS bf16x8*)(kb + 32 * AK_PITCH + s * 32);
;         s0 = __builtin_amdgcn_mfma_f32_32x32x16_bf16(ka, qf[s], s0, 0, 0, 0); s1 = __builtin_amdgcn_mfma_f32_32x32x16_bf16(kc, qf[s], s1, 0, 0, 0); }
;     if (MASKED) {
; #pragma unroll
;         for (int r = 0; r < 16; ++r) { const int kv = 64 * jl + crow(r, hi); if (kv > qrel) s0[r] = -1e30f; if (kv + 32 > qrel) s1[r] = -1e30f; }
;     }
;     float mx = __builtin_fmaxf(s0[0], s1[0]);
; #pragma unroll
;     for (int r = 1; r < 16; ++r) mx = __builtin_fmaxf(__builtin_fmaxf(mx, s0[r]), s1[r]);
;     { auto rr = __builtin_amdgcn_permlane32_swap(__float_as_uint(mx), __float_as_uint(mx), false, false);
;       mx = __builtin_fmaxf(__uint_as_float(rr[0]), __uint_as_float(rr[1])); }
;     if (__any(first || mx > ATT_THR)) {
;         const float d = first ? mx : __builtin_fmaxf(mx, 0.f), f = __builtin_amdgcn_exp2f(-d);
;         mrun += d; o2[0] *= f;
; #pragma unroll
;         for (int r = 0; r < 16; ++r) { s0[r] -= d; s1[r] -= d; o0[r] *= f; o1[r] *= f; negm[r] = -mrun; }
;     }
.LBB0_330:
	ds_read_b128 v[2:5], v211
	ds_read_b128 v[6:9], v211 offset:32
	s_add_i32 s20, s41, 2
	s_min_u32 s44, s20, s40
	v_mad_u64_u32 v[14:15], s[38:39], s44, v230, v[200:201]
	s_waitcnt lgkmcnt(0)
	v_mfma_f32_32x32x16_bf16 v[96:111], v[2:5], v[152:155], v[64:79]
	ds_read_b128 v[2:5], v211 offset:6656
	ds_read_b128 v[10:13], v211 offset:6688
	s_lshl_b32 s48, s44, 1
	s_waitcnt lgkmcnt(1)
	v_mfma_f32_32x32x16_bf16 v[112:127], v[2:5], v[152:155], v[64:79]
	v_mfma_f32_32x32x16_bf16 v[96:111], v[6:9], v[148:151], v[96:111]
	ds_read_b128 v[2:5], v211 offset:64
	ds_read_b128 v[6:9], v211 offset:96
	s_waitcnt lgkmcnt(2)
	v_mfma_f32_32x32x16_bf16 v[112:127], v[10:13], v[148:151], v[112:127]
	s_waitcnt lgkmcnt(1)
	v_mfma_f32_32x32x16_bf16 v[96:111], v[2:5], v[144:147], v[96:111]
	ds_read_b128 v[2:5], v211 offset:6720
	ds_read_b128 v[10:13], v211 offset:6752
	s_waitcnt lgkmcnt(1)
	v_mfma_f32_32x32x16_bf16 v[112:127], v[2:5], v[144:147], v[112:127]
	ds_read_b128 v[2:5], v211 offset:128
	s_waitcnt lgkmcnt(1)
	v_mfma_f32_32x32x16_bf16 v[112:127], v[10:13], v[140:143], v[112:127]
	ds_read_b128 v[10:13], v211 offset:6784
	ds_read_b128 v[80:83], v211 offset:160
	v_mfma_f32_32x32x16_bf16 v[96:111], v[6:9], v[140:143], v[96:111]
	v_mad_u64_u32 v[6:7], s[38:39], s44, v230, v[196:197]
	v_mad_u64_u32 v[8:9], s[38:39], s44, v230, v[198:199]
	s_lshl_b64 s[38:39], s[48:49], 13
	s_or_b32 s48, s48, 1
	s_waitcnt lgkmcnt(1)
	v_mfma_f32_32x32x16_bf16 v[112:127], v[10:13], v[136:139], v[112:127]
	v_lshl_add_u64 v[10:11], v[202:203], 0, s[38:39]
	s_lshl_b64 s[38:39], s[48:49], 13
	s_cmp_eq_u32 s41, 0
	v_mfma_f32_32x32x16_bf16 v[96:111], v[2:5], v[136:139], v[96:111]
	global_load_dwordx4 v[2:5], v[6:7], off
	s_nop 0
	global_load_dwordx4 v[6:9], v[8:9], off
	ds_read_b128 v[84:87], v211 offset:6816
	global_load_dwordx4 v[176:179], v[14:15], off
	s_nop 0
	global_load_dwordx4 v[10:13], v[10:11], off
	v_lshl_add_u64 v[14:15], v[202:203], 0, s[38:39]
	global_load_dwordx4 v[180:183], v[14:15], off
	s_cselect_b64 s[38:39], -1, 0
	s_waitcnt lgkmcnt(0)
	v_mfma_f32_32x32x16_bf16 v[112:127], v[84:87], v[132:135], v[112:127]
	v_mfma_f32_32x32x16_bf16 v[96:111], v[80:83], v[132:135], v[96:111]
	s_nop 10
	v_max_f32_e32 v0, v112, v112
	v_max_f32_e32 v14, v96, v96
	v_max_f32_e32 v0, v14, v0
	v_max3_f32 v0, v0, v97, v113
	v_max3_f32 v0, v0, v98, v114
	v_max3_f32 v0, v0, v99, v115
	v_max3_f32 v0, v0, v100, v116
	v_max3_f32 v0, v0, v101, v117
	v_max3_f32 v0, v0, v102, v118
	v_max3_f32 v0, v0, v103, v119
	v_max3_f32 v0, v0, v104, v120
	v_max3_f32 v0, v0, v105, v121
	v_max3_f32 v0, v0, v106, v122
	v_max3_f32 v0, v0, v107, v123
	v_max3_f32 v0, v0, v108, v124
	v_max3_f32 v0, v0, v109, v125
	v_max3_f32 v0, v0, v110, v126
	v_max3_f32 v0, v0, v111, v127
	v_mov_b32_e32 v14, v0
	s_nop 1
	v_permlane32_swap_b32_e32 v0, v14
	v_max_f32_e32 v14, v14, v14
	v_max_f32_e32 v0, v0, v0
	v_max_f32_e32 v0, v0, v14
	v_cmp_lt_f32_e32 vcc, s23, v0
	s_or_b64 vcc, s[38:39], vcc
	s_cbranch_vccz .LBB0_332
	v_max_f32_e32 v14, v0, v0
	v_max_f32_e32 v14, 0, v14
	v_cndmask_b32_e64 v0, v14, v0, s[38:39]
	v_exp_f32_e64 v14, -v0
	v_add_f32_e32 v213, v213, v0
	v_xor_b32_e32 v80, 0x80000000, v213
	v_pk_add_f32 v[96:97], v[96:97], v[0:1] op_sel_hi:[1,0] neg_lo:[0,1] neg_hi:[0,1]
	v_mul_f32_e32 v48, v48, v14
	v_mul_f32_e32 v250, v250, v14
	v_mul_f32_e32 v251, v251, v14
	v_pk_add_f32 v[112:113], v[112:113], v[0:1] op_sel_hi:[1,0] neg_lo:[0,1] neg_hi:[0,1]
	v_pk_add_f32 v[98:99], v[98:99], v[0:1] op_sel_hi:[1,0] neg_lo:[0,1] neg_hi:[0,1]
	v_pk_add_f32 v[114:115], v[114:115], v[0:1] op_sel_hi:[1,0] neg_lo:[0,1] neg_hi:[0,1]
	v_pk_add_f32 v[100:101], v[100:101], v[0:1] op_sel_hi:[1,0] neg_lo:[0,1] neg_hi:[0,1]
	v_pk_add_f32 v[116:117], v[116:117], v[0:1] op_sel_hi:[1,0] neg_lo:[0,1] neg_hi:[0,1]
	v_pk_add_f32 v[102:103], v[102:103], v[0:1] op_sel_hi:[1,0] neg_lo:[0,1] neg_hi:[0,1]
	v_pk_add_f32 v[118:119], v[118:119], v[0:1] op_sel_hi:[1,0] neg_lo:[0,1] neg_hi:[0,1]
	v_pk_add_f32 v[104:105], v[104:105], v[0:1] op_sel_hi:[1,0] neg_lo:[0,1] neg_hi:[0,1]
	v_pk_add_f32 v[120:121], v[120:121], v[0:1] op_sel_hi:[1,0] neg_lo:[0,1] neg_hi:[0,1]
	v_pk_add_f32 v[106:107], v[106:107], v[0:1] op_sel_hi:[1,0] neg_lo:[0,1] neg_hi:[0,1]
	v_pk_add_f32 v[122:123], v[122:123], v[0:1] op_sel_hi:[1,0] neg_lo:[0,1] neg_hi:[0,1]
	v_pk_add_f32 v[108:109], v[108:109], v[0:1] op_sel_hi:[1,0] neg_lo:[0,1] neg_hi:[0,1]
	v_pk_add_f32 v[124:125], v[124:125], v[0:1] op_sel_hi:[1,0] neg_lo:[0,1] neg_hi:[0,1]
	v_pk_add_f32 v[110:111], v[110:111], v[0:1] op_sel_hi:[1,0] neg_lo:[0,1] neg_hi:[0,1]
	v_pk_add_f32 v[126:127], v[126:127], v[0:1] op_sel_hi:[1,0] neg_lo:[0,1] neg_hi:[0,1]
	v_pk_mul_f32 v[46:47], v[46:47], v[14:15] op_sel_hi:[1,0]
	v_pk_mul_f32 v[44:45], v[44:45], v[14:15] op_sel_hi:[1,0]
	v_pk_mul_f32 v[42:43], v[42:43], v[14:15] op_sel_hi:[1,0]
	v_pk_mul_f32 v[40:41], v[40:41], v[14:15] op_sel_hi:[1,0]
	v_pk_mul_f32 v[38:39], v[38:39], v[14:15] op_sel_hi:[1,0]
	v_pk_mul_f32 v[36:37], v[36:37], v[14:15] op_sel_hi:[1,0]
	v_pk_mul_f32 v[34:35], v[34:35], v[14:15] op_sel_hi:[1,0]
	v_pk_mul_f32 v[32:33], v[32:33], v[14:15] op_sel_hi:[1,0]
	v_pk_mul_f32 v[30:31], v[30:31], v[14:15] op_sel_hi:[1,0]
	v_pk_mul_f32 v[28:29], v[28:29], v[14:15] op_sel_hi:[1,0]
	v_pk_mul_f32 v[26:27], v[26:27], v[14:15] op_sel_hi:[1,0]
	v_pk_mul_f32 v[24:25], v[24:25], v[14:15] op_sel_hi:[1,0]
	v_pk_mul_f32 v[22:23], v[22:23], v[14:15] op_sel_hi:[1,0]
	v_pk_mul_f32 v[20:21], v[20:21], v[14:15] op_sel_hi:[1,0]
	v_pk_mul_f32 v[18:19], v[18:19], v[14:15] op_sel_hi:[1,0]
	v_pk_mul_f32 v[16:17], v[16:17], v[14:15] op_sel_hi:[1,0]
	v_mov_b32_e32 v81, v80
	v_mov_b32_e32 v82, v80
	v_mov_b32_e32 v83, v80
	v_mov_b32_e32 v84, v80
	v_mov_b32_e32 v85, v80
	v_mov_b32_e32 v86, v80
	v_mov_b32_e32 v87, v80
	v_mov_b32_e32 v88, v80
	v_mov_b32_e32 v89, v80
	v_mov_b32_e32 v90, v80
	v_mov_b32_e32 v91, v80
	v_mov_b32_e32 v92, v80
	v_mov_b32_e32 v93, v80
	v_mov_b32_e32 v94, v80
	v_mov_b32_e32 v95, v80
	v_mov_b32_e32 v64, v80
	v_mov_b32_e32 v65, v80
	v_mov_b32_e32 v66, v80
	v_mov_b32_e32 v67, v80
	v_mov_b32_e32 v68, v80
	v_mov_b32_e32 v69, v80
	v_mov_b32_e32 v70, v80
	v_mov_b32_e32 v71, v80
	v_mov_b32_e32 v72, v80
	v_mov_b32_e32 v73, v80
	v_mov_b32_e32 v74, v80
	v_mov_b32_e32 v75, v80
	v_mov_b32_e32 v76, v80
	v_mov_b32_e32 v77, v80
	v_mov_b32_e32 v78, v80
	v_mov_b32_e32 v79, v80
	s_branch .LBB0_333

; #define LAS __attribute__((address_space(3)))
; template <bool MASKED> ...
;     ...
;     f32x16 s0, s1;
;     { const bf16x8 ka = *(const LAS bf16x8*)(kb), kc = *(const LAS bf16x8*)(kb + 32 * AK_PITCH);
;       s0 = __builtin_amdgcn_mfma_f32_32x32x16_bf16(ka, qf[0], negm, 0, 0, 0); s1 = __builtin_amdgcn_mfma_f32_32x32x16_bf16(kc, qf[0], negm, 0, 0, 0); }
; #pragma unroll
;     for (int s = 1; s < 6; ++s) { const bf16x8 ka = *(const LAS bf16x8*)(kb + s * 32), kc = *(const LAS bf16x8*)(kb + 32 * AK_PITCH + s * 32);
;         s0 = __builtin_amdgcn_mfma_f32_32x32x16_bf16(ka, qf[s], s0, 0, 0, 0); s1 = __builtin_amdgcn_mfma_f32_32x32x16_bf16(kc, qf[s], s1, 0, 0, 0); }
;     if (MASKED) {
; #pragma unroll
;         for (int r = 0; r < 16; ++r) { const int kv = 64 * jl + crow(r, hi); if (kv > qrel) s0[r] = -1e30f; if (kv + 32 > qrel) s1[r] = -1e30f; }
;     }
;     float mx = __builtin_fmaxf(s0[0], s1[0]);
; #pragma unroll
;     for (int r = 1; r < 16; ++r) mx = __builtin_fmaxf(__builtin_fmaxf(mx, s0[r]), s1[r]);
;     { auto rr = __builtin_amdgcn_permlane32_swap(__float_as_uint(mx), __float_as_uint(mx), false, false);
;       mx = __builtin_fmaxf(__uint_as_float(rr[0]), __uint_as_float(rr[1])); }
;     if (__any(first || mx > ATT_THR)) {
;         const float d = first ? mx : __builtin_fmaxf(mx, 0.f), f = __builtin_amdgcn_exp2f(-d);
;         mrun += d; o2[0] *= f;
; #pragma unroll
;         for (int r = 0; r < 16; ++r) { s0[r] -= d; s1[r] -= d; o0[r] *= f; o1[r] *= f; negm[r] = -mrun; }
;     }
; #pragma unroll
;     for (int r = 0; r < 16; ++r) { s0[r] = __builtin_amdgcn_exp2f(s0[r]); s1[r] = __builtin_amdgcn_exp2f(s1[r]); }
;     u32x4 pw[4];
;     pw[0] = (u32x4){pk2(s0[0], s0[1]), pk2(s0[2], s0[3]), pk2(s0[4], s0[5]), pk2(s0[6], s0[7])};
;     pw[1] = (u32x4){pk2(s0[8], s0[9]), pk2(s0[10], s0[11]), pk2(s0[12], s0[13]), pk2(s0[14], s0[15])};
;     pw[2] = (u32x4){pk2(s1[0], s1[1]), pk2(s1[2], s1[3]), pk2(s1[4], s1[5]), pk2(s1[6], s1[7])};
;     pw[3] = (u32x4){pk2(s1[8], s1[9]), pk2(s1[10], s1[11]), pk2(s1[12], s1[13]), pk2(s1[14], s1[15])};
; #pragma unroll
;     for (int ks = 0; ks < 4; ++ks) {
;         const s16x4 a0 = *(const LAS s16x4*)(vb + 32 * ks), a1 = *(const LAS s16x4*)(vb + 32 * ks + 16);
;         const s16x4 c0 = *(const LAS s16x4*)(vb + 32 * AV_PITCH + 32 * ks), c1 = *(const LAS s16x4*)(vb + 32 * AV_PITCH + 32 * ks + 16);
.LBB0_333:
	v_exp_f32_e32 v0, v96
	v_exp_f32_e32 v14, v112
	v_exp_f32_e32 v15, v97
	v_exp_f32_e32 v96, v113
	v_exp_f32_e32 v97, v98
	v_exp_f32_e32 v98, v114
	v_exp_f32_e32 v99, v99
	v_exp_f32_e32 v112, v115
	v_exp_f32_e32 v113, v100
	v_exp_f32_e32 v114, v116
	v_exp_f32_e32 v115, v101
	v_exp_f32_e32 v116, v117
	v_exp_f32_e32 v117, v102
	v_exp_f32_e32 v103, v103
	v_exp_f32_e32 v118, v118
	v_exp_f32_e32 v119, v119
	v_exp_f32_e32 v104, v104
	v_exp_f32_e32 v105, v105
	v_exp_f32_e32 v106, v106
	v_exp_f32_e32 v107, v107
	v_exp_f32_e32 v108, v108
	v_exp_f32_e32 v109, v109
	v_exp_f32_e32 v110, v110
	v_exp_f32_e32 v111, v111
	v_add_f32_e32 v250, v250, v0
	v_add_f32_e32 v250, v250, v15
	v_cvt_pk_bf16_f32 v100, v0, v15
	v_add_f32_e32 v250, v250, v97
	v_add_f32_e32 v250, v250, v99
	v_cvt_pk_bf16_f32 v101, v97, v99
	v_add_f32_e32 v250, v250, v113
	v_add_f32_e32 v250, v250, v115
	v_cvt_pk_bf16_f32 v102, v113, v115
	v_add_f32_e32 v250, v250, v117
	v_add_f32_e32 v251, v251, v103
	v_cvt_pk_bf16_f32 v103, v117, v103
	v_add_u32_e32 v0, 0xf000, v214
	v_add_f32_e32 v250, v250, v104
	v_add_f32_e32 v251, v251, v105
	v_cvt_pk_bf16_f32 v104, v104, v105
	v_add_f32_e32 v250, v250, v106
	v_add_f32_e32 v251, v251, v107
	v_cvt_pk_bf16_f32 v105, v106, v107
	v_add_f32_e32 v250, v250, v108
	v_add_f32_e32 v251, v251, v109
	v_cvt_pk_bf16_f32 v106, v108, v109
	v_add_f32_e32 v250, v250, v110
	v_add_f32_e32 v251, v251, v111
	v_cvt_pk_bf16_f32 v107, v110, v111
	v_add_f32_e32 v251, v251, v98
	v_add_f32_e32 v251, v251, v112
	v_cvt_pk_bf16_f32 v109, v98, v112
	v_add_f32_e32 v251, v251, v114
	v_add_f32_e32 v251, v251, v116
	v_cvt_pk_bf16_f32 v110, v114, v116
	v_add_f32_e32 v250, v250, v118
	v_add_f32_e32 v251, v251, v119
	v_cvt_pk_bf16_f32 v111, v118, v119
	s_nop 0
	ds_read2_b64 v[112:115], v0 offset0:32 offset1:34
	ds_read2_b64 v[116:119], v209 offset1:2
	v_exp_f32_e32 v120, v120
	v_exp_f32_e32 v121, v121
	v_exp_f32_e32 v122, v122
	v_exp_f32_e32 v123, v123
	v_add_f32_e32 v251, v251, v14
	v_add_f32_e32 v251, v251, v96
	v_cvt_pk_bf16_f32 v108, v14, v96
	v_add_f32_e32 v250, v250, v120
	v_add_f32_e32 v251, v251, v121
	v_cvt_pk_bf16_f32 v96, v120, v121
	s_waitcnt lgkmcnt(0)
	v_mfma_f32_32x32x16_bf16 v[32:47], v[116:119], v[100:103], v[32:47]
	v_add_f32_e32 v250, v250, v122
	v_add_f32_e32 v251, v251, v123
	v_cvt_pk_bf16_f32 v97, v122, v123
	ds_read2_b64 v[120:123], v209 offset0:4 offset1:6
	ds_read_b128 v[218:221], v211 offset:19968
	v_exp_f32_e32 v124, v124
	v_exp_f32_e32 v125, v125
	v_exp_f32_e32 v126, v126
	v_exp_f32_e32 v127, v127
	v_mfma_f32_32x32x16_bf16 v[16:31], v[112:115], v[100:103], v[16:31]
	ds_read2_b64 v[100:103], v0 offset0:36 offset1:38
	ds_read_b128 v[112:115], v211 offset:13312
	v_add_f32_e32 v250, v250, v124
	v_add_f32_e32 v251, v251, v125
	v_cvt_pk_bf16_f32 v98, v124, v125
	v_add_f32_e32 v250, v250, v126
	v_add_f32_e32 v251, v251, v127
	v_cvt_pk_bf16_f32 v99, v126, v127
	s_waitcnt lgkmcnt(3)
	v_mfma_f32_32x32x16_bf16 v[32:47], v[120:123], v[104:107], v[32:47]
	ds_read_b128 v[232:235], v211 offset:13344
	s_waitcnt lgkmcnt(2)
	v_mfma_f32_32x32x16_bf16 v[16:31], v[100:103], v[104:107], v[16:31]
	ds_read2_b64 v[100:103], v209 offset0:8 offset1:10
	s_nop 0
	ds_read2_b64 v[104:107], v0 offset0:40 offset1:42
	s_waitcnt lgkmcnt(1)
	v_mfma_f32_32x32x16_bf16 v[32:47], v[100:103], v[108:111], v[32:47]
	ds_read2_b64 v[100:103], v209 offset0:12 offset1:14
	s_waitcnt lgkmcnt(1)
	v_mfma_f32_32x32x16_bf16 v[16:31], v[104:107], v[108:111], v[16:31]
	ds_read2_b64 v[104:107], v0 offset0:44 offset1:46
	s_nop 0
	s_waitcnt lgkmcnt(1)
	v_mfma_f32_32x32x16_bf16 v[32:47], v[100:103], v[96:99], v[32:47]
	s_waitcnt lgkmcnt(0)
	v_mfma_f32_32x32x16_bf16 v[16:31], v[104:107], v[96:99], v[16:31]
	s_nop 0
	v_mfma_f32_32x32x16_bf16 v[96:111], v[112:115], v[152:155], v[80:95]
	v_mfma_f32_32x32x16_bf16 v[112:127], v[218:221], v[152:155], v[80:95]
	ds_read_b128 v[218:221], v211 offset:20000
	v_mfma_f32_32x32x16_bf16 v[96:111], v[232:235], v[148:151], v[96:111]
	ds_read_b128 v[232:235], v211 offset:20032
	s_waitcnt lgkmcnt(1)
	v_mfma_f32_32x32x16_bf16 v[112:127], v[218:221], v[148:151], v[112:127]
	ds_read_b128 v[218:221], v211 offset:13376
	s_waitcnt lgkmcnt(0)
	v_mfma_f32_32x32x16_bf16 v[96:111], v[218:221], v[144:147], v[96:111]
	ds_read_b128 v[218:221], v211 offset:13408
	v_mfma_f32_32x32x16_bf16 v[112:127], v[232:235], v[144:147], v[112:127]
	ds_read_b128 v[232:235], v211 offset:20064
	s_waitcnt lgkmcnt(1)
	v_mfma_f32_32x32x16_bf16 v[96:111], v[218:221], v[140:143], v[96:111]
	ds_read_b128 v[218:221], v211 offset:13440
	s_waitcnt lgkmcnt(1)
	v_mfma_f32_32x32x16_bf16 v[112:127], v[232:235], v[140:143], v[112:127]
	ds_read_b128 v[232:235], v211 offset:20096
	s_waitcnt lgkmcnt(1)
	v_mfma_f32_32x32x16_bf16 v[96:111], v[218:221], v[136:139], v[96:111]
	ds_read_b128 v[218:221], v211 offset:13472
	s_waitcnt lgkmcnt(1)
	v_mfma_f32_32x32x16_bf16 v[112:127], v[232:235], v[136:139], v[112:127]
	ds_read_b128 v[232:235], v211 offset:20128
	s_waitcnt lgkmcnt(1)
	v_mfma_f32_32x32x16_bf16 v[96:111], v[218:221], v[132:135], v[96:111]
	s_waitcnt lgkmcnt(0)
	v_mfma_f32_32x32x16_bf16 v[112:127], v[232:235], v[132:135], v[112:127]
	s_nop 10
	v_max_f32_e32 v15, v96, v96
	v_max_f32_e32 v14, v112, v112
	v_max_f32_e32 v14, v15, v14
	v_max3_f32 v14, v14, v97, v113
	v_max3_f32 v14, v14, v98, v114
	v_max3_f32 v14, v14, v99, v115
	v_max3_f32 v14, v14, v100, v116
	v_max3_f32 v14, v14, v101, v117
	v_max3_f32 v14, v14, v102, v118
	v_max3_f32 v14, v14, v103, v119
	v_max3_f32 v14, v14, v104, v120
	v_max3_f32 v14, v14, v105, v121
	v_max3_f32 v14, v14, v106, v122
	v_max3_f32 v14, v14, v107, v123
	v_max3_f32 v14, v14, v108, v124
	v_max3_f32 v14, v14, v109, v125
	v_max3_f32 v14, v14, v110, v126
	v_max3_f32 v14, v14, v111, v127
	v_mov_b32_e32 v15, v14
	s_nop 1
	v_permlane32_swap_b32_e32 v14, v15
	v_max_f32_e32 v15, v15, v15
	v_max_f32_e32 v14, v14, v14
	v_max_f32_e32 v14, v14, v15
	v_cmp_lt_f32_e32 vcc, s23, v14
	s_cbranch_vccz .LBB0_335
; #define LAS __attribute__((address_space(3)))
; __device__ __forceinline__ unsigned pk2(float lo, float hi) { f32x2 v = {lo, hi}; bf16x2_t b = __builtin_convertvector(v, bf16x2_t); return __builtin_bit_cast(unsigned, b); }
; template <bool MASKED> ...
;     ...
;         const float d = first ? mx : __builtin_fmaxf(mx, 0.f), f = __builtin_amdgcn_exp2f(-d);
;         mrun += d; o2[0] *= f;
; #pragma unroll
;         for (int r = 0; r < 16; ++r) { s0[r] -= d; s1[r] -= d; o0[r] *= f; o1[r] *= f; negm[r] = -mrun; }
;     }
; #pragma unroll
;     for (int r = 0; r < 16; ++r) { s0[r] = __builtin_amdgcn_exp2f(s0[r]); s1[r] = __builtin_amdgcn_exp2f(s1[r]); }
;     u32x4 pw[4];
;     pw[0] = (u32x4){pk2(s0[0], s0[1]), pk2(s0[2], s0[3]), pk2(s0[4], s0[5]), pk2(s0[6], s0[7])};
;     pw[1] = (u32x4){pk2(s0[8], s0[9]), pk2(s0[10], s0[11]), pk2(s0[12], s0[13]), pk2(s0[14], s0[15])};
;     pw[2] = (u32x4){pk2(s1[0], s1[1]), pk2(s1[2], s1[3]), pk2(s1[4], s1[5]), pk2(s1[6], s1[7])};
;     pw[3] = (u32x4){pk2(s1[8], s1[9]), pk2(s1[10], s1[11]), pk2(s1[12], s1[13]), pk2(s1[14], s1[15])};
; #pragma unroll
;     for (int ks = 0; ks < 4; ++ks) {
;         const s16x4 a0 = *(const LAS s16x4*)(vb + 32 * ks), a1 = *(const LAS s16x4*)(vb + 32 * ks + 16);
;         const s16x4 c0 = *(const LAS s16x4*)(vb + 32 * AV_PITCH + 32 * ks), c1 = *(const LAS s16x4*)(vb + 32 * AV_PITCH + 32 * ks + 16);
;         const bf16x8 vf0 = (bf16x8){a0[0], a0[1], a0[2], a0[3], a1[0], a1[1], a1[2], a1[3]}, vf1 = (bf16x8){c0[0], c0[1], c0[2], c0[3], c1[0], c1[1], c1[2], c1[3]};
;         const bf16x8 pf = __builtin_bit_cast(bf16x8, pw[ks]);
;         o0 = __builtin_amdgcn_mfma_f32_32x32x16_bf16(vf0, pf, o0, 0, 0, 0); o1 = __builtin_amdgcn_mfma_f32_32x32x16_bf16(vf1, pf, o1, 0, 0, 0);
;         o2 = __builtin_amdgcn_mfma_f32_32x32x16_bf16(ones, pf, o2, 0, 0, 0);
;     }
	v_max_f32_e32 v14, v14, v14
	v_max_f32_e32 v14, 0, v14
	v_exp_f32_e64 v64, -v14
	v_add_f32_e32 v213, v213, v14
	v_xor_b32_e32 v80, 0x80000000, v213
	v_pk_add_f32 v[96:97], v[96:97], v[14:15] op_sel_hi:[1,0] neg_lo:[0,1] neg_hi:[0,1]
	v_mul_f32_e32 v48, v48, v64
	v_mul_f32_e32 v250, v250, v64
	v_mul_f32_e32 v251, v251, v64
	v_pk_add_f32 v[112:113], v[112:113], v[14:15] op_sel_hi:[1,0] neg_lo:[0,1] neg_hi:[0,1]
	v_pk_add_f32 v[98:99], v[98:99], v[14:15] op_sel_hi:[1,0] neg_lo:[0,1] neg_hi:[0,1]
	v_pk_add_f32 v[114:115], v[114:115], v[14:15] op_sel_hi:[1,0] neg_lo:[0,1] neg_hi:[0,1]
	v_pk_add_f32 v[100:101], v[100:101], v[14:15] op_sel_hi:[1,0] neg_lo:[0,1] neg_hi:[0,1]
	v_pk_add_f32 v[116:117], v[116:117], v[14:15] op_sel_hi:[1,0] neg_lo:[0,1] neg_hi:[0,1]
	v_pk_add_f32 v[102:103], v[102:103], v[14:15] op_sel_hi:[1,0] neg_lo:[0,1] neg_hi:[0,1]
	v_pk_add_f32 v[118:119], v[118:119], v[14:15] op_sel_hi:[1,0] neg_lo:[0,1] neg_hi:[0,1]
	v_pk_add_f32 v[104:105], v[104:105], v[14:15] op_sel_hi:[1,0] neg_lo:[0,1] neg_hi:[0,1]
	v_pk_add_f32 v[120:121], v[120:121], v[14:15] op_sel_hi:[1,0] neg_lo:[0,1] neg_hi:[0,1]
	v_pk_add_f32 v[106:107], v[106:107], v[14:15] op_sel_hi:[1,0] neg_lo:[0,1] neg_hi:[0,1]
	v_pk_add_f32 v[122:123], v[122:123], v[14:15] op_sel_hi:[1,0] neg_lo:[0,1] neg_hi:[0,1]
	v_pk_add_f32 v[108:109], v[108:109], v[14:15] op_sel_hi:[1,0] neg_lo:[0,1] neg_hi:[0,1]
	v_pk_add_f32 v[124:125], v[124:125], v[14:15] op_sel_hi:[1,0] neg_lo:[0,1] neg_hi:[0,1]
	v_pk_add_f32 v[110:111], v[110:111], v[14:15] op_sel_hi:[1,0] neg_lo:[0,1] neg_hi:[0,1]
	v_pk_add_f32 v[126:127], v[126:127], v[14:15] op_sel_hi:[1,0] neg_lo:[0,1] neg_hi:[0,1]
	v_pk_mul_f32 v[46:47], v[46:47], v[64:65] op_sel_hi:[1,0]
	v_pk_mul_f32 v[44:45], v[44:45], v[64:65] op_sel_hi:[1,0]
	v_pk_mul_f32 v[42:43], v[42:43], v[64:65] op_sel_hi:[1,0]
	v_pk_mul_f32 v[40:41], v[40:41], v[64:65] op_sel_hi:[1,0]
	v_pk_mul_f32 v[38:39], v[38:39], v[64:65] op_sel_hi:[1,0]
	v_pk_mul_f32 v[36:37], v[36:37], v[64:65] op_sel_hi:[1,0]
	v_pk_mul_f32 v[34:35], v[34:35], v[64:65] op_sel_hi:[1,0]
	v_pk_mul_f32 v[32:33], v[32:33], v[64:65] op_sel_hi:[1,0]
	v_pk_mul_f32 v[30:31], v[30:31], v[64:65] op_sel_hi:[1,0]
	v_pk_mul_f32 v[28:29], v[28:29], v[64:65] op_sel_hi:[1,0]
	v_pk_mul_f32 v[26:27], v[26:27], v[64:65] op_sel_hi:[1,0]
	v_pk_mul_f32 v[24:25], v[24:25], v[64:65] op_sel_hi:[1,0]
	v_pk_mul_f32 v[22:23], v[22:23], v[64:65] op_sel_hi:[1,0]
	v_pk_mul_f32 v[20:21], v[20:21], v[64:65] op_sel_hi:[1,0]
	v_pk_mul_f32 v[18:19], v[18:19], v[64:65] op_sel_hi:[1,0]
	v_pk_mul_f32 v[16:17], v[16:17], v[64:65] op_sel_hi:[1,0]
	v_mov_b32_e32 v81, v80
	v_mov_b32_e32 v82, v80
	v_mov_b32_e32 v83, v80
	v_mov_b32_e32 v84, v80
	v_mov_b32_e32 v85, v80
	v_mov_b32_e32 v86, v80
	v_mov_b32_e32 v87, v80
	v_mov_b32_e32 v88, v80
	v_mov_b32_e32 v89, v80
	v_mov_b32_e32 v90, v80
	v_mov_b32_e32 v91, v80
	v_mov_b32_e32 v92, v80
	v_mov_b32_e32 v93, v80
	v_mov_b32_e32 v94, v80
	v_mov_b32_e32 v95, v80
	v_mov_b32_e32 v64, v80
	v_mov_b32_e32 v65, v80
	v_mov_b32_e32 v66, v80
	v_mov_b32_e32 v67, v80
	v_mov_b32_e32 v68, v80
	v_mov_b32_e32 v69, v80
	v_mov_b32_e32 v70, v80
	v_mov_b32_e32 v71, v80
	v_mov_b32_e32 v72, v80
	v_mov_b32_e32 v73, v80
	v_mov_b32_e32 v74, v80
	v_mov_b32_e32 v75, v80
	v_mov_b32_e32 v76, v80
	v_mov_b32_e32 v77, v80
	v_mov_b32_e32 v78, v80
	v_mov_b32_e32 v79, v80
.LBB0_335:
	v_exp_f32_e32 v14, v96
	v_exp_f32_e32 v15, v112
	v_exp_f32_e32 v96, v97
	v_exp_f32_e32 v97, v113
	v_exp_f32_e32 v98, v98
	v_exp_f32_e32 v112, v114
	v_exp_f32_e32 v99, v99
	v_exp_f32_e32 v113, v115
	v_exp_f32_e32 v114, v100
	v_exp_f32_e32 v115, v116
	v_exp_f32_e32 v116, v101
	v_exp_f32_e32 v217, v102
	v_exp_f32_e32 v103, v103
	v_exp_f32_e32 v117, v117
	v_exp_f32_e32 v104, v104
	v_exp_f32_e32 v105, v105
	v_exp_f32_e32 v106, v106
	v_exp_f32_e32 v107, v107
	v_exp_f32_e32 v108, v108
	v_exp_f32_e32 v109, v109
	v_exp_f32_e32 v110, v110
	v_exp_f32_e32 v111, v111
	v_add_f32_e32 v250, v250, v14
	v_add_f32_e32 v250, v250, v96
	v_cvt_pk_bf16_f32 v100, v14, v96
	v_add_f32_e32 v250, v250, v98
	v_add_f32_e32 v250, v250, v99
	v_cvt_pk_bf16_f32 v101, v98, v99
	v_add_f32_e32 v250, v250, v114
	v_add_f32_e32 v250, v250, v116
	v_cvt_pk_bf16_f32 v102, v114, v116
	v_add_f32_e32 v251, v251, v217
	v_add_f32_e32 v250, v250, v103
	v_cvt_pk_bf16_f32 v103, v217, v103
	v_add_f32_e32 v250, v250, v104
	v_add_f32_e32 v251, v251, v105
	v_cvt_pk_bf16_f32 v104, v104, v105
	v_add_f32_e32 v250, v250, v106
	v_add_f32_e32 v251, v251, v107
	v_cvt_pk_bf16_f32 v105, v106, v107
	v_add_f32_e32 v250, v250, v108
	v_add_f32_e32 v251, v251, v109
	v_cvt_pk_bf16_f32 v106, v108, v109
	v_add_f32_e32 v250, v250, v110
	v_add_f32_e32 v251, v251, v111
	v_cvt_pk_bf16_f32 v107, v110, v111
	v_add_f32_e32 v251, v251, v112
	v_add_f32_e32 v251, v251, v113
	v_cvt_pk_bf16_f32 v109, v112, v113
	v_add_f32_e32 v251, v251, v115
	v_add_f32_e32 v251, v251, v117
	v_cvt_pk_bf16_f32 v110, v115, v117
	s_nop 0
	ds_read2_b64 v[112:115], v0 offset0:48 offset1:50
	v_exp_f32_e32 v118, v118
	v_exp_f32_e32 v119, v119
	v_exp_f32_e32 v120, v120
	v_exp_f32_e32 v121, v121
	v_exp_f32_e32 v122, v122
	v_add_f32_e32 v250, v250, v118
	v_add_f32_e32 v251, v251, v119
	v_cvt_pk_bf16_f32 v111, v118, v119
	ds_read2_b64 v[116:119], v209 offset0:16 offset1:18
	s_waitcnt lgkmcnt(0)
; #define LAS __attribute__((address_space(3)))
; template <bool MASKED> ...
;     ...
;     f32x16 s0, s1;
;     { const bf16x8 ka = *(const LAS bf16x8*)(kb), kc = *(const LAS bf16x8*)(kb + 32 * AK_PITCH);
;       s0 = __builtin_amdgcn_mfma_f32_32x32x16_bf16(ka, qf[0], negm, 0, 0, 0); s1 = __builtin_amdgcn_mfma_f32_32x32x16_bf16(kc, qf[0], negm, 0, 0, 0); }
; #pragma unroll
;     for (int s = 1; s < 6; ++s) { const bf16x8 ka = *(const LAS bf16x8*)(kb + s * 32), kc = *(const LAS bf16x8*)(kb + 32 * AK_PITCH + s * 32);
;         s0 = __builtin_amdgcn_mfma_f32_32x32x16_bf16(ka, qf[s], s0, 0, 0, 0); s1 = __builtin_amdgcn_mfma_f32_32x32x16_bf16(kc, qf[s], s1, 0, 0, 0); }
;     if (MASKED) {
; #pragma unroll
;         for (int r = 0; r < 16; ++r) { const int kv = 64 * jl + crow(r, hi); if (kv > qrel) s0[r] = -1e30f; if (kv + 32 > qrel) s1[r] = -1e30f; }
;     }
;     float mx = __builtin_fmaxf(s0[0], s1[0]);
; #pragma unroll
;     for (int r = 1; r < 16; ++r) mx = __builtin_fmaxf(__builtin_fmaxf(mx, s0[r]), s1[r]);
;     { auto rr = __builtin_amdgcn_permlane32_swap(__float_as_uint(mx), __float_as_uint(mx), false, false);
;       mx = __builtin_fmaxf(__uint_as_float(rr[0]), __uint_as_float(rr[1])); }
;     if (__any(first || mx > ATT_THR)) {
;         const float d = first ? mx : __builtin_fmaxf(mx, 0.f), f = __builtin_amdgcn_exp2f(-d);
;         mrun += d; o2[0] *= f;
; #pragma unroll
;         for (int r = 0; r < 16; ++r) { s0[r] -= d; s1[r] -= d; o0[r] *= f; o1[r] *= f; negm[r] = -mrun; }
;     }
; #pragma unroll
;     for (int r = 0; r < 16; ++r) { s0[r] = __builtin_amdgcn_exp2f(s0[r]); s1[r] = __builtin_amdgcn_exp2f(s1[r]); }
;     u32x4 pw[4];
;     pw[0] = (u32x4){pk2(s0[0], s0[1]), pk2(s0[2], s0[3]), pk2(s0[4], s0[5]), pk2(s0[6], s0[7])};
;     pw[1] = (u32x4){pk2(s0[8], s0[9]), pk2(s0[10], s0[11]), pk2(s0[12], s0[13]), pk2(s0[14], s0[15])};
;     pw[2] = (u32x4){pk2(s1[0], s1[1]), pk2(s1[2], s1[3]), pk2(s1[4], s1[5]), pk2(s1[6], s1[7])};
;     pw[3] = (u32x4){pk2(s1[8], s1[9]), pk2(s1[10], s1[11]), pk2(s1[12], s1[13]), pk2(s1[14], s1[15])};
; #pragma unroll
;     for (int ks = 0; ks < 4; ++ks) {
;         const s16x4 a0 = *(const LAS s16x4*)(vb + 32 * ks), a1 = *(const LAS s16x4*)(vb + 32 * ks + 16);
;         const s16x4 c0 = *(const LAS s16x4*)(vb + 32 * AV_PITCH + 32 * ks), c1 = *(const LAS s16x4*)(vb + 32 * AV_PITCH + 32 * ks + 16);
	v_mfma_f32_32x32x16_bf16 v[16:31], v[112:115], v[100:103], v[16:31]
	ds_read2_b64 v[112:115], v0 offset0:52 offset1:54
	v_exp_f32_e32 v123, v123
	v_exp_f32_e32 v124, v124
	v_exp_f32_e32 v125, v125
	v_exp_f32_e32 v126, v126
	v_exp_f32_e32 v127, v127
	v_add_f32_e32 v251, v251, v15
	v_add_f32_e32 v251, v251, v97
	v_cvt_pk_bf16_f32 v108, v15, v97
	v_add_f32_e32 v250, v250, v120
	v_add_f32_e32 v251, v251, v121
	v_cvt_pk_bf16_f32 v96, v120, v121
	v_add_f32_e32 v250, v250, v122
	v_add_f32_e32 v251, v251, v123
	v_cvt_pk_bf16_f32 v97, v122, v123
	v_add_f32_e32 v250, v250, v124
	v_add_f32_e32 v251, v251, v125
	v_cvt_pk_bf16_f32 v98, v124, v125
	v_add_f32_e32 v250, v250, v126
	v_add_f32_e32 v251, v251, v127
	v_cvt_pk_bf16_f32 v99, v126, v127
	ds_read2_b64 v[120:123], v209 offset0:20 offset1:22
	s_waitcnt lgkmcnt(1)
	v_mfma_f32_32x32x16_bf16 v[16:31], v[112:115], v[104:107], v[16:31]
	ds_read2_b64 v[124:127], v0 offset0:56 offset1:58
	ds_read2_b64 v[112:115], v209 offset0:24 offset1:26
	s_add_i32 s38, s41, 3
	s_min_u32 s41, s38, s40
	s_lshl_b32 s48, s41, 1
	s_waitcnt lgkmcnt(1)
	v_mfma_f32_32x32x16_bf16 v[16:31], v[124:127], v[108:111], v[16:31]
	ds_read2_b64 v[218:221], v0 offset0:60 offset1:62
	ds_read2_b64 v[124:127], v209 offset0:28 offset1:30
	v_add_u32_e32 v0, 0, v212
	v_add_u32_e32 v14, 0x4200, v0
	v_add_u32_e32 v0, 0x4280, v0
	s_waitcnt lgkmcnt(1)
	v_mfma_f32_32x32x16_bf16 v[16:31], v[218:221], v[96:99], v[16:31]
	s_waitcnt vmcnt(0)
	ds_write_b128 v185, v[156:159] offset:26624
	ds_write_b128 v205, v[160:163] offset:26624
	v_mfma_f32_32x32x16_bf16 v[32:47], v[116:119], v[100:103], v[32:47]
	ds_write_b128 v206, v[168:171] offset:26624
	ds_write2_b64 v14, v[164:165], v[166:167] offset1:1
	v_mad_u64_u32 v[14:15], s[38:39], s41, v230, v[196:197]
	v_mfma_f32_32x32x16_bf16 v[32:47], v[120:123], v[104:107], v[32:47]
	ds_write2_b64 v0, v[172:173], v[174:175] offset1:1
	s_waitcnt lgkmcnt(0)
	s_barrier
	ds_read_b128 v[218:221], v211 offset:33280
	global_load_dwordx4 v[156:159], v[14:15], off
	v_mad_u64_u32 v[14:15], s[38:39], s41, v230, v[198:199]
	global_load_dwordx4 v[160:163], v[14:15], off
	v_mfma_f32_32x32x16_bf16 v[32:47], v[112:115], v[108:111], v[32:47]
	ds_read_b128 v[112:115], v211 offset:26624
	ds_read_b128 v[232:235], v211 offset:26656
	v_mad_u64_u32 v[14:15], s[38:39], s41, v230, v[200:201]
	s_lshl_b64 s[38:39], s[48:49], 13
	s_or_b32 s48, s48, 1
	global_load_dwordx4 v[168:171], v[14:15], off
	v_mfma_f32_32x32x16_bf16 v[32:47], v[124:127], v[96:99], v[32:47]
	v_lshl_add_u64 v[14:15], v[202:203], 0, s[38:39]
	s_lshl_b64 s[38:39], s[48:49], 13
	global_load_dwordx4 v[164:167], v[14:15], off
	v_lshl_add_u64 v[14:15], v[202:203], 0, s[38:39]
	global_load_dwordx4 v[172:175], v[14:15], off
	s_nop 0
	s_nop 0
	s_nop 0
	s_waitcnt lgkmcnt(1)
	v_mfma_f32_32x32x16_bf16 v[96:111], v[112:115], v[152:155], v[80:95]
	v_mfma_f32_32x32x16_bf16 v[112:127], v[218:221], v[152:155], v[80:95]
	ds_read_b128 v[218:221], v211 offset:33312
	s_waitcnt lgkmcnt(1)
	v_mfma_f32_32x32x16_bf16 v[96:111], v[232:235], v[148:151], v[96:111]
	ds_read_b128 v[232:235], v211 offset:33344
	s_waitcnt lgkmcnt(1)
	v_mfma_f32_32x32x16_bf16 v[112:127], v[218:221], v[148:151], v[112:127]
	ds_read_b128 v[218:221], v211 offset:26688
	s_waitcnt lgkmcnt(0)
	v_mfma_f32_32x32x16_bf16 v[96:111], v[218:221], v[144:147], v[96:111]
	ds_read_b128 v[218:221], v211 offset:26720
	v_mfma_f32_32x32x16_bf16 v[112:127], v[232:235], v[144:147], v[112:127]
	ds_read_b128 v[232:235], v211 offset:33376
	s_waitcnt lgkmcnt(1)
	v_mfma_f32_32x32x16_bf16 v[96:111], v[218:221], v[140:143], v[96:111]
	ds_read_b128 v[218:221], v211 offset:26752
	s_waitcnt lgkmcnt(1)
	v_mfma_f32_32x32x16_bf16 v[112:127], v[232:235], v[140:143], v[112:127]
	ds_read_b128 v[232:235], v211 offset:33408
	s_waitcnt lgkmcnt(1)
	v_mfma_f32_32x32x16_bf16 v[96:111], v[218:221], v[136:139], v[96:111]
	ds_read_b128 v[218:221], v211 offset:26784
	s_waitcnt lgkmcnt(1)
	v_mfma_f32_32x32x16_bf16 v[112:127], v[232:235], v[136:139], v[112:127]
	ds_read_b128 v[232:235], v211 offset:33440
	s_waitcnt lgkmcnt(1)
	v_mfma_f32_32x32x16_bf16 v[96:111], v[218:221], v[132:135], v[96:111]
	s_waitcnt lgkmcnt(0)
	v_mfma_f32_32x32x16_bf16 v[112:127], v[232:235], v[132:135], v[112:127]
	s_nop 10
	v_max_f32_e32 v14, v96, v96
	v_max_f32_e32 v0, v112, v112
	v_max_f32_e32 v0, v14, v0
	v_max3_f32 v0, v0, v97, v113
	v_max3_f32 v0, v0, v98, v114
	v_max3_f32 v0, v0, v99, v115
	v_max3_f32 v0, v0, v100, v116
	v_max3_f32 v0, v0, v101, v117
	v_max3_f32 v0, v0, v102, v118
	v_max3_f32 v0, v0, v103, v119
	v_max3_f32 v0, v0, v104, v120
	v_max3_f32 v0, v0, v105, v121
	v_max3_f32 v0, v0, v106, v122
	v_max3_f32 v0, v0, v107, v123
	v_max3_f32 v0, v0, v108, v124
	v_max3_f32 v0, v0, v109, v125
	v_max3_f32 v0, v0, v110, v126
	v_max3_f32 v0, v0, v111, v127
	v_mov_b32_e32 v14, v0
	s_nop 1
	v_permlane32_swap_b32_e32 v0, v14
	v_max_f32_e32 v14, v14, v14
	v_max_f32_e32 v0, v0, v0
	v_max_f32_e32 v0, v0, v14
	v_cmp_lt_f32_e32 vcc, s23, v0
	s_cbranch_vccz .LBB0_337
; #define LAS __attribute__((address_space(3)))
; __device__ __forceinline__ unsigned pk2(float lo, float hi) { f32x2 v = {lo, hi}; bf16x2_t b = __builtin_convertvector(v, bf16x2_t); return __builtin_bit_cast(unsigned, b); }
; template <bool MASKED> ...
;     ...
;         const float d = first ? mx : __builtin_fmaxf(mx, 0.f), f = __builtin_amdgcn_exp2f(-d);
;         mrun += d; o2[0] *= f;
; #pragma unroll
;         for (int r = 0; r < 16; ++r) { s0[r] -= d; s1[r] -= d; o0[r] *= f; o1[r] *= f; negm[r] = -mrun; }
;     }
; #pragma unroll
;     for (int r = 0; r < 16; ++r) { s0[r] = __builtin_amdgcn_exp2f(s0[r]); s1[r] = __builtin_amdgcn_exp2f(s1[r]); }
;     u32x4 pw[4];
;     pw[0] = (u32x4){pk2(s0[0], s0[1]), pk2(s0[2], s0[3]), pk2(s0[4], s0[5]), pk2(s0[6], s0[7])};
;     pw[1] = (u32x4){pk2(s0[8], s0[9]), pk2(s0[10], s0[11]), pk2(s0[12], s0[13]), pk2(s0[14], s0[15])};
;     pw[2] = (u32x4){pk2(s1[0], s1[1]), pk2(s1[2], s1[3]), pk2(s1[4], s1[5]), pk2(s1[6], s1[7])};
;     pw[3] = (u32x4){pk2(s1[8], s1[9]), pk2(s1[10], s1[11]), pk2(s1[12], s1[13]), pk2(s1[14], s1[15])};
; #pragma unroll
;     for (int ks = 0; ks < 4; ++ks) {
;         const s16x4 a0 = *(const LAS s16x4*)(vb + 32 * ks), a1 = *(const LAS s16x4*)(vb + 32 * ks + 16);
;         const s16x4 c0 = *(const LAS s16x4*)(vb + 32 * AV_PITCH + 32 * ks), c1 = *(const LAS s16x4*)(vb + 32 * AV_PITCH + 32 * ks + 16);
;         const bf16x8 vf0 = (bf16x8){a0[0], a0[1], a0[2], a0[3], a1[0], a1[1], a1[2], a1[3]}, vf1 = (bf16x8){c0[0], c0[1], c0[2], c0[3], c1[0], c1[1], c1[2], c1[3]};
;         const bf16x8 pf = __builtin_bit_cast(bf16x8, pw[ks]);
;         o0 = __builtin_amdgcn_mfma_f32_32x32x16_bf16(vf0, pf, o0, 0, 0, 0); o1 = __builtin_amdgcn_mfma_f32_32x32x16_bf16(vf1, pf, o1, 0, 0, 0);
;         o2 = __builtin_amdgcn_mfma_f32_32x32x16_bf16(ones, pf, o2, 0, 0, 0);
;     }
	v_max_f32_e32 v0, v0, v0
	v_max_f32_e32 v0, 0, v0
	v_exp_f32_e64 v14, -v0
	v_add_f32_e32 v213, v213, v0
	v_xor_b32_e32 v80, 0x80000000, v213
	v_pk_add_f32 v[96:97], v[96:97], v[0:1] op_sel_hi:[1,0] neg_lo:[0,1] neg_hi:[0,1]
	v_mul_f32_e32 v48, v48, v14
	v_mul_f32_e32 v250, v250, v14
	v_mul_f32_e32 v251, v251, v14
	v_pk_add_f32 v[112:113], v[112:113], v[0:1] op_sel_hi:[1,0] neg_lo:[0,1] neg_hi:[0,1]
	v_pk_add_f32 v[98:99], v[98:99], v[0:1] op_sel_hi:[1,0] neg_lo:[0,1] neg_hi:[0,1]
	v_pk_add_f32 v[114:115], v[114:115], v[0:1] op_sel_hi:[1,0] neg_lo:[0,1] neg_hi:[0,1]
	v_pk_add_f32 v[100:101], v[100:101], v[0:1] op_sel_hi:[1,0] neg_lo:[0,1] neg_hi:[0,1]
	v_pk_add_f32 v[116:117], v[116:117], v[0:1] op_sel_hi:[1,0] neg_lo:[0,1] neg_hi:[0,1]
	v_pk_add_f32 v[102:103], v[102:103], v[0:1] op_sel_hi:[1,0] neg_lo:[0,1] neg_hi:[0,1]
	v_pk_add_f32 v[118:119], v[118:119], v[0:1] op_sel_hi:[1,0] neg_lo:[0,1] neg_hi:[0,1]
	v_pk_add_f32 v[104:105], v[104:105], v[0:1] op_sel_hi:[1,0] neg_lo:[0,1] neg_hi:[0,1]
	v_pk_add_f32 v[120:121], v[120:121], v[0:1] op_sel_hi:[1,0] neg_lo:[0,1] neg_hi:[0,1]
	v_pk_add_f32 v[106:107], v[106:107], v[0:1] op_sel_hi:[1,0] neg_lo:[0,1] neg_hi:[0,1]
	v_pk_add_f32 v[122:123], v[122:123], v[0:1] op_sel_hi:[1,0] neg_lo:[0,1] neg_hi:[0,1]
	v_pk_add_f32 v[108:109], v[108:109], v[0:1] op_sel_hi:[1,0] neg_lo:[0,1] neg_hi:[0,1]
	v_pk_add_f32 v[124:125], v[124:125], v[0:1] op_sel_hi:[1,0] neg_lo:[0,1] neg_hi:[0,1]
	v_pk_add_f32 v[110:111], v[110:111], v[0:1] op_sel_hi:[1,0] neg_lo:[0,1] neg_hi:[0,1]
	v_pk_add_f32 v[126:127], v[126:127], v[0:1] op_sel_hi:[1,0] neg_lo:[0,1] neg_hi:[0,1]
	v_pk_mul_f32 v[46:47], v[46:47], v[14:15] op_sel_hi:[1,0]
	v_pk_mul_f32 v[44:45], v[44:45], v[14:15] op_sel_hi:[1,0]
	v_pk_mul_f32 v[42:43], v[42:43], v[14:15] op_sel_hi:[1,0]
	v_pk_mul_f32 v[40:41], v[40:41], v[14:15] op_sel_hi:[1,0]
	v_pk_mul_f32 v[38:39], v[38:39], v[14:15] op_sel_hi:[1,0]
	v_pk_mul_f32 v[36:37], v[36:37], v[14:15] op_sel_hi:[1,0]
	v_pk_mul_f32 v[34:35], v[34:35], v[14:15] op_sel_hi:[1,0]
	v_pk_mul_f32 v[32:33], v[32:33], v[14:15] op_sel_hi:[1,0]
	v_pk_mul_f32 v[30:31], v[30:31], v[14:15] op_sel_hi:[1,0]
	v_pk_mul_f32 v[28:29], v[28:29], v[14:15] op_sel_hi:[1,0]
	v_pk_mul_f32 v[26:27], v[26:27], v[14:15] op_sel_hi:[1,0]
	v_pk_mul_f32 v[24:25], v[24:25], v[14:15] op_sel_hi:[1,0]
	v_pk_mul_f32 v[22:23], v[22:23], v[14:15] op_sel_hi:[1,0]
	v_pk_mul_f32 v[20:21], v[20:21], v[14:15] op_sel_hi:[1,0]
	v_pk_mul_f32 v[18:19], v[18:19], v[14:15] op_sel_hi:[1,0]
	v_pk_mul_f32 v[16:17], v[16:17], v[14:15] op_sel_hi:[1,0]
	v_mov_b32_e32 v81, v80
	v_mov_b32_e32 v82, v80
	v_mov_b32_e32 v83, v80
	v_mov_b32_e32 v84, v80
	v_mov_b32_e32 v85, v80
	v_mov_b32_e32 v86, v80
	v_mov_b32_e32 v87, v80
	v_mov_b32_e32 v88, v80
	v_mov_b32_e32 v89, v80
	v_mov_b32_e32 v90, v80
	v_mov_b32_e32 v91, v80
	v_mov_b32_e32 v92, v80
	v_mov_b32_e32 v93, v80
	v_mov_b32_e32 v94, v80
	v_mov_b32_e32 v95, v80
	v_mov_b32_e32 v64, v80
	v_mov_b32_e32 v65, v80
	v_mov_b32_e32 v66, v80
	v_mov_b32_e32 v67, v80
	v_mov_b32_e32 v68, v80
	v_mov_b32_e32 v69, v80
	v_mov_b32_e32 v70, v80
	v_mov_b32_e32 v71, v80
	v_mov_b32_e32 v72, v80
	v_mov_b32_e32 v73, v80
	v_mov_b32_e32 v74, v80
	v_mov_b32_e32 v75, v80
	v_mov_b32_e32 v76, v80
	v_mov_b32_e32 v77, v80
	v_mov_b32_e32 v78, v80
	v_mov_b32_e32 v79, v80
.LBB0_337:
	v_exp_f32_e32 v0, v96
	v_exp_f32_e32 v14, v112
	v_exp_f32_e32 v15, v97
	v_exp_f32_e32 v96, v113
	v_exp_f32_e32 v97, v98
	v_exp_f32_e32 v98, v114
	v_exp_f32_e32 v99, v99
	v_exp_f32_e32 v112, v115
	v_exp_f32_e32 v113, v100
	v_exp_f32_e32 v114, v116
	v_exp_f32_e32 v115, v101
	v_exp_f32_e32 v116, v117
	v_exp_f32_e32 v117, v102
	v_exp_f32_e32 v103, v103
	v_exp_f32_e32 v104, v104
	v_exp_f32_e32 v105, v105
	v_exp_f32_e32 v106, v106
	v_exp_f32_e32 v107, v107
	v_exp_f32_e32 v108, v108
	v_exp_f32_e32 v109, v109
	v_exp_f32_e32 v118, v118
	v_exp_f32_e32 v119, v119
	v_exp_f32_e32 v110, v110
	v_exp_f32_e32 v111, v111
	v_add_f32_e32 v250, v250, v0
	v_add_f32_e32 v250, v250, v15
	v_cvt_pk_bf16_f32 v100, v0, v15
	v_add_f32_e32 v250, v250, v97
	v_add_f32_e32 v250, v250, v99
	v_cvt_pk_bf16_f32 v101, v97, v99
	v_add_f32_e32 v250, v250, v113
	v_add_f32_e32 v250, v250, v115
	v_cvt_pk_bf16_f32 v102, v113, v115
	v_add_f32_e32 v250, v250, v117
	v_add_f32_e32 v251, v251, v103
	v_cvt_pk_bf16_f32 v103, v117, v103
	v_add_f32_e32 v250, v250, v104
	v_add_f32_e32 v251, v251, v105
	v_cvt_pk_bf16_f32 v104, v104, v105
	v_add_f32_e32 v250, v250, v106
	v_add_f32_e32 v251, v251, v107
	v_cvt_pk_bf16_f32 v105, v106, v107
	v_add_f32_e32 v250, v250, v108
	v_add_f32_e32 v251, v251, v109
	v_cvt_pk_bf16_f32 v106, v108, v109
	v_add_f32_e32 v251, v251, v14
	v_add_f32_e32 v251, v251, v96
	v_cvt_pk_bf16_f32 v108, v14, v96
	v_add_u32_e32 v0, 0x6000, v209
	v_add_u32_e32 v14, 0x4000, v209
	v_add_f32_e32 v250, v250, v110
	v_add_f32_e32 v251, v251, v111
	v_cvt_pk_bf16_f32 v107, v110, v111
	v_add_f32_e32 v251, v251, v98
	v_add_f32_e32 v251, v251, v112
	v_cvt_pk_bf16_f32 v109, v98, v112
	v_add_f32_e32 v251, v251, v114
	v_add_f32_e32 v251, v251, v116
	v_cvt_pk_bf16_f32 v110, v114, v116
	v_add_f32_e32 v250, v250, v118
	v_add_f32_e32 v251, v251, v119
	v_cvt_pk_bf16_f32 v111, v118, v119
	s_nop 0
	ds_read2_b64 v[112:115], v0 offset0:96 offset1:98
	ds_read2_b64 v[116:119], v14 offset0:64 offset1:66
	v_exp_f32_e32 v120, v120
	v_exp_f32_e32 v121, v121
	v_exp_f32_e32 v122, v122
	v_exp_f32_e32 v123, v123
	v_exp_f32_e32 v124, v124
	v_add_f32_e32 v250, v250, v120
	v_add_f32_e32 v251, v251, v121
	v_cvt_pk_bf16_f32 v96, v120, v121
	s_waitcnt lgkmcnt(0)
; #define LAS __attribute__((address_space(3)))
; template <bool MASKED> ...
;     ...
;     f32x16 s0, s1;
;     { const bf16x8 ka = *(const LAS bf16x8*)(kb), kc = *(const LAS bf16x8*)(kb + 32 * AK_PITCH);
;       s0 = __builtin_amdgcn_mfma_f32_32x32x16_bf16(ka, qf[0], negm, 0, 0, 0); s1 = __builtin_amdgcn_mfma_f32_32x32x16_bf16(kc, qf[0], negm, 0, 0, 0); }
; #pragma unroll
;     for (int s = 1; s < 6; ++s) { const bf16x8 ka = *(const LAS bf16x8*)(kb + s * 32), kc = *(const LAS bf16x8*)(kb + 32 * AK_PITCH + s * 32);
;         s0 = __builtin_amdgcn_mfma_f32_32x32x16_bf16(ka, qf[s], s0, 0, 0, 0); s1 = __builtin_amdgcn_mfma_f32_32x32x16_bf16(kc, qf[s], s1, 0, 0, 0); }
;     if (MASKED) {
; #pragma unroll
;         for (int r = 0; r < 16; ++r) { const int kv = 64 * jl + crow(r, hi); if (kv > qrel) s0[r] = -1e30f; if (kv + 32 > qrel) s1[r] = -1e30f; }
;     }
;     float mx = __builtin_fmaxf(s0[0], s1[0]);
; #pragma unroll
;     for (int r = 1; r < 16; ++r) mx = __builtin_fmaxf(__builtin_fmaxf(mx, s0[r]), s1[r]);
;     { auto rr = __builtin_amdgcn_permlane32_swap(__float_as_uint(mx), __float_as_uint(mx), false, false);
;       mx = __builtin_fmaxf(__uint_as_float(rr[0]), __uint_as_float(rr[1])); }
;     if (__any(first || mx > ATT_THR)) {
;         const float d = first ? mx : __builtin_fmaxf(mx, 0.f), f = __builtin_amdgcn_exp2f(-d);
;         mrun += d; o2[0] *= f;
; #pragma unroll
;         for (int r = 0; r < 16; ++r) { s0[r] -= d; s1[r] -= d; o0[r] *= f; o1[r] *= f; negm[r] = -mrun; }
;     }
; #pragma unroll
;     for (int r = 0; r < 16; ++r) { s0[r] = __builtin_amdgcn_exp2f(s0[r]); s1[r] = __builtin_amdgcn_exp2f(s1[r]); }
;     u32x4 pw[4];
;     pw[0] = (u32x4){pk2(s0[0], s0[1]), pk2(s0[2], s0[3]), pk2(s0[4], s0[5]), pk2(s0[6], s0[7])};
;     pw[1] = (u32x4){pk2(s0[8], s0[9]), pk2(s0[10], s0[11]), pk2(s0[12], s0[13]), pk2(s0[14], s0[15])};
;     pw[2] = (u32x4){pk2(s1[0], s1[1]), pk2(s1[2], s1[3]), pk2(s1[4], s1[5]), pk2(s1[6], s1[7])};
;     pw[3] = (u32x4){pk2(s1[8], s1[9]), pk2(s1[10], s1[11]), pk2(s1[12], s1[13]), pk2(s1[14], s1[15])};
; #pragma unroll
;     for (int ks = 0; ks < 4; ++ks) {
;         const s16x4 a0 = *(const LAS s16x4*)(vb + 32 * ks), a1 = *(const LAS s16x4*)(vb + 32 * ks + 16);
;         const s16x4 c0 = *(const LAS s16x4*)(vb + 32 * AV_PITCH + 32 * ks), c1 = *(const LAS s16x4*)(vb + 32 * AV_PITCH + 32 * ks + 16);
	v_mfma_f32_32x32x16_bf16 v[32:47], v[116:119], v[100:103], v[32:47]
	v_add_f32_e32 v250, v250, v122
	v_add_f32_e32 v251, v251, v123
	v_cvt_pk_bf16_f32 v97, v122, v123
	ds_read2_b64 v[120:123], v14 offset0:68 offset1:70
	ds_read_b128 v[116:119], v211 offset:39936
	v_exp_f32_e32 v125, v125
	v_exp_f32_e32 v126, v126
	v_exp_f32_e32 v127, v127
	v_add_f32_e32 v250, v250, v124
	v_add_f32_e32 v251, v251, v125
	v_cvt_pk_bf16_f32 v98, v124, v125
	v_mfma_f32_32x32x16_bf16 v[16:31], v[112:115], v[100:103], v[16:31]
	ds_read2_b64 v[100:103], v0 offset0:100 offset1:102
	ds_read_b128 v[112:115], v211 offset:46592
	v_add_f32_e32 v250, v250, v126
	v_add_f32_e32 v251, v251, v127
	v_cvt_pk_bf16_f32 v99, v126, v127
	s_waitcnt lgkmcnt(3)
	v_mfma_f32_32x32x16_bf16 v[32:47], v[120:123], v[104:107], v[32:47]
	ds_read_b128 v[120:123], v211 offset:39968
	s_waitcnt lgkmcnt(2)
	v_mfma_f32_32x32x16_bf16 v[16:31], v[100:103], v[104:107], v[16:31]
	ds_read2_b64 v[100:103], v14 offset0:72 offset1:74
	s_nop 0
	ds_read2_b64 v[104:107], v0 offset0:104 offset1:106
	s_waitcnt lgkmcnt(1)
	v_mfma_f32_32x32x16_bf16 v[32:47], v[100:103], v[108:111], v[32:47]
	ds_read2_b64 v[100:103], v14 offset0:76 offset1:78
	s_waitcnt lgkmcnt(1)
	v_mfma_f32_32x32x16_bf16 v[16:31], v[104:107], v[108:111], v[16:31]
	ds_read2_b64 v[104:107], v0 offset0:108 offset1:110
	s_nop 0
	s_waitcnt lgkmcnt(1)
	v_mfma_f32_32x32x16_bf16 v[32:47], v[100:103], v[96:99], v[32:47]
	s_waitcnt lgkmcnt(0)
	v_mfma_f32_32x32x16_bf16 v[16:31], v[104:107], v[96:99], v[16:31]
	s_nop 0
	v_mfma_f32_32x32x16_bf16 v[96:111], v[116:119], v[152:155], v[80:95]
	ds_read_b128 v[116:119], v211 offset:46656
	v_mfma_f32_32x32x16_bf16 v[80:95], v[112:115], v[152:155], v[80:95]
	ds_read_b128 v[112:115], v211 offset:46624
	v_mfma_f32_32x32x16_bf16 v[96:111], v[120:123], v[148:151], v[96:111]
	s_waitcnt lgkmcnt(0)
	v_mfma_f32_32x32x16_bf16 v[80:95], v[112:115], v[148:151], v[80:95]
	ds_read_b128 v[112:115], v211 offset:40000
	s_waitcnt lgkmcnt(0)
	v_mfma_f32_32x32x16_bf16 v[96:111], v[112:115], v[144:147], v[96:111]
	ds_read_b128 v[112:115], v211 offset:40032
	v_mfma_f32_32x32x16_bf16 v[80:95], v[116:119], v[144:147], v[80:95]
	ds_read_b128 v[116:119], v211 offset:46688
	s_waitcnt lgkmcnt(1)
	v_mfma_f32_32x32x16_bf16 v[96:111], v[112:115], v[140:143], v[96:111]
	ds_read_b128 v[112:115], v211 offset:40064
	s_waitcnt lgkmcnt(1)
	v_mfma_f32_32x32x16_bf16 v[80:95], v[116:119], v[140:143], v[80:95]
	ds_read_b128 v[116:119], v211 offset:46720
	s_waitcnt lgkmcnt(1)
	v_mfma_f32_32x32x16_bf16 v[96:111], v[112:115], v[136:139], v[96:111]
	ds_read_b128 v[112:115], v211 offset:40096
	s_waitcnt lgkmcnt(1)
	v_mfma_f32_32x32x16_bf16 v[80:95], v[116:119], v[136:139], v[80:95]
	ds_read_b128 v[116:119], v211 offset:46752
	s_waitcnt lgkmcnt(1)
	v_mfma_f32_32x32x16_bf16 v[96:111], v[112:115], v[132:135], v[96:111]
	s_waitcnt lgkmcnt(0)
	v_mfma_f32_32x32x16_bf16 v[80:95], v[116:119], v[132:135], v[80:95]
	s_nop 10
	v_max_f32_e32 v112, v96, v96
	v_max_f32_e32 v15, v80, v80
	v_max_f32_e32 v15, v112, v15
	v_max3_f32 v15, v15, v97, v81
	v_max3_f32 v15, v15, v98, v82
	v_max3_f32 v15, v15, v99, v83
	v_max3_f32 v15, v15, v100, v84
	v_max3_f32 v15, v15, v101, v85
	v_max3_f32 v15, v15, v102, v86
	v_max3_f32 v15, v15, v103, v87
	v_max3_f32 v15, v15, v104, v88
	v_max3_f32 v15, v15, v105, v89
	v_max3_f32 v15, v15, v106, v90
	v_max3_f32 v15, v15, v107, v91
	v_max3_f32 v15, v15, v108, v92
	v_max3_f32 v15, v15, v109, v93
	v_max3_f32 v15, v15, v110, v94
	v_max3_f32 v15, v15, v111, v95
	v_mov_b32_e32 v112, v15
	s_nop 1
	v_permlane32_swap_b32_e32 v15, v112
	v_max_f32_e32 v112, v112, v112
	v_max_f32_e32 v15, v15, v15
	v_max_f32_e32 v15, v15, v112
	v_cmp_lt_f32_e32 vcc, s23, v15
	s_cbranch_vccz .LBB0_339
	v_max_f32_e32 v15, v15, v15
	v_max_f32_e32 v66, 0, v15
	v_exp_f32_e64 v68, -v66
	v_add_f32_e32 v213, v213, v66
	v_xor_b32_e32 v64, 0x80000000, v213
	v_pk_add_f32 v[96:97], v[96:97], v[66:67] op_sel_hi:[1,0] neg_lo:[0,1] neg_hi:[0,1]
	v_mul_f32_e32 v48, v48, v68
	v_mul_f32_e32 v250, v250, v68
	v_mul_f32_e32 v251, v251, v68
	v_pk_add_f32 v[80:81], v[80:81], v[66:67] op_sel_hi:[1,0] neg_lo:[0,1] neg_hi:[0,1]
	v_pk_add_f32 v[98:99], v[98:99], v[66:67] op_sel_hi:[1,0] neg_lo:[0,1] neg_hi:[0,1]
	v_pk_add_f32 v[82:83], v[82:83], v[66:67] op_sel_hi:[1,0] neg_lo:[0,1] neg_hi:[0,1]
	v_pk_add_f32 v[100:101], v[100:101], v[66:67] op_sel_hi:[1,0] neg_lo:[0,1] neg_hi:[0,1]
	v_pk_add_f32 v[84:85], v[84:85], v[66:67] op_sel_hi:[1,0] neg_lo:[0,1] neg_hi:[0,1]
	v_pk_add_f32 v[102:103], v[102:103], v[66:67] op_sel_hi:[1,0] neg_lo:[0,1] neg_hi:[0,1]
	v_pk_add_f32 v[86:87], v[86:87], v[66:67] op_sel_hi:[1,0] neg_lo:[0,1] neg_hi:[0,1]
	v_pk_add_f32 v[104:105], v[104:105], v[66:67] op_sel_hi:[1,0] neg_lo:[0,1] neg_hi:[0,1]
	v_pk_add_f32 v[88:89], v[88:89], v[66:67] op_sel_hi:[1,0] neg_lo:[0,1] neg_hi:[0,1]
	v_pk_add_f32 v[106:107], v[106:107], v[66:67] op_sel_hi:[1,0] neg_lo:[0,1] neg_hi:[0,1]
	v_pk_add_f32 v[90:91], v[90:91], v[66:67] op_sel_hi:[1,0] neg_lo:[0,1] neg_hi:[0,1]
	v_pk_add_f32 v[108:109], v[108:109], v[66:67] op_sel_hi:[1,0] neg_lo:[0,1] neg_hi:[0,1]
	v_pk_add_f32 v[92:93], v[92:93], v[66:67] op_sel_hi:[1,0] neg_lo:[0,1] neg_hi:[0,1]
	v_pk_add_f32 v[110:111], v[110:111], v[66:67] op_sel_hi:[1,0] neg_lo:[0,1] neg_hi:[0,1]
	v_pk_add_f32 v[94:95], v[94:95], v[66:67] op_sel_hi:[1,0] neg_lo:[0,1] neg_hi:[0,1]
	v_pk_mul_f32 v[46:47], v[46:47], v[68:69] op_sel_hi:[1,0]
	v_pk_mul_f32 v[44:45], v[44:45], v[68:69] op_sel_hi:[1,0]
	v_pk_mul_f32 v[42:43], v[42:43], v[68:69] op_sel_hi:[1,0]
	v_pk_mul_f32 v[40:41], v[40:41], v[68:69] op_sel_hi:[1,0]
	v_pk_mul_f32 v[38:39], v[38:39], v[68:69] op_sel_hi:[1,0]
	v_pk_mul_f32 v[36:37], v[36:37], v[68:69] op_sel_hi:[1,0]
	v_pk_mul_f32 v[34:35], v[34:35], v[68:69] op_sel_hi:[1,0]
	v_pk_mul_f32 v[32:33], v[32:33], v[68:69] op_sel_hi:[1,0]
	v_pk_mul_f32 v[30:31], v[30:31], v[68:69] op_sel_hi:[1,0]
	v_pk_mul_f32 v[28:29], v[28:29], v[68:69] op_sel_hi:[1,0]
	v_pk_mul_f32 v[26:27], v[26:27], v[68:69] op_sel_hi:[1,0]
	v_pk_mul_f32 v[24:25], v[24:25], v[68:69] op_sel_hi:[1,0]
	v_pk_mul_f32 v[22:23], v[22:23], v[68:69] op_sel_hi:[1,0]
	v_pk_mul_f32 v[20:21], v[20:21], v[68:69] op_sel_hi:[1,0]
	v_pk_mul_f32 v[18:19], v[18:19], v[68:69] op_sel_hi:[1,0]
	v_pk_mul_f32 v[16:17], v[16:17], v[68:69] op_sel_hi:[1,0]
	v_mov_b32_e32 v65, v64
	v_mov_b32_e32 v66, v64
	v_mov_b32_e32 v67, v64
	v_mov_b32_e32 v68, v64
	v_mov_b32_e32 v69, v64
	v_mov_b32_e32 v70, v64
	v_mov_b32_e32 v71, v64
	v_mov_b32_e32 v72, v64
	v_mov_b32_e32 v73, v64
	v_mov_b32_e32 v74, v64
	v_mov_b32_e32 v75, v64
	v_mov_b32_e32 v76, v64
	v_mov_b32_e32 v77, v64
	v_mov_b32_e32 v78, v64
	v_mov_b32_e32 v79, v64
; #define LAS __attribute__((address_space(3)))
; __device__ __forceinline__ unsigned pk2(float lo, float hi) { f32x2 v = {lo, hi}; bf16x2_t b = __builtin_convertvector(v, bf16x2_t); return __builtin_bit_cast(unsigned, b); }
; template <bool MASKED> ...
;     ...
; #pragma unroll
;     for (int r = 0; r < 16; ++r) { s0[r] = __builtin_amdgcn_exp2f(s0[r]); s1[r] = __builtin_amdgcn_exp2f(s1[r]); }
;     u32x4 pw[4];
;     pw[0] = (u32x4){pk2(s0[0], s0[1]), pk2(s0[2], s0[3]), pk2(s0[4], s0[5]), pk2(s0[6], s0[7])};
;     pw[1] = (u32x4){pk2(s0[8], s0[9]), pk2(s0[10], s0[11]), pk2(s0[12], s0[13]), pk2(s0[14], s0[15])};
;     pw[2] = (u32x4){pk2(s1[0], s1[1]), pk2(s1[2], s1[3]), pk2(s1[4], s1[5]), pk2(s1[6], s1[7])};
;     pw[3] = (u32x4){pk2(s1[8], s1[9]), pk2(s1[10], s1[11]), pk2(s1[12], s1[13]), pk2(s1[14], s1[15])};
; #pragma unroll
;     for (int ks = 0; ks < 4; ++ks) {
;         const s16x4 a0 = *(const LAS s16x4*)(vb + 32 * ks), a1 = *(const LAS s16x4*)(vb + 32 * ks + 16);
;         const s16x4 c0 = *(const LAS s16x4*)(vb + 32 * AV_PITCH + 32 * ks), c1 = *(const LAS s16x4*)(vb + 32 * AV_PITCH + 32 * ks + 16);
;         const bf16x8 vf0 = (bf16x8){a0[0], a0[1], a0[2], a0[3], a1[0], a1[1], a1[2], a1[3]}, vf1 = (bf16x8){c0[0], c0[1], c0[2], c0[3], c1[0], c1[1], c1[2], c1[3]};
;         const bf16x8 pf = __builtin_bit_cast(bf16x8, pw[ks]);
;         o0 = __builtin_amdgcn_mfma_f32_32x32x16_bf16(vf0, pf, o0, 0, 0, 0); o1 = __builtin_amdgcn_mfma_f32_32x32x16_bf16(vf1, pf, o1, 0, 0, 0);
;         o2 = __builtin_amdgcn_mfma_f32_32x32x16_bf16(ones, pf, o2, 0, 0, 0);
;     }
; __device__ __forceinline__ void attn_unit(int b, int h, int qb, const bf16_t* __restrict__ Q, const bf16_t* __restrict__ Kb, const bf16_t* __restrict__ Vt, bf16_t* __restrict__ O, LAS unsigned char* lds) {
;     ...
;     for (; J < NT2 - 2; J += 2) { ATT_ITER(false, J, sA, sB, 0); ATT_ITER(false, J + 1, sB, sA, 1); }
.LBB0_339:
	v_exp_f32_e32 v15, v96
	v_exp_f32_e32 v96, v80
	v_exp_f32_e32 v80, v97
	v_exp_f32_e32 v97, v81
	v_exp_f32_e32 v81, v98
	v_exp_f32_e32 v98, v82
	v_exp_f32_e32 v82, v99
	v_exp_f32_e32 v99, v83
	v_exp_f32_e32 v83, v100
	v_exp_f32_e32 v100, v84
	v_exp_f32_e32 v84, v101
	v_exp_f32_e32 v101, v85
	v_exp_f32_e32 v85, v102
	v_exp_f32_e32 v102, v86
	v_exp_f32_e32 v86, v103
	v_exp_f32_e32 v103, v104
	v_exp_f32_e32 v104, v105
	v_exp_f32_e32 v105, v106
	v_exp_f32_e32 v106, v107
	v_exp_f32_e32 v107, v108
	v_exp_f32_e32 v108, v92
	v_exp_f32_e32 v112, v93
	v_exp_f32_e32 v113, v94
	v_exp_f32_e32 v114, v95
	v_add_f32_e32 v250, v250, v15
	v_add_f32_e32 v250, v250, v80
	v_cvt_pk_bf16_f32 v92, v15, v80
	v_add_f32_e32 v250, v250, v81
	v_add_f32_e32 v250, v250, v82
	v_cvt_pk_bf16_f32 v93, v81, v82
	v_add_f32_e32 v250, v250, v83
	v_add_f32_e32 v250, v250, v84
	v_cvt_pk_bf16_f32 v94, v83, v84
	v_add_f32_e32 v250, v250, v85
	v_add_f32_e32 v250, v250, v86
	v_cvt_pk_bf16_f32 v95, v85, v86
	v_add_f32_e32 v251, v251, v96
	v_add_f32_e32 v251, v251, v97
	v_cvt_pk_bf16_f32 v84, v96, v97
	v_add_f32_e32 v251, v251, v98
	v_add_f32_e32 v251, v251, v99
	v_cvt_pk_bf16_f32 v85, v98, v99
	s_nop 0
	ds_read2_b64 v[96:99], v0 offset0:112 offset1:114
	v_exp_f32_e32 v87, v87
	v_add_f32_e32 v251, v251, v103
	v_add_f32_e32 v250, v250, v104
	v_cvt_pk_bf16_f32 v80, v103, v104
	v_add_f32_e32 v251, v251, v100
	v_add_f32_e32 v251, v251, v101
	v_cvt_pk_bf16_f32 v86, v100, v101
	v_exp_f32_e32 v109, v109
	v_add_f32_e32 v251, v251, v102
	v_add_f32_e32 v250, v250, v87
	v_cvt_pk_bf16_f32 v87, v102, v87
	ds_read2_b64 v[100:103], v14 offset0:80 offset1:82
	s_waitcnt lgkmcnt(0)
	v_mfma_f32_32x32x16_bf16 v[16:31], v[96:99], v[92:95], v[16:31]
	ds_read2_b64 v[96:99], v0 offset0:116 offset1:118
	v_exp_f32_e32 v110, v110
	v_exp_f32_e32 v111, v111
	v_exp_f32_e32 v88, v88
	v_exp_f32_e32 v89, v89
	v_exp_f32_e32 v90, v90
	v_exp_f32_e32 v91, v91
	v_add_f32_e32 v251, v251, v105
	v_add_f32_e32 v250, v250, v106
	v_cvt_pk_bf16_f32 v81, v105, v106
	v_add_f32_e32 v251, v251, v107
	v_add_f32_e32 v251, v251, v109
	v_cvt_pk_bf16_f32 v82, v107, v109
	v_add_f32_e32 v250, v250, v110
	v_add_f32_e32 v251, v251, v111
	v_cvt_pk_bf16_f32 v83, v110, v111
	v_add_f32_e32 v250, v250, v88
	v_add_f32_e32 v251, v251, v89
	v_cvt_pk_bf16_f32 v88, v88, v89
	v_add_f32_e32 v250, v250, v90
	v_add_f32_e32 v251, v251, v91
	v_cvt_pk_bf16_f32 v89, v90, v91
	v_add_f32_e32 v250, v250, v108
	v_add_f32_e32 v251, v251, v112
	v_cvt_pk_bf16_f32 v90, v108, v112
	ds_read2_b64 v[104:107], v14 offset0:84 offset1:86
	s_waitcnt lgkmcnt(1)
	v_mfma_f32_32x32x16_bf16 v[16:31], v[96:99], v[80:83], v[16:31]
	ds_read2_b64 v[108:111], v0 offset0:120 offset1:122
	v_add_f32_e32 v250, v250, v113
	v_add_f32_e32 v251, v251, v114
	v_cvt_pk_bf16_f32 v91, v113, v114
	ds_read2_b64 v[96:99], v14 offset0:88 offset1:90
	s_cmp_lt_u32 s20, s21
	s_waitcnt lgkmcnt(1)
	v_mfma_f32_32x32x16_bf16 v[16:31], v[108:111], v[84:87], v[16:31]
	ds_read2_b64 v[112:115], v0 offset0:124 offset1:126
	ds_read2_b64 v[108:111], v14 offset0:92 offset1:94
	s_waitcnt lgkmcnt(1)
	v_mfma_f32_32x32x16_bf16 v[16:31], v[112:115], v[88:91], v[16:31]
	ds_write_b128 v185, v[2:5]
	ds_write_b128 v205, v[6:9]
	v_mfma_f32_32x32x16_bf16 v[32:47], v[100:103], v[92:95], v[32:47]
	ds_write_b128 v206, v[176:179]
	ds_write2_b64 v207, v[10:11], v[12:13] offset1:1
	v_mfma_f32_32x32x16_bf16 v[32:47], v[104:107], v[80:83], v[32:47]
	ds_write2_b64 v208, v[180:181], v[182:183] offset1:1
	s_waitcnt lgkmcnt(0)
	s_barrier
	v_mfma_f32_32x32x16_bf16 v[32:47], v[96:99], v[84:87], v[32:47]
	v_mfma_f32_32x32x16_bf16 v[32:47], v[108:111], v[88:91], v[32:47]
	s_nop 0
	s_nop 0
	s_nop 0
	s_cbranch_scc0 .LBB0_342
	s_mov_b32 s41, s20
	s_branch .LBB0_330

; #define LAS __attribute__((address_space(3)))
; __device__ __forceinline__ int crow(int r, int hi) { return (r & 3) + 8 * (r >> 2) + 4 * hi; }
; template <bool MASKED> ...
;     if (MASKED) { if (64 * jl > __builtin_amdgcn_readfirstlane(qrel | 31)) return; }
;     f32x16 s0, s1;
;     { const bf16x8 ka = *(const LAS bf16x8*)(kb), kc = *(const LAS bf16x8*)(kb + 32 * AK_PITCH);
;       s0 = __builtin_amdgcn_mfma_f32_32x32x16_bf16(ka, qf[0], negm, 0, 0, 0); s1 = __builtin_amdgcn_mfma_f32_32x32x16_bf16(kc, qf[0], negm, 0, 0, 0); }
; #pragma unroll
;     for (int s = 1; s < 6; ++s) { const bf16x8 ka = *(const LAS bf16x8*)(kb + s * 32), kc = *(const LAS bf16x8*)(kb + 32 * AK_PITCH + s * 32);
;         s0 = __builtin_amdgcn_mfma_f32_32x32x16_bf16(ka, qf[s], s0, 0, 0, 0); s1 = __builtin_amdgcn_mfma_f32_32x32x16_bf16(kc, qf[s], s1, 0, 0, 0); }
;     if (MASKED) {
; #pragma unroll
;         for (int r = 0; r < 16; ++r) { const int kv = 64 * jl + crow(r, hi); if (kv > qrel) s0[r] = -1e30f; if (kv + 32 > qrel) s1[r] = -1e30f; }
;     }
;     float mx = __builtin_fmaxf(s0[0], s1[0]);
; #pragma unroll
;     for (int r = 1; r < 16; ++r) mx = __builtin_fmaxf(__builtin_fmaxf(mx, s0[r]), s1[r]);
;     { auto rr = __builtin_amdgcn_permlane32_swap(__float_as_uint(mx), __float_as_uint(mx), false, false);
;       mx = __builtin_fmaxf(__uint_as_float(rr[0]), __uint_as_float(rr[1])); }
;     if (__any(first || mx > ATT_THR)) {
.LBB0_342:
	v_or_b32_e32 v125, s19, v195
	s_add_i32 s19, s20, 2
	s_min_u32 s19, s19, s40
	v_mad_u64_u32 v[2:3], s[38:39], s19, v230, v[196:197]
	v_mad_u64_u32 v[6:7], s[38:39], s19, v230, v[198:199]
	v_mad_u64_u32 v[10:11], s[38:39], s19, v230, v[200:201]
	s_lshl_b32 s48, s19, 1
	s_lshl_b64 s[38:39], s[48:49], 13
	s_or_b32 s48, s48, 1
	v_lshl_add_u64 v[14:15], v[202:203], 0, s[38:39]
	s_lshl_b64 s[38:39], s[48:49], 13
	global_load_dwordx4 v[10:13], v[10:11], off
	s_sub_i32 s19, s20, s21
	global_load_dwordx4 v[112:115], v[14:15], off
	v_lshl_add_u64 v[14:15], v[202:203], 0, s[38:39]
	global_load_dwordx4 v[2:5], v[2:3], off
	v_readfirstlane_b32 s21, v125
	global_load_dwordx4 v[6:9], v[6:7], off
	s_lshl_b32 s19, s19, 7
	global_load_dwordx4 v[116:119], v[14:15], off
	s_or_b32 s21, s21, 31
	v_and_b32_e32 v0, 63, v215
	v_lshlrev_b32_e32 v124, 3, v216
	s_cmp_gt_i32 s19, s21
	s_cbranch_scc1 .LBB0_346
	ds_read_b128 v[120:123], v211 offset:6656
	ds_read_b128 v[96:99], v211
	ds_read_b128 v[176:179], v211 offset:32
	v_lshl_or_b32 v126, v210, 2, s19
	v_cmp_le_i32_e32 vcc, v126, v125
	v_or_b32_e32 v15, 33, v126
	s_waitcnt lgkmcnt(0)
	v_mfma_f32_32x32x16_bf16 v[80:95], v[96:99], v[152:155], v[64:79]
	v_mov_b64_e32 v[110:111], v[78:79]
	v_mov_b64_e32 v[108:109], v[76:77]
	v_mov_b64_e32 v[106:107], v[74:75]
	v_mov_b64_e32 v[104:105], v[72:73]
	v_mov_b64_e32 v[102:103], v[70:71]
	v_mov_b64_e32 v[100:101], v[68:69]
	v_mov_b64_e32 v[98:99], v[66:67]
	v_mov_b64_e32 v[96:97], v[64:65]
	v_mfma_f32_32x32x16_bf16 v[80:95], v[176:179], v[148:151], v[80:95]
	v_or_b32_e32 v14, 32, v126
	v_cmp_le_i32_e64 s[40:41], v14, v125
	s_cmp_eq_u32 s20, 0
	s_cselect_b64 s[38:39], -1, 0
	v_mfma_f32_32x32x16_bf16 v[96:111], v[120:123], v[152:155], v[96:111]
	ds_read_b128 v[120:123], v211 offset:6688
	s_waitcnt lgkmcnt(0)
	v_mfma_f32_32x32x16_bf16 v[96:111], v[120:123], v[148:151], v[96:111]
	ds_read_b128 v[120:123], v211 offset:64
	ds_read_b128 v[176:179], v211 offset:6720
	s_waitcnt lgkmcnt(1)
	v_mfma_f32_32x32x16_bf16 v[80:95], v[120:123], v[144:147], v[80:95]
	s_waitcnt lgkmcnt(0)
	v_mfma_f32_32x32x16_bf16 v[96:111], v[176:179], v[144:147], v[96:111]
	ds_read_b128 v[120:123], v211 offset:96
	ds_read_b128 v[176:179], v211 offset:6752
	s_waitcnt lgkmcnt(1)
	v_mfma_f32_32x32x16_bf16 v[80:95], v[120:123], v[140:143], v[80:95]
	s_waitcnt lgkmcnt(0)
	v_mfma_f32_32x32x16_bf16 v[96:111], v[176:179], v[140:143], v[96:111]
	ds_read_b128 v[120:123], v211 offset:128
	ds_read_b128 v[176:179], v211 offset:6784
	s_waitcnt lgkmcnt(1)
	v_mfma_f32_32x32x16_bf16 v[80:95], v[120:123], v[136:139], v[80:95]
	s_waitcnt lgkmcnt(0)
	v_mfma_f32_32x32x16_bf16 v[96:111], v[176:179], v[136:139], v[96:111]
	ds_read_b128 v[120:123], v211 offset:160
	ds_read_b128 v[176:179], v211 offset:6816
	s_waitcnt lgkmcnt(1)
	v_mfma_f32_32x32x16_bf16 v[80:95], v[120:123], v[132:135], v[80:95]
	s_waitcnt lgkmcnt(0)
	v_mfma_f32_32x32x16_bf16 v[96:111], v[176:179], v[132:135], v[96:111]
	s_nop 10
	v_cndmask_b32_e32 v122, v231, v80, vcc
	v_cmp_le_i32_e32 vcc, v15, v125
	v_or_b32_e32 v80, 2, v126
	s_nop 0
	v_cndmask_b32_e32 v15, v231, v97, vcc
	v_cmp_le_i32_e32 vcc, v80, v125
	v_or_b32_e32 v80, 34, v126
	v_cndmask_b32_e64 v14, v231, v96, s[40:41]
	v_cndmask_b32_e32 v96, v231, v82, vcc
	v_cmp_le_i32_e32 vcc, v80, v125
	v_or_b32_e32 v80, 3, v126
	v_cmp_lt_i32_e64 s[40:41], v126, v125
	v_cndmask_b32_e32 v120, v231, v98, vcc
	v_cmp_le_i32_e32 vcc, v80, v125
	v_or_b32_e32 v80, 35, v126
	v_cndmask_b32_e64 v123, v231, v81, s[40:41]
	v_cndmask_b32_e32 v97, v231, v83, vcc
	v_cmp_le_i32_e32 vcc, v80, v125
	v_or_b32_e32 v80, 8, v126
	v_or_b32_e32 v81, 42, v126
	v_cndmask_b32_e32 v121, v231, v99, vcc
	v_cmp_le_i32_e32 vcc, v80, v125
	v_or_b32_e32 v80, 40, v126
	s_nop 0
	v_cndmask_b32_e32 v82, v231, v84, vcc
	v_cmp_le_i32_e32 vcc, v80, v125
	v_or_b32_e32 v80, 9, v126
	s_nop 0
	v_cndmask_b32_e32 v98, v231, v100, vcc
	v_cmp_le_i32_e32 vcc, v80, v125
	v_or_b32_e32 v80, 41, v126
	v_or_b32_e32 v100, 18, v126
	v_cndmask_b32_e32 v83, v231, v85, vcc
	v_cmp_le_i32_e32 vcc, v80, v125
	v_or_b32_e32 v80, 10, v126
	v_or_b32_e32 v85, 43, v126
	v_cndmask_b32_e32 v99, v231, v101, vcc
	v_cmp_le_i32_e32 vcc, v80, v125
	v_or_b32_e32 v101, 19, v126
	s_nop 0
	v_cndmask_b32_e32 v80, v231, v86, vcc
	v_cmp_le_i32_e32 vcc, v81, v125
	v_or_b32_e32 v81, 11, v126
	v_or_b32_e32 v86, 16, v126
	v_cndmask_b32_e32 v84, v231, v102, vcc
	v_cmp_le_i32_e32 vcc, v81, v125
	v_or_b32_e32 v102, 24, v126
	s_nop 0
	v_cndmask_b32_e32 v81, v231, v87, vcc
	v_cmp_le_i32_e32 vcc, v85, v125
	v_or_b32_e32 v87, 48, v126
	s_nop 0
	v_cndmask_b32_e32 v85, v231, v103, vcc
	v_cmp_le_i32_e32 vcc, v86, v125
	v_or_b32_e32 v103, 25, v126
	s_nop 0
	v_cndmask_b32_e32 v86, v231, v88, vcc
	v_cmp_le_i32_e32 vcc, v87, v125
	v_or_b32_e32 v87, 17, v126
	s_nop 0
	v_cndmask_b32_e32 v88, v231, v104, vcc
	v_cmp_le_i32_e32 vcc, v87, v125
	v_or_b32_e32 v104, 26, v126
	s_nop 0
	v_cndmask_b32_e32 v87, v231, v89, vcc
	v_or_b32_e32 v89, 49, v126
	v_cmp_le_i32_e32 vcc, v89, v125
	s_nop 1
	v_cndmask_b32_e32 v89, v231, v105, vcc
	v_cmp_le_i32_e32 vcc, v100, v125
	v_or_b32_e32 v100, 50, v126
	v_or_b32_e32 v105, 27, v126
	v_cndmask_b32_e32 v90, v231, v90, vcc
	v_cmp_le_i32_e32 vcc, v100, v125
	s_nop 1
	v_cndmask_b32_e32 v100, v231, v106, vcc
	v_cmp_le_i32_e32 vcc, v101, v125
	v_or_b32_e32 v101, 51, v126
	v_max_f32_e32 v106, v14, v14
	v_cndmask_b32_e32 v91, v231, v91, vcc
	v_cmp_le_i32_e32 vcc, v101, v125
	s_nop 1
	v_cndmask_b32_e32 v101, v231, v107, vcc
	v_max_f32_e32 v107, v122, v122
	v_max_f32_e32 v106, v107, v106
	v_max3_f32 v106, v106, v123, v15
	v_max3_f32 v106, v106, v96, v120
	v_max3_f32 v106, v106, v97, v121
	v_max3_f32 v106, v106, v82, v98
	v_max3_f32 v106, v106, v83, v99
	v_cmp_le_i32_e32 vcc, v102, v125
	v_or_b32_e32 v102, 56, v126
	v_max3_f32 v106, v106, v80, v84
	v_cndmask_b32_e32 v92, v231, v92, vcc
	v_cmp_le_i32_e32 vcc, v102, v125
	v_max3_f32 v106, v106, v81, v85
	v_max3_f32 v106, v106, v86, v88
	v_cndmask_b32_e32 v102, v231, v108, vcc
	v_cmp_le_i32_e32 vcc, v103, v125
	v_or_b32_e32 v103, 57, v126
	v_max3_f32 v106, v106, v87, v89
	v_cndmask_b32_e32 v93, v231, v93, vcc
	v_cmp_le_i32_e32 vcc, v103, v125
	v_max3_f32 v106, v106, v90, v100
	v_max3_f32 v106, v106, v91, v101
	v_cndmask_b32_e32 v103, v231, v109, vcc
	v_cmp_le_i32_e32 vcc, v104, v125
	v_or_b32_e32 v104, 58, v126
	v_max3_f32 v106, v106, v92, v102
	v_cndmask_b32_e32 v94, v231, v94, vcc
	v_cmp_le_i32_e32 vcc, v104, v125
	v_max3_f32 v106, v106, v93, v103
	s_nop 0
	v_cndmask_b32_e32 v104, v231, v110, vcc
	v_cmp_le_i32_e32 vcc, v105, v125
	v_or_b32_e32 v105, 59, v126
	v_max3_f32 v106, v106, v94, v104
	v_cndmask_b32_e32 v95, v231, v95, vcc
	v_cmp_le_i32_e32 vcc, v105, v125
	s_nop 1
	v_cndmask_b32_e32 v105, v231, v111, vcc
	v_max3_f32 v106, v106, v95, v105
	v_mov_b32_e32 v107, v106
	s_nop 1
	v_permlane32_swap_b32_e32 v106, v107
	v_max_f32_e32 v107, v107, v107
	v_max_f32_e32 v106, v106, v106
	v_max_f32_e32 v106, v106, v107
	v_cmp_lt_f32_e32 vcc, s23, v106
	s_or_b64 vcc, s[38:39], vcc
	s_cbranch_vccz .LBB0_345
; #define LAS __attribute__((address_space(3)))
; __device__ __forceinline__ unsigned pk2(float lo, float hi) { f32x2 v = {lo, hi}; bf16x2_t b = __builtin_convertvector(v, bf16x2_t); return __builtin_bit_cast(unsigned, b); }
; template <bool MASKED> ...
;     ...
;         const float d = first ? mx : __builtin_fmaxf(mx, 0.f), f = __builtin_amdgcn_exp2f(-d);
;         mrun += d; o2[0] *= f;
; #pragma unroll
;         for (int r = 0; r < 16; ++r) { s0[r] -= d; s1[r] -= d; o0[r] *= f; o1[r] *= f; negm[r] = -mrun; }
;     }
; #pragma unroll
;     for (int r = 0; r < 16; ++r) { s0[r] = __builtin_amdgcn_exp2f(s0[r]); s1[r] = __builtin_amdgcn_exp2f(s1[r]); }
;     u32x4 pw[4];
;     pw[0] = (u32x4){pk2(s0[0], s0[1]), pk2(s0[2], s0[3]), pk2(s0[4], s0[5]), pk2(s0[6], s0[7])};
;     pw[1] = (u32x4){pk2(s0[8], s0[9]), pk2(s0[10], s0[11]), pk2(s0[12], s0[13]), pk2(s0[14], s0[15])};
;     pw[2] = (u32x4){pk2(s1[0], s1[1]), pk2(s1[2], s1[3]), pk2(s1[4], s1[5]), pk2(s1[6], s1[7])};
;     pw[3] = (u32x4){pk2(s1[8], s1[9]), pk2(s1[10], s1[11]), pk2(s1[12], s1[13]), pk2(s1[14], s1[15])};
; #pragma unroll
;     for (int ks = 0; ks < 4; ++ks) {
;         const s16x4 a0 = *(const LAS s16x4*)(vb + 32 * ks), a1 = *(const LAS s16x4*)(vb + 32 * ks + 16);
;         const s16x4 c0 = *(const LAS s16x4*)(vb + 32 * AV_PITCH + 32 * ks), c1 = *(const LAS s16x4*)(vb + 32 * AV_PITCH + 32 * ks + 16);
;         const bf16x8 vf0 = (bf16x8){a0[0], a0[1], a0[2], a0[3], a1[0], a1[1], a1[2], a1[3]}, vf1 = (bf16x8){c0[0], c0[1], c0[2], c0[3], c1[0], c1[1], c1[2], c1[3]};
;         const bf16x8 pf = __builtin_bit_cast(bf16x8, pw[ks]);
;         o0 = __builtin_amdgcn_mfma_f32_32x32x16_bf16(vf0, pf, o0, 0, 0, 0); o1 = __builtin_amdgcn_mfma_f32_32x32x16_bf16(vf1, pf, o1, 0, 0, 0);
;         o2 = __builtin_amdgcn_mfma_f32_32x32x16_bf16(ones, pf, o2, 0, 0, 0);
;     }
	v_max_f32_e32 v64, v106, v106
	v_max_f32_e32 v64, 0, v64
	v_cndmask_b32_e64 v66, v64, v106, s[38:39]
	v_exp_f32_e64 v68, -v66
	v_add_f32_e32 v213, v213, v66
	v_xor_b32_e32 v64, 0x80000000, v213
	v_pk_add_f32 v[122:123], v[122:123], v[66:67] op_sel_hi:[1,0] neg_lo:[0,1] neg_hi:[0,1]
	v_mul_f32_e32 v48, v48, v68
	v_mul_f32_e32 v250, v250, v68
	v_mul_f32_e32 v251, v251, v68
	v_pk_add_f32 v[14:15], v[14:15], v[66:67] op_sel_hi:[1,0] neg_lo:[0,1] neg_hi:[0,1]
	v_pk_add_f32 v[96:97], v[96:97], v[66:67] op_sel_hi:[1,0] neg_lo:[0,1] neg_hi:[0,1]
	v_pk_add_f32 v[120:121], v[120:121], v[66:67] op_sel_hi:[1,0] neg_lo:[0,1] neg_hi:[0,1]
	v_pk_add_f32 v[82:83], v[82:83], v[66:67] op_sel_hi:[1,0] neg_lo:[0,1] neg_hi:[0,1]
	v_pk_add_f32 v[98:99], v[98:99], v[66:67] op_sel_hi:[1,0] neg_lo:[0,1] neg_hi:[0,1]
	v_pk_add_f32 v[80:81], v[80:81], v[66:67] op_sel_hi:[1,0] neg_lo:[0,1] neg_hi:[0,1]
	v_pk_add_f32 v[84:85], v[84:85], v[66:67] op_sel_hi:[1,0] neg_lo:[0,1] neg_hi:[0,1]
	v_pk_add_f32 v[86:87], v[86:87], v[66:67] op_sel_hi:[1,0] neg_lo:[0,1] neg_hi:[0,1]
	v_pk_add_f32 v[88:89], v[88:89], v[66:67] op_sel_hi:[1,0] neg_lo:[0,1] neg_hi:[0,1]
	v_pk_add_f32 v[90:91], v[90:91], v[66:67] op_sel_hi:[1,0] neg_lo:[0,1] neg_hi:[0,1]
	v_pk_add_f32 v[100:101], v[100:101], v[66:67] op_sel_hi:[1,0] neg_lo:[0,1] neg_hi:[0,1]
	v_pk_add_f32 v[92:93], v[92:93], v[66:67] op_sel_hi:[1,0] neg_lo:[0,1] neg_hi:[0,1]
	v_pk_add_f32 v[102:103], v[102:103], v[66:67] op_sel_hi:[1,0] neg_lo:[0,1] neg_hi:[0,1]
	v_pk_add_f32 v[94:95], v[94:95], v[66:67] op_sel_hi:[1,0] neg_lo:[0,1] neg_hi:[0,1]
	v_pk_add_f32 v[104:105], v[104:105], v[66:67] op_sel_hi:[1,0] neg_lo:[0,1] neg_hi:[0,1]
	v_pk_mul_f32 v[46:47], v[46:47], v[68:69] op_sel_hi:[1,0]
	v_pk_mul_f32 v[44:45], v[44:45], v[68:69] op_sel_hi:[1,0]
	v_pk_mul_f32 v[42:43], v[42:43], v[68:69] op_sel_hi:[1,0]
	v_pk_mul_f32 v[40:41], v[40:41], v[68:69] op_sel_hi:[1,0]
	v_pk_mul_f32 v[38:39], v[38:39], v[68:69] op_sel_hi:[1,0]
	v_pk_mul_f32 v[36:37], v[36:37], v[68:69] op_sel_hi:[1,0]
	v_pk_mul_f32 v[34:35], v[34:35], v[68:69] op_sel_hi:[1,0]
	v_pk_mul_f32 v[32:33], v[32:33], v[68:69] op_sel_hi:[1,0]
	v_pk_mul_f32 v[30:31], v[30:31], v[68:69] op_sel_hi:[1,0]
	v_pk_mul_f32 v[28:29], v[28:29], v[68:69] op_sel_hi:[1,0]
	v_pk_mul_f32 v[26:27], v[26:27], v[68:69] op_sel_hi:[1,0]
	v_pk_mul_f32 v[24:25], v[24:25], v[68:69] op_sel_hi:[1,0]
	v_pk_mul_f32 v[22:23], v[22:23], v[68:69] op_sel_hi:[1,0]
	v_pk_mul_f32 v[20:21], v[20:21], v[68:69] op_sel_hi:[1,0]
	v_pk_mul_f32 v[18:19], v[18:19], v[68:69] op_sel_hi:[1,0]
	v_pk_mul_f32 v[16:17], v[16:17], v[68:69] op_sel_hi:[1,0]
	v_mov_b32_e32 v65, v64
	v_mov_b32_e32 v66, v64
	v_mov_b32_e32 v67, v64
	v_mov_b32_e32 v68, v64
	v_mov_b32_e32 v69, v64
	v_mov_b32_e32 v70, v64
	v_mov_b32_e32 v71, v64
	v_mov_b32_e32 v72, v64
	v_mov_b32_e32 v73, v64
	v_mov_b32_e32 v74, v64
	v_mov_b32_e32 v75, v64
	v_mov_b32_e32 v76, v64
	v_mov_b32_e32 v77, v64
	v_mov_b32_e32 v78, v64
	v_mov_b32_e32 v79, v64
.LBB0_345:
	v_exp_f32_e32 v106, v122
	v_exp_f32_e32 v14, v14
	v_exp_f32_e32 v107, v123
	v_exp_f32_e32 v15, v15
	v_exp_f32_e32 v96, v96
	v_exp_f32_e32 v97, v97
	v_exp_f32_e32 v82, v82
	v_exp_f32_e32 v83, v83
	v_exp_f32_e32 v80, v80
	v_exp_f32_e32 v81, v81
	v_exp_f32_e32 v122, v89
	v_exp_f32_e32 v89, v90
	v_exp_f32_e32 v90, v91
	v_exp_f32_e32 v91, v92
	v_exp_f32_e32 v92, v93
	v_exp_f32_e32 v98, v98
	v_exp_f32_e32 v99, v99
	v_exp_f32_e32 v100, v100
	v_exp_f32_e32 v101, v101
	v_exp_f32_e32 v102, v102
	v_exp_f32_e32 v103, v103
	v_exp_f32_e32 v93, v94
	v_exp_f32_e32 v94, v95
	v_exp_f32_e32 v108, v120
	v_exp_f32_e32 v109, v121
	v_exp_f32_e32 v110, v84
	v_exp_f32_e32 v111, v85
	v_exp_f32_e32 v120, v86
	v_exp_f32_e32 v121, v88
	v_exp_f32_e32 v88, v87
	v_add_f32_e32 v250, v250, v106
	v_add_f32_e32 v250, v250, v107
	v_cvt_pk_bf16_f32 v84, v106, v107
	v_add_f32_e32 v250, v250, v96
	v_add_f32_e32 v251, v251, v97
	v_cvt_pk_bf16_f32 v85, v96, v97
	v_add_f32_e32 v250, v250, v82
	v_add_f32_e32 v251, v251, v83
	v_cvt_pk_bf16_f32 v86, v82, v83
	v_add_f32_e32 v250, v250, v80
	v_add_f32_e32 v251, v251, v81
	v_cvt_pk_bf16_f32 v87, v80, v81
	v_add_f32_e32 v251, v251, v89
	v_add_f32_e32 v250, v250, v90
	v_cvt_pk_bf16_f32 v89, v89, v90
	v_add_f32_e32 v251, v251, v91
	v_add_f32_e32 v250, v250, v92
	v_cvt_pk_bf16_f32 v90, v91, v92
	v_add_f32_e32 v251, v251, v14
	v_add_f32_e32 v251, v251, v15
	v_cvt_pk_bf16_f32 v92, v14, v15
	v_add_u32_e32 v14, 0xf000, v214
	v_add_f32_e32 v251, v251, v93
	v_add_f32_e32 v250, v250, v94
	v_cvt_pk_bf16_f32 v91, v93, v94
	v_add_f32_e32 v251, v251, v98
	v_add_f32_e32 v250, v250, v99
	v_cvt_pk_bf16_f32 v94, v98, v99
	v_add_f32_e32 v251, v251, v100
	v_add_f32_e32 v250, v250, v101
	v_cvt_pk_bf16_f32 v81, v100, v101
	v_add_f32_e32 v251, v251, v102
	v_add_f32_e32 v250, v250, v103
	v_cvt_pk_bf16_f32 v82, v102, v103
	s_nop 0
	ds_read2_b64 v[96:99], v14 offset0:32 offset1:34
	ds_read2_b64 v[100:103], v209 offset1:2
	v_exp_f32_e32 v104, v104
	v_exp_f32_e32 v105, v105
	v_add_f32_e32 v251, v251, v120
	v_add_f32_e32 v251, v251, v88
	v_cvt_pk_bf16_f32 v88, v120, v88
	v_add_f32_e32 v251, v251, v108
	v_add_f32_e32 v250, v250, v109
	v_cvt_pk_bf16_f32 v93, v108, v109
	v_add_f32_e32 v251, v251, v110
	v_add_f32_e32 v250, v250, v111
	v_cvt_pk_bf16_f32 v95, v110, v111
	v_add_f32_e32 v250, v250, v104
	v_add_f32_e32 v251, v251, v105
	v_cvt_pk_bf16_f32 v83, v104, v105
	s_waitcnt lgkmcnt(0)
	v_mfma_f32_32x32x16_bf16 v[32:47], v[100:103], v[84:87], v[32:47]
	ds_read2_b64 v[104:107], v209 offset0:4 offset1:6
	v_add_f32_e32 v250, v250, v122
	v_add_f32_e32 v250, v250, v121
	v_cvt_pk_bf16_f32 v80, v121, v122
	v_mfma_f32_32x32x16_bf16 v[16:31], v[96:99], v[84:87], v[16:31]
	ds_read2_b64 v[84:87], v14 offset0:36 offset1:38
	s_waitcnt lgkmcnt(1)
	v_mfma_f32_32x32x16_bf16 v[32:47], v[104:107], v[88:91], v[32:47]
	s_waitcnt lgkmcnt(0)
	v_mfma_f32_32x32x16_bf16 v[16:31], v[84:87], v[88:91], v[16:31]
	ds_read2_b64 v[84:87], v209 offset0:8 offset1:10
	s_nop 0
	ds_read2_b64 v[88:91], v14 offset0:40 offset1:42
	s_waitcnt lgkmcnt(1)
	v_mfma_f32_32x32x16_bf16 v[32:47], v[84:87], v[92:95], v[32:47]
	ds_read2_b64 v[84:87], v209 offset0:12 offset1:14
	s_waitcnt lgkmcnt(1)
	v_mfma_f32_32x32x16_bf16 v[16:31], v[88:91], v[92:95], v[16:31]
	ds_read2_b64 v[88:91], v14 offset0:44 offset1:46
	s_nop 0
	s_waitcnt lgkmcnt(1)
	v_mfma_f32_32x32x16_bf16 v[32:47], v[84:87], v[80:83], v[32:47]
	s_waitcnt lgkmcnt(0)
	v_mfma_f32_32x32x16_bf16 v[16:31], v[88:91], v[80:83], v[16:31]
	s_nop 0
; #define LAS __attribute__((address_space(3)))
; __device__ __forceinline__ int crow(int r, int hi) { return (r & 3) + 8 * (r >> 2) + 4 * hi; }
; template <bool MASKED> ...
;     if (MASKED) { if (64 * jl > __builtin_amdgcn_readfirstlane(qrel | 31)) return; }
;     f32x16 s0, s1;
;     { const bf16x8 ka = *(const LAS bf16x8*)(kb), kc = *(const LAS bf16x8*)(kb + 32 * AK_PITCH);
;       s0 = __builtin_amdgcn_mfma_f32_32x32x16_bf16(ka, qf[0], negm, 0, 0, 0); s1 = __builtin_amdgcn_mfma_f32_32x32x16_bf16(kc, qf[0], negm, 0, 0, 0); }
; #pragma unroll
;     for (int s = 1; s < 6; ++s) { const bf16x8 ka = *(const LAS bf16x8*)(kb + s * 32), kc = *(const LAS bf16x8*)(kb + 32 * AK_PITCH + s * 32);
;         s0 = __builtin_amdgcn_mfma_f32_32x32x16_bf16(ka, qf[s], s0, 0, 0, 0); s1 = __builtin_amdgcn_mfma_f32_32x32x16_bf16(kc, qf[s], s1, 0, 0, 0); }
;     if (MASKED) {
; #pragma unroll
;         for (int r = 0; r < 16; ++r) { const int kv = 64 * jl + crow(r, hi); if (kv > qrel) s0[r] = -1e30f; if (kv + 32 > qrel) s1[r] = -1e30f; }
;     }
;     float mx = __builtin_fmaxf(s0[0], s1[0]);
; #pragma unroll
;     for (int r = 1; r < 16; ++r) mx = __builtin_fmaxf(__builtin_fmaxf(mx, s0[r]), s1[r]);
;     { auto rr = __builtin_amdgcn_permlane32_swap(__float_as_uint(mx), __float_as_uint(mx), false, false);
;       mx = __builtin_fmaxf(__uint_as_float(rr[0]), __uint_as_float(rr[1])); }
;     if (__any(first || mx > ATT_THR)) {
.LBB0_346:
	v_readfirstlane_b32 s21, v125
	s_or_b32 s19, s19, 64
	s_or_b32 s21, s21, 31
	s_cmp_gt_i32 s19, s21
	s_cbranch_scc1 .LBB0_350
	ds_read_b128 v[80:83], v211 offset:13312
	ds_read_b128 v[120:123], v211 offset:19968
	v_lshl_or_b32 v126, v210, 2, s19
	v_or_b32_e32 v14, 32, v126
	v_cmp_le_i32_e32 vcc, v14, v125
	v_or_b32_e32 v15, 33, v126
	s_waitcnt lgkmcnt(0)
	v_mfma_f32_32x32x16_bf16 v[96:111], v[80:83], v[152:155], v[64:79]
	v_mfma_f32_32x32x16_bf16 v[80:95], v[120:123], v[152:155], v[64:79]
	ds_read_b128 v[120:123], v211 offset:13344
	s_waitcnt lgkmcnt(0)
	v_mfma_f32_32x32x16_bf16 v[96:111], v[120:123], v[148:151], v[96:111]
	ds_read_b128 v[120:123], v211 offset:20000
	s_waitcnt lgkmcnt(0)
	v_mfma_f32_32x32x16_bf16 v[80:95], v[120:123], v[148:151], v[80:95]
	ds_read_b128 v[120:123], v211 offset:13376
	s_waitcnt lgkmcnt(0)
	v_mfma_f32_32x32x16_bf16 v[96:111], v[120:123], v[144:147], v[96:111]
	ds_read_b128 v[120:123], v211 offset:20032
	s_waitcnt lgkmcnt(0)
	v_mfma_f32_32x32x16_bf16 v[80:95], v[120:123], v[144:147], v[80:95]
	ds_read_b128 v[120:123], v211 offset:13408
	s_waitcnt lgkmcnt(0)
	v_mfma_f32_32x32x16_bf16 v[96:111], v[120:123], v[140:143], v[96:111]
	ds_read_b128 v[120:123], v211 offset:20064
	s_waitcnt lgkmcnt(0)
	v_mfma_f32_32x32x16_bf16 v[80:95], v[120:123], v[140:143], v[80:95]
	ds_read_b128 v[120:123], v211 offset:13440
	s_waitcnt lgkmcnt(0)
	v_mfma_f32_32x32x16_bf16 v[96:111], v[120:123], v[136:139], v[96:111]
	ds_read_b128 v[120:123], v211 offset:20096
	s_waitcnt lgkmcnt(0)
	v_mfma_f32_32x32x16_bf16 v[80:95], v[120:123], v[136:139], v[80:95]
	ds_read_b128 v[120:123], v211 offset:20128
	s_waitcnt lgkmcnt(0)
	v_mfma_f32_32x32x16_bf16 v[80:95], v[120:123], v[132:135], v[80:95]
	ds_read_b128 v[120:123], v211 offset:13472
	s_waitcnt lgkmcnt(0)
	v_mfma_f32_32x32x16_bf16 v[96:111], v[120:123], v[132:135], v[96:111]
	s_nop 8
	v_cndmask_b32_e32 v14, v231, v80, vcc
	v_cmp_lt_i32_e32 vcc, v126, v125
	v_or_b32_e32 v80, 2, v126
	s_nop 0
	v_cndmask_b32_e32 v123, v231, v97, vcc
	v_cmp_le_i32_e32 vcc, v126, v125
	s_nop 1
	v_cndmask_b32_e32 v122, v231, v96, vcc
	v_cmp_le_i32_e32 vcc, v15, v125
	s_nop 1
	v_cndmask_b32_e32 v15, v231, v81, vcc
	v_cmp_le_i32_e32 vcc, v80, v125
	v_or_b32_e32 v80, 34, v126
	v_or_b32_e32 v81, 42, v126
	v_cndmask_b32_e32 v96, v231, v98, vcc
	v_cmp_le_i32_e32 vcc, v80, v125
	v_or_b32_e32 v80, 3, v126
	s_nop 0
	v_cndmask_b32_e32 v120, v231, v82, vcc
	v_cmp_le_i32_e32 vcc, v80, v125
	v_or_b32_e32 v80, 35, v126
	s_nop 0
	v_cndmask_b32_e32 v97, v231, v99, vcc
	v_cmp_le_i32_e32 vcc, v80, v125
	v_or_b32_e32 v80, 8, v126
	s_nop 0
	v_cndmask_b32_e32 v121, v231, v83, vcc
	v_cmp_le_i32_e32 vcc, v80, v125
	v_or_b32_e32 v80, 40, v126
	s_nop 0
	v_cndmask_b32_e32 v82, v231, v100, vcc
	v_cmp_le_i32_e32 vcc, v80, v125
	v_or_b32_e32 v80, 9, v126
	v_or_b32_e32 v100, 49, v126
	v_cndmask_b32_e32 v98, v231, v84, vcc
	v_cmp_le_i32_e32 vcc, v80, v125
	v_or_b32_e32 v80, 41, v126
	s_nop 0
	v_cndmask_b32_e32 v83, v231, v101, vcc
	v_cmp_le_i32_e32 vcc, v80, v125
	v_or_b32_e32 v80, 10, v126
	v_or_b32_e32 v101, 50, v126
	v_cndmask_b32_e32 v99, v231, v85, vcc
	v_cmp_le_i32_e32 vcc, v80, v125
	v_or_b32_e32 v85, 43, v126
	s_nop 0
	v_cndmask_b32_e32 v80, v231, v102, vcc
	v_cmp_le_i32_e32 vcc, v81, v125
	v_or_b32_e32 v81, 11, v126
	v_or_b32_e32 v102, 51, v126
	v_cndmask_b32_e32 v84, v231, v86, vcc
	v_cmp_le_i32_e32 vcc, v81, v125
	v_or_b32_e32 v86, 16, v126
	s_nop 0
	v_cndmask_b32_e32 v81, v231, v103, vcc
	v_cmp_le_i32_e32 vcc, v85, v125
	v_or_b32_e32 v103, 56, v126
	s_nop 0
	v_cndmask_b32_e32 v85, v231, v87, vcc
	v_cmp_le_i32_e32 vcc, v86, v125
	v_or_b32_e32 v87, 48, v126
	s_nop 0
	v_cndmask_b32_e32 v86, v231, v104, vcc
	v_cmp_le_i32_e32 vcc, v87, v125
	v_or_b32_e32 v87, 17, v126
	v_or_b32_e32 v104, 57, v126
	v_cndmask_b32_e32 v88, v231, v88, vcc
	v_cmp_le_i32_e32 vcc, v87, v125
	s_nop 1
	v_cndmask_b32_e32 v87, v231, v105, vcc
	v_cmp_le_i32_e32 vcc, v100, v125
	v_or_b32_e32 v100, 18, v126
	v_or_b32_e32 v105, 58, v126
	v_cndmask_b32_e32 v89, v231, v89, vcc
	v_cmp_le_i32_e32 vcc, v100, v125
	s_nop 1
	v_cndmask_b32_e32 v100, v231, v106, vcc
	v_cmp_le_i32_e32 vcc, v101, v125
	v_or_b32_e32 v101, 19, v126
	v_or_b32_e32 v106, 59, v126
	v_cndmask_b32_e32 v90, v231, v90, vcc
	v_cmp_le_i32_e32 vcc, v101, v125
	s_nop 1
	v_cndmask_b32_e32 v101, v231, v107, vcc
	v_cmp_le_i32_e32 vcc, v102, v125
	v_or_b32_e32 v102, 24, v126
	v_max_f32_e32 v107, v122, v122
	v_cndmask_b32_e32 v91, v231, v91, vcc
	v_cmp_le_i32_e32 vcc, v102, v125
	s_nop 1
	v_cndmask_b32_e32 v102, v231, v108, vcc
	v_cmp_le_i32_e32 vcc, v103, v125
	v_or_b32_e32 v103, 25, v126
	s_nop 0
	v_cndmask_b32_e32 v92, v231, v92, vcc
	v_cmp_le_i32_e32 vcc, v103, v125
	s_nop 1
	v_cndmask_b32_e32 v103, v231, v109, vcc
	v_cmp_le_i32_e32 vcc, v104, v125
	v_or_b32_e32 v104, 26, v126
	s_nop 0
	v_cndmask_b32_e32 v93, v231, v93, vcc
	v_cmp_le_i32_e32 vcc, v104, v125
	s_nop 1
	v_cndmask_b32_e32 v104, v231, v110, vcc
	v_cmp_le_i32_e32 vcc, v105, v125
	v_or_b32_e32 v105, 27, v126
	s_nop 0
	v_cndmask_b32_e32 v94, v231, v94, vcc
	v_cmp_le_i32_e32 vcc, v105, v125
	s_nop 1
	v_cndmask_b32_e32 v105, v231, v111, vcc
	v_cmp_le_i32_e32 vcc, v106, v125
	v_max_f32_e32 v106, v14, v14
	v_max_f32_e32 v106, v107, v106
	v_max3_f32 v106, v106, v123, v15
	v_max3_f32 v106, v106, v96, v120
	v_max3_f32 v106, v106, v97, v121
	v_max3_f32 v106, v106, v82, v98
	v_max3_f32 v106, v106, v83, v99
	v_max3_f32 v106, v106, v80, v84
	v_max3_f32 v106, v106, v81, v85
	v_max3_f32 v106, v106, v86, v88
	v_max3_f32 v106, v106, v87, v89
	v_max3_f32 v106, v106, v100, v90
	v_max3_f32 v106, v106, v101, v91
	v_max3_f32 v106, v106, v102, v92
	v_max3_f32 v106, v106, v103, v93
	v_cndmask_b32_e32 v95, v231, v95, vcc
	v_max3_f32 v106, v106, v104, v94
	v_max3_f32 v106, v106, v105, v95
	v_mov_b32_e32 v107, v106
	s_nop 1
	v_permlane32_swap_b32_e32 v106, v107
	v_max_f32_e32 v107, v107, v107
	v_max_f32_e32 v106, v106, v106
	v_max_f32_e32 v106, v106, v107
	v_cmp_lt_f32_e32 vcc, s23, v106
	s_cbranch_vccz .LBB0_349
; #define LAS __attribute__((address_space(3)))
; __device__ __forceinline__ unsigned pk2(float lo, float hi) { f32x2 v = {lo, hi}; bf16x2_t b = __builtin_convertvector(v, bf16x2_t); return __builtin_bit_cast(unsigned, b); }
; template <bool MASKED> ...
;     ...
;         const float d = first ? mx : __builtin_fmaxf(mx, 0.f), f = __builtin_amdgcn_exp2f(-d);
;         mrun += d; o2[0] *= f;
; #pragma unroll
;         for (int r = 0; r < 16; ++r) { s0[r] -= d; s1[r] -= d; o0[r] *= f; o1[r] *= f; negm[r] = -mrun; }
;     }
; #pragma unroll
;     for (int r = 0; r < 16; ++r) { s0[r] = __builtin_amdgcn_exp2f(s0[r]); s1[r] = __builtin_amdgcn_exp2f(s1[r]); }
;     u32x4 pw[4];
;     pw[0] = (u32x4){pk2(s0[0], s0[1]), pk2(s0[2], s0[3]), pk2(s0[4], s0[5]), pk2(s0[6], s0[7])};
;     pw[1] = (u32x4){pk2(s0[8], s0[9]), pk2(s0[10], s0[11]), pk2(s0[12], s0[13]), pk2(s0[14], s0[15])};
;     pw[2] = (u32x4){pk2(s1[0], s1[1]), pk2(s1[2], s1[3]), pk2(s1[4], s1[5]), pk2(s1[6], s1[7])};
;     pw[3] = (u32x4){pk2(s1[8], s1[9]), pk2(s1[10], s1[11]), pk2(s1[12], s1[13]), pk2(s1[14], s1[15])};
; #pragma unroll
;     for (int ks = 0; ks < 4; ++ks) {
;         const s16x4 a0 = *(const LAS s16x4*)(vb + 32 * ks), a1 = *(const LAS s16x4*)(vb + 32 * ks + 16);
;         const s16x4 c0 = *(const LAS s16x4*)(vb + 32 * AV_PITCH + 32 * ks), c1 = *(const LAS s16x4*)(vb + 32 * AV_PITCH + 32 * ks + 16);
;         const bf16x8 vf0 = (bf16x8){a0[0], a0[1], a0[2], a0[3], a1[0], a1[1], a1[2], a1[3]}, vf1 = (bf16x8){c0[0], c0[1], c0[2], c0[3], c1[0], c1[1], c1[2], c1[3]};
;         const bf16x8 pf = __builtin_bit_cast(bf16x8, pw[ks]);
;         o0 = __builtin_amdgcn_mfma_f32_32x32x16_bf16(vf0, pf, o0, 0, 0, 0); o1 = __builtin_amdgcn_mfma_f32_32x32x16_bf16(vf1, pf, o1, 0, 0, 0);
;         o2 = __builtin_amdgcn_mfma_f32_32x32x16_bf16(ones, pf, o2, 0, 0, 0);
;     }
	v_max_f32_e32 v64, v106, v106
	v_max_f32_e32 v66, 0, v64
	v_exp_f32_e64 v68, -v66
	v_add_f32_e32 v213, v213, v66
	v_xor_b32_e32 v64, 0x80000000, v213
	v_pk_add_f32 v[122:123], v[122:123], v[66:67] op_sel_hi:[1,0] neg_lo:[0,1] neg_hi:[0,1]
	v_mul_f32_e32 v48, v48, v68
	v_mul_f32_e32 v250, v250, v68
	v_mul_f32_e32 v251, v251, v68
	v_pk_add_f32 v[14:15], v[14:15], v[66:67] op_sel_hi:[1,0] neg_lo:[0,1] neg_hi:[0,1]
	v_pk_add_f32 v[96:97], v[96:97], v[66:67] op_sel_hi:[1,0] neg_lo:[0,1] neg_hi:[0,1]
	v_pk_add_f32 v[120:121], v[120:121], v[66:67] op_sel_hi:[1,0] neg_lo:[0,1] neg_hi:[0,1]
	v_pk_add_f32 v[82:83], v[82:83], v[66:67] op_sel_hi:[1,0] neg_lo:[0,1] neg_hi:[0,1]
	v_pk_add_f32 v[98:99], v[98:99], v[66:67] op_sel_hi:[1,0] neg_lo:[0,1] neg_hi:[0,1]
	v_pk_add_f32 v[80:81], v[80:81], v[66:67] op_sel_hi:[1,0] neg_lo:[0,1] neg_hi:[0,1]
	v_pk_add_f32 v[84:85], v[84:85], v[66:67] op_sel_hi:[1,0] neg_lo:[0,1] neg_hi:[0,1]
	v_pk_add_f32 v[86:87], v[86:87], v[66:67] op_sel_hi:[1,0] neg_lo:[0,1] neg_hi:[0,1]
	v_pk_add_f32 v[88:89], v[88:89], v[66:67] op_sel_hi:[1,0] neg_lo:[0,1] neg_hi:[0,1]
	v_pk_add_f32 v[100:101], v[100:101], v[66:67] op_sel_hi:[1,0] neg_lo:[0,1] neg_hi:[0,1]
	v_pk_add_f32 v[90:91], v[90:91], v[66:67] op_sel_hi:[1,0] neg_lo:[0,1] neg_hi:[0,1]
	v_pk_add_f32 v[102:103], v[102:103], v[66:67] op_sel_hi:[1,0] neg_lo:[0,1] neg_hi:[0,1]
	v_pk_add_f32 v[92:93], v[92:93], v[66:67] op_sel_hi:[1,0] neg_lo:[0,1] neg_hi:[0,1]
	v_pk_add_f32 v[104:105], v[104:105], v[66:67] op_sel_hi:[1,0] neg_lo:[0,1] neg_hi:[0,1]
	v_pk_add_f32 v[94:95], v[94:95], v[66:67] op_sel_hi:[1,0] neg_lo:[0,1] neg_hi:[0,1]
	v_pk_mul_f32 v[46:47], v[46:47], v[68:69] op_sel_hi:[1,0]
	v_pk_mul_f32 v[44:45], v[44:45], v[68:69] op_sel_hi:[1,0]
	v_pk_mul_f32 v[42:43], v[42:43], v[68:69] op_sel_hi:[1,0]
	v_pk_mul_f32 v[40:41], v[40:41], v[68:69] op_sel_hi:[1,0]
	v_pk_mul_f32 v[38:39], v[38:39], v[68:69] op_sel_hi:[1,0]
	v_pk_mul_f32 v[36:37], v[36:37], v[68:69] op_sel_hi:[1,0]
	v_pk_mul_f32 v[34:35], v[34:35], v[68:69] op_sel_hi:[1,0]
	v_pk_mul_f32 v[32:33], v[32:33], v[68:69] op_sel_hi:[1,0]
	v_pk_mul_f32 v[30:31], v[30:31], v[68:69] op_sel_hi:[1,0]
	v_pk_mul_f32 v[28:29], v[28:29], v[68:69] op_sel_hi:[1,0]
	v_pk_mul_f32 v[26:27], v[26:27], v[68:69] op_sel_hi:[1,0]
	v_pk_mul_f32 v[24:25], v[24:25], v[68:69] op_sel_hi:[1,0]
	v_pk_mul_f32 v[22:23], v[22:23], v[68:69] op_sel_hi:[1,0]
	v_pk_mul_f32 v[20:21], v[20:21], v[68:69] op_sel_hi:[1,0]
	v_pk_mul_f32 v[18:19], v[18:19], v[68:69] op_sel_hi:[1,0]
	v_pk_mul_f32 v[16:17], v[16:17], v[68:69] op_sel_hi:[1,0]
	v_mov_b32_e32 v65, v64
	v_mov_b32_e32 v66, v64
	v_mov_b32_e32 v67, v64
	v_mov_b32_e32 v68, v64
	v_mov_b32_e32 v69, v64
	v_mov_b32_e32 v70, v64
	v_mov_b32_e32 v71, v64
	v_mov_b32_e32 v72, v64
	v_mov_b32_e32 v73, v64
	v_mov_b32_e32 v74, v64
	v_mov_b32_e32 v75, v64
	v_mov_b32_e32 v76, v64
	v_mov_b32_e32 v77, v64
	v_mov_b32_e32 v78, v64
	v_mov_b32_e32 v79, v64
.LBB0_349:
	v_exp_f32_e32 v106, v122
	v_exp_f32_e32 v14, v14
	v_exp_f32_e32 v107, v123
	v_exp_f32_e32 v15, v15
	v_exp_f32_e32 v96, v96
	v_exp_f32_e32 v97, v97
	v_exp_f32_e32 v82, v82
	v_exp_f32_e32 v83, v83
	v_exp_f32_e32 v80, v80
	v_exp_f32_e32 v81, v81
	v_exp_f32_e32 v122, v89
	v_exp_f32_e32 v89, v100
	v_exp_f32_e32 v100, v90
	v_exp_f32_e32 v90, v101
	v_exp_f32_e32 v101, v91
	v_exp_f32_e32 v91, v102
	v_exp_f32_e32 v102, v92
	v_exp_f32_e32 v92, v103
	v_exp_f32_e32 v98, v98
	v_exp_f32_e32 v99, v99
	v_exp_f32_e32 v103, v93
	v_exp_f32_e32 v93, v104
	v_exp_f32_e32 v104, v94
	v_exp_f32_e32 v94, v105
	v_exp_f32_e32 v108, v120
	v_exp_f32_e32 v109, v121
	v_exp_f32_e32 v110, v84
	v_exp_f32_e32 v111, v85
	v_exp_f32_e32 v120, v86
	v_exp_f32_e32 v121, v88
	v_exp_f32_e32 v88, v87
	v_add_f32_e32 v250, v250, v106
	v_add_f32_e32 v250, v250, v107
	v_cvt_pk_bf16_f32 v84, v106, v107
	v_add_f32_e32 v250, v250, v96
	v_add_f32_e32 v251, v251, v97
	v_cvt_pk_bf16_f32 v85, v96, v97
	v_add_f32_e32 v250, v250, v82
	v_add_f32_e32 v251, v251, v83
	v_cvt_pk_bf16_f32 v86, v82, v83
	v_add_f32_e32 v250, v250, v80
	v_add_f32_e32 v251, v251, v81
	v_cvt_pk_bf16_f32 v87, v80, v81
	v_add_f32_e32 v251, v251, v89
	v_add_f32_e32 v251, v251, v90
	v_cvt_pk_bf16_f32 v89, v89, v90
	v_add_f32_e32 v251, v251, v91
	v_add_f32_e32 v251, v251, v92
	v_cvt_pk_bf16_f32 v90, v91, v92
	v_add_f32_e32 v251, v251, v14
	v_add_f32_e32 v251, v251, v15
	v_cvt_pk_bf16_f32 v92, v14, v15
	v_add_u32_e32 v14, 0xf000, v214
	v_add_f32_e32 v251, v251, v93
	v_add_f32_e32 v251, v251, v94
	v_cvt_pk_bf16_f32 v91, v93, v94
	v_add_f32_e32 v250, v250, v98
	v_add_f32_e32 v251, v251, v99
	v_cvt_pk_bf16_f32 v94, v98, v99
	v_add_f32_e32 v250, v250, v100
	v_add_f32_e32 v250, v250, v101
	v_cvt_pk_bf16_f32 v81, v100, v101
	v_add_f32_e32 v250, v250, v102
	v_add_f32_e32 v250, v250, v103
	v_cvt_pk_bf16_f32 v82, v102, v103
	s_nop 0
	ds_read2_b64 v[96:99], v14 offset0:48 offset1:50
	ds_read2_b64 v[100:103], v209 offset0:16 offset1:18
	v_exp_f32_e32 v105, v95
	v_add_f32_e32 v250, v250, v120
	v_add_f32_e32 v250, v250, v88
	v_cvt_pk_bf16_f32 v88, v120, v88
	v_add_f32_e32 v250, v250, v108
	v_add_f32_e32 v251, v251, v109
	v_cvt_pk_bf16_f32 v93, v108, v109
	v_add_f32_e32 v250, v250, v110
	v_add_f32_e32 v251, v251, v111
	v_cvt_pk_bf16_f32 v95, v110, v111
	v_add_f32_e32 v250, v250, v104
	v_add_f32_e32 v251, v251, v105
	v_cvt_pk_bf16_f32 v83, v104, v105
	s_waitcnt lgkmcnt(0)
	v_mfma_f32_32x32x16_bf16 v[32:47], v[100:103], v[84:87], v[32:47]
	ds_read2_b64 v[104:107], v209 offset0:20 offset1:22
	v_add_f32_e32 v250, v250, v122
	v_add_f32_e32 v251, v251, v121
	v_cvt_pk_bf16_f32 v80, v121, v122
	v_mfma_f32_32x32x16_bf16 v[16:31], v[96:99], v[84:87], v[16:31]
	ds_read2_b64 v[84:87], v14 offset0:52 offset1:54
	s_waitcnt lgkmcnt(1)
	v_mfma_f32_32x32x16_bf16 v[32:47], v[104:107], v[88:91], v[32:47]
	s_waitcnt lgkmcnt(0)
	v_mfma_f32_32x32x16_bf16 v[16:31], v[84:87], v[88:91], v[16:31]
	ds_read2_b64 v[84:87], v209 offset0:24 offset1:26
	s_nop 0
	ds_read2_b64 v[88:91], v14 offset0:56 offset1:58
	s_waitcnt lgkmcnt(1)
	v_mfma_f32_32x32x16_bf16 v[32:47], v[84:87], v[92:95], v[32:47]
	ds_read2_b64 v[84:87], v209 offset0:28 offset1:30
	s_waitcnt lgkmcnt(1)
	v_mfma_f32_32x32x16_bf16 v[16:31], v[88:91], v[92:95], v[16:31]
	ds_read2_b64 v[88:91], v14 offset0:60 offset1:62
	s_nop 0
	s_waitcnt lgkmcnt(1)
	v_mfma_f32_32x32x16_bf16 v[32:47], v[84:87], v[80:83], v[32:47]
	s_waitcnt lgkmcnt(0)
	v_mfma_f32_32x32x16_bf16 v[16:31], v[88:91], v[80:83], v[16:31]
	s_nop 0
; #define LAS __attribute__((address_space(3)))
; __device__ __forceinline__ int crow(int r, int hi) { return (r & 3) + 8 * (r >> 2) + 4 * hi; }
; template <bool MASKED> ...
;     if (MASKED) { if (64 * jl > __builtin_amdgcn_readfirstlane(qrel | 31)) return; }
;     f32x16 s0, s1;
;     { const bf16x8 ka = *(const LAS bf16x8*)(kb), kc = *(const LAS bf16x8*)(kb + 32 * AK_PITCH);
;       s0 = __builtin_amdgcn_mfma_f32_32x32x16_bf16(ka, qf[0], negm, 0, 0, 0); s1 = __builtin_amdgcn_mfma_f32_32x32x16_bf16(kc, qf[0], negm, 0, 0, 0); }
; #pragma unroll
;     for (int s = 1; s < 6; ++s) { const bf16x8 ka = *(const LAS bf16x8*)(kb + s * 32), kc = *(const LAS bf16x8*)(kb + 32 * AK_PITCH + s * 32);
;         s0 = __builtin_amdgcn_mfma_f32_32x32x16_bf16(ka, qf[s], s0, 0, 0, 0); s1 = __builtin_amdgcn_mfma_f32_32x32x16_bf16(kc, qf[s], s1, 0, 0, 0); }
;     if (MASKED) {
; #pragma unroll
;         for (int r = 0; r < 16; ++r) { const int kv = 64 * jl + crow(r, hi); if (kv > qrel) s0[r] = -1e30f; if (kv + 32 > qrel) s1[r] = -1e30f; }
;     }
;     float mx = __builtin_fmaxf(s0[0], s1[0]);
; #pragma unroll
;     for (int r = 1; r < 16; ++r) mx = __builtin_fmaxf(__builtin_fmaxf(mx, s0[r]), s1[r]);
;     { auto rr = __builtin_amdgcn_permlane32_swap(__float_as_uint(mx), __float_as_uint(mx), false, false);
;       mx = __builtin_fmaxf(__uint_as_float(rr[0]), __uint_as_float(rr[1])); }
;     if (__any(first || mx > ATT_THR)) {
.LBB0_350:
	v_add_u32_e32 v14, 0, v212
	v_add_u32_e32 v15, 0x4200, v14
	v_add_u32_e32 v14, 0x4280, v14
	s_waitcnt vmcnt(0) lgkmcnt(0)
	ds_write_b128 v185, v[156:159] offset:26624
	ds_write_b128 v205, v[160:163] offset:26624
	ds_write_b128 v206, v[168:171] offset:26624
	ds_write2_b64 v15, v[164:165], v[166:167] offset1:1
	ds_write2_b64 v14, v[172:173], v[174:175] offset1:1
	s_sub_i32 s1, s20, s1
	s_lshl_b32 s1, s1, 7
	v_readfirstlane_b32 s19, v125
	s_waitcnt lgkmcnt(0)
	s_barrier
	s_addk_i32 s1, 0x180
	s_or_b32 s19, s19, 31
	s_cmp_gt_i32 s1, s19
	s_cbranch_scc1 .LBB0_354
	ds_read_b128 v[80:83], v211 offset:26624
	ds_read_b128 v[120:123], v211 offset:33280
	v_lshl_or_b32 v126, v210, 2, s1
	v_or_b32_e32 v14, 32, v126
	v_cmp_le_i32_e32 vcc, v14, v125
	v_or_b32_e32 v15, 33, v126
	s_waitcnt lgkmcnt(1)
	v_mfma_f32_32x32x16_bf16 v[96:111], v[80:83], v[152:155], v[64:79]
	s_waitcnt lgkmcnt(0)
	v_mfma_f32_32x32x16_bf16 v[80:95], v[120:123], v[152:155], v[64:79]
	ds_read_b128 v[120:123], v211 offset:26656
	s_waitcnt lgkmcnt(0)
	v_mfma_f32_32x32x16_bf16 v[96:111], v[120:123], v[148:151], v[96:111]
	ds_read_b128 v[120:123], v211 offset:33312
	s_waitcnt lgkmcnt(0)
	v_mfma_f32_32x32x16_bf16 v[80:95], v[120:123], v[148:151], v[80:95]
	ds_read_b128 v[120:123], v211 offset:26688
	s_waitcnt lgkmcnt(0)
	v_mfma_f32_32x32x16_bf16 v[96:111], v[120:123], v[144:147], v[96:111]
	ds_read_b128 v[120:123], v211 offset:33344
	s_waitcnt lgkmcnt(0)
	v_mfma_f32_32x32x16_bf16 v[80:95], v[120:123], v[144:147], v[80:95]
	ds_read_b128 v[120:123], v211 offset:26720
	s_waitcnt lgkmcnt(0)
	v_mfma_f32_32x32x16_bf16 v[96:111], v[120:123], v[140:143], v[96:111]
	ds_read_b128 v[120:123], v211 offset:33376
	s_waitcnt lgkmcnt(0)
	v_mfma_f32_32x32x16_bf16 v[80:95], v[120:123], v[140:143], v[80:95]
	ds_read_b128 v[120:123], v211 offset:26752
	s_waitcnt lgkmcnt(0)
	v_mfma_f32_32x32x16_bf16 v[96:111], v[120:123], v[136:139], v[96:111]
	ds_read_b128 v[120:123], v211 offset:33408
	s_waitcnt lgkmcnt(0)
	v_mfma_f32_32x32x16_bf16 v[80:95], v[120:123], v[136:139], v[80:95]
	ds_read_b128 v[120:123], v211 offset:33440
	s_waitcnt lgkmcnt(0)
	v_mfma_f32_32x32x16_bf16 v[80:95], v[120:123], v[132:135], v[80:95]
	ds_read_b128 v[120:123], v211 offset:26784
	s_waitcnt lgkmcnt(0)
	v_mfma_f32_32x32x16_bf16 v[96:111], v[120:123], v[132:135], v[96:111]
	s_nop 8
	v_cndmask_b32_e32 v14, v231, v80, vcc
	v_cmp_lt_i32_e32 vcc, v126, v125
	v_or_b32_e32 v80, 2, v126
	s_nop 0
	v_cndmask_b32_e32 v123, v231, v97, vcc
	v_cmp_le_i32_e32 vcc, v126, v125
	s_nop 1
	v_cndmask_b32_e32 v122, v231, v96, vcc
	v_cmp_le_i32_e32 vcc, v15, v125
	s_nop 1
	v_cndmask_b32_e32 v15, v231, v81, vcc
	v_cmp_le_i32_e32 vcc, v80, v125
	v_or_b32_e32 v80, 34, v126
	v_or_b32_e32 v81, 42, v126
	v_cndmask_b32_e32 v96, v231, v98, vcc
	v_cmp_le_i32_e32 vcc, v80, v125
	v_or_b32_e32 v80, 3, v126
	s_nop 0
	v_cndmask_b32_e32 v120, v231, v82, vcc
	v_cmp_le_i32_e32 vcc, v80, v125
	v_or_b32_e32 v80, 35, v126
	s_nop 0
	v_cndmask_b32_e32 v97, v231, v99, vcc
	v_cmp_le_i32_e32 vcc, v80, v125
	v_or_b32_e32 v80, 8, v126
	s_nop 0
	v_cndmask_b32_e32 v121, v231, v83, vcc
	v_cmp_le_i32_e32 vcc, v80, v125
	v_or_b32_e32 v80, 40, v126
	s_nop 0
	v_cndmask_b32_e32 v82, v231, v100, vcc
	v_cmp_le_i32_e32 vcc, v80, v125
	v_or_b32_e32 v80, 9, v126
	v_or_b32_e32 v100, 49, v126
	v_cndmask_b32_e32 v98, v231, v84, vcc
	v_cmp_le_i32_e32 vcc, v80, v125
	v_or_b32_e32 v80, 41, v126
	s_nop 0
	v_cndmask_b32_e32 v83, v231, v101, vcc
	v_cmp_le_i32_e32 vcc, v80, v125
	v_or_b32_e32 v80, 10, v126
	v_or_b32_e32 v101, 50, v126
	v_cndmask_b32_e32 v99, v231, v85, vcc
	v_cmp_le_i32_e32 vcc, v80, v125
	v_or_b32_e32 v85, 43, v126
	s_nop 0
	v_cndmask_b32_e32 v80, v231, v102, vcc
	v_cmp_le_i32_e32 vcc, v81, v125
	v_or_b32_e32 v81, 11, v126
	v_or_b32_e32 v102, 51, v126
	v_cndmask_b32_e32 v84, v231, v86, vcc
	v_cmp_le_i32_e32 vcc, v81, v125
	v_or_b32_e32 v86, 16, v126
	s_nop 0
	v_cndmask_b32_e32 v81, v231, v103, vcc
	v_cmp_le_i32_e32 vcc, v85, v125
	v_or_b32_e32 v103, 56, v126
	s_nop 0
	v_cndmask_b32_e32 v85, v231, v87, vcc
	v_cmp_le_i32_e32 vcc, v86, v125
	v_or_b32_e32 v87, 48, v126
	s_nop 0
	v_cndmask_b32_e32 v86, v231, v104, vcc
	v_cmp_le_i32_e32 vcc, v87, v125
	v_or_b32_e32 v87, 17, v126
	v_or_b32_e32 v104, 57, v126
	v_cndmask_b32_e32 v88, v231, v88, vcc
	v_cmp_le_i32_e32 vcc, v87, v125
	s_nop 1
	v_cndmask_b32_e32 v87, v231, v105, vcc
	v_cmp_le_i32_e32 vcc, v100, v125
	v_or_b32_e32 v100, 18, v126
	v_or_b32_e32 v105, 58, v126
	v_cndmask_b32_e32 v89, v231, v89, vcc
	v_cmp_le_i32_e32 vcc, v100, v125
	s_nop 1
	v_cndmask_b32_e32 v100, v231, v106, vcc
	v_cmp_le_i32_e32 vcc, v101, v125
	v_or_b32_e32 v101, 19, v126
	v_or_b32_e32 v106, 59, v126
	v_cndmask_b32_e32 v90, v231, v90, vcc
	v_cmp_le_i32_e32 vcc, v101, v125
	s_nop 1
	v_cndmask_b32_e32 v101, v231, v107, vcc
	v_cmp_le_i32_e32 vcc, v102, v125
	v_or_b32_e32 v102, 24, v126
	v_max_f32_e32 v107, v122, v122
	v_cndmask_b32_e32 v91, v231, v91, vcc
	v_cmp_le_i32_e32 vcc, v102, v125
	s_nop 1
	v_cndmask_b32_e32 v102, v231, v108, vcc
	v_cmp_le_i32_e32 vcc, v103, v125
	v_or_b32_e32 v103, 25, v126
	s_nop 0
	v_cndmask_b32_e32 v92, v231, v92, vcc
	v_cmp_le_i32_e32 vcc, v103, v125
	s_nop 1
	v_cndmask_b32_e32 v103, v231, v109, vcc
	v_cmp_le_i32_e32 vcc, v104, v125
	v_or_b32_e32 v104, 26, v126
	s_nop 0
	v_cndmask_b32_e32 v93, v231, v93, vcc
	v_cmp_le_i32_e32 vcc, v104, v125
	s_nop 1
	v_cndmask_b32_e32 v104, v231, v110, vcc
	v_cmp_le_i32_e32 vcc, v105, v125
	v_or_b32_e32 v105, 27, v126
	s_nop 0
	v_cndmask_b32_e32 v94, v231, v94, vcc
	v_cmp_le_i32_e32 vcc, v105, v125
	s_nop 1
	v_cndmask_b32_e32 v105, v231, v111, vcc
	v_cmp_le_i32_e32 vcc, v106, v125
	v_max_f32_e32 v106, v14, v14
	v_max_f32_e32 v106, v107, v106
	v_max3_f32 v106, v106, v123, v15
	v_max3_f32 v106, v106, v96, v120
	v_max3_f32 v106, v106, v97, v121
	v_max3_f32 v106, v106, v82, v98
	v_max3_f32 v106, v106, v83, v99
	v_max3_f32 v106, v106, v80, v84
	v_max3_f32 v106, v106, v81, v85
	v_max3_f32 v106, v106, v86, v88
	v_max3_f32 v106, v106, v87, v89
	v_max3_f32 v106, v106, v100, v90
	v_max3_f32 v106, v106, v101, v91
	v_max3_f32 v106, v106, v102, v92
	v_max3_f32 v106, v106, v103, v93
	v_cndmask_b32_e32 v95, v231, v95, vcc
	v_max3_f32 v106, v106, v104, v94
	v_max3_f32 v106, v106, v105, v95
	v_mov_b32_e32 v107, v106
	s_nop 1
	v_permlane32_swap_b32_e32 v106, v107
	v_max_f32_e32 v107, v107, v107
	v_max_f32_e32 v106, v106, v106
	v_max_f32_e32 v106, v106, v107
	v_cmp_lt_f32_e32 vcc, s23, v106
	s_cbranch_vccz .LBB0_353
; #define LAS __attribute__((address_space(3)))
; __device__ __forceinline__ unsigned pk2(float lo, float hi) { f32x2 v = {lo, hi}; bf16x2_t b = __builtin_convertvector(v, bf16x2_t); return __builtin_bit_cast(unsigned, b); }
; template <bool MASKED> ...
;     ...
;     if (__any(first || mx > ATT_THR)) {
;         const float d = first ? mx : __builtin_fmaxf(mx, 0.f), f = __builtin_amdgcn_exp2f(-d);
;         mrun += d; o2[0] *= f;
; #pragma unroll
;         for (int r = 0; r < 16; ++r) { s0[r] -= d; s1[r] -= d; o0[r] *= f; o1[r] *= f; negm[r] = -mrun; }
;     }
; #pragma unroll
;     for (int r = 0; r < 16; ++r) { s0[r] = __builtin_amdgcn_exp2f(s0[r]); s1[r] = __builtin_amdgcn_exp2f(s1[r]); }
;     u32x4 pw[4];
;     pw[0] = (u32x4){pk2(s0[0], s0[1]), pk2(s0[2], s0[3]), pk2(s0[4], s0[5]), pk2(s0[6], s0[7])};
;     pw[1] = (u32x4){pk2(s0[8], s0[9]), pk2(s0[10], s0[11]), pk2(s0[12], s0[13]), pk2(s0[14], s0[15])};
;     pw[2] = (u32x4){pk2(s1[0], s1[1]), pk2(s1[2], s1[3]), pk2(s1[4], s1[5]), pk2(s1[6], s1[7])};
;     pw[3] = (u32x4){pk2(s1[8], s1[9]), pk2(s1[10], s1[11]), pk2(s1[12], s1[13]), pk2(s1[14], s1[15])};
; #pragma unroll
;     for (int ks = 0; ks < 4; ++ks) {
;         const s16x4 a0 = *(const LAS s16x4*)(vb + 32 * ks), a1 = *(const LAS s16x4*)(vb + 32 * ks + 16);
;         const s16x4 c0 = *(const LAS s16x4*)(vb + 32 * AV_PITCH + 32 * ks), c1 = *(const LAS s16x4*)(vb + 32 * AV_PITCH + 32 * ks + 16);
;         const bf16x8 vf0 = (bf16x8){a0[0], a0[1], a0[2], a0[3], a1[0], a1[1], a1[2], a1[3]}, vf1 = (bf16x8){c0[0], c0[1], c0[2], c0[3], c1[0], c1[1], c1[2], c1[3]};
;         const bf16x8 pf = __builtin_bit_cast(bf16x8, pw[ks]);
;         o0 = __builtin_amdgcn_mfma_f32_32x32x16_bf16(vf0, pf, o0, 0, 0, 0); o1 = __builtin_amdgcn_mfma_f32_32x32x16_bf16(vf1, pf, o1, 0, 0, 0);
;         o2 = __builtin_amdgcn_mfma_f32_32x32x16_bf16(ones, pf, o2, 0, 0, 0);
;     }
	v_max_f32_e32 v64, v106, v106
	v_max_f32_e32 v66, 0, v64
	v_exp_f32_e64 v68, -v66
	v_add_f32_e32 v64, v213, v66
	v_xor_b32_e32 v64, 0x80000000, v64
	v_pk_add_f32 v[122:123], v[122:123], v[66:67] op_sel_hi:[1,0] neg_lo:[0,1] neg_hi:[0,1]
	v_mul_f32_e32 v48, v48, v68
	v_mul_f32_e32 v250, v250, v68
	v_mul_f32_e32 v251, v251, v68
	v_pk_add_f32 v[14:15], v[14:15], v[66:67] op_sel_hi:[1,0] neg_lo:[0,1] neg_hi:[0,1]
	v_pk_add_f32 v[96:97], v[96:97], v[66:67] op_sel_hi:[1,0] neg_lo:[0,1] neg_hi:[0,1]
	v_pk_add_f32 v[120:121], v[120:121], v[66:67] op_sel_hi:[1,0] neg_lo:[0,1] neg_hi:[0,1]
	v_pk_add_f32 v[82:83], v[82:83], v[66:67] op_sel_hi:[1,0] neg_lo:[0,1] neg_hi:[0,1]
	v_pk_add_f32 v[98:99], v[98:99], v[66:67] op_sel_hi:[1,0] neg_lo:[0,1] neg_hi:[0,1]
	v_pk_add_f32 v[80:81], v[80:81], v[66:67] op_sel_hi:[1,0] neg_lo:[0,1] neg_hi:[0,1]
	v_pk_add_f32 v[84:85], v[84:85], v[66:67] op_sel_hi:[1,0] neg_lo:[0,1] neg_hi:[0,1]
	v_pk_add_f32 v[86:87], v[86:87], v[66:67] op_sel_hi:[1,0] neg_lo:[0,1] neg_hi:[0,1]
	v_pk_add_f32 v[88:89], v[88:89], v[66:67] op_sel_hi:[1,0] neg_lo:[0,1] neg_hi:[0,1]
	v_pk_add_f32 v[100:101], v[100:101], v[66:67] op_sel_hi:[1,0] neg_lo:[0,1] neg_hi:[0,1]
	v_pk_add_f32 v[90:91], v[90:91], v[66:67] op_sel_hi:[1,0] neg_lo:[0,1] neg_hi:[0,1]
	v_pk_add_f32 v[102:103], v[102:103], v[66:67] op_sel_hi:[1,0] neg_lo:[0,1] neg_hi:[0,1]
	v_pk_add_f32 v[92:93], v[92:93], v[66:67] op_sel_hi:[1,0] neg_lo:[0,1] neg_hi:[0,1]
	v_pk_add_f32 v[104:105], v[104:105], v[66:67] op_sel_hi:[1,0] neg_lo:[0,1] neg_hi:[0,1]
	v_pk_add_f32 v[94:95], v[94:95], v[66:67] op_sel_hi:[1,0] neg_lo:[0,1] neg_hi:[0,1]
	v_pk_mul_f32 v[46:47], v[46:47], v[68:69] op_sel_hi:[1,0]
	v_pk_mul_f32 v[44:45], v[44:45], v[68:69] op_sel_hi:[1,0]
	v_pk_mul_f32 v[42:43], v[42:43], v[68:69] op_sel_hi:[1,0]
	v_pk_mul_f32 v[40:41], v[40:41], v[68:69] op_sel_hi:[1,0]
	v_pk_mul_f32 v[38:39], v[38:39], v[68:69] op_sel_hi:[1,0]
	v_pk_mul_f32 v[36:37], v[36:37], v[68:69] op_sel_hi:[1,0]
	v_pk_mul_f32 v[34:35], v[34:35], v[68:69] op_sel_hi:[1,0]
	v_pk_mul_f32 v[32:33], v[32:33], v[68:69] op_sel_hi:[1,0]
	v_pk_mul_f32 v[30:31], v[30:31], v[68:69] op_sel_hi:[1,0]
	v_pk_mul_f32 v[28:29], v[28:29], v[68:69] op_sel_hi:[1,0]
	v_pk_mul_f32 v[26:27], v[26:27], v[68:69] op_sel_hi:[1,0]
	v_pk_mul_f32 v[24:25], v[24:25], v[68:69] op_sel_hi:[1,0]
	v_pk_mul_f32 v[22:23], v[22:23], v[68:69] op_sel_hi:[1,0]
	v_pk_mul_f32 v[20:21], v[20:21], v[68:69] op_sel_hi:[1,0]
	v_pk_mul_f32 v[18:19], v[18:19], v[68:69] op_sel_hi:[1,0]
	v_pk_mul_f32 v[16:17], v[16:17], v[68:69] op_sel_hi:[1,0]
	v_mov_b32_e32 v65, v64
	v_mov_b32_e32 v66, v64
	v_mov_b32_e32 v67, v64
	v_mov_b32_e32 v68, v64
	v_mov_b32_e32 v69, v64
	v_mov_b32_e32 v70, v64
	v_mov_b32_e32 v71, v64
	v_mov_b32_e32 v72, v64
	v_mov_b32_e32 v73, v64
	v_mov_b32_e32 v74, v64
	v_mov_b32_e32 v75, v64
	v_mov_b32_e32 v76, v64
	v_mov_b32_e32 v77, v64
	v_mov_b32_e32 v78, v64
	v_mov_b32_e32 v79, v64
.LBB0_353:
	v_exp_f32_e32 v106, v122
	v_exp_f32_e32 v14, v14
	v_exp_f32_e32 v107, v123
	v_exp_f32_e32 v15, v15
	v_exp_f32_e32 v96, v96
	v_exp_f32_e32 v97, v97
	v_exp_f32_e32 v82, v82
	v_exp_f32_e32 v83, v83
	v_exp_f32_e32 v80, v80
	v_exp_f32_e32 v81, v81
	v_exp_f32_e32 v122, v89
	v_exp_f32_e32 v89, v100
	v_exp_f32_e32 v100, v90
	v_exp_f32_e32 v90, v101
	v_exp_f32_e32 v101, v91
	v_exp_f32_e32 v91, v102
	v_exp_f32_e32 v102, v92
	v_exp_f32_e32 v92, v103
	v_exp_f32_e32 v98, v98
	v_exp_f32_e32 v99, v99
	v_exp_f32_e32 v103, v93
	v_exp_f32_e32 v93, v104
	v_exp_f32_e32 v104, v94
	v_exp_f32_e32 v94, v105
	v_exp_f32_e32 v108, v120
	v_exp_f32_e32 v109, v121
	v_exp_f32_e32 v110, v84
	v_exp_f32_e32 v111, v85
	v_exp_f32_e32 v120, v86
	v_exp_f32_e32 v121, v88
	v_exp_f32_e32 v88, v87
	v_add_f32_e32 v250, v250, v106
	v_add_f32_e32 v250, v250, v107
	v_cvt_pk_bf16_f32 v84, v106, v107
	v_add_f32_e32 v250, v250, v96
	v_add_f32_e32 v251, v251, v97
	v_cvt_pk_bf16_f32 v85, v96, v97
	v_add_f32_e32 v250, v250, v82
	v_add_f32_e32 v251, v251, v83
	v_cvt_pk_bf16_f32 v86, v82, v83
	v_add_f32_e32 v250, v250, v80
	v_add_f32_e32 v251, v251, v81
	v_cvt_pk_bf16_f32 v87, v80, v81
	v_add_f32_e32 v251, v251, v89
	v_add_f32_e32 v251, v251, v90
	v_cvt_pk_bf16_f32 v89, v89, v90
	v_add_f32_e32 v251, v251, v91
	v_add_f32_e32 v251, v251, v92
	v_cvt_pk_bf16_f32 v90, v91, v92
	v_add_f32_e32 v251, v251, v14
	v_add_f32_e32 v251, v251, v15
	v_cvt_pk_bf16_f32 v92, v14, v15
	v_add_u32_e32 v14, 0x6000, v209
	v_add_u32_e32 v15, 0x4000, v209
	v_add_f32_e32 v251, v251, v93
	v_add_f32_e32 v251, v251, v94
	v_cvt_pk_bf16_f32 v91, v93, v94
	v_add_f32_e32 v250, v250, v98
	v_add_f32_e32 v251, v251, v99
	v_cvt_pk_bf16_f32 v94, v98, v99
	v_add_f32_e32 v250, v250, v100
	v_add_f32_e32 v250, v250, v101
	v_cvt_pk_bf16_f32 v81, v100, v101
	v_add_f32_e32 v250, v250, v102
	v_add_f32_e32 v250, v250, v103
	v_cvt_pk_bf16_f32 v82, v102, v103
	s_nop 0
	ds_read2_b64 v[96:99], v14 offset0:96 offset1:98
	ds_read2_b64 v[100:103], v15 offset0:64 offset1:66
	v_exp_f32_e32 v105, v95
	v_add_f32_e32 v250, v250, v120
	v_add_f32_e32 v250, v250, v88
	v_cvt_pk_bf16_f32 v88, v120, v88
	v_add_f32_e32 v250, v250, v108
	v_add_f32_e32 v251, v251, v109
	v_cvt_pk_bf16_f32 v93, v108, v109
	v_add_f32_e32 v250, v250, v110
	v_add_f32_e32 v251, v251, v111
	v_cvt_pk_bf16_f32 v95, v110, v111
	v_add_f32_e32 v250, v250, v104
	v_add_f32_e32 v251, v251, v105
	v_cvt_pk_bf16_f32 v83, v104, v105
	s_waitcnt lgkmcnt(0)
	v_mfma_f32_32x32x16_bf16 v[32:47], v[100:103], v[84:87], v[32:47]
	ds_read2_b64 v[104:107], v15 offset0:68 offset1:70
	v_add_f32_e32 v250, v250, v122
	v_add_f32_e32 v251, v251, v121
	v_cvt_pk_bf16_f32 v80, v121, v122
	v_mfma_f32_32x32x16_bf16 v[16:31], v[96:99], v[84:87], v[16:31]
	ds_read2_b64 v[84:87], v14 offset0:100 offset1:102
	s_waitcnt lgkmcnt(1)
	v_mfma_f32_32x32x16_bf16 v[32:47], v[104:107], v[88:91], v[32:47]
	s_waitcnt lgkmcnt(0)
	v_mfma_f32_32x32x16_bf16 v[16:31], v[84:87], v[88:91], v[16:31]
	ds_read2_b64 v[84:87], v15 offset0:72 offset1:74
	s_nop 0
	ds_read2_b64 v[88:91], v14 offset0:104 offset1:106
	s_waitcnt lgkmcnt(1)
	v_mfma_f32_32x32x16_bf16 v[32:47], v[84:87], v[92:95], v[32:47]
	ds_read2_b64 v[84:87], v15 offset0:76 offset1:78
	s_waitcnt lgkmcnt(1)
	v_mfma_f32_32x32x16_bf16 v[16:31], v[88:91], v[92:95], v[16:31]
	ds_read2_b64 v[88:91], v14 offset0:108 offset1:110
	s_nop 0
	s_waitcnt lgkmcnt(1)
	v_mfma_f32_32x32x16_bf16 v[32:47], v[84:87], v[80:83], v[32:47]
	s_waitcnt lgkmcnt(0)
	v_mfma_f32_32x32x16_bf16 v[16:31], v[88:91], v[80:83], v[16:31]
	s_nop 0
; #define LAS __attribute__((address_space(3)))
; __device__ __forceinline__ int crow(int r, int hi) { return (r & 3) + 8 * (r >> 2) + 4 * hi; }
; template <bool MASKED> ...
;     if (MASKED) { if (64 * jl > __builtin_amdgcn_readfirstlane(qrel | 31)) return; }
;     f32x16 s0, s1;
;     { const bf16x8 ka = *(const LAS bf16x8*)(kb), kc = *(const LAS bf16x8*)(kb + 32 * AK_PITCH);
;       s0 = __builtin_amdgcn_mfma_f32_32x32x16_bf16(ka, qf[0], negm, 0, 0, 0); s1 = __builtin_amdgcn_mfma_f32_32x32x16_bf16(kc, qf[0], negm, 0, 0, 0); }
; #pragma unroll
;     for (int s = 1; s < 6; ++s) { const bf16x8 ka = *(const LAS bf16x8*)(kb + s * 32), kc = *(const LAS bf16x8*)(kb + 32 * AK_PITCH + s * 32);
;         s0 = __builtin_amdgcn_mfma_f32_32x32x16_bf16(ka, qf[s], s0, 0, 0, 0); s1 = __builtin_amdgcn_mfma_f32_32x32x16_bf16(kc, qf[s], s1, 0, 0, 0); }
;     if (MASKED) {
; #pragma unroll
;         for (int r = 0; r < 16; ++r) { const int kv = 64 * jl + crow(r, hi); if (kv > qrel) s0[r] = -1e30f; if (kv + 32 > qrel) s1[r] = -1e30f; }
;     }
;     float mx = __builtin_fmaxf(s0[0], s1[0]);
; #pragma unroll
;     for (int r = 1; r < 16; ++r) mx = __builtin_fmaxf(__builtin_fmaxf(mx, s0[r]), s1[r]);
;     { auto rr = __builtin_amdgcn_permlane32_swap(__float_as_uint(mx), __float_as_uint(mx), false, false);
;       mx = __builtin_fmaxf(__uint_as_float(rr[0]), __uint_as_float(rr[1])); }
;     if (__any(first || mx > ATT_THR)) {
.LBB0_354:
	v_readfirstlane_b32 s19, v125
	s_or_b32 s1, s1, 64
	s_or_b32 s19, s19, 31
	s_cmp_gt_i32 s1, s19
	s_cbranch_scc1 .LBB0_318
	ds_read_b128 v[96:99], v211 offset:39936
	v_lshl_or_b32 v100, v210, 2, s1
	v_or_b32_e32 v14, 32, v100
	v_cmp_le_i32_e32 vcc, v14, v125
	v_or_b32_e32 v15, 33, v100
	s_waitcnt lgkmcnt(0)
	v_mfma_f32_32x32x16_bf16 v[80:95], v[96:99], v[152:155], v[64:79]
	ds_read_b128 v[96:99], v211 offset:46592
	s_waitcnt lgkmcnt(0)
	v_mfma_f32_32x32x16_bf16 v[64:79], v[96:99], v[152:155], v[64:79]
	ds_read_b128 v[96:99], v211 offset:39968
	s_waitcnt lgkmcnt(0)
	v_mfma_f32_32x32x16_bf16 v[80:95], v[96:99], v[148:151], v[80:95]
	ds_read_b128 v[96:99], v211 offset:46624
	s_waitcnt lgkmcnt(0)
	v_mfma_f32_32x32x16_bf16 v[64:79], v[96:99], v[148:151], v[64:79]
	ds_read_b128 v[96:99], v211 offset:40000
	s_waitcnt lgkmcnt(0)
	v_mfma_f32_32x32x16_bf16 v[80:95], v[96:99], v[144:147], v[80:95]
	ds_read_b128 v[96:99], v211 offset:46656
	s_waitcnt lgkmcnt(0)
	v_mfma_f32_32x32x16_bf16 v[64:79], v[96:99], v[144:147], v[64:79]
	ds_read_b128 v[96:99], v211 offset:40032
	s_waitcnt lgkmcnt(0)
	v_mfma_f32_32x32x16_bf16 v[80:95], v[96:99], v[140:143], v[80:95]
	ds_read_b128 v[96:99], v211 offset:46688
	s_waitcnt lgkmcnt(0)
	v_mfma_f32_32x32x16_bf16 v[64:79], v[96:99], v[140:143], v[64:79]
	ds_read_b128 v[96:99], v211 offset:40064
	s_waitcnt lgkmcnt(0)
	v_mfma_f32_32x32x16_bf16 v[80:95], v[96:99], v[136:139], v[80:95]
	ds_read_b128 v[96:99], v211 offset:46720
	s_waitcnt lgkmcnt(0)
	v_mfma_f32_32x32x16_bf16 v[64:79], v[96:99], v[136:139], v[64:79]
	ds_read_b128 v[96:99], v211 offset:46752
	s_waitcnt lgkmcnt(0)
	v_mfma_f32_32x32x16_bf16 v[64:79], v[96:99], v[132:135], v[64:79]
	ds_read_b128 v[96:99], v211 offset:40096
	s_waitcnt lgkmcnt(0)
	v_mfma_f32_32x32x16_bf16 v[80:95], v[96:99], v[132:135], v[80:95]
	s_nop 8
	v_cndmask_b32_e32 v14, v231, v64, vcc
	v_cmp_lt_i32_e32 vcc, v100, v125
	v_or_b32_e32 v64, 2, v100
	s_nop 0
	v_cndmask_b32_e32 v99, v231, v81, vcc
	v_cmp_le_i32_e32 vcc, v100, v125
	s_nop 1
	v_cndmask_b32_e32 v98, v231, v80, vcc
	v_cmp_le_i32_e32 vcc, v15, v125
	s_nop 1
	v_cndmask_b32_e32 v15, v231, v65, vcc
	v_cmp_le_i32_e32 vcc, v64, v125
	v_or_b32_e32 v64, 34, v100
	v_or_b32_e32 v65, 42, v100
	v_cndmask_b32_e32 v80, v231, v82, vcc
	v_cmp_le_i32_e32 vcc, v64, v125
	v_or_b32_e32 v64, 3, v100
	s_nop 0
	v_cndmask_b32_e32 v96, v231, v66, vcc
	v_cmp_le_i32_e32 vcc, v64, v125
	v_or_b32_e32 v64, 35, v100
	s_nop 0
	v_cndmask_b32_e32 v81, v231, v83, vcc
	v_cmp_le_i32_e32 vcc, v64, v125
	v_or_b32_e32 v64, 8, v100
	s_nop 0
	v_cndmask_b32_e32 v97, v231, v67, vcc
	v_cmp_le_i32_e32 vcc, v64, v125
	v_or_b32_e32 v64, 40, v100
	s_nop 0
	v_cndmask_b32_e32 v66, v231, v84, vcc
	v_cmp_le_i32_e32 vcc, v64, v125
	v_or_b32_e32 v64, 9, v100
	v_or_b32_e32 v84, 49, v100
	v_cndmask_b32_e32 v82, v231, v68, vcc
	v_cmp_le_i32_e32 vcc, v64, v125
	v_or_b32_e32 v64, 41, v100
	s_nop 0
	v_cndmask_b32_e32 v67, v231, v85, vcc
	v_cmp_le_i32_e32 vcc, v64, v125
	v_or_b32_e32 v64, 10, v100
	v_or_b32_e32 v85, 50, v100
	v_cndmask_b32_e32 v83, v231, v69, vcc
	v_cmp_le_i32_e32 vcc, v64, v125
	v_or_b32_e32 v69, 43, v100
	s_nop 0
	v_cndmask_b32_e32 v64, v231, v86, vcc
	v_cmp_le_i32_e32 vcc, v65, v125
	v_or_b32_e32 v65, 11, v100
	v_or_b32_e32 v86, 51, v100
	v_cndmask_b32_e32 v68, v231, v70, vcc
	v_cmp_le_i32_e32 vcc, v65, v125
	v_or_b32_e32 v70, 16, v100
	s_nop 0
	v_cndmask_b32_e32 v65, v231, v87, vcc
	v_cmp_le_i32_e32 vcc, v69, v125
	v_or_b32_e32 v87, 56, v100
	s_nop 0
	v_cndmask_b32_e32 v69, v231, v71, vcc
	v_cmp_le_i32_e32 vcc, v70, v125
	v_or_b32_e32 v71, 48, v100
	s_nop 0
	v_cndmask_b32_e32 v70, v231, v88, vcc
	v_cmp_le_i32_e32 vcc, v71, v125
	v_or_b32_e32 v71, 17, v100
	v_or_b32_e32 v88, 57, v100
	v_cndmask_b32_e32 v72, v231, v72, vcc
	v_cmp_le_i32_e32 vcc, v71, v125
	s_nop 1
	v_cndmask_b32_e32 v71, v231, v89, vcc
	v_cmp_le_i32_e32 vcc, v84, v125
	v_or_b32_e32 v84, 18, v100
	v_or_b32_e32 v89, 58, v100
	v_cndmask_b32_e32 v73, v231, v73, vcc
	v_cmp_le_i32_e32 vcc, v84, v125
	s_nop 1
	v_cndmask_b32_e32 v84, v231, v90, vcc
	v_cmp_le_i32_e32 vcc, v85, v125
	v_or_b32_e32 v85, 19, v100
	v_or_b32_e32 v90, 59, v100
	v_cndmask_b32_e32 v74, v231, v74, vcc
	v_cmp_le_i32_e32 vcc, v85, v125
	s_nop 1
	v_cndmask_b32_e32 v85, v231, v91, vcc
	v_cmp_le_i32_e32 vcc, v86, v125
	v_or_b32_e32 v86, 24, v100
	v_max_f32_e32 v91, v98, v98
	v_cndmask_b32_e32 v75, v231, v75, vcc
	v_cmp_le_i32_e32 vcc, v86, v125
	s_nop 1
	v_cndmask_b32_e32 v86, v231, v92, vcc
	v_cmp_le_i32_e32 vcc, v87, v125
	v_or_b32_e32 v87, 25, v100
	s_nop 0
	v_cndmask_b32_e32 v76, v231, v76, vcc
	v_cmp_le_i32_e32 vcc, v87, v125
	s_nop 1
	v_cndmask_b32_e32 v87, v231, v93, vcc
	v_cmp_le_i32_e32 vcc, v88, v125
	v_or_b32_e32 v88, 26, v100
	s_nop 0
	v_cndmask_b32_e32 v77, v231, v77, vcc
	v_cmp_le_i32_e32 vcc, v88, v125
	s_nop 1
	v_cndmask_b32_e32 v88, v231, v94, vcc
	v_cmp_le_i32_e32 vcc, v89, v125
	v_or_b32_e32 v89, 27, v100
	s_nop 0
	v_cndmask_b32_e32 v78, v231, v78, vcc
	v_cmp_le_i32_e32 vcc, v89, v125
	s_nop 1
	v_cndmask_b32_e32 v89, v231, v95, vcc
	v_cmp_le_i32_e32 vcc, v90, v125
	v_max_f32_e32 v90, v14, v14
	v_max_f32_e32 v90, v91, v90
	v_max3_f32 v90, v90, v99, v15
	v_max3_f32 v90, v90, v80, v96
	v_max3_f32 v90, v90, v81, v97
	v_max3_f32 v90, v90, v66, v82
	v_max3_f32 v90, v90, v67, v83
	v_max3_f32 v90, v90, v64, v68
	v_max3_f32 v90, v90, v65, v69
	v_max3_f32 v90, v90, v70, v72
	v_max3_f32 v90, v90, v71, v73
	v_max3_f32 v90, v90, v84, v74
	v_max3_f32 v90, v90, v85, v75
	v_max3_f32 v90, v90, v86, v76
	v_max3_f32 v90, v90, v87, v77
	v_cndmask_b32_e32 v79, v231, v79, vcc
	v_max3_f32 v90, v90, v88, v78
	v_max3_f32 v90, v90, v89, v79
	v_mov_b32_e32 v91, v90
	s_nop 1
	v_permlane32_swap_b32_e32 v90, v91
	v_max_f32_e32 v91, v91, v91
	v_max_f32_e32 v90, v90, v90
	v_max_f32_e32 v90, v90, v91
	v_cmp_lt_f32_e32 vcc, s23, v90
	s_cbranch_vccz .LBB0_317
; template <bool MASKED> ...
;     ...
;     if (__any(first || mx > ATT_THR)) {
;         const float d = first ? mx : __builtin_fmaxf(mx, 0.f), f = __builtin_amdgcn_exp2f(-d);
;         mrun += d; o2[0] *= f;
; #pragma unroll
;         for (int r = 0; r < 16; ++r) { s0[r] -= d; s1[r] -= d; o0[r] *= f; o1[r] *= f; negm[r] = -mrun; }
;     }
	v_max_f32_e32 v90, v90, v90
	v_max_f32_e32 v90, 0, v90
	v_exp_f32_e64 v92, -v90
	v_pk_add_f32 v[98:99], v[98:99], v[90:91] op_sel_hi:[1,0] neg_lo:[0,1] neg_hi:[0,1]
	v_pk_add_f32 v[14:15], v[14:15], v[90:91] op_sel_hi:[1,0] neg_lo:[0,1] neg_hi:[0,1]
	v_pk_add_f32 v[80:81], v[80:81], v[90:91] op_sel_hi:[1,0] neg_lo:[0,1] neg_hi:[0,1]
	v_mul_f32_e32 v48, v48, v92
	v_mul_f32_e32 v250, v250, v92
	v_mul_f32_e32 v251, v251, v92
	v_pk_add_f32 v[96:97], v[96:97], v[90:91] op_sel_hi:[1,0] neg_lo:[0,1] neg_hi:[0,1]
	v_pk_add_f32 v[66:67], v[66:67], v[90:91] op_sel_hi:[1,0] neg_lo:[0,1] neg_hi:[0,1]
	v_pk_add_f32 v[82:83], v[82:83], v[90:91] op_sel_hi:[1,0] neg_lo:[0,1] neg_hi:[0,1]
	v_pk_add_f32 v[64:65], v[64:65], v[90:91] op_sel_hi:[1,0] neg_lo:[0,1] neg_hi:[0,1]
	v_pk_add_f32 v[68:69], v[68:69], v[90:91] op_sel_hi:[1,0] neg_lo:[0,1] neg_hi:[0,1]
	v_pk_add_f32 v[70:71], v[70:71], v[90:91] op_sel_hi:[1,0] neg_lo:[0,1] neg_hi:[0,1]
	v_pk_add_f32 v[72:73], v[72:73], v[90:91] op_sel_hi:[1,0] neg_lo:[0,1] neg_hi:[0,1]
	v_pk_add_f32 v[84:85], v[84:85], v[90:91] op_sel_hi:[1,0] neg_lo:[0,1] neg_hi:[0,1]
	v_pk_add_f32 v[74:75], v[74:75], v[90:91] op_sel_hi:[1,0] neg_lo:[0,1] neg_hi:[0,1]
	v_pk_add_f32 v[86:87], v[86:87], v[90:91] op_sel_hi:[1,0] neg_lo:[0,1] neg_hi:[0,1]
	v_pk_add_f32 v[76:77], v[76:77], v[90:91] op_sel_hi:[1,0] neg_lo:[0,1] neg_hi:[0,1]
	v_pk_add_f32 v[88:89], v[88:89], v[90:91] op_sel_hi:[1,0] neg_lo:[0,1] neg_hi:[0,1]
	v_pk_add_f32 v[78:79], v[78:79], v[90:91] op_sel_hi:[1,0] neg_lo:[0,1] neg_hi:[0,1]
	v_pk_mul_f32 v[46:47], v[46:47], v[92:93] op_sel_hi:[1,0]
	v_pk_mul_f32 v[44:45], v[44:45], v[92:93] op_sel_hi:[1,0]
	v_pk_mul_f32 v[42:43], v[42:43], v[92:93] op_sel_hi:[1,0]
	v_pk_mul_f32 v[40:41], v[40:41], v[92:93] op_sel_hi:[1,0]
	v_pk_mul_f32 v[38:39], v[38:39], v[92:93] op_sel_hi:[1,0]
	v_pk_mul_f32 v[36:37], v[36:37], v[92:93] op_sel_hi:[1,0]
	v_pk_mul_f32 v[34:35], v[34:35], v[92:93] op_sel_hi:[1,0]
	v_pk_mul_f32 v[32:33], v[32:33], v[92:93] op_sel_hi:[1,0]
	v_pk_mul_f32 v[30:31], v[30:31], v[92:93] op_sel_hi:[1,0]
	v_pk_mul_f32 v[28:29], v[28:29], v[92:93] op_sel_hi:[1,0]
	v_pk_mul_f32 v[26:27], v[26:27], v[92:93] op_sel_hi:[1,0]
	v_pk_mul_f32 v[24:25], v[24:25], v[92:93] op_sel_hi:[1,0]
	v_pk_mul_f32 v[22:23], v[22:23], v[92:93] op_sel_hi:[1,0]
	v_pk_mul_f32 v[20:21], v[20:21], v[92:93] op_sel_hi:[1,0]
	v_pk_mul_f32 v[18:19], v[18:19], v[92:93] op_sel_hi:[1,0]
	v_pk_mul_f32 v[16:17], v[16:17], v[92:93] op_sel_hi:[1,0]
	s_branch .LBB0_317

; #define PG8_STAGE(bufoff, gbase, voff) do { _Pragma("unroll") for (int _i = 0; _i < 2; ++_i) \
;         __builtin_amdgcn_global_load_lds((const unsigned*)((const char*)(gbase) + (voff)[_i]), (LAS unsigned*)(lds + (bufoff) + ldsw + _i * 8192), 16, 0, 0); } while (0)
; #define PG8_LDA(dst, b, h) do { _Pragma("unroll") for (int m = 0; m < 4; ++m) _Pragma("unroll") for (int k = 0; k < 2; ++k) dst[m][k] = *(const LAS bf16x8*)(lds + PG8_SA(b, h) + aoff + m * 2048 + k * 1024); } while (0)
; #define PG8_LDB(dst, b, h) do { _Pragma("unroll") for (int n = 0; n < 2; ++n) _Pragma("unroll") for (int k = 0; k < 2; ++k) dst[n][k] = *(const LAS bf16x8*)(lds + PG8_SB(b, h) + boff + n * 2048 + k * 1024); } while (0)
; #define PG8_MMA(ai, bj, At, Bt) do { __builtin_amdgcn_s_setprio(1); _Pragma("unroll") for (int m = 0; m < 4; ++m) _Pragma("unroll") for (int n = 0; n < 2; ++n) _Pragma("unroll") for (int k = 0; k < 2; ++k) \
;         acc[ai][bj][m][n] = __builtin_amdgcn_mfma_f32_16x16x32_bf16(Bt[n][k], At[m][k], acc[ai][bj][m][n], 0, 0, 0); __builtin_amdgcn_s_setprio(0); } while (0)
; #define PG8_WAIT_V(n) asm volatile("s_waitcnt vmcnt(" #n ")" ::: "memory")
; #define PG8_WAIT_L(n) asm volatile("s_waitcnt lgkmcnt(" #n ")" ::: "memory")
; #define PG8_BAR __builtin_amdgcn_s_barrier()
; #define PG8_SCHED __builtin_amdgcn_sched_barrier(0)
; template <class Epi, class Sched>
; __device__ __forceinline__ void gemm_phase(LAS unsigned char* lds, const Gemm g, const Sched& S, const Epi& E) {
;     ...
;             const bool last = (t == nt - 2);
;             const char* a1 = cA + (size_t)(t + 1) * kstep;
;             const char* a2 = last ? nA : cA + (size_t)(t + 2) * kstep; const char* b2 = last ? nB : cB + (size_t)(t + 2) * kstep;
;             const char* a3 = a2 + kstep; const char* b3 = b2 + kstep;
;             PG8_LDB(B0, 0, 0); PG8_LDB(B1, 0, 1); PG8_SCHED; PG8_LDA(At, 0, 0); PG8_STAGE(PG8_SA(1, 1), a1 + hstepA, voffA);
;             PG8_WAIT_V(8); PG8_WAIT_L(0); PG8_BAR; PG8_MMA(0, 0, At, B0); PG8_MMA(0, 1, At, B1); PG8_BAR; PG8_SCHED;
;             PG8_LDA(At, 0, 1); PG8_STAGE(PG8_SB(0, 0), b2, voffB); PG8_STAGE(PG8_SB(0, 1), b2 + hstepB, voffB); PG8_STAGE(PG8_SA(0, 0), a2, voffA);
;             PG8_WAIT_V(8); PG8_WAIT_L(0); PG8_BAR; PG8_MMA(1, 0, At, B0); PG8_MMA(1, 1, At, B1); PG8_BAR; PG8_SCHED;
.LBB0_375:
	s_add_i32 s63, s40, 2
	s_add_u32 s0, s20, 0x100
	s_addc_u32 s1, s21, 0
	s_add_i32 s72, 0, 0x10000
	s_cmp_eq_u32 s77, s40
	s_cselect_b32 s43, s91, s1
	s_cselect_b32 s42, s90, s0
	v_add_u32_e32 v0, s72, v178
	s_cselect_b32 s41, s93, s62
	s_cselect_b32 s40, s92, s68
	s_add_i32 s76, 0, 0x14000
	ds_read_b128 v[142:145], v0
	ds_read_b128 v[146:149], v0 offset:1024
	ds_read_b128 v[150:153], v0 offset:2048
	ds_read_b128 v[154:157], v0 offset:3072
	v_add_u32_e32 v0, s76, v178
	ds_read_b128 v[158:161], v0
	ds_read_b128 v[162:165], v0 offset:1024
	ds_read_b128 v[166:169], v0 offset:2048
	ds_read_b128 v[170:173], v0 offset:3072
	v_lshl_add_u64 v[174:175], s[20:21], 0, v[140:141]
	s_add_i32 m0, s17, 0xc000
	ds_read_b128 v[180:183], v179
	ds_read_b128 v[196:199], v179 offset:1024
	ds_read_b128 v[200:203], v179 offset:2048
	ds_read_b128 v[204:207], v179 offset:3072
	ds_read_b128 v[208:211], v179 offset:4096
	ds_read_b128 v[212:215], v179 offset:5120
	ds_read_b128 v[216:219], v179 offset:6144
	ds_read_b128 v[248:251], v179 offset:7168
	global_load_lds_dwordx4 v[174:175], off
	v_lshl_add_u64 v[174:175], s[20:21], 0, v[138:139]
	s_add_i32 m0, s17, 0xe000
	s_nop 0
	global_load_lds_dwordx4 v[174:175], off
	s_waitcnt vmcnt(8)
	s_waitcnt lgkmcnt(0)
	s_barrier
	s_setprio 1
	s_waitcnt lgkmcnt(0)
	v_mfma_f32_16x16x32_bf16 v[126:129], v[142:145], v[180:183], v[126:129]
	v_mfma_f32_16x16x32_bf16 v[122:125], v[150:153], v[180:183], v[122:125]
	v_mfma_f32_16x16x32_bf16 v[118:121], v[142:145], v[200:203], v[118:121]
	v_mfma_f32_16x16x32_bf16 v[114:117], v[150:153], v[200:203], v[114:117]
	v_mfma_f32_16x16x32_bf16 v[110:113], v[142:145], v[208:211], v[110:113]
	v_mfma_f32_16x16x32_bf16 v[106:109], v[150:153], v[208:211], v[106:109]
	v_mfma_f32_16x16x32_bf16 v[102:105], v[142:145], v[216:219], v[102:105]
	v_mfma_f32_16x16x32_bf16 v[98:101], v[150:153], v[216:219], v[98:101]
	v_mfma_f32_16x16x32_bf16 v[126:129], v[146:149], v[196:199], v[126:129]
	v_mfma_f32_16x16x32_bf16 v[122:125], v[154:157], v[196:199], v[122:125]
	v_mfma_f32_16x16x32_bf16 v[118:121], v[146:149], v[204:207], v[118:121]
	v_mfma_f32_16x16x32_bf16 v[114:117], v[154:157], v[204:207], v[114:117]
	v_mfma_f32_16x16x32_bf16 v[110:113], v[146:149], v[212:215], v[110:113]
	v_mfma_f32_16x16x32_bf16 v[106:109], v[154:157], v[212:215], v[106:109]
	v_mfma_f32_16x16x32_bf16 v[102:105], v[146:149], v[248:251], v[102:105]
	v_mfma_f32_16x16x32_bf16 v[98:101], v[154:157], v[248:251], v[98:101]
	v_mfma_f32_16x16x32_bf16 v[62:65], v[158:161], v[180:183], v[62:65]
	v_mfma_f32_16x16x32_bf16 v[58:61], v[166:169], v[180:183], v[58:61]
	v_mfma_f32_16x16x32_bf16 v[54:57], v[158:161], v[200:203], v[54:57]
	v_mfma_f32_16x16x32_bf16 v[50:53], v[166:169], v[200:203], v[50:53]
	v_mfma_f32_16x16x32_bf16 v[46:49], v[158:161], v[208:211], v[46:49]
	v_mfma_f32_16x16x32_bf16 v[42:45], v[166:169], v[208:211], v[42:45]
	v_mfma_f32_16x16x32_bf16 v[38:41], v[158:161], v[216:219], v[38:41]
	v_mfma_f32_16x16x32_bf16 v[34:37], v[166:169], v[216:219], v[34:37]
	v_mfma_f32_16x16x32_bf16 v[62:65], v[162:165], v[196:199], v[62:65]
	v_mfma_f32_16x16x32_bf16 v[58:61], v[170:173], v[196:199], v[58:61]
	v_mfma_f32_16x16x32_bf16 v[54:57], v[162:165], v[204:207], v[54:57]
	v_mfma_f32_16x16x32_bf16 v[50:53], v[170:173], v[204:207], v[50:53]
	v_mfma_f32_16x16x32_bf16 v[46:49], v[162:165], v[212:215], v[46:49]
	v_mfma_f32_16x16x32_bf16 v[42:45], v[170:173], v[212:215], v[42:45]
	v_mfma_f32_16x16x32_bf16 v[38:41], v[162:165], v[248:251], v[38:41]
	v_mfma_f32_16x16x32_bf16 v[34:37], v[170:173], v[248:251], v[34:37]
	s_setprio 0
	s_barrier
	s_add_i32 s20, s72, s16
	v_lshl_add_u64 v[174:175], s[40:41], 0, v[132:133]
	s_mov_b32 m0, s20
	ds_read_b128 v[180:183], v179 offset:16384
	ds_read_b128 v[196:199], v179 offset:17408
	ds_read_b128 v[200:203], v179 offset:18432
	ds_read_b128 v[204:207], v179 offset:19456
	ds_read_b128 v[208:211], v179 offset:20480
	ds_read_b128 v[212:215], v179 offset:21504
	ds_read_b128 v[216:219], v179 offset:22528
	ds_read_b128 v[248:251], v179 offset:23552
	global_load_lds_dwordx4 v[174:175], off
	s_add_i32 m0, s20, 0x2000
	s_add_u32 s20, s40, 0x18000
	v_lshl_add_u64 v[184:185], s[40:41], 0, v[136:137]
	s_addc_u32 s21, s41, 0
	s_add_i32 s72, s76, s16
	global_load_lds_dwordx4 v[184:185], off
	v_lshl_add_u64 v[220:221], s[20:21], 0, v[132:133]
	s_mov_b32 m0, s72
	v_lshl_add_u64 v[232:233], s[42:43], 0, v[134:135]
	global_load_lds_dwordx4 v[220:221], off
	v_lshl_add_u64 v[220:221], s[20:21], 0, v[136:137]
	s_add_i32 m0, s72, 0x2000
	s_nop 0
	global_load_lds_dwordx4 v[220:221], off
	v_lshl_add_u64 v[220:221], s[42:43], 0, v[130:131]
	s_mov_b32 m0, s17
	s_nop 0
	global_load_lds_dwordx4 v[220:221], off
	s_mov_b32 m0, s44
	s_nop 0
	global_load_lds_dwordx4 v[232:233], off
	s_waitcnt vmcnt(8)
	s_waitcnt lgkmcnt(0)
	s_barrier
; #define PG8_STAGE(bufoff, gbase, voff) do { _Pragma("unroll") for (int _i = 0; _i < 2; ++_i) \
;         __builtin_amdgcn_global_load_lds((const unsigned*)((const char*)(gbase) + (voff)[_i]), (LAS unsigned*)(lds + (bufoff) + ldsw + _i * 8192), 16, 0, 0); } while (0)
; #define PG8_LDA(dst, b, h) do { _Pragma("unroll") for (int m = 0; m < 4; ++m) _Pragma("unroll") for (int k = 0; k < 2; ++k) dst[m][k] = *(const LAS bf16x8*)(lds + PG8_SA(b, h) + aoff + m * 2048 + k * 1024); } while (0)
; #define PG8_LDB(dst, b, h) do { _Pragma("unroll") for (int n = 0; n < 2; ++n) _Pragma("unroll") for (int k = 0; k < 2; ++k) dst[n][k] = *(const LAS bf16x8*)(lds + PG8_SB(b, h) + boff + n * 2048 + k * 1024); } while (0)
; #define PG8_MMA(ai, bj, At, Bt) do { __builtin_amdgcn_s_setprio(1); _Pragma("unroll") for (int m = 0; m < 4; ++m) _Pragma("unroll") for (int n = 0; n < 2; ++n) _Pragma("unroll") for (int k = 0; k < 2; ++k) \
;         acc[ai][bj][m][n] = __builtin_amdgcn_mfma_f32_16x16x32_bf16(Bt[n][k], At[m][k], acc[ai][bj][m][n], 0, 0, 0); __builtin_amdgcn_s_setprio(0); } while (0)
; #define PG8_WAIT_V(n) asm volatile("s_waitcnt vmcnt(" #n ")" ::: "memory")
; #define PG8_WAIT_L(n) asm volatile("s_waitcnt lgkmcnt(" #n ")" ::: "memory")
; #define PG8_BAR __builtin_amdgcn_s_barrier()
; #define PG8_SCHED __builtin_amdgcn_sched_barrier(0)
; template <class Epi, class Sched>
; __device__ __forceinline__ void gemm_phase(LAS unsigned char* lds, const Gemm g, const Sched& S, const Epi& E) {
;     ...
;             PG8_WAIT_V(8); PG8_WAIT_L(0); PG8_BAR; PG8_MMA(1, 0, At, B0); PG8_MMA(1, 1, At, B1); PG8_BAR; PG8_SCHED;
;             PG8_LDB(B0, 1, 0); PG8_LDB(B1, 1, 1); PG8_SCHED; PG8_LDA(At, 1, 0); PG8_STAGE(PG8_SA(0, 1), a2 + hstepA, voffA);
;             PG8_WAIT_V(8); PG8_WAIT_L(0); PG8_BAR; PG8_MMA(0, 0, At, B0); PG8_MMA(0, 1, At, B1); PG8_BAR; PG8_SCHED;
	s_setprio 1
	s_waitcnt lgkmcnt(0)
	v_mfma_f32_16x16x32_bf16 v[94:97], v[142:145], v[180:183], v[94:97]
	v_mfma_f32_16x16x32_bf16 v[90:93], v[150:153], v[180:183], v[90:93]
	v_mfma_f32_16x16x32_bf16 v[86:89], v[142:145], v[200:203], v[86:89]
	v_mfma_f32_16x16x32_bf16 v[82:85], v[150:153], v[200:203], v[82:85]
	v_mfma_f32_16x16x32_bf16 v[78:81], v[142:145], v[208:211], v[78:81]
	v_mfma_f32_16x16x32_bf16 v[74:77], v[150:153], v[208:211], v[74:77]
	v_mfma_f32_16x16x32_bf16 v[70:73], v[142:145], v[216:219], v[70:73]
	v_mfma_f32_16x16x32_bf16 v[66:69], v[150:153], v[216:219], v[66:69]
	v_mfma_f32_16x16x32_bf16 v[94:97], v[146:149], v[196:199], v[94:97]
	v_mfma_f32_16x16x32_bf16 v[90:93], v[154:157], v[196:199], v[90:93]
	v_mfma_f32_16x16x32_bf16 v[86:89], v[146:149], v[204:207], v[86:89]
	v_mfma_f32_16x16x32_bf16 v[82:85], v[154:157], v[204:207], v[82:85]
	v_mfma_f32_16x16x32_bf16 v[78:81], v[146:149], v[212:215], v[78:81]
	v_mfma_f32_16x16x32_bf16 v[74:77], v[154:157], v[212:215], v[74:77]
	v_mfma_f32_16x16x32_bf16 v[70:73], v[146:149], v[248:251], v[70:73]
	v_mfma_f32_16x16x32_bf16 v[66:69], v[154:157], v[248:251], v[66:69]
	v_mfma_f32_16x16x32_bf16 v[30:33], v[158:161], v[180:183], v[30:33]
	v_mfma_f32_16x16x32_bf16 v[26:29], v[166:169], v[180:183], v[26:29]
	v_mfma_f32_16x16x32_bf16 v[22:25], v[158:161], v[200:203], v[22:25]
	v_mfma_f32_16x16x32_bf16 v[18:21], v[166:169], v[200:203], v[18:21]
	v_mfma_f32_16x16x32_bf16 v[14:17], v[158:161], v[208:211], v[14:17]
	v_mfma_f32_16x16x32_bf16 v[10:13], v[166:169], v[208:211], v[10:13]
	v_mfma_f32_16x16x32_bf16 v[6:9], v[158:161], v[216:219], v[6:9]
	v_mfma_f32_16x16x32_bf16 v[2:5], v[166:169], v[216:219], v[2:5]
	v_mfma_f32_16x16x32_bf16 v[30:33], v[162:165], v[196:199], v[30:33]
	v_mfma_f32_16x16x32_bf16 v[26:29], v[170:173], v[196:199], v[26:29]
	v_mfma_f32_16x16x32_bf16 v[22:25], v[162:165], v[204:207], v[22:25]
	v_mfma_f32_16x16x32_bf16 v[18:21], v[170:173], v[204:207], v[18:21]
	v_mfma_f32_16x16x32_bf16 v[14:17], v[162:165], v[212:215], v[14:17]
	v_mfma_f32_16x16x32_bf16 v[10:13], v[170:173], v[212:215], v[10:13]
	v_mfma_f32_16x16x32_bf16 v[6:9], v[162:165], v[248:251], v[6:9]
	v_mfma_f32_16x16x32_bf16 v[2:5], v[170:173], v[248:251], v[2:5]
	s_setprio 0
	s_barrier
	s_add_i32 s72, 0, 0x18000
	v_add_u32_e32 v0, s72, v178
	s_add_i32 s76, 0, 0x1c000
	ds_read_b128 v[142:145], v0
	ds_read_b128 v[146:149], v0 offset:1024
	ds_read_b128 v[150:153], v0 offset:2048
	ds_read_b128 v[154:157], v0 offset:3072
	v_add_u32_e32 v0, s76, v178
	ds_read_b128 v[158:161], v0
	ds_read_b128 v[162:165], v0 offset:1024
	ds_read_b128 v[166:169], v0 offset:2048
	ds_read_b128 v[170:173], v0 offset:3072
	s_add_u32 s20, s42, 0x50000
	s_addc_u32 s21, s43, 0
	s_mov_b32 m0, s45
	v_lshl_add_u64 v[234:235], s[20:21], 0, v[130:131]
	ds_read_b128 v[180:183], v179 offset:32768
	ds_read_b128 v[196:199], v179 offset:33792
	ds_read_b128 v[200:203], v179 offset:34816
	ds_read_b128 v[204:207], v179 offset:35840
	ds_read_b128 v[208:211], v179 offset:36864
	ds_read_b128 v[212:215], v179 offset:37888
	ds_read_b128 v[216:219], v179 offset:38912
	ds_read_b128 v[248:251], v179 offset:39936
	global_load_lds_dwordx4 v[234:235], off
	v_lshl_add_u64 v[234:235], s[20:21], 0, v[134:135]
	s_mov_b32 m0, s46
	s_nop 0
	global_load_lds_dwordx4 v[234:235], off
	s_waitcnt vmcnt(8)
	s_waitcnt lgkmcnt(0)
	s_barrier
	s_setprio 1
	s_waitcnt lgkmcnt(0)
	v_mfma_f32_16x16x32_bf16 v[126:129], v[142:145], v[180:183], v[126:129]
	v_mfma_f32_16x16x32_bf16 v[122:125], v[150:153], v[180:183], v[122:125]
	v_mfma_f32_16x16x32_bf16 v[118:121], v[142:145], v[200:203], v[118:121]
	v_mfma_f32_16x16x32_bf16 v[114:117], v[150:153], v[200:203], v[114:117]
	v_mfma_f32_16x16x32_bf16 v[110:113], v[142:145], v[208:211], v[110:113]
	v_mfma_f32_16x16x32_bf16 v[106:109], v[150:153], v[208:211], v[106:109]
	v_mfma_f32_16x16x32_bf16 v[102:105], v[142:145], v[216:219], v[102:105]
	v_mfma_f32_16x16x32_bf16 v[98:101], v[150:153], v[216:219], v[98:101]
	v_mfma_f32_16x16x32_bf16 v[126:129], v[146:149], v[196:199], v[126:129]
	v_mfma_f32_16x16x32_bf16 v[122:125], v[154:157], v[196:199], v[122:125]
	v_mfma_f32_16x16x32_bf16 v[118:121], v[146:149], v[204:207], v[118:121]
	v_mfma_f32_16x16x32_bf16 v[114:117], v[154:157], v[204:207], v[114:117]
	v_mfma_f32_16x16x32_bf16 v[110:113], v[146:149], v[212:215], v[110:113]
	v_mfma_f32_16x16x32_bf16 v[106:109], v[154:157], v[212:215], v[106:109]
	v_mfma_f32_16x16x32_bf16 v[102:105], v[146:149], v[248:251], v[102:105]
	v_mfma_f32_16x16x32_bf16 v[98:101], v[154:157], v[248:251], v[98:101]
	v_mfma_f32_16x16x32_bf16 v[62:65], v[158:161], v[180:183], v[62:65]
	v_mfma_f32_16x16x32_bf16 v[58:61], v[166:169], v[180:183], v[58:61]
	v_mfma_f32_16x16x32_bf16 v[54:57], v[158:161], v[200:203], v[54:57]
	v_mfma_f32_16x16x32_bf16 v[50:53], v[166:169], v[200:203], v[50:53]
	v_mfma_f32_16x16x32_bf16 v[46:49], v[158:161], v[208:211], v[46:49]
	v_mfma_f32_16x16x32_bf16 v[42:45], v[166:169], v[208:211], v[42:45]
	v_mfma_f32_16x16x32_bf16 v[38:41], v[158:161], v[216:219], v[38:41]
	v_mfma_f32_16x16x32_bf16 v[34:37], v[166:169], v[216:219], v[34:37]
	v_mfma_f32_16x16x32_bf16 v[62:65], v[162:165], v[196:199], v[62:65]
	v_mfma_f32_16x16x32_bf16 v[58:61], v[170:173], v[196:199], v[58:61]
	v_mfma_f32_16x16x32_bf16 v[54:57], v[162:165], v[204:207], v[54:57]
	v_mfma_f32_16x16x32_bf16 v[50:53], v[170:173], v[204:207], v[50:53]
	v_mfma_f32_16x16x32_bf16 v[46:49], v[162:165], v[212:215], v[46:49]
	v_mfma_f32_16x16x32_bf16 v[42:45], v[170:173], v[212:215], v[42:45]
	v_mfma_f32_16x16x32_bf16 v[38:41], v[162:165], v[248:251], v[38:41]
	v_mfma_f32_16x16x32_bf16 v[34:37], v[170:173], v[248:251], v[34:37]
	s_setprio 0
	s_barrier
; #define PG8_STAGE(bufoff, gbase, voff) do { _Pragma("unroll") for (int _i = 0; _i < 2; ++_i) \
;         __builtin_amdgcn_global_load_lds((const unsigned*)((const char*)(gbase) + (voff)[_i]), (LAS unsigned*)(lds + (bufoff) + ldsw + _i * 8192), 16, 0, 0); } while (0)
; #define PG8_LDA(dst, b, h) do { _Pragma("unroll") for (int m = 0; m < 4; ++m) _Pragma("unroll") for (int k = 0; k < 2; ++k) dst[m][k] = *(const LAS bf16x8*)(lds + PG8_SA(b, h) + aoff + m * 2048 + k * 1024); } while (0)
; #define PG8_MMA(ai, bj, At, Bt) do { __builtin_amdgcn_s_setprio(1); _Pragma("unroll") for (int m = 0; m < 4; ++m) _Pragma("unroll") for (int n = 0; n < 2; ++n) _Pragma("unroll") for (int k = 0; k < 2; ++k) \
;         acc[ai][bj][m][n] = __builtin_amdgcn_mfma_f32_16x16x32_bf16(Bt[n][k], At[m][k], acc[ai][bj][m][n], 0, 0, 0); __builtin_amdgcn_s_setprio(0); } while (0)
; #define PG8_WAIT_V(n) asm volatile("s_waitcnt vmcnt(" #n ")" ::: "memory")
; #define PG8_WAIT_L(n) asm volatile("s_waitcnt lgkmcnt(" #n ")" ::: "memory")
; #define PG8_BAR __builtin_amdgcn_s_barrier()
; #define PG8_SCHED __builtin_amdgcn_sched_barrier(0)
; template <class Epi, class Sched>
; __device__ __forceinline__ void gemm_phase(LAS unsigned char* lds, const Gemm g, const Sched& S, const Epi& E) {
;     ...
;             PG8_LDA(At, 1, 1); PG8_STAGE(PG8_SB(1, 0), b3, voffB); PG8_STAGE(PG8_SB(1, 1), b3 + hstepB, voffB); PG8_STAGE(PG8_SA(1, 0), a3, voffA);
;             PG8_WAIT_V(8); PG8_WAIT_L(0); PG8_BAR; PG8_MMA(1, 0, At, B0); PG8_MMA(1, 1, At, B1); PG8_BAR; PG8_SCHED;
;         }
	s_add_i32 s20, s72, s16
	v_lshl_add_u64 v[174:175], v[174:175], 0, s[26:27]
	s_mov_b32 m0, s20
	ds_read_b128 v[180:183], v179 offset:49152
	ds_read_b128 v[196:199], v179 offset:50176
	ds_read_b128 v[200:203], v179 offset:51200
	ds_read_b128 v[204:207], v179 offset:52224
	ds_read_b128 v[208:211], v179 offset:53248
	ds_read_b128 v[212:215], v179 offset:54272
	ds_read_b128 v[216:219], v179 offset:55296
	ds_read_b128 v[248:251], v179 offset:56320
	global_load_lds_dwordx4 v[174:175], off
	s_add_i32 m0, s20, 0x2000
	s_add_u32 s20, s40, 0x18080
	v_lshl_add_u64 v[174:175], v[184:185], 0, s[26:27]
	s_addc_u32 s21, s41, 0
	s_add_i32 s40, s76, s16
	global_load_lds_dwordx4 v[174:175], off
	v_lshl_add_u64 v[174:175], s[20:21], 0, v[132:133]
	s_mov_b32 m0, s40
	s_nop 0
	global_load_lds_dwordx4 v[174:175], off
	v_lshl_add_u64 v[174:175], s[20:21], 0, v[136:137]
	s_add_i32 m0, s40, 0x2000
	s_nop 0
	global_load_lds_dwordx4 v[174:175], off
	v_lshl_add_u64 v[174:175], v[220:221], 0, s[26:27]
	s_mov_b32 m0, s71
	s_nop 0
	global_load_lds_dwordx4 v[174:175], off
	v_lshl_add_u64 v[174:175], v[232:233], 0, s[26:27]
	s_mov_b32 m0, s74
	s_nop 0
	global_load_lds_dwordx4 v[174:175], off
	s_waitcnt vmcnt(8)
	s_waitcnt lgkmcnt(0)
	s_barrier
	s_setprio 1
	s_waitcnt lgkmcnt(0)
	v_mfma_f32_16x16x32_bf16 v[94:97], v[142:145], v[180:183], v[94:97]
	v_mfma_f32_16x16x32_bf16 v[90:93], v[150:153], v[180:183], v[90:93]
	v_mfma_f32_16x16x32_bf16 v[86:89], v[142:145], v[200:203], v[86:89]
	v_mfma_f32_16x16x32_bf16 v[82:85], v[150:153], v[200:203], v[82:85]
	v_mfma_f32_16x16x32_bf16 v[78:81], v[142:145], v[208:211], v[78:81]
	v_mfma_f32_16x16x32_bf16 v[74:77], v[150:153], v[208:211], v[74:77]
	v_mfma_f32_16x16x32_bf16 v[70:73], v[142:145], v[216:219], v[70:73]
	v_mfma_f32_16x16x32_bf16 v[66:69], v[150:153], v[216:219], v[66:69]
	v_mfma_f32_16x16x32_bf16 v[94:97], v[146:149], v[196:199], v[94:97]
	v_mfma_f32_16x16x32_bf16 v[90:93], v[154:157], v[196:199], v[90:93]
	v_mfma_f32_16x16x32_bf16 v[86:89], v[146:149], v[204:207], v[86:89]
	v_mfma_f32_16x16x32_bf16 v[82:85], v[154:157], v[204:207], v[82:85]
	v_mfma_f32_16x16x32_bf16 v[78:81], v[146:149], v[212:215], v[78:81]
	v_mfma_f32_16x16x32_bf16 v[74:77], v[154:157], v[212:215], v[74:77]
	v_mfma_f32_16x16x32_bf16 v[70:73], v[146:149], v[248:251], v[70:73]
	v_mfma_f32_16x16x32_bf16 v[66:69], v[154:157], v[248:251], v[66:69]
	v_mfma_f32_16x16x32_bf16 v[30:33], v[158:161], v[180:183], v[30:33]
	v_mfma_f32_16x16x32_bf16 v[26:29], v[166:169], v[180:183], v[26:29]
	v_mfma_f32_16x16x32_bf16 v[22:25], v[158:161], v[200:203], v[22:25]
	v_mfma_f32_16x16x32_bf16 v[18:21], v[166:169], v[200:203], v[18:21]
	v_mfma_f32_16x16x32_bf16 v[14:17], v[158:161], v[208:211], v[14:17]
	v_mfma_f32_16x16x32_bf16 v[10:13], v[166:169], v[208:211], v[10:13]
	v_mfma_f32_16x16x32_bf16 v[6:9], v[158:161], v[216:219], v[6:9]
	v_mfma_f32_16x16x32_bf16 v[2:5], v[166:169], v[216:219], v[2:5]
	v_mfma_f32_16x16x32_bf16 v[30:33], v[162:165], v[196:199], v[30:33]
	v_mfma_f32_16x16x32_bf16 v[26:29], v[170:173], v[196:199], v[26:29]
	v_mfma_f32_16x16x32_bf16 v[22:25], v[162:165], v[204:207], v[22:25]
	v_mfma_f32_16x16x32_bf16 v[18:21], v[170:173], v[204:207], v[18:21]
	v_mfma_f32_16x16x32_bf16 v[14:17], v[162:165], v[212:215], v[14:17]
	v_mfma_f32_16x16x32_bf16 v[10:13], v[170:173], v[212:215], v[10:13]
	v_mfma_f32_16x16x32_bf16 v[6:9], v[162:165], v[248:251], v[6:9]
	v_mfma_f32_16x16x32_bf16 v[2:5], v[170:173], v[248:251], v[2:5]
	s_setprio 0
	s_barrier
	s_add_u32 s68, s68, 0x100
	s_addc_u32 s62, s62, 0
	s_cmp_ge_i32 s63, s48
	s_mov_b64 s[20:21], s[0:1]
	s_mov_b32 s40, s63
	s_cbranch_scc0 .LBB0_375

; #define PG8_STAGE(bufoff, gbase, voff) do { _Pragma("unroll") for (int _i = 0; _i < 2; ++_i) \
;         __builtin_amdgcn_global_load_lds((const unsigned*)((const char*)(gbase) + (voff)[_i]), (LAS unsigned*)(lds + (bufoff) + ldsw + _i * 8192), 16, 0, 0); } while (0)
; #define PG8_LDA(dst, b, h) do { _Pragma("unroll") for (int m = 0; m < 4; ++m) _Pragma("unroll") for (int k = 0; k < 2; ++k) dst[m][k] = *(const LAS bf16x8*)(lds + PG8_SA(b, h) + aoff + m * 2048 + k * 1024); } while (0)
; #define PG8_LDB(dst, b, h) do { _Pragma("unroll") for (int n = 0; n < 2; ++n) _Pragma("unroll") for (int k = 0; k < 2; ++k) dst[n][k] = *(const LAS bf16x8*)(lds + PG8_SB(b, h) + boff + n * 2048 + k * 1024); } while (0)
; #define PG8_MMA(ai, bj, At, Bt) do { __builtin_amdgcn_s_setprio(1); _Pragma("unroll") for (int m = 0; m < 4; ++m) _Pragma("unroll") for (int n = 0; n < 2; ++n) _Pragma("unroll") for (int k = 0; k < 2; ++k) \
;         acc[ai][bj][m][n] = __builtin_amdgcn_mfma_f32_16x16x32_bf16(Bt[n][k], At[m][k], acc[ai][bj][m][n], 0, 0, 0); __builtin_amdgcn_s_setprio(0); } while (0)
; #define PG8_WAIT_V(n) asm volatile("s_waitcnt vmcnt(" #n ")" ::: "memory")
; #define PG8_WAIT_L(n) asm volatile("s_waitcnt lgkmcnt(" #n ")" ::: "memory")
; #define PG8_BAR __builtin_amdgcn_s_barrier()
; #define PG8_SCHED __builtin_amdgcn_sched_barrier(0)
; template <class Epi, class Sched>
; __device__ __forceinline__ void gemm_phase(LAS unsigned char* lds, const Gemm g, const Sched& S, const Epi& E) {
;     ...
;             const bool last = (t == nt - 2);
;             const char* a1 = cA + (size_t)(t + 1) * kstep;
;             const char* a2 = last ? nA : cA + (size_t)(t + 2) * kstep; const char* b2 = last ? nB : cB + (size_t)(t + 2) * kstep;
;             const char* a3 = a2 + kstep; const char* b3 = b2 + kstep;
;             PG8_LDB(B0, 0, 0); PG8_LDB(B1, 0, 1); PG8_SCHED; PG8_LDA(At, 0, 0); PG8_STAGE(PG8_SA(1, 1), a1 + hstepA, voffA);
;             PG8_WAIT_V(8); PG8_WAIT_L(0); PG8_BAR; PG8_MMA(0, 0, At, B0); PG8_MMA(0, 1, At, B1); PG8_BAR; PG8_SCHED;
;             PG8_LDA(At, 0, 1); PG8_STAGE(PG8_SB(0, 0), b2, voffB); PG8_STAGE(PG8_SB(0, 1), b2 + hstepB, voffB); PG8_STAGE(PG8_SA(0, 0), a2, voffA);
;             PG8_WAIT_V(8); PG8_WAIT_L(0); PG8_BAR; PG8_MMA(1, 0, At, B0); PG8_MMA(1, 1, At, B1); PG8_BAR; PG8_SCHED;
.LBB0_499:
	s_add_i32 s76, s94, 2
	s_add_u32 s40, s92, 0x100
	s_addc_u32 s41, s93, 0
	s_add_i32 s52, 0, 0x10000
	s_cmp_eq_u32 s71, s94
	s_cselect_b32 vcc_hi, s21, s41
	s_cselect_b32 vcc_lo, s20, s40
	v_add_u32_e32 v0, s52, v169
	s_cselect_b32 s95, s91, s63
	s_cselect_b32 s94, s68, s62
	s_add_i32 s53, 0, 0x14000
	ds_read_b128 v[130:133], v0
	ds_read_b128 v[134:137], v0 offset:1024
	ds_read_b128 v[150:153], v0 offset:2048
	ds_read_b128 v[154:157], v0 offset:3072
	v_add_u32_e32 v0, s53, v169
	ds_read_b128 v[158:161], v0
	ds_read_b128 v[174:177], v0 offset:1024
	ds_read_b128 v[178:181], v0 offset:2048
	ds_read_b128 v[182:185], v0 offset:3072
	v_lshl_add_u64 v[164:165], s[92:93], 0, v[148:149]
	s_add_i32 m0, s19, 0xc000
	ds_read_b128 v[196:199], v173
	ds_read_b128 v[200:203], v173 offset:1024
	ds_read_b128 v[204:207], v173 offset:2048
	ds_read_b128 v[208:211], v173 offset:3072
	ds_read_b128 v[212:215], v173 offset:4096
	ds_read_b128 v[216:219], v173 offset:5120
	ds_read_b128 v[248:251], v173 offset:6144
	ds_read_b128 v[232:235], v173 offset:7168
	global_load_lds_dwordx4 v[164:165], off
	v_lshl_add_u64 v[164:165], s[92:93], 0, v[146:147]
	s_add_i32 m0, s19, 0xe000
	s_nop 0
	global_load_lds_dwordx4 v[164:165], off
	s_waitcnt vmcnt(8)
	s_waitcnt lgkmcnt(0)
	s_barrier
	s_setprio 1
	s_waitcnt lgkmcnt(0)
	v_mfma_f32_16x16x32_bf16 v[126:129], v[130:133], v[196:199], v[126:129]
	v_mfma_f32_16x16x32_bf16 v[122:125], v[150:153], v[196:199], v[122:125]
	v_mfma_f32_16x16x32_bf16 v[110:113], v[130:133], v[204:207], v[110:113]
	v_mfma_f32_16x16x32_bf16 v[106:109], v[150:153], v[204:207], v[106:109]
	v_mfma_f32_16x16x32_bf16 v[94:97], v[130:133], v[212:215], v[94:97]
	v_mfma_f32_16x16x32_bf16 v[90:93], v[150:153], v[212:215], v[90:93]
	v_mfma_f32_16x16x32_bf16 v[78:81], v[130:133], v[248:251], v[78:81]
	v_mfma_f32_16x16x32_bf16 v[74:77], v[150:153], v[248:251], v[74:77]
	v_mfma_f32_16x16x32_bf16 v[126:129], v[134:137], v[200:203], v[126:129]
	v_mfma_f32_16x16x32_bf16 v[122:125], v[154:157], v[200:203], v[122:125]
	v_mfma_f32_16x16x32_bf16 v[110:113], v[134:137], v[208:211], v[110:113]
	v_mfma_f32_16x16x32_bf16 v[106:109], v[154:157], v[208:211], v[106:109]
	v_mfma_f32_16x16x32_bf16 v[94:97], v[134:137], v[216:219], v[94:97]
	v_mfma_f32_16x16x32_bf16 v[90:93], v[154:157], v[216:219], v[90:93]
	v_mfma_f32_16x16x32_bf16 v[78:81], v[134:137], v[232:235], v[78:81]
	v_mfma_f32_16x16x32_bf16 v[74:77], v[154:157], v[232:235], v[74:77]
	v_mfma_f32_16x16x32_bf16 v[118:121], v[158:161], v[196:199], v[118:121]
	v_mfma_f32_16x16x32_bf16 v[114:117], v[178:181], v[196:199], v[114:117]
	v_mfma_f32_16x16x32_bf16 v[102:105], v[158:161], v[204:207], v[102:105]
	v_mfma_f32_16x16x32_bf16 v[98:101], v[178:181], v[204:207], v[98:101]
	v_mfma_f32_16x16x32_bf16 v[86:89], v[158:161], v[212:215], v[86:89]
	v_mfma_f32_16x16x32_bf16 v[82:85], v[178:181], v[212:215], v[82:85]
	v_mfma_f32_16x16x32_bf16 v[70:73], v[158:161], v[248:251], v[70:73]
	v_mfma_f32_16x16x32_bf16 v[66:69], v[178:181], v[248:251], v[66:69]
	v_mfma_f32_16x16x32_bf16 v[118:121], v[174:177], v[200:203], v[118:121]
	v_mfma_f32_16x16x32_bf16 v[114:117], v[182:185], v[200:203], v[114:117]
	v_mfma_f32_16x16x32_bf16 v[102:105], v[174:177], v[208:211], v[102:105]
	v_mfma_f32_16x16x32_bf16 v[98:101], v[182:185], v[208:211], v[98:101]
	v_mfma_f32_16x16x32_bf16 v[86:89], v[174:177], v[216:219], v[86:89]
	v_mfma_f32_16x16x32_bf16 v[82:85], v[182:185], v[216:219], v[82:85]
	v_mfma_f32_16x16x32_bf16 v[70:73], v[174:177], v[232:235], v[70:73]
	v_mfma_f32_16x16x32_bf16 v[66:69], v[182:185], v[232:235], v[66:69]
	s_setprio 0
	s_barrier
	s_add_i32 s52, s52, s17
	v_lshl_add_u64 v[164:165], s[94:95], 0, v[140:141]
	s_mov_b32 m0, s52
	ds_read_b128 v[196:199], v173 offset:16384
	ds_read_b128 v[200:203], v173 offset:17408
	ds_read_b128 v[204:207], v173 offset:18432
	ds_read_b128 v[208:211], v173 offset:19456
	ds_read_b128 v[212:215], v173 offset:20480
	ds_read_b128 v[216:219], v173 offset:21504
	ds_read_b128 v[232:235], v173 offset:22528
	ds_read_b128 v[248:251], v173 offset:23552
	global_load_lds_dwordx4 v[164:165], off
	s_add_i32 m0, s52, 0x2000
	s_add_u32 s92, s94, 0x10000
	v_lshl_add_u64 v[170:171], s[94:95], 0, v[144:145]
	s_addc_u32 s93, s95, 0
	s_add_i32 s52, s53, s17
	global_load_lds_dwordx4 v[170:171], off
	v_lshl_add_u64 v[220:221], s[92:93], 0, v[140:141]
	s_mov_b32 m0, s52
	v_lshl_add_u64 v[246:247], vcc, 0, v[142:143]
	global_load_lds_dwordx4 v[220:221], off
	v_lshl_add_u64 v[220:221], s[92:93], 0, v[144:145]
	s_add_i32 m0, s52, 0x2000
	s_nop 0
	global_load_lds_dwordx4 v[220:221], off
	v_lshl_add_u64 v[220:221], vcc, 0, v[138:139]
	s_mov_b32 m0, s19
	s_nop 0
	global_load_lds_dwordx4 v[220:221], off
	s_mov_b32 m0, s44
	s_nop 0
	global_load_lds_dwordx4 v[246:247], off
	s_waitcnt vmcnt(8)
	s_waitcnt lgkmcnt(0)
	s_barrier
; #define PG8_STAGE(bufoff, gbase, voff) do { _Pragma("unroll") for (int _i = 0; _i < 2; ++_i) \
;         __builtin_amdgcn_global_load_lds((const unsigned*)((const char*)(gbase) + (voff)[_i]), (LAS unsigned*)(lds + (bufoff) + ldsw + _i * 8192), 16, 0, 0); } while (0)
; #define PG8_LDA(dst, b, h) do { _Pragma("unroll") for (int m = 0; m < 4; ++m) _Pragma("unroll") for (int k = 0; k < 2; ++k) dst[m][k] = *(const LAS bf16x8*)(lds + PG8_SA(b, h) + aoff + m * 2048 + k * 1024); } while (0)
; #define PG8_LDB(dst, b, h) do { _Pragma("unroll") for (int n = 0; n < 2; ++n) _Pragma("unroll") for (int k = 0; k < 2; ++k) dst[n][k] = *(const LAS bf16x8*)(lds + PG8_SB(b, h) + boff + n * 2048 + k * 1024); } while (0)
; #define PG8_MMA(ai, bj, At, Bt) do { __builtin_amdgcn_s_setprio(1); _Pragma("unroll") for (int m = 0; m < 4; ++m) _Pragma("unroll") for (int n = 0; n < 2; ++n) _Pragma("unroll") for (int k = 0; k < 2; ++k) \
;         acc[ai][bj][m][n] = __builtin_amdgcn_mfma_f32_16x16x32_bf16(Bt[n][k], At[m][k], acc[ai][bj][m][n], 0, 0, 0); __builtin_amdgcn_s_setprio(0); } while (0)
; #define PG8_WAIT_V(n) asm volatile("s_waitcnt vmcnt(" #n ")" ::: "memory")
; #define PG8_WAIT_L(n) asm volatile("s_waitcnt lgkmcnt(" #n ")" ::: "memory")
; #define PG8_BAR __builtin_amdgcn_s_barrier()
; #define PG8_SCHED __builtin_amdgcn_sched_barrier(0)
; template <class Epi, class Sched>
; __device__ __forceinline__ void gemm_phase(LAS unsigned char* lds, const Gemm g, const Sched& S, const Epi& E) {
;     ...
;             PG8_WAIT_V(8); PG8_WAIT_L(0); PG8_BAR; PG8_MMA(1, 0, At, B0); PG8_MMA(1, 1, At, B1); PG8_BAR; PG8_SCHED;
;             PG8_LDB(B0, 1, 0); PG8_LDB(B1, 1, 1); PG8_SCHED; PG8_LDA(At, 1, 0); PG8_STAGE(PG8_SA(0, 1), a2 + hstepA, voffA);
;             PG8_WAIT_V(8); PG8_WAIT_L(0); PG8_BAR; PG8_MMA(0, 0, At, B0); PG8_MMA(0, 1, At, B1); PG8_BAR; PG8_SCHED;
	s_setprio 1
	s_waitcnt lgkmcnt(0)
	v_mfma_f32_16x16x32_bf16 v[62:65], v[130:133], v[196:199], v[62:65]
	v_mfma_f32_16x16x32_bf16 v[58:61], v[150:153], v[196:199], v[58:61]
	v_mfma_f32_16x16x32_bf16 v[46:49], v[130:133], v[204:207], v[46:49]
	v_mfma_f32_16x16x32_bf16 v[42:45], v[150:153], v[204:207], v[42:45]
	v_mfma_f32_16x16x32_bf16 v[30:33], v[130:133], v[212:215], v[30:33]
	v_mfma_f32_16x16x32_bf16 v[26:29], v[150:153], v[212:215], v[26:29]
	v_mfma_f32_16x16x32_bf16 v[14:17], v[130:133], v[232:235], v[14:17]
	v_mfma_f32_16x16x32_bf16 v[10:13], v[150:153], v[232:235], v[10:13]
	v_mfma_f32_16x16x32_bf16 v[62:65], v[134:137], v[200:203], v[62:65]
	v_mfma_f32_16x16x32_bf16 v[58:61], v[154:157], v[200:203], v[58:61]
	v_mfma_f32_16x16x32_bf16 v[46:49], v[134:137], v[208:211], v[46:49]
	v_mfma_f32_16x16x32_bf16 v[42:45], v[154:157], v[208:211], v[42:45]
	v_mfma_f32_16x16x32_bf16 v[30:33], v[134:137], v[216:219], v[30:33]
	v_mfma_f32_16x16x32_bf16 v[26:29], v[154:157], v[216:219], v[26:29]
	v_mfma_f32_16x16x32_bf16 v[14:17], v[134:137], v[248:251], v[14:17]
	v_mfma_f32_16x16x32_bf16 v[10:13], v[154:157], v[248:251], v[10:13]
	v_mfma_f32_16x16x32_bf16 v[54:57], v[158:161], v[196:199], v[54:57]
	v_mfma_f32_16x16x32_bf16 v[50:53], v[178:181], v[196:199], v[50:53]
	v_mfma_f32_16x16x32_bf16 v[38:41], v[158:161], v[204:207], v[38:41]
	v_mfma_f32_16x16x32_bf16 v[34:37], v[178:181], v[204:207], v[34:37]
	v_mfma_f32_16x16x32_bf16 v[22:25], v[158:161], v[212:215], v[22:25]
	v_mfma_f32_16x16x32_bf16 v[18:21], v[178:181], v[212:215], v[18:21]
	v_mfma_f32_16x16x32_bf16 v[6:9], v[158:161], v[232:235], v[6:9]
	v_mfma_f32_16x16x32_bf16 v[2:5], v[178:181], v[232:235], v[2:5]
	v_mfma_f32_16x16x32_bf16 v[54:57], v[174:177], v[200:203], v[54:57]
	v_mfma_f32_16x16x32_bf16 v[50:53], v[182:185], v[200:203], v[50:53]
	v_mfma_f32_16x16x32_bf16 v[38:41], v[174:177], v[208:211], v[38:41]
	v_mfma_f32_16x16x32_bf16 v[34:37], v[182:185], v[208:211], v[34:37]
	v_mfma_f32_16x16x32_bf16 v[22:25], v[174:177], v[216:219], v[22:25]
	v_mfma_f32_16x16x32_bf16 v[18:21], v[182:185], v[216:219], v[18:21]
	v_mfma_f32_16x16x32_bf16 v[6:9], v[174:177], v[248:251], v[6:9]
	v_mfma_f32_16x16x32_bf16 v[2:5], v[182:185], v[248:251], v[2:5]
	s_setprio 0
	s_barrier
	s_add_i32 s52, 0, 0x18000
	v_add_u32_e32 v0, s52, v169
	s_add_i32 s53, 0, 0x1c000
	ds_read_b128 v[130:133], v0
	ds_read_b128 v[134:137], v0 offset:1024
	ds_read_b128 v[150:153], v0 offset:2048
	ds_read_b128 v[154:157], v0 offset:3072
	v_add_u32_e32 v0, s53, v169
	ds_read_b128 v[158:161], v0
	ds_read_b128 v[174:177], v0 offset:1024
	ds_read_b128 v[178:181], v0 offset:2048
	ds_read_b128 v[182:185], v0 offset:3072
	s_add_u32 s92, vcc_lo, 0x50000
	s_addc_u32 s93, vcc_hi, 0
	s_mov_b32 m0, s45
	v_lshl_add_u64 v[236:237], s[92:93], 0, v[138:139]
	ds_read_b128 v[196:199], v173 offset:32768
	ds_read_b128 v[200:203], v173 offset:33792
	ds_read_b128 v[204:207], v173 offset:34816
	ds_read_b128 v[208:211], v173 offset:35840
	ds_read_b128 v[212:215], v173 offset:36864
	ds_read_b128 v[216:219], v173 offset:37888
	ds_read_b128 v[232:235], v173 offset:38912
	ds_read_b128 v[248:251], v173 offset:39936
	global_load_lds_dwordx4 v[236:237], off
	v_lshl_add_u64 v[236:237], s[92:93], 0, v[142:143]
	s_mov_b32 m0, s46
	s_nop 0
	global_load_lds_dwordx4 v[236:237], off
	s_waitcnt vmcnt(8)
	s_waitcnt lgkmcnt(0)
	s_barrier
	s_setprio 1
	s_waitcnt lgkmcnt(0)
	v_mfma_f32_16x16x32_bf16 v[126:129], v[130:133], v[196:199], v[126:129]
	v_mfma_f32_16x16x32_bf16 v[122:125], v[150:153], v[196:199], v[122:125]
	v_mfma_f32_16x16x32_bf16 v[110:113], v[130:133], v[204:207], v[110:113]
	v_mfma_f32_16x16x32_bf16 v[106:109], v[150:153], v[204:207], v[106:109]
	v_mfma_f32_16x16x32_bf16 v[94:97], v[130:133], v[212:215], v[94:97]
	v_mfma_f32_16x16x32_bf16 v[90:93], v[150:153], v[212:215], v[90:93]
	v_mfma_f32_16x16x32_bf16 v[78:81], v[130:133], v[232:235], v[78:81]
	v_mfma_f32_16x16x32_bf16 v[74:77], v[150:153], v[232:235], v[74:77]
	v_mfma_f32_16x16x32_bf16 v[126:129], v[134:137], v[200:203], v[126:129]
	v_mfma_f32_16x16x32_bf16 v[122:125], v[154:157], v[200:203], v[122:125]
	v_mfma_f32_16x16x32_bf16 v[110:113], v[134:137], v[208:211], v[110:113]
	v_mfma_f32_16x16x32_bf16 v[106:109], v[154:157], v[208:211], v[106:109]
	v_mfma_f32_16x16x32_bf16 v[94:97], v[134:137], v[216:219], v[94:97]
	v_mfma_f32_16x16x32_bf16 v[90:93], v[154:157], v[216:219], v[90:93]
	v_mfma_f32_16x16x32_bf16 v[78:81], v[134:137], v[248:251], v[78:81]
	v_mfma_f32_16x16x32_bf16 v[74:77], v[154:157], v[248:251], v[74:77]
	v_mfma_f32_16x16x32_bf16 v[118:121], v[158:161], v[196:199], v[118:121]
	v_mfma_f32_16x16x32_bf16 v[114:117], v[178:181], v[196:199], v[114:117]
	v_mfma_f32_16x16x32_bf16 v[102:105], v[158:161], v[204:207], v[102:105]
	v_mfma_f32_16x16x32_bf16 v[98:101], v[178:181], v[204:207], v[98:101]
	v_mfma_f32_16x16x32_bf16 v[86:89], v[158:161], v[212:215], v[86:89]
	v_mfma_f32_16x16x32_bf16 v[82:85], v[178:181], v[212:215], v[82:85]
	v_mfma_f32_16x16x32_bf16 v[70:73], v[158:161], v[232:235], v[70:73]
	v_mfma_f32_16x16x32_bf16 v[66:69], v[178:181], v[232:235], v[66:69]
	v_mfma_f32_16x16x32_bf16 v[118:121], v[174:177], v[200:203], v[118:121]
	v_mfma_f32_16x16x32_bf16 v[114:117], v[182:185], v[200:203], v[114:117]
	v_mfma_f32_16x16x32_bf16 v[102:105], v[174:177], v[208:211], v[102:105]
	v_mfma_f32_16x16x32_bf16 v[98:101], v[182:185], v[208:211], v[98:101]
	v_mfma_f32_16x16x32_bf16 v[86:89], v[174:177], v[216:219], v[86:89]
	v_mfma_f32_16x16x32_bf16 v[82:85], v[182:185], v[216:219], v[82:85]
	v_mfma_f32_16x16x32_bf16 v[70:73], v[174:177], v[248:251], v[70:73]
	v_mfma_f32_16x16x32_bf16 v[66:69], v[182:185], v[248:251], v[66:69]
	s_setprio 0
	s_barrier
; #define PG8_STAGE(bufoff, gbase, voff) do { _Pragma("unroll") for (int _i = 0; _i < 2; ++_i) \
;         __builtin_amdgcn_global_load_lds((const unsigned*)((const char*)(gbase) + (voff)[_i]), (LAS unsigned*)(lds + (bufoff) + ldsw + _i * 8192), 16, 0, 0); } while (0)
; #define PG8_LDA(dst, b, h) do { _Pragma("unroll") for (int m = 0; m < 4; ++m) _Pragma("unroll") for (int k = 0; k < 2; ++k) dst[m][k] = *(const LAS bf16x8*)(lds + PG8_SA(b, h) + aoff + m * 2048 + k * 1024); } while (0)
; #define PG8_MMA(ai, bj, At, Bt) do { __builtin_amdgcn_s_setprio(1); _Pragma("unroll") for (int m = 0; m < 4; ++m) _Pragma("unroll") for (int n = 0; n < 2; ++n) _Pragma("unroll") for (int k = 0; k < 2; ++k) \
;         acc[ai][bj][m][n] = __builtin_amdgcn_mfma_f32_16x16x32_bf16(Bt[n][k], At[m][k], acc[ai][bj][m][n], 0, 0, 0); __builtin_amdgcn_s_setprio(0); } while (0)
; #define PG8_WAIT_V(n) asm volatile("s_waitcnt vmcnt(" #n ")" ::: "memory")
; #define PG8_WAIT_L(n) asm volatile("s_waitcnt lgkmcnt(" #n ")" ::: "memory")
; #define PG8_BAR __builtin_amdgcn_s_barrier()
; #define PG8_SCHED __builtin_amdgcn_sched_barrier(0)
; template <class Epi, class Sched>
; __device__ __forceinline__ void gemm_phase(LAS unsigned char* lds, const Gemm g, const Sched& S, const Epi& E) {
;     ...
;             PG8_LDA(At, 1, 1); PG8_STAGE(PG8_SB(1, 0), b3, voffB); PG8_STAGE(PG8_SB(1, 1), b3 + hstepB, voffB); PG8_STAGE(PG8_SA(1, 0), a3, voffA);
;             PG8_WAIT_V(8); PG8_WAIT_L(0); PG8_BAR; PG8_MMA(1, 0, At, B0); PG8_MMA(1, 1, At, B1); PG8_BAR; PG8_SCHED;
;         }
	s_add_i32 s52, s52, s17
	v_lshl_add_u64 v[164:165], v[164:165], 0, s[26:27]
	s_mov_b32 m0, s52
	ds_read_b128 v[196:199], v173 offset:49152
	ds_read_b128 v[200:203], v173 offset:50176
	ds_read_b128 v[204:207], v173 offset:51200
	ds_read_b128 v[208:211], v173 offset:52224
	ds_read_b128 v[212:215], v173 offset:53248
	ds_read_b128 v[216:219], v173 offset:54272
	ds_read_b128 v[232:235], v173 offset:55296
	ds_read_b128 v[248:251], v173 offset:56320
	global_load_lds_dwordx4 v[164:165], off
	s_add_i32 m0, s52, 0x2000
	s_add_u32 s92, s94, 0x10080
	v_lshl_add_u64 v[164:165], v[170:171], 0, s[26:27]
	s_addc_u32 s93, s95, 0
	s_add_i32 s52, s53, s17
	global_load_lds_dwordx4 v[164:165], off
	v_lshl_add_u64 v[164:165], s[92:93], 0, v[140:141]
	s_mov_b32 m0, s52
	s_nop 0
	global_load_lds_dwordx4 v[164:165], off
	v_lshl_add_u64 v[164:165], s[92:93], 0, v[144:145]
	s_add_i32 m0, s52, 0x2000
	s_nop 0
	global_load_lds_dwordx4 v[164:165], off
	v_lshl_add_u64 v[164:165], v[220:221], 0, s[26:27]
	s_mov_b32 m0, s67
	s_nop 0
	global_load_lds_dwordx4 v[164:165], off
	v_lshl_add_u64 v[164:165], v[246:247], 0, s[26:27]
	s_mov_b32 m0, s69
	s_nop 0
	global_load_lds_dwordx4 v[164:165], off
	s_waitcnt vmcnt(8)
	s_waitcnt lgkmcnt(0)
	s_barrier
	s_setprio 1
	s_waitcnt lgkmcnt(0)
	v_mfma_f32_16x16x32_bf16 v[62:65], v[130:133], v[196:199], v[62:65]
	v_mfma_f32_16x16x32_bf16 v[58:61], v[150:153], v[196:199], v[58:61]
	v_mfma_f32_16x16x32_bf16 v[46:49], v[130:133], v[204:207], v[46:49]
	v_mfma_f32_16x16x32_bf16 v[42:45], v[150:153], v[204:207], v[42:45]
	v_mfma_f32_16x16x32_bf16 v[30:33], v[130:133], v[212:215], v[30:33]
	v_mfma_f32_16x16x32_bf16 v[26:29], v[150:153], v[212:215], v[26:29]
	v_mfma_f32_16x16x32_bf16 v[14:17], v[130:133], v[232:235], v[14:17]
	v_mfma_f32_16x16x32_bf16 v[10:13], v[150:153], v[232:235], v[10:13]
	v_mfma_f32_16x16x32_bf16 v[62:65], v[134:137], v[200:203], v[62:65]
	v_mfma_f32_16x16x32_bf16 v[58:61], v[154:157], v[200:203], v[58:61]
	v_mfma_f32_16x16x32_bf16 v[46:49], v[134:137], v[208:211], v[46:49]
	v_mfma_f32_16x16x32_bf16 v[42:45], v[154:157], v[208:211], v[42:45]
	v_mfma_f32_16x16x32_bf16 v[30:33], v[134:137], v[216:219], v[30:33]
	v_mfma_f32_16x16x32_bf16 v[26:29], v[154:157], v[216:219], v[26:29]
	v_mfma_f32_16x16x32_bf16 v[14:17], v[134:137], v[248:251], v[14:17]
	v_mfma_f32_16x16x32_bf16 v[10:13], v[154:157], v[248:251], v[10:13]
	v_mfma_f32_16x16x32_bf16 v[54:57], v[158:161], v[196:199], v[54:57]
	v_mfma_f32_16x16x32_bf16 v[50:53], v[178:181], v[196:199], v[50:53]
	v_mfma_f32_16x16x32_bf16 v[38:41], v[158:161], v[204:207], v[38:41]
	v_mfma_f32_16x16x32_bf16 v[34:37], v[178:181], v[204:207], v[34:37]
	v_mfma_f32_16x16x32_bf16 v[22:25], v[158:161], v[212:215], v[22:25]
	v_mfma_f32_16x16x32_bf16 v[18:21], v[178:181], v[212:215], v[18:21]
	v_mfma_f32_16x16x32_bf16 v[6:9], v[158:161], v[232:235], v[6:9]
	v_mfma_f32_16x16x32_bf16 v[2:5], v[178:181], v[232:235], v[2:5]
	v_mfma_f32_16x16x32_bf16 v[54:57], v[174:177], v[200:203], v[54:57]
	v_mfma_f32_16x16x32_bf16 v[50:53], v[182:185], v[200:203], v[50:53]
	v_mfma_f32_16x16x32_bf16 v[38:41], v[174:177], v[208:211], v[38:41]
	v_mfma_f32_16x16x32_bf16 v[34:37], v[182:185], v[208:211], v[34:37]
	v_mfma_f32_16x16x32_bf16 v[22:25], v[174:177], v[216:219], v[22:25]
	v_mfma_f32_16x16x32_bf16 v[18:21], v[182:185], v[216:219], v[18:21]
	v_mfma_f32_16x16x32_bf16 v[6:9], v[174:177], v[248:251], v[6:9]
	v_mfma_f32_16x16x32_bf16 v[2:5], v[182:185], v[248:251], v[2:5]
	s_setprio 0
	s_barrier
	s_add_u32 s62, s62, 0x100
	s_addc_u32 s63, s63, 0
	s_cmp_ge_i32 s76, s47
	s_mov_b64 s[92:93], s[40:41]
	s_mov_b32 s94, s76
	s_cbranch_scc0 .LBB0_499

; #define PG8_STAGE(bufoff, gbase, voff) do { _Pragma("unroll") for (int _i = 0; _i < 2; ++_i) \
;         __builtin_amdgcn_global_load_lds((const unsigned*)((const char*)(gbase) + (voff)[_i]), (LAS unsigned*)(lds + (bufoff) + ldsw + _i * 8192), 16, 0, 0); } while (0)
; #define PG8_LDA(dst, b, h) do { _Pragma("unroll") for (int m = 0; m < 4; ++m) _Pragma("unroll") for (int k = 0; k < 2; ++k) dst[m][k] = *(const LAS bf16x8*)(lds + PG8_SA(b, h) + aoff + m * 2048 + k * 1024); } while (0)
; #define PG8_LDB(dst, b, h) do { _Pragma("unroll") for (int n = 0; n < 2; ++n) _Pragma("unroll") for (int k = 0; k < 2; ++k) dst[n][k] = *(const LAS bf16x8*)(lds + PG8_SB(b, h) + boff + n * 2048 + k * 1024); } while (0)
; #define PG8_MMA(ai, bj, At, Bt) do { __builtin_amdgcn_s_setprio(1); _Pragma("unroll") for (int m = 0; m < 4; ++m) _Pragma("unroll") for (int n = 0; n < 2; ++n) _Pragma("unroll") for (int k = 0; k < 2; ++k) \
;         acc[ai][bj][m][n] = __builtin_amdgcn_mfma_f32_16x16x32_bf16(Bt[n][k], At[m][k], acc[ai][bj][m][n], 0, 0, 0); __builtin_amdgcn_s_setprio(0); } while (0)
; #define PG8_WAIT_V(n) asm volatile("s_waitcnt vmcnt(" #n ")" ::: "memory")
; #define PG8_WAIT_L(n) asm volatile("s_waitcnt lgkmcnt(" #n ")" ::: "memory")
; #define PG8_BAR __builtin_amdgcn_s_barrier()
; #define PG8_SCHED __builtin_amdgcn_sched_barrier(0)
; template <class Epi, class Sched>
; __device__ __forceinline__ void gemm_phase(LAS unsigned char* lds, const Gemm g, const Sched& S, const Epi& E) {
;     ...
;             const bool last = (t == nt - 2);
;             const char* a1 = cA + (size_t)(t + 1) * kstep;
;             const char* a2 = last ? nA : cA + (size_t)(t + 2) * kstep; const char* b2 = last ? nB : cB + (size_t)(t + 2) * kstep;
;             const char* a3 = a2 + kstep; const char* b3 = b2 + kstep;
;             PG8_LDB(B0, 0, 0); PG8_LDB(B1, 0, 1); PG8_SCHED; PG8_LDA(At, 0, 0); PG8_STAGE(PG8_SA(1, 1), a1 + hstepA, voffA);
;             PG8_WAIT_V(8); PG8_WAIT_L(0); PG8_BAR; PG8_MMA(0, 0, At, B0); PG8_MMA(0, 1, At, B1); PG8_BAR; PG8_SCHED;
;             PG8_LDA(At, 0, 1); PG8_STAGE(PG8_SB(0, 0), b2, voffB); PG8_STAGE(PG8_SB(0, 1), b2 + hstepB, voffB); PG8_STAGE(PG8_SA(0, 0), a2, voffA);
;             PG8_WAIT_V(8); PG8_WAIT_L(0); PG8_BAR; PG8_MMA(1, 0, At, B0); PG8_MMA(1, 1, At, B1); PG8_BAR; PG8_SCHED;
.LBB0_526:
	s_add_i32 s62, s0, 2
	s_add_u32 s1, s20, 0xffff0080
	s_addc_u32 s38, s21, -1
	s_add_i32 s39, 0, 0x10000
	s_cmp_eq_u32 s71, s0
	s_cselect_b32 s43, s61, s38
	s_cselect_b32 s42, s96, s1
	v_add_u32_e32 v0, s39, v201
	s_cselect_b32 s1, s91, vcc_lo
	s_cselect_b32 s0, s90, s97
	s_add_i32 s52, 0, 0x14000
	ds_read_b128 v[130:133], v0
	ds_read_b128 v[134:137], v0 offset:1024
	ds_read_b128 v[138:141], v0 offset:2048
	ds_read_b128 v[142:145], v0 offset:3072
	v_add_u32_e32 v0, s52, v201
	ds_read_b128 v[146:149], v0
	ds_read_b128 v[150:153], v0 offset:1024
	ds_read_b128 v[154:157], v0 offset:2048
	ds_read_b128 v[158:161], v0 offset:3072
	v_lshl_add_u64 v[220:221], s[20:21], 0, v[176:177]
	s_add_i32 m0, s19, 0xc000
	ds_read_b128 v[162:165], v202
	ds_read_b128 v[178:181], v202 offset:1024
	ds_read_b128 v[182:185], v202 offset:2048
	ds_read_b128 v[196:199], v202 offset:3072
	ds_read_b128 v[204:207], v202 offset:4096
	ds_read_b128 v[208:211], v202 offset:5120
	ds_read_b128 v[212:215], v202 offset:6144
	ds_read_b128 v[216:219], v202 offset:7168
	global_load_lds_dwordx4 v[220:221], off
	v_lshl_add_u64 v[220:221], s[20:21], 0, v[174:175]
	s_add_i32 m0, s19, 0xe000
	s_nop 0
	global_load_lds_dwordx4 v[220:221], off
	s_waitcnt vmcnt(8)
	s_waitcnt lgkmcnt(0)
	s_barrier
	s_setprio 1
	s_waitcnt lgkmcnt(0)
	v_mfma_f32_16x16x32_bf16 v[126:129], v[130:133], v[162:165], v[126:129]
	v_mfma_f32_16x16x32_bf16 v[122:125], v[138:141], v[162:165], v[122:125]
	v_mfma_f32_16x16x32_bf16 v[110:113], v[130:133], v[182:185], v[110:113]
	v_mfma_f32_16x16x32_bf16 v[106:109], v[138:141], v[182:185], v[106:109]
	v_mfma_f32_16x16x32_bf16 v[94:97], v[130:133], v[204:207], v[94:97]
	v_mfma_f32_16x16x32_bf16 v[90:93], v[138:141], v[204:207], v[90:93]
	v_mfma_f32_16x16x32_bf16 v[78:81], v[130:133], v[212:215], v[78:81]
	v_mfma_f32_16x16x32_bf16 v[74:77], v[138:141], v[212:215], v[74:77]
	v_mfma_f32_16x16x32_bf16 v[126:129], v[134:137], v[178:181], v[126:129]
	v_mfma_f32_16x16x32_bf16 v[122:125], v[142:145], v[178:181], v[122:125]
	v_mfma_f32_16x16x32_bf16 v[110:113], v[134:137], v[196:199], v[110:113]
	v_mfma_f32_16x16x32_bf16 v[106:109], v[142:145], v[196:199], v[106:109]
	v_mfma_f32_16x16x32_bf16 v[94:97], v[134:137], v[208:211], v[94:97]
	v_mfma_f32_16x16x32_bf16 v[90:93], v[142:145], v[208:211], v[90:93]
	v_mfma_f32_16x16x32_bf16 v[78:81], v[134:137], v[216:219], v[78:81]
	v_mfma_f32_16x16x32_bf16 v[74:77], v[142:145], v[216:219], v[74:77]
	v_mfma_f32_16x16x32_bf16 v[118:121], v[146:149], v[162:165], v[118:121]
	v_mfma_f32_16x16x32_bf16 v[114:117], v[154:157], v[162:165], v[114:117]
	v_mfma_f32_16x16x32_bf16 v[102:105], v[146:149], v[182:185], v[102:105]
	v_mfma_f32_16x16x32_bf16 v[98:101], v[154:157], v[182:185], v[98:101]
	v_mfma_f32_16x16x32_bf16 v[86:89], v[146:149], v[204:207], v[86:89]
	v_mfma_f32_16x16x32_bf16 v[82:85], v[154:157], v[204:207], v[82:85]
	v_mfma_f32_16x16x32_bf16 v[70:73], v[146:149], v[212:215], v[70:73]
	v_mfma_f32_16x16x32_bf16 v[66:69], v[154:157], v[212:215], v[66:69]
	v_mfma_f32_16x16x32_bf16 v[118:121], v[150:153], v[178:181], v[118:121]
	v_mfma_f32_16x16x32_bf16 v[114:117], v[158:161], v[178:181], v[114:117]
	v_mfma_f32_16x16x32_bf16 v[102:105], v[150:153], v[196:199], v[102:105]
	v_mfma_f32_16x16x32_bf16 v[98:101], v[158:161], v[196:199], v[98:101]
	v_mfma_f32_16x16x32_bf16 v[86:89], v[150:153], v[208:211], v[86:89]
	v_mfma_f32_16x16x32_bf16 v[82:85], v[158:161], v[208:211], v[82:85]
	v_mfma_f32_16x16x32_bf16 v[70:73], v[150:153], v[216:219], v[70:73]
	v_mfma_f32_16x16x32_bf16 v[66:69], v[158:161], v[216:219], v[66:69]
	s_setprio 0
	s_barrier
	s_add_i32 s38, s39, s17
	v_lshl_add_u64 v[220:221], s[0:1], 0, v[168:169]
	s_mov_b32 m0, s38
	ds_read_b128 v[162:165], v202 offset:16384
	ds_read_b128 v[178:181], v202 offset:17408
	ds_read_b128 v[182:185], v202 offset:18432
	ds_read_b128 v[196:199], v202 offset:19456
	ds_read_b128 v[204:207], v202 offset:20480
	ds_read_b128 v[208:211], v202 offset:21504
	ds_read_b128 v[212:215], v202 offset:22528
	ds_read_b128 v[216:219], v202 offset:23552
	global_load_lds_dwordx4 v[220:221], off
	s_add_i32 m0, s38, 0x2000
	s_add_u32 s38, s0, 0x50000
	v_lshl_add_u64 v[232:233], s[0:1], 0, v[172:173]
	s_addc_u32 s39, s1, 0
	s_add_i32 s52, s52, s17
	global_load_lds_dwordx4 v[232:233], off
	v_lshl_add_u64 v[234:235], s[38:39], 0, v[168:169]
	s_mov_b32 m0, s52
	v_lshl_add_u64 v[236:237], s[42:43], 0, v[170:171]
	global_load_lds_dwordx4 v[234:235], off
	v_lshl_add_u64 v[234:235], s[38:39], 0, v[172:173]
	s_add_i32 m0, s52, 0x2000
	s_nop 0
	global_load_lds_dwordx4 v[234:235], off
	v_lshl_add_u64 v[234:235], s[42:43], 0, v[166:167]
	s_mov_b32 m0, s19
	s_nop 0
	global_load_lds_dwordx4 v[234:235], off
	s_mov_b32 m0, s44
	s_nop 0
	global_load_lds_dwordx4 v[236:237], off
	s_waitcnt vmcnt(8)
	s_waitcnt lgkmcnt(0)
	s_barrier
; #define PG8_STAGE(bufoff, gbase, voff) do { _Pragma("unroll") for (int _i = 0; _i < 2; ++_i) \
;         __builtin_amdgcn_global_load_lds((const unsigned*)((const char*)(gbase) + (voff)[_i]), (LAS unsigned*)(lds + (bufoff) + ldsw + _i * 8192), 16, 0, 0); } while (0)
; #define PG8_LDA(dst, b, h) do { _Pragma("unroll") for (int m = 0; m < 4; ++m) _Pragma("unroll") for (int k = 0; k < 2; ++k) dst[m][k] = *(const LAS bf16x8*)(lds + PG8_SA(b, h) + aoff + m * 2048 + k * 1024); } while (0)
; #define PG8_LDB(dst, b, h) do { _Pragma("unroll") for (int n = 0; n < 2; ++n) _Pragma("unroll") for (int k = 0; k < 2; ++k) dst[n][k] = *(const LAS bf16x8*)(lds + PG8_SB(b, h) + boff + n * 2048 + k * 1024); } while (0)
; #define PG8_MMA(ai, bj, At, Bt) do { __builtin_amdgcn_s_setprio(1); _Pragma("unroll") for (int m = 0; m < 4; ++m) _Pragma("unroll") for (int n = 0; n < 2; ++n) _Pragma("unroll") for (int k = 0; k < 2; ++k) \
;         acc[ai][bj][m][n] = __builtin_amdgcn_mfma_f32_16x16x32_bf16(Bt[n][k], At[m][k], acc[ai][bj][m][n], 0, 0, 0); __builtin_amdgcn_s_setprio(0); } while (0)
; #define PG8_WAIT_V(n) asm volatile("s_waitcnt vmcnt(" #n ")" ::: "memory")
; #define PG8_WAIT_L(n) asm volatile("s_waitcnt lgkmcnt(" #n ")" ::: "memory")
; #define PG8_BAR __builtin_amdgcn_s_barrier()
; #define PG8_SCHED __builtin_amdgcn_sched_barrier(0)
; template <class Epi, class Sched>
; __device__ __forceinline__ void gemm_phase(LAS unsigned char* lds, const Gemm g, const Sched& S, const Epi& E) {
;     ...
;             PG8_WAIT_V(8); PG8_WAIT_L(0); PG8_BAR; PG8_MMA(1, 0, At, B0); PG8_MMA(1, 1, At, B1); PG8_BAR; PG8_SCHED;
;             PG8_LDB(B0, 1, 0); PG8_LDB(B1, 1, 1); PG8_SCHED; PG8_LDA(At, 1, 0); PG8_STAGE(PG8_SA(0, 1), a2 + hstepA, voffA);
;             PG8_WAIT_V(8); PG8_WAIT_L(0); PG8_BAR; PG8_MMA(0, 0, At, B0); PG8_MMA(0, 1, At, B1); PG8_BAR; PG8_SCHED;
	s_setprio 1
	s_waitcnt lgkmcnt(0)
	v_mfma_f32_16x16x32_bf16 v[62:65], v[130:133], v[162:165], v[62:65]
	v_mfma_f32_16x16x32_bf16 v[58:61], v[138:141], v[162:165], v[58:61]
	v_mfma_f32_16x16x32_bf16 v[46:49], v[130:133], v[182:185], v[46:49]
	v_mfma_f32_16x16x32_bf16 v[42:45], v[138:141], v[182:185], v[42:45]
	v_mfma_f32_16x16x32_bf16 v[30:33], v[130:133], v[204:207], v[30:33]
	v_mfma_f32_16x16x32_bf16 v[26:29], v[138:141], v[204:207], v[26:29]
	v_mfma_f32_16x16x32_bf16 v[14:17], v[130:133], v[212:215], v[14:17]
	v_mfma_f32_16x16x32_bf16 v[10:13], v[138:141], v[212:215], v[10:13]
	v_mfma_f32_16x16x32_bf16 v[62:65], v[134:137], v[178:181], v[62:65]
	v_mfma_f32_16x16x32_bf16 v[58:61], v[142:145], v[178:181], v[58:61]
	v_mfma_f32_16x16x32_bf16 v[46:49], v[134:137], v[196:199], v[46:49]
	v_mfma_f32_16x16x32_bf16 v[42:45], v[142:145], v[196:199], v[42:45]
	v_mfma_f32_16x16x32_bf16 v[30:33], v[134:137], v[208:211], v[30:33]
	v_mfma_f32_16x16x32_bf16 v[26:29], v[142:145], v[208:211], v[26:29]
	v_mfma_f32_16x16x32_bf16 v[14:17], v[134:137], v[216:219], v[14:17]
	v_mfma_f32_16x16x32_bf16 v[10:13], v[142:145], v[216:219], v[10:13]
	v_mfma_f32_16x16x32_bf16 v[54:57], v[146:149], v[162:165], v[54:57]
	v_mfma_f32_16x16x32_bf16 v[50:53], v[154:157], v[162:165], v[50:53]
	v_mfma_f32_16x16x32_bf16 v[38:41], v[146:149], v[182:185], v[38:41]
	v_mfma_f32_16x16x32_bf16 v[34:37], v[154:157], v[182:185], v[34:37]
	v_mfma_f32_16x16x32_bf16 v[22:25], v[146:149], v[204:207], v[22:25]
	v_mfma_f32_16x16x32_bf16 v[18:21], v[154:157], v[204:207], v[18:21]
	v_mfma_f32_16x16x32_bf16 v[6:9], v[146:149], v[212:215], v[6:9]
	v_mfma_f32_16x16x32_bf16 v[2:5], v[154:157], v[212:215], v[2:5]
	v_mfma_f32_16x16x32_bf16 v[54:57], v[150:153], v[178:181], v[54:57]
	v_mfma_f32_16x16x32_bf16 v[50:53], v[158:161], v[178:181], v[50:53]
	v_mfma_f32_16x16x32_bf16 v[38:41], v[150:153], v[196:199], v[38:41]
	v_mfma_f32_16x16x32_bf16 v[34:37], v[158:161], v[196:199], v[34:37]
	v_mfma_f32_16x16x32_bf16 v[22:25], v[150:153], v[208:211], v[22:25]
	v_mfma_f32_16x16x32_bf16 v[18:21], v[158:161], v[208:211], v[18:21]
	v_mfma_f32_16x16x32_bf16 v[6:9], v[150:153], v[216:219], v[6:9]
	v_mfma_f32_16x16x32_bf16 v[2:5], v[158:161], v[216:219], v[2:5]
	s_setprio 0
	s_barrier
	s_add_i32 s52, 0, 0x18000
	v_add_u32_e32 v0, s52, v201
	s_add_i32 s53, 0, 0x1c000
	ds_read_b128 v[130:133], v0
	ds_read_b128 v[134:137], v0 offset:1024
	ds_read_b128 v[138:141], v0 offset:2048
	ds_read_b128 v[142:145], v0 offset:3072
	v_add_u32_e32 v0, s53, v201
	ds_read_b128 v[146:149], v0
	ds_read_b128 v[150:153], v0 offset:1024
	ds_read_b128 v[154:157], v0 offset:2048
	ds_read_b128 v[158:161], v0 offset:3072
	s_add_u32 s38, s42, 0x10000
	s_addc_u32 s39, s43, 0
	s_mov_b32 m0, s45
	v_lshl_add_u64 v[246:247], s[38:39], 0, v[166:167]
	ds_read_b128 v[162:165], v202 offset:32768
	ds_read_b128 v[178:181], v202 offset:33792
	ds_read_b128 v[182:185], v202 offset:34816
	ds_read_b128 v[196:199], v202 offset:35840
	ds_read_b128 v[204:207], v202 offset:36864
	ds_read_b128 v[208:211], v202 offset:37888
	ds_read_b128 v[212:215], v202 offset:38912
	ds_read_b128 v[216:219], v202 offset:39936
	global_load_lds_dwordx4 v[246:247], off
	v_lshl_add_u64 v[246:247], s[38:39], 0, v[170:171]
	s_mov_b32 m0, s46
	s_nop 0
	global_load_lds_dwordx4 v[246:247], off
	s_waitcnt vmcnt(8)
	s_waitcnt lgkmcnt(0)
	s_barrier
	s_setprio 1
	s_waitcnt lgkmcnt(0)
	v_mfma_f32_16x16x32_bf16 v[126:129], v[130:133], v[162:165], v[126:129]
	v_mfma_f32_16x16x32_bf16 v[122:125], v[138:141], v[162:165], v[122:125]
	v_mfma_f32_16x16x32_bf16 v[110:113], v[130:133], v[182:185], v[110:113]
	v_mfma_f32_16x16x32_bf16 v[106:109], v[138:141], v[182:185], v[106:109]
	v_mfma_f32_16x16x32_bf16 v[94:97], v[130:133], v[204:207], v[94:97]
	v_mfma_f32_16x16x32_bf16 v[90:93], v[138:141], v[204:207], v[90:93]
	v_mfma_f32_16x16x32_bf16 v[78:81], v[130:133], v[212:215], v[78:81]
	v_mfma_f32_16x16x32_bf16 v[74:77], v[138:141], v[212:215], v[74:77]
	v_mfma_f32_16x16x32_bf16 v[126:129], v[134:137], v[178:181], v[126:129]
	v_mfma_f32_16x16x32_bf16 v[122:125], v[142:145], v[178:181], v[122:125]
	v_mfma_f32_16x16x32_bf16 v[110:113], v[134:137], v[196:199], v[110:113]
	v_mfma_f32_16x16x32_bf16 v[106:109], v[142:145], v[196:199], v[106:109]
	v_mfma_f32_16x16x32_bf16 v[94:97], v[134:137], v[208:211], v[94:97]
	v_mfma_f32_16x16x32_bf16 v[90:93], v[142:145], v[208:211], v[90:93]
	v_mfma_f32_16x16x32_bf16 v[78:81], v[134:137], v[216:219], v[78:81]
	v_mfma_f32_16x16x32_bf16 v[74:77], v[142:145], v[216:219], v[74:77]
	v_mfma_f32_16x16x32_bf16 v[118:121], v[146:149], v[162:165], v[118:121]
	v_mfma_f32_16x16x32_bf16 v[114:117], v[154:157], v[162:165], v[114:117]
	v_mfma_f32_16x16x32_bf16 v[102:105], v[146:149], v[182:185], v[102:105]
	v_mfma_f32_16x16x32_bf16 v[98:101], v[154:157], v[182:185], v[98:101]
	v_mfma_f32_16x16x32_bf16 v[86:89], v[146:149], v[204:207], v[86:89]
	v_mfma_f32_16x16x32_bf16 v[82:85], v[154:157], v[204:207], v[82:85]
	v_mfma_f32_16x16x32_bf16 v[70:73], v[146:149], v[212:215], v[70:73]
	v_mfma_f32_16x16x32_bf16 v[66:69], v[154:157], v[212:215], v[66:69]
	v_mfma_f32_16x16x32_bf16 v[118:121], v[150:153], v[178:181], v[118:121]
	v_mfma_f32_16x16x32_bf16 v[114:117], v[158:161], v[178:181], v[114:117]
	v_mfma_f32_16x16x32_bf16 v[102:105], v[150:153], v[196:199], v[102:105]
	v_mfma_f32_16x16x32_bf16 v[98:101], v[158:161], v[196:199], v[98:101]
	v_mfma_f32_16x16x32_bf16 v[86:89], v[150:153], v[208:211], v[86:89]
	v_mfma_f32_16x16x32_bf16 v[82:85], v[158:161], v[208:211], v[82:85]
	v_mfma_f32_16x16x32_bf16 v[70:73], v[150:153], v[216:219], v[70:73]
	v_mfma_f32_16x16x32_bf16 v[66:69], v[158:161], v[216:219], v[66:69]
	s_setprio 0
	s_barrier
; #define PG8_STAGE(bufoff, gbase, voff) do { _Pragma("unroll") for (int _i = 0; _i < 2; ++_i) \
;         __builtin_amdgcn_global_load_lds((const unsigned*)((const char*)(gbase) + (voff)[_i]), (LAS unsigned*)(lds + (bufoff) + ldsw + _i * 8192), 16, 0, 0); } while (0)
; #define PG8_LDA(dst, b, h) do { _Pragma("unroll") for (int m = 0; m < 4; ++m) _Pragma("unroll") for (int k = 0; k < 2; ++k) dst[m][k] = *(const LAS bf16x8*)(lds + PG8_SA(b, h) + aoff + m * 2048 + k * 1024); } while (0)
; #define PG8_MMA(ai, bj, At, Bt) do { __builtin_amdgcn_s_setprio(1); _Pragma("unroll") for (int m = 0; m < 4; ++m) _Pragma("unroll") for (int n = 0; n < 2; ++n) _Pragma("unroll") for (int k = 0; k < 2; ++k) \
;         acc[ai][bj][m][n] = __builtin_amdgcn_mfma_f32_16x16x32_bf16(Bt[n][k], At[m][k], acc[ai][bj][m][n], 0, 0, 0); __builtin_amdgcn_s_setprio(0); } while (0)
; #define PG8_WAIT_V(n) asm volatile("s_waitcnt vmcnt(" #n ")" ::: "memory")
; #define PG8_WAIT_L(n) asm volatile("s_waitcnt lgkmcnt(" #n ")" ::: "memory")
; #define PG8_BAR __builtin_amdgcn_s_barrier()
; #define PG8_SCHED __builtin_amdgcn_sched_barrier(0)
; template <class Epi, class Sched>
; __device__ __forceinline__ void gemm_phase(LAS unsigned char* lds, const Gemm g, const Sched& S, const Epi& E) {
;     ...
;             PG8_LDA(At, 1, 1); PG8_STAGE(PG8_SB(1, 0), b3, voffB); PG8_STAGE(PG8_SB(1, 1), b3 + hstepB, voffB); PG8_STAGE(PG8_SA(1, 0), a3, voffA);
;             PG8_WAIT_V(8); PG8_WAIT_L(0); PG8_BAR; PG8_MMA(1, 0, At, B0); PG8_MMA(1, 1, At, B1); PG8_BAR; PG8_SCHED;
;         }
	s_add_i32 s38, s52, s17
	v_lshl_add_u64 v[220:221], v[220:221], 0, s[26:27]
	s_mov_b32 m0, s38
	ds_read_b128 v[162:165], v202 offset:49152
	ds_read_b128 v[178:181], v202 offset:50176
	ds_read_b128 v[182:185], v202 offset:51200
	ds_read_b128 v[196:199], v202 offset:52224
	ds_read_b128 v[204:207], v202 offset:53248
	ds_read_b128 v[208:211], v202 offset:54272
	ds_read_b128 v[212:215], v202 offset:55296
	ds_read_b128 v[216:219], v202 offset:56320
	global_load_lds_dwordx4 v[220:221], off
	s_add_i32 m0, s38, 0x2000
	s_add_u32 s0, s0, 0x50080
	v_lshl_add_u64 v[220:221], v[232:233], 0, s[26:27]
	s_addc_u32 s1, s1, 0
	s_add_i32 s38, s53, s17
	global_load_lds_dwordx4 v[220:221], off
	v_lshl_add_u64 v[220:221], s[0:1], 0, v[168:169]
	s_mov_b32 m0, s38
	s_nop 0
	global_load_lds_dwordx4 v[220:221], off
	v_lshl_add_u64 v[220:221], s[0:1], 0, v[172:173]
	s_add_i32 m0, s38, 0x2000
	s_nop 0
	global_load_lds_dwordx4 v[220:221], off
	v_lshl_add_u64 v[220:221], v[234:235], 0, s[26:27]
	s_mov_b32 m0, s67
	s_nop 0
	global_load_lds_dwordx4 v[220:221], off
	v_lshl_add_u64 v[220:221], v[236:237], 0, s[26:27]
	s_mov_b32 m0, s69
	s_nop 0
	global_load_lds_dwordx4 v[220:221], off
	s_waitcnt vmcnt(8)
	s_waitcnt lgkmcnt(0)
	s_barrier
	s_setprio 1
	s_waitcnt lgkmcnt(0)
	v_mfma_f32_16x16x32_bf16 v[62:65], v[130:133], v[162:165], v[62:65]
	v_mfma_f32_16x16x32_bf16 v[58:61], v[138:141], v[162:165], v[58:61]
	v_mfma_f32_16x16x32_bf16 v[46:49], v[130:133], v[182:185], v[46:49]
	v_mfma_f32_16x16x32_bf16 v[42:45], v[138:141], v[182:185], v[42:45]
	v_mfma_f32_16x16x32_bf16 v[30:33], v[130:133], v[204:207], v[30:33]
	v_mfma_f32_16x16x32_bf16 v[26:29], v[138:141], v[204:207], v[26:29]
	v_mfma_f32_16x16x32_bf16 v[14:17], v[130:133], v[212:215], v[14:17]
	v_mfma_f32_16x16x32_bf16 v[10:13], v[138:141], v[212:215], v[10:13]
	v_mfma_f32_16x16x32_bf16 v[62:65], v[134:137], v[178:181], v[62:65]
	v_mfma_f32_16x16x32_bf16 v[58:61], v[142:145], v[178:181], v[58:61]
	v_mfma_f32_16x16x32_bf16 v[46:49], v[134:137], v[196:199], v[46:49]
	v_mfma_f32_16x16x32_bf16 v[42:45], v[142:145], v[196:199], v[42:45]
	v_mfma_f32_16x16x32_bf16 v[30:33], v[134:137], v[208:211], v[30:33]
	v_mfma_f32_16x16x32_bf16 v[26:29], v[142:145], v[208:211], v[26:29]
	v_mfma_f32_16x16x32_bf16 v[14:17], v[134:137], v[216:219], v[14:17]
	v_mfma_f32_16x16x32_bf16 v[10:13], v[142:145], v[216:219], v[10:13]
	v_mfma_f32_16x16x32_bf16 v[54:57], v[146:149], v[162:165], v[54:57]
	v_mfma_f32_16x16x32_bf16 v[50:53], v[154:157], v[162:165], v[50:53]
	v_mfma_f32_16x16x32_bf16 v[38:41], v[146:149], v[182:185], v[38:41]
	v_mfma_f32_16x16x32_bf16 v[34:37], v[154:157], v[182:185], v[34:37]
	v_mfma_f32_16x16x32_bf16 v[22:25], v[146:149], v[204:207], v[22:25]
	v_mfma_f32_16x16x32_bf16 v[18:21], v[154:157], v[204:207], v[18:21]
	v_mfma_f32_16x16x32_bf16 v[6:9], v[146:149], v[212:215], v[6:9]
	v_mfma_f32_16x16x32_bf16 v[2:5], v[154:157], v[212:215], v[2:5]
	v_mfma_f32_16x16x32_bf16 v[54:57], v[150:153], v[178:181], v[54:57]
	v_mfma_f32_16x16x32_bf16 v[50:53], v[158:161], v[178:181], v[50:53]
	v_mfma_f32_16x16x32_bf16 v[38:41], v[150:153], v[196:199], v[38:41]
	v_mfma_f32_16x16x32_bf16 v[34:37], v[158:161], v[196:199], v[34:37]
	v_mfma_f32_16x16x32_bf16 v[22:25], v[150:153], v[208:211], v[22:25]
	v_mfma_f32_16x16x32_bf16 v[18:21], v[158:161], v[208:211], v[18:21]
	v_mfma_f32_16x16x32_bf16 v[6:9], v[150:153], v[216:219], v[6:9]
	v_mfma_f32_16x16x32_bf16 v[2:5], v[158:161], v[216:219], v[2:5]
	s_setprio 0
	s_barrier
	s_add_u32 s97, s97, 0x100
	s_addc_u32 vcc_lo, vcc_lo, 0
	s_add_u32 s20, s20, 0x100
	s_addc_u32 s21, s21, 0
	s_cmp_ge_i32 s62, s47
	s_mov_b32 s0, s62
	s_cbranch_scc0 .LBB0_526

; #define PG8_STAGE(bufoff, gbase, voff) do { _Pragma("unroll") for (int _i = 0; _i < 2; ++_i) \
;         __builtin_amdgcn_global_load_lds((const unsigned*)((const char*)(gbase) + (voff)[_i]), (LAS unsigned*)(lds + (bufoff) + ldsw + _i * 8192), 16, 0, 0); } while (0)
; #define PG8_LDA(dst, b, h) do { _Pragma("unroll") for (int m = 0; m < 4; ++m) _Pragma("unroll") for (int k = 0; k < 2; ++k) dst[m][k] = *(const LAS bf16x8*)(lds + PG8_SA(b, h) + aoff + m * 2048 + k * 1024); } while (0)
; #define PG8_LDB(dst, b, h) do { _Pragma("unroll") for (int n = 0; n < 2; ++n) _Pragma("unroll") for (int k = 0; k < 2; ++k) dst[n][k] = *(const LAS bf16x8*)(lds + PG8_SB(b, h) + boff + n * 2048 + k * 1024); } while (0)
; #define PG8_MMA(ai, bj, At, Bt) do { __builtin_amdgcn_s_setprio(1); _Pragma("unroll") for (int m = 0; m < 4; ++m) _Pragma("unroll") for (int n = 0; n < 2; ++n) _Pragma("unroll") for (int k = 0; k < 2; ++k) \
;         acc[ai][bj][m][n] = __builtin_amdgcn_mfma_f32_16x16x32_bf16(Bt[n][k], At[m][k], acc[ai][bj][m][n], 0, 0, 0); __builtin_amdgcn_s_setprio(0); } while (0)
; #define PG8_WAIT_V(n) asm volatile("s_waitcnt vmcnt(" #n ")" ::: "memory")
; #define PG8_WAIT_L(n) asm volatile("s_waitcnt lgkmcnt(" #n ")" ::: "memory")
; #define PG8_BAR __builtin_amdgcn_s_barrier()
; #define PG8_SCHED __builtin_amdgcn_sched_barrier(0)
; template <class Epi, class Sched>
; __device__ __forceinline__ void gemm_phase(LAS unsigned char* lds, const Gemm g, const Sched& S, const Epi& E) {
;     ...
;             const bool last = (t == nt - 2);
;             const char* a1 = cA + (size_t)(t + 1) * kstep;
;             const char* a2 = last ? nA : cA + (size_t)(t + 2) * kstep; const char* b2 = last ? nB : cB + (size_t)(t + 2) * kstep;
;             const char* a3 = a2 + kstep; const char* b3 = b2 + kstep;
;             PG8_LDB(B0, 0, 0); PG8_LDB(B1, 0, 1); PG8_SCHED; PG8_LDA(At, 0, 0); PG8_STAGE(PG8_SA(1, 1), a1 + hstepA, voffA);
;             PG8_WAIT_V(8); PG8_WAIT_L(0); PG8_BAR; PG8_MMA(0, 0, At, B0); PG8_MMA(0, 1, At, B1); PG8_BAR; PG8_SCHED;
;             PG8_LDA(At, 0, 1); PG8_STAGE(PG8_SB(0, 0), b2, voffB); PG8_STAGE(PG8_SB(0, 1), b2 + hstepB, voffB); PG8_STAGE(PG8_SA(0, 0), a2, voffA);
;             PG8_WAIT_V(8); PG8_WAIT_L(0); PG8_BAR; PG8_MMA(1, 0, At, B0); PG8_MMA(1, 1, At, B1); PG8_BAR; PG8_SCHED;
.LBB0_551:
	s_add_i32 s62, s0, 2
	s_add_u32 s1, s20, 0xffff0080
	s_addc_u32 s42, s21, -1
	s_add_i32 s43, 0, 0x10000
	s_cmp_eq_u32 s71, s0
	s_cselect_b32 vcc_hi, s19, s42
	s_cselect_b32 vcc_lo, s25, s1
	s_cselect_b32 s1, s41, s72
	s_cselect_b32 s0, s67, s69
	s_add_i32 s52, 0, 0x14000
	v_add_u32_e32 v38, s43, v251
	v_add_u32_e32 v70, s52, v251
	ds_read_b128 v[26:29], v38
	ds_read_b128 v[30:33], v38 offset:1024
	ds_read_b128 v[34:37], v38 offset:2048
	ds_read_b128 v[38:41], v38 offset:3072
	ds_read_b128 v[50:53], v70
	ds_read_b128 v[54:57], v70 offset:1024
	ds_read_b128 v[58:61], v70 offset:2048
	ds_read_b128 v[70:73], v70 offset:3072
	v_lshl_add_u64 v[214:215], s[20:21], 0, v[204:205]
	s_add_i32 m0, s46, 0xc000
	ds_read_b128 v[90:93], v252
	ds_read_b128 v[110:113], v252 offset:1024
	ds_read_b128 v[126:129], v252 offset:2048
	ds_read_b128 v[142:145], v252 offset:3072
	ds_read_b128 v[162:165], v252 offset:4096
	ds_read_b128 v[182:185], v252 offset:5120
	ds_read_b128 v[206:209], v252 offset:6144
	ds_read_b128 v[210:213], v252 offset:7168
	global_load_lds_dwordx4 v[214:215], off
	v_lshl_add_u64 v[214:215], s[20:21], 0, v[202:203]
	s_add_i32 m0, s46, 0xe000
	s_nop 0
	global_load_lds_dwordx4 v[214:215], off
	s_waitcnt vmcnt(8)
	s_waitcnt lgkmcnt(0)
	s_barrier
	s_setprio 1
	s_waitcnt lgkmcnt(0)
	v_mfma_f32_16x16x32_bf16 v[178:181], v[26:29], v[90:93], v[178:181]
	v_mfma_f32_16x16x32_bf16 v[170:173], v[34:37], v[90:93], v[170:173]
	v_mfma_f32_16x16x32_bf16 v[158:161], v[26:29], v[126:129], v[158:161]
	v_mfma_f32_16x16x32_bf16 v[150:153], v[34:37], v[126:129], v[150:153]
	v_mfma_f32_16x16x32_bf16 v[138:141], v[26:29], v[162:165], v[138:141]
	v_mfma_f32_16x16x32_bf16 v[130:133], v[34:37], v[162:165], v[130:133]
	v_mfma_f32_16x16x32_bf16 v[118:121], v[26:29], v[206:209], v[118:121]
	v_mfma_f32_16x16x32_bf16 v[106:109], v[34:37], v[206:209], v[106:109]
	v_mfma_f32_16x16x32_bf16 v[178:181], v[30:33], v[110:113], v[178:181]
	v_mfma_f32_16x16x32_bf16 v[170:173], v[38:41], v[110:113], v[170:173]
	v_mfma_f32_16x16x32_bf16 v[158:161], v[30:33], v[142:145], v[158:161]
	v_mfma_f32_16x16x32_bf16 v[150:153], v[38:41], v[142:145], v[150:153]
	v_mfma_f32_16x16x32_bf16 v[138:141], v[30:33], v[182:185], v[138:141]
	v_mfma_f32_16x16x32_bf16 v[130:133], v[38:41], v[182:185], v[130:133]
	v_mfma_f32_16x16x32_bf16 v[118:121], v[30:33], v[210:213], v[118:121]
	v_mfma_f32_16x16x32_bf16 v[106:109], v[38:41], v[210:213], v[106:109]
	v_mfma_f32_16x16x32_bf16 v[174:177], v[50:53], v[90:93], v[174:177]
	v_mfma_f32_16x16x32_bf16 v[90:93], v[58:61], v[90:93], v[166:169]
	v_mfma_f32_16x16x32_bf16 v[134:137], v[50:53], v[162:165], v[134:137]
	v_mfma_f32_16x16x32_bf16 v[122:125], v[58:61], v[162:165], v[122:125]
	v_mfma_f32_16x16x32_bf16 v[114:117], v[50:53], v[206:209], v[114:117]
	v_mfma_f32_16x16x32_bf16 v[102:105], v[58:61], v[206:209], v[102:105]
	v_mfma_f32_16x16x32_bf16 v[174:177], v[54:57], v[110:113], v[174:177]
	v_mfma_f32_16x16x32_bf16 v[90:93], v[70:73], v[110:113], v[90:93]
	v_mfma_f32_16x16x32_bf16 v[110:113], v[50:53], v[126:129], v[154:157]
	v_mfma_f32_16x16x32_bf16 v[126:129], v[58:61], v[126:129], v[146:149]
	v_mfma_f32_16x16x32_bf16 v[134:137], v[54:57], v[182:185], v[134:137]
	v_mfma_f32_16x16x32_bf16 v[122:125], v[70:73], v[182:185], v[122:125]
	v_mfma_f32_16x16x32_bf16 v[114:117], v[54:57], v[210:213], v[114:117]
	v_mfma_f32_16x16x32_bf16 v[102:105], v[70:73], v[210:213], v[102:105]
	v_mfma_f32_16x16x32_bf16 v[110:113], v[54:57], v[142:145], v[110:113]
	v_mfma_f32_16x16x32_bf16 v[126:129], v[70:73], v[142:145], v[126:129]
	s_setprio 0
	s_barrier
	s_add_i32 s42, s43, s45
	v_lshl_add_u64 v[232:233], s[0:1], 0, v[0:1]
	s_mov_b32 m0, s42
	ds_read_b128 v[142:145], v252 offset:16384
	ds_read_b128 v[146:149], v252 offset:17408
	ds_read_b128 v[154:157], v252 offset:18432
	ds_read_b128 v[162:165], v252 offset:19456
	ds_read_b128 v[166:169], v252 offset:20480
	ds_read_b128 v[182:185], v252 offset:21504
	ds_read_b128 v[206:209], v252 offset:22528
	ds_read_b128 v[210:213], v252 offset:23552
	global_load_lds_dwordx4 v[232:233], off
	s_add_i32 m0, s42, 0x2000
	s_add_u32 s42, s0, 0x10000
	v_lshl_add_u64 v[234:235], s[0:1], 0, v[200:201]
	s_addc_u32 s43, s1, 0
	s_add_i32 s52, s52, s45
	global_load_lds_dwordx4 v[234:235], off
	v_lshl_add_u64 v[214:215], s[42:43], 0, v[0:1]
	s_mov_b32 m0, s52
	v_lshl_add_u64 v[236:237], vcc, 0, v[196:197]
	global_load_lds_dwordx4 v[214:215], off
	v_lshl_add_u64 v[214:215], s[42:43], 0, v[200:201]
	s_add_i32 m0, s52, 0x2000
	v_lshl_add_u64 v[246:247], vcc, 0, v[198:199]
	global_load_lds_dwordx4 v[214:215], off
	s_mov_b32 m0, s46
	s_nop 0
	global_load_lds_dwordx4 v[236:237], off
	s_mov_b32 m0, s47
	s_nop 0
	global_load_lds_dwordx4 v[246:247], off
	s_waitcnt vmcnt(8)
	s_waitcnt lgkmcnt(0)
	s_barrier
; #define PG8_STAGE(bufoff, gbase, voff) do { _Pragma("unroll") for (int _i = 0; _i < 2; ++_i) \
;         __builtin_amdgcn_global_load_lds((const unsigned*)((const char*)(gbase) + (voff)[_i]), (LAS unsigned*)(lds + (bufoff) + ldsw + _i * 8192), 16, 0, 0); } while (0)
; #define PG8_LDA(dst, b, h) do { _Pragma("unroll") for (int m = 0; m < 4; ++m) _Pragma("unroll") for (int k = 0; k < 2; ++k) dst[m][k] = *(const LAS bf16x8*)(lds + PG8_SA(b, h) + aoff + m * 2048 + k * 1024); } while (0)
; #define PG8_LDB(dst, b, h) do { _Pragma("unroll") for (int n = 0; n < 2; ++n) _Pragma("unroll") for (int k = 0; k < 2; ++k) dst[n][k] = *(const LAS bf16x8*)(lds + PG8_SB(b, h) + boff + n * 2048 + k * 1024); } while (0)
; #define PG8_MMA(ai, bj, At, Bt) do { __builtin_amdgcn_s_setprio(1); _Pragma("unroll") for (int m = 0; m < 4; ++m) _Pragma("unroll") for (int n = 0; n < 2; ++n) _Pragma("unroll") for (int k = 0; k < 2; ++k) \
;         acc[ai][bj][m][n] = __builtin_amdgcn_mfma_f32_16x16x32_bf16(Bt[n][k], At[m][k], acc[ai][bj][m][n], 0, 0, 0); __builtin_amdgcn_s_setprio(0); } while (0)
; #define PG8_WAIT_V(n) asm volatile("s_waitcnt vmcnt(" #n ")" ::: "memory")
; #define PG8_WAIT_L(n) asm volatile("s_waitcnt lgkmcnt(" #n ")" ::: "memory")
; #define PG8_BAR __builtin_amdgcn_s_barrier()
; #define PG8_SCHED __builtin_amdgcn_sched_barrier(0)
; template <class Epi, class Sched>
; __device__ __forceinline__ void gemm_phase(LAS unsigned char* lds, const Gemm g, const Sched& S, const Epi& E) {
;     ...
;             PG8_WAIT_V(8); PG8_WAIT_L(0); PG8_BAR; PG8_MMA(1, 0, At, B0); PG8_MMA(1, 1, At, B1); PG8_BAR; PG8_SCHED;
;             PG8_LDB(B0, 1, 0); PG8_LDB(B1, 1, 1); PG8_SCHED; PG8_LDA(At, 1, 0); PG8_STAGE(PG8_SA(0, 1), a2 + hstepA, voffA);
;             PG8_WAIT_V(8); PG8_WAIT_L(0); PG8_BAR; PG8_MMA(0, 0, At, B0); PG8_MMA(0, 1, At, B1); PG8_BAR; PG8_SCHED;
	s_setprio 1
	s_waitcnt lgkmcnt(0)
	v_mfma_f32_16x16x32_bf16 v[98:101], v[26:29], v[142:145], v[98:101]
	v_mfma_f32_16x16x32_bf16 v[86:89], v[34:37], v[142:145], v[86:89]
	v_mfma_f32_16x16x32_bf16 v[78:81], v[26:29], v[154:157], v[78:81]
	v_mfma_f32_16x16x32_bf16 v[66:69], v[34:37], v[154:157], v[66:69]
	v_mfma_f32_16x16x32_bf16 v[46:49], v[26:29], v[166:169], v[46:49]
	v_mfma_f32_16x16x32_bf16 v[22:25], v[34:37], v[166:169], v[22:25]
	v_mfma_f32_16x16x32_bf16 v[14:17], v[26:29], v[206:209], v[14:17]
	v_mfma_f32_16x16x32_bf16 v[6:9], v[34:37], v[206:209], v[6:9]
	v_mfma_f32_16x16x32_bf16 v[98:101], v[30:33], v[146:149], v[98:101]
	v_mfma_f32_16x16x32_bf16 v[86:89], v[38:41], v[146:149], v[86:89]
	v_mfma_f32_16x16x32_bf16 v[78:81], v[30:33], v[162:165], v[78:81]
	v_mfma_f32_16x16x32_bf16 v[66:69], v[38:41], v[162:165], v[66:69]
	v_mfma_f32_16x16x32_bf16 v[46:49], v[30:33], v[182:185], v[46:49]
	v_mfma_f32_16x16x32_bf16 v[22:25], v[38:41], v[182:185], v[22:25]
	v_mfma_f32_16x16x32_bf16 v[14:17], v[30:33], v[210:213], v[14:17]
	v_mfma_f32_16x16x32_bf16 v[6:9], v[38:41], v[210:213], v[6:9]
	v_mfma_f32_16x16x32_bf16 v[42:45], v[50:53], v[166:169], v[42:45]
	v_mfma_f32_16x16x32_bf16 v[18:21], v[58:61], v[166:169], v[18:21]
	v_mfma_f32_16x16x32_bf16 v[10:13], v[50:53], v[206:209], v[10:13]
	v_mfma_f32_16x16x32_bf16 v[2:5], v[58:61], v[206:209], v[2:5]
	v_mfma_f32_16x16x32_bf16 v[26:29], v[50:53], v[142:145], v[94:97]
	v_mfma_f32_16x16x32_bf16 v[30:33], v[58:61], v[142:145], v[82:85]
	v_mfma_f32_16x16x32_bf16 v[34:37], v[50:53], v[154:157], v[74:77]
	v_mfma_f32_16x16x32_bf16 v[38:41], v[58:61], v[154:157], v[62:65]
	v_mfma_f32_16x16x32_bf16 v[42:45], v[54:57], v[182:185], v[42:45]
	v_mfma_f32_16x16x32_bf16 v[18:21], v[70:73], v[182:185], v[18:21]
	v_mfma_f32_16x16x32_bf16 v[10:13], v[54:57], v[210:213], v[10:13]
	v_mfma_f32_16x16x32_bf16 v[2:5], v[70:73], v[210:213], v[2:5]
	v_mfma_f32_16x16x32_bf16 v[26:29], v[54:57], v[146:149], v[26:29]
	v_mfma_f32_16x16x32_bf16 v[30:33], v[70:73], v[146:149], v[30:33]
	v_mfma_f32_16x16x32_bf16 v[34:37], v[54:57], v[162:165], v[34:37]
	v_mfma_f32_16x16x32_bf16 v[38:41], v[70:73], v[162:165], v[38:41]
	s_setprio 0
	s_barrier
	s_add_i32 s52, 0, 0x18000
	s_add_i32 s53, 0, 0x1c000
	v_add_u32_e32 v62, s52, v251
	v_add_u32_e32 v74, s53, v251
	ds_read_b128 v[50:53], v62
	ds_read_b128 v[54:57], v62 offset:1024
	ds_read_b128 v[58:61], v62 offset:2048
	ds_read_b128 v[62:65], v62 offset:3072
	ds_read_b128 v[70:73], v74
	ds_read_b128 v[142:145], v74 offset:1024
	ds_read_b128 v[162:165], v74 offset:2048
	ds_read_b128 v[182:185], v74 offset:3072
	s_add_u32 s42, vcc_lo, 0x10000
	s_addc_u32 s43, vcc_hi, 0
	s_mov_b32 m0, s48
	v_lshl_add_u64 v[154:155], s[42:43], 0, v[196:197]
	ds_read_b128 v[74:77], v252 offset:32768
	ds_read_b128 v[82:85], v252 offset:33792
	ds_read_b128 v[94:97], v252 offset:34816
	ds_read_b128 v[146:149], v252 offset:35840
	ds_read_b128 v[206:209], v252 offset:36864
	ds_read_b128 v[210:213], v252 offset:37888
	ds_read_b128 v[214:217], v252 offset:38912
	ds_read_b128 v[218:221], v252 offset:39936
	global_load_lds_dwordx4 v[154:155], off
	v_lshl_add_u64 v[154:155], s[42:43], 0, v[198:199]
	s_mov_b32 m0, s65
	s_nop 0
	global_load_lds_dwordx4 v[154:155], off
	s_waitcnt vmcnt(8)
	s_waitcnt lgkmcnt(0)
	s_barrier
	s_setprio 1
	s_waitcnt lgkmcnt(0)
	v_mfma_f32_16x16x32_bf16 v[154:157], v[50:53], v[74:77], v[178:181]
	v_mfma_f32_16x16x32_bf16 v[178:181], v[54:57], v[82:85], v[154:157]
	v_mfma_f32_16x16x32_bf16 v[154:157], v[58:61], v[74:77], v[170:173]
	v_mfma_f32_16x16x32_bf16 v[170:173], v[62:65], v[82:85], v[154:157]
	v_mfma_f32_16x16x32_bf16 v[154:157], v[50:53], v[94:97], v[158:161]
	v_mfma_f32_16x16x32_bf16 v[150:153], v[58:61], v[94:97], v[150:153]
	v_mfma_f32_16x16x32_bf16 v[138:141], v[50:53], v[206:209], v[138:141]
	v_mfma_f32_16x16x32_bf16 v[130:133], v[58:61], v[206:209], v[130:133]
	v_mfma_f32_16x16x32_bf16 v[118:121], v[50:53], v[214:217], v[118:121]
	v_mfma_f32_16x16x32_bf16 v[106:109], v[58:61], v[214:217], v[106:109]
	v_mfma_f32_16x16x32_bf16 v[158:161], v[54:57], v[146:149], v[154:157]
	v_mfma_f32_16x16x32_bf16 v[150:153], v[62:65], v[146:149], v[150:153]
	v_mfma_f32_16x16x32_bf16 v[138:141], v[54:57], v[210:213], v[138:141]
	v_mfma_f32_16x16x32_bf16 v[130:133], v[62:65], v[210:213], v[130:133]
	v_mfma_f32_16x16x32_bf16 v[118:121], v[54:57], v[218:221], v[118:121]
	v_mfma_f32_16x16x32_bf16 v[106:109], v[62:65], v[218:221], v[106:109]
	v_mfma_f32_16x16x32_bf16 v[154:157], v[70:73], v[74:77], v[174:177]
	v_mfma_f32_16x16x32_bf16 v[74:77], v[162:165], v[74:77], v[90:93]
	v_mfma_f32_16x16x32_bf16 v[166:169], v[182:185], v[82:85], v[74:77]
	v_mfma_f32_16x16x32_bf16 v[74:77], v[70:73], v[94:97], v[110:113]
	v_mfma_f32_16x16x32_bf16 v[174:177], v[142:145], v[82:85], v[154:157]
	v_mfma_f32_16x16x32_bf16 v[154:157], v[142:145], v[146:149], v[74:77]
	v_mfma_f32_16x16x32_bf16 v[74:77], v[162:165], v[94:97], v[126:129]
	v_mfma_f32_16x16x32_bf16 v[146:149], v[182:185], v[146:149], v[74:77]
	v_mfma_f32_16x16x32_bf16 v[74:77], v[70:73], v[206:209], v[134:137]
	v_mfma_f32_16x16x32_bf16 v[134:137], v[142:145], v[210:213], v[74:77]
	v_mfma_f32_16x16x32_bf16 v[74:77], v[162:165], v[206:209], v[122:125]
	v_mfma_f32_16x16x32_bf16 v[122:125], v[182:185], v[210:213], v[74:77]
	v_mfma_f32_16x16x32_bf16 v[74:77], v[70:73], v[214:217], v[114:117]
	v_mfma_f32_16x16x32_bf16 v[114:117], v[142:145], v[218:221], v[74:77]
	v_mfma_f32_16x16x32_bf16 v[74:77], v[162:165], v[214:217], v[102:105]
	v_mfma_f32_16x16x32_bf16 v[102:105], v[182:185], v[218:221], v[74:77]
	s_setprio 0
	s_barrier
; #define PG8_STAGE(bufoff, gbase, voff) do { _Pragma("unroll") for (int _i = 0; _i < 2; ++_i) \
;         __builtin_amdgcn_global_load_lds((const unsigned*)((const char*)(gbase) + (voff)[_i]), (LAS unsigned*)(lds + (bufoff) + ldsw + _i * 8192), 16, 0, 0); } while (0)
; #define PG8_LDA(dst, b, h) do { _Pragma("unroll") for (int m = 0; m < 4; ++m) _Pragma("unroll") for (int k = 0; k < 2; ++k) dst[m][k] = *(const LAS bf16x8*)(lds + PG8_SA(b, h) + aoff + m * 2048 + k * 1024); } while (0)
; #define PG8_MMA(ai, bj, At, Bt) do { __builtin_amdgcn_s_setprio(1); _Pragma("unroll") for (int m = 0; m < 4; ++m) _Pragma("unroll") for (int n = 0; n < 2; ++n) _Pragma("unroll") for (int k = 0; k < 2; ++k) \
;         acc[ai][bj][m][n] = __builtin_amdgcn_mfma_f32_16x16x32_bf16(Bt[n][k], At[m][k], acc[ai][bj][m][n], 0, 0, 0); __builtin_amdgcn_s_setprio(0); } while (0)
; #define PG8_WAIT_V(n) asm volatile("s_waitcnt vmcnt(" #n ")" ::: "memory")
; #define PG8_WAIT_L(n) asm volatile("s_waitcnt lgkmcnt(" #n ")" ::: "memory")
; #define PG8_BAR __builtin_amdgcn_s_barrier()
; #define PG8_SCHED __builtin_amdgcn_sched_barrier(0)
; template <class Epi, class Sched>
; __device__ __forceinline__ void gemm_phase(LAS unsigned char* lds, const Gemm g, const Sched& S, const Epi& E) {
;     ...
;             PG8_LDA(At, 1, 1); PG8_STAGE(PG8_SB(1, 0), b3, voffB); PG8_STAGE(PG8_SB(1, 1), b3 + hstepB, voffB); PG8_STAGE(PG8_SA(1, 0), a3, voffA);
;             PG8_WAIT_V(8); PG8_WAIT_L(0); PG8_BAR; PG8_MMA(1, 0, At, B0); PG8_MMA(1, 1, At, B1); PG8_BAR; PG8_SCHED;
;         }
	s_add_i32 s42, s52, s45
	v_lshl_add_u64 v[94:95], v[232:233], 0, s[26:27]
	s_mov_b32 m0, s42
	s_nop 1
	ds_read_b128 v[74:77], v252 offset:49152
	ds_read_b128 v[82:85], v252 offset:50176
	ds_read_b128 v[90:93], v252 offset:51200
	ds_read_b128 v[110:113], v252 offset:52224
	ds_read_b128 v[126:129], v252 offset:53248
	ds_read_b128 v[206:209], v252 offset:54272
	ds_read_b128 v[210:213], v252 offset:55296
	ds_read_b128 v[214:217], v252 offset:56320
	global_load_lds_dwordx4 v[94:95], off
	s_add_i32 m0, s42, 0x2000
	s_add_u32 s0, s0, 0x10080
	v_lshl_add_u64 v[94:95], v[234:235], 0, s[26:27]
	s_addc_u32 s1, s1, 0
	s_add_i32 s42, s53, s45
	global_load_lds_dwordx4 v[94:95], off
	v_lshl_add_u64 v[94:95], s[0:1], 0, v[0:1]
	s_mov_b32 m0, s42
	s_nop 0
	global_load_lds_dwordx4 v[94:95], off
	v_lshl_add_u64 v[94:95], s[0:1], 0, v[200:201]
	s_add_i32 m0, s42, 0x2000
	s_nop 0
	global_load_lds_dwordx4 v[94:95], off
	v_lshl_add_u64 v[94:95], v[236:237], 0, s[26:27]
	s_mov_b32 m0, s96
	s_nop 0
	global_load_lds_dwordx4 v[94:95], off
	v_lshl_add_u64 v[94:95], v[246:247], 0, s[26:27]
	s_mov_b32 m0, s97
	s_nop 0
	global_load_lds_dwordx4 v[94:95], off
	s_waitcnt vmcnt(8)
	s_waitcnt lgkmcnt(0)
	s_barrier
	s_setprio 1
	s_waitcnt lgkmcnt(0)
	v_mfma_f32_16x16x32_bf16 v[94:97], v[50:53], v[74:77], v[98:101]
	v_mfma_f32_16x16x32_bf16 v[86:89], v[58:61], v[74:77], v[86:89]
	v_mfma_f32_16x16x32_bf16 v[78:81], v[50:53], v[90:93], v[78:81]
	v_mfma_f32_16x16x32_bf16 v[66:69], v[58:61], v[90:93], v[66:69]
	v_mfma_f32_16x16x32_bf16 v[46:49], v[50:53], v[126:129], v[46:49]
	v_mfma_f32_16x16x32_bf16 v[22:25], v[58:61], v[126:129], v[22:25]
	v_mfma_f32_16x16x32_bf16 v[14:17], v[50:53], v[210:213], v[14:17]
	v_mfma_f32_16x16x32_bf16 v[6:9], v[58:61], v[210:213], v[6:9]
	v_mfma_f32_16x16x32_bf16 v[98:101], v[54:57], v[82:85], v[94:97]
	v_mfma_f32_16x16x32_bf16 v[86:89], v[62:65], v[82:85], v[86:89]
	v_mfma_f32_16x16x32_bf16 v[78:81], v[54:57], v[110:113], v[78:81]
	v_mfma_f32_16x16x32_bf16 v[66:69], v[62:65], v[110:113], v[66:69]
	v_mfma_f32_16x16x32_bf16 v[46:49], v[54:57], v[206:209], v[46:49]
	v_mfma_f32_16x16x32_bf16 v[22:25], v[62:65], v[206:209], v[22:25]
	v_mfma_f32_16x16x32_bf16 v[14:17], v[54:57], v[214:217], v[14:17]
	v_mfma_f32_16x16x32_bf16 v[6:9], v[62:65], v[214:217], v[6:9]
	v_mfma_f32_16x16x32_bf16 v[26:29], v[70:73], v[74:77], v[26:29]
	v_mfma_f32_16x16x32_bf16 v[94:97], v[142:145], v[82:85], v[26:29]
	v_mfma_f32_16x16x32_bf16 v[26:29], v[162:165], v[74:77], v[30:33]
	v_mfma_f32_16x16x32_bf16 v[82:85], v[182:185], v[82:85], v[26:29]
	v_mfma_f32_16x16x32_bf16 v[26:29], v[70:73], v[90:93], v[34:37]
	v_mfma_f32_16x16x32_bf16 v[74:77], v[142:145], v[110:113], v[26:29]
	v_mfma_f32_16x16x32_bf16 v[26:29], v[162:165], v[90:93], v[38:41]
	v_mfma_f32_16x16x32_bf16 v[62:65], v[182:185], v[110:113], v[26:29]
	v_mfma_f32_16x16x32_bf16 v[26:29], v[70:73], v[126:129], v[42:45]
	v_mfma_f32_16x16x32_bf16 v[18:21], v[162:165], v[126:129], v[18:21]
	v_mfma_f32_16x16x32_bf16 v[10:13], v[70:73], v[210:213], v[10:13]
	v_mfma_f32_16x16x32_bf16 v[2:5], v[162:165], v[210:213], v[2:5]
	v_mfma_f32_16x16x32_bf16 v[42:45], v[142:145], v[206:209], v[26:29]
	v_mfma_f32_16x16x32_bf16 v[18:21], v[182:185], v[206:209], v[18:21]
	v_mfma_f32_16x16x32_bf16 v[10:13], v[142:145], v[214:217], v[10:13]
	v_mfma_f32_16x16x32_bf16 v[2:5], v[182:185], v[214:217], v[2:5]
	s_setprio 0
	s_barrier
	s_add_u32 s69, s69, 0x100
	s_addc_u32 s72, s72, 0
	s_add_u32 s20, s20, 0x100
	s_addc_u32 s21, s21, 0
	s_cmp_ge_i32 s62, s14
	s_mov_b32 s0, s62
	s_cbranch_scc0 .LBB0_551

; #define PG8_STAGE(bufoff, gbase, voff) do { _Pragma("unroll") for (int _i = 0; _i < 2; ++_i) \
;         __builtin_amdgcn_global_load_lds((const unsigned*)((const char*)(gbase) + (voff)[_i]), (LAS unsigned*)(lds + (bufoff) + ldsw + _i * 8192), 16, 0, 0); } while (0)
; #define PG8_LDA(dst, b, h) do { _Pragma("unroll") for (int m = 0; m < 4; ++m) _Pragma("unroll") for (int k = 0; k < 2; ++k) dst[m][k] = *(const LAS bf16x8*)(lds + PG8_SA(b, h) + aoff + m * 2048 + k * 1024); } while (0)
; #define PG8_LDB(dst, b, h) do { _Pragma("unroll") for (int n = 0; n < 2; ++n) _Pragma("unroll") for (int k = 0; k < 2; ++k) dst[n][k] = *(const LAS bf16x8*)(lds + PG8_SB(b, h) + boff + n * 2048 + k * 1024); } while (0)
; #define PG8_MMA(ai, bj, At, Bt) do { __builtin_amdgcn_s_setprio(1); _Pragma("unroll") for (int m = 0; m < 4; ++m) _Pragma("unroll") for (int n = 0; n < 2; ++n) _Pragma("unroll") for (int k = 0; k < 2; ++k) \
;         acc[ai][bj][m][n] = __builtin_amdgcn_mfma_f32_16x16x32_bf16(Bt[n][k], At[m][k], acc[ai][bj][m][n], 0, 0, 0); __builtin_amdgcn_s_setprio(0); } while (0)
; #define PG8_WAIT_V(n) asm volatile("s_waitcnt vmcnt(" #n ")" ::: "memory")
; #define PG8_WAIT_L(n) asm volatile("s_waitcnt lgkmcnt(" #n ")" ::: "memory")
; #define PG8_BAR __builtin_amdgcn_s_barrier()
; #define PG8_SCHED __builtin_amdgcn_sched_barrier(0)
; template <class Epi, class Sched>
; __device__ __forceinline__ void gemm_phase(LAS unsigned char* lds, const Gemm g, const Sched& S, const Epi& E) {
;     ...
;             const bool last = (t == nt - 2);
;             const char* a1 = cA + (size_t)(t + 1) * kstep;
;             const char* a2 = last ? nA : cA + (size_t)(t + 2) * kstep; const char* b2 = last ? nB : cB + (size_t)(t + 2) * kstep;
;             const char* a3 = a2 + kstep; const char* b3 = b2 + kstep;
;             PG8_LDB(B0, 0, 0); PG8_LDB(B1, 0, 1); PG8_SCHED; PG8_LDA(At, 0, 0); PG8_STAGE(PG8_SA(1, 1), a1 + hstepA, voffA);
;             PG8_WAIT_V(8); PG8_WAIT_L(0); PG8_BAR; PG8_MMA(0, 0, At, B0); PG8_MMA(0, 1, At, B1); PG8_BAR; PG8_SCHED;
;             PG8_LDA(At, 0, 1); PG8_STAGE(PG8_SB(0, 0), b2, voffB); PG8_STAGE(PG8_SB(0, 1), b2 + hstepB, voffB); PG8_STAGE(PG8_SA(0, 0), a2, voffA);
;             PG8_WAIT_V(8); PG8_WAIT_L(0); PG8_BAR; PG8_MMA(1, 0, At, B0); PG8_MMA(1, 1, At, B1); PG8_BAR; PG8_SCHED;
.LBB0_742:
	s_add_i32 s68, s0, 2
	s_add_u32 s1, s20, 0xfffc0080
	s_addc_u32 s44, s21, -1
	s_add_i32 s76, 0, 0x10000
	s_cmp_eq_u32 s69, s0
	s_cselect_b32 s45, s41, s44
	s_cselect_b32 s44, s43, s1
	s_cselect_b32 s1, s48, s77
	s_cselect_b32 s0, s53, s55
	s_add_i32 s82, 0, 0x14000
	v_add_u32_e32 v152, s76, v176
	v_add_u32_e32 v168, s82, v176
	ds_read_b128 v[140:143], v152
	ds_read_b128 v[144:147], v152 offset:1024
	ds_read_b128 v[148:151], v152 offset:2048
	ds_read_b128 v[152:155], v152 offset:3072
	ds_read_b128 v[156:159], v168
	ds_read_b128 v[160:163], v168 offset:1024
	ds_read_b128 v[164:167], v168 offset:2048
	ds_read_b128 v[168:171], v168 offset:3072
	v_lshl_add_u64 v[172:173], s[20:21], 0, v[138:139]
	s_add_i32 m0, s13, 0xc000
	ds_read_b128 v[178:181], v177
	ds_read_b128 v[182:185], v177 offset:1024
	ds_read_b128 v[196:199], v177 offset:2048
	ds_read_b128 v[200:203], v177 offset:3072
	ds_read_b128 v[204:207], v177 offset:4096
	ds_read_b128 v[208:211], v177 offset:5120
	ds_read_b128 v[212:215], v177 offset:6144
	ds_read_b128 v[216:219], v177 offset:7168
	global_load_lds_dwordx4 v[172:173], off
	v_lshl_add_u64 v[172:173], s[20:21], 0, v[136:137]
	s_add_i32 m0, s13, 0xe000
	s_nop 0
	global_load_lds_dwordx4 v[172:173], off
	s_waitcnt vmcnt(8)
	s_waitcnt lgkmcnt(0)
	s_barrier
	s_setprio 1
	s_waitcnt lgkmcnt(0)
	v_mfma_f32_16x16x32_bf16 v[126:129], v[140:143], v[178:181], v[126:129]
	v_mfma_f32_16x16x32_bf16 v[122:125], v[148:151], v[178:181], v[122:125]
	v_mfma_f32_16x16x32_bf16 v[110:113], v[140:143], v[196:199], v[110:113]
	v_mfma_f32_16x16x32_bf16 v[106:109], v[148:151], v[196:199], v[106:109]
	v_mfma_f32_16x16x32_bf16 v[94:97], v[140:143], v[204:207], v[94:97]
	v_mfma_f32_16x16x32_bf16 v[90:93], v[148:151], v[204:207], v[90:93]
	v_mfma_f32_16x16x32_bf16 v[78:81], v[140:143], v[212:215], v[78:81]
	v_mfma_f32_16x16x32_bf16 v[74:77], v[148:151], v[212:215], v[74:77]
	v_mfma_f32_16x16x32_bf16 v[126:129], v[144:147], v[182:185], v[126:129]
	v_mfma_f32_16x16x32_bf16 v[122:125], v[152:155], v[182:185], v[122:125]
	v_mfma_f32_16x16x32_bf16 v[110:113], v[144:147], v[200:203], v[110:113]
	v_mfma_f32_16x16x32_bf16 v[106:109], v[152:155], v[200:203], v[106:109]
	v_mfma_f32_16x16x32_bf16 v[94:97], v[144:147], v[208:211], v[94:97]
	v_mfma_f32_16x16x32_bf16 v[90:93], v[152:155], v[208:211], v[90:93]
	v_mfma_f32_16x16x32_bf16 v[78:81], v[144:147], v[216:219], v[78:81]
	v_mfma_f32_16x16x32_bf16 v[74:77], v[152:155], v[216:219], v[74:77]
	v_mfma_f32_16x16x32_bf16 v[118:121], v[156:159], v[178:181], v[118:121]
	v_mfma_f32_16x16x32_bf16 v[114:117], v[164:167], v[178:181], v[114:117]
	v_mfma_f32_16x16x32_bf16 v[102:105], v[156:159], v[196:199], v[102:105]
	v_mfma_f32_16x16x32_bf16 v[98:101], v[164:167], v[196:199], v[98:101]
	v_mfma_f32_16x16x32_bf16 v[86:89], v[156:159], v[204:207], v[86:89]
	v_mfma_f32_16x16x32_bf16 v[82:85], v[164:167], v[204:207], v[82:85]
	v_mfma_f32_16x16x32_bf16 v[70:73], v[156:159], v[212:215], v[70:73]
	v_mfma_f32_16x16x32_bf16 v[66:69], v[164:167], v[212:215], v[66:69]
	v_mfma_f32_16x16x32_bf16 v[118:121], v[160:163], v[182:185], v[118:121]
	v_mfma_f32_16x16x32_bf16 v[114:117], v[168:171], v[182:185], v[114:117]
	v_mfma_f32_16x16x32_bf16 v[102:105], v[160:163], v[200:203], v[102:105]
	v_mfma_f32_16x16x32_bf16 v[98:101], v[168:171], v[200:203], v[98:101]
	v_mfma_f32_16x16x32_bf16 v[86:89], v[160:163], v[208:211], v[86:89]
	v_mfma_f32_16x16x32_bf16 v[82:85], v[168:171], v[208:211], v[82:85]
	v_mfma_f32_16x16x32_bf16 v[70:73], v[160:163], v[216:219], v[70:73]
	v_mfma_f32_16x16x32_bf16 v[66:69], v[168:171], v[216:219], v[66:69]
	s_setprio 0
	s_barrier
	s_add_i32 s76, s76, s12
	v_lshl_add_u64 v[172:173], s[0:1], 0, v[0:1]
	s_mov_b32 m0, s76
	ds_read_b128 v[178:181], v177 offset:16384
	ds_read_b128 v[182:185], v177 offset:17408
	ds_read_b128 v[196:199], v177 offset:18432
	ds_read_b128 v[200:203], v177 offset:19456
	ds_read_b128 v[204:207], v177 offset:20480
	ds_read_b128 v[208:211], v177 offset:21504
	ds_read_b128 v[212:215], v177 offset:22528
	ds_read_b128 v[216:219], v177 offset:23552
	global_load_lds_dwordx4 v[172:173], off
	s_add_i32 m0, s76, 0x2000
	s_add_u32 s80, s0, 0x40000
	v_lshl_add_u64 v[220:221], s[0:1], 0, v[134:135]
	s_addc_u32 s81, s1, 0
	s_add_i32 s76, s82, s12
	global_load_lds_dwordx4 v[220:221], off
	v_lshl_add_u64 v[232:233], s[80:81], 0, v[0:1]
	s_mov_b32 m0, s76
	v_lshl_add_u64 v[234:235], s[44:45], 0, v[132:133]
	global_load_lds_dwordx4 v[232:233], off
	v_lshl_add_u64 v[232:233], s[80:81], 0, v[134:135]
	s_add_i32 m0, s76, 0x2000
	s_nop 0
	global_load_lds_dwordx4 v[232:233], off
	v_lshl_add_u64 v[232:233], s[44:45], 0, v[130:131]
	s_mov_b32 m0, s13
	s_nop 0
	global_load_lds_dwordx4 v[232:233], off
	s_mov_b32 m0, s14
	s_nop 0
	global_load_lds_dwordx4 v[234:235], off
	s_waitcnt vmcnt(8)
	s_waitcnt lgkmcnt(0)
	s_barrier
; #define PG8_STAGE(bufoff, gbase, voff) do { _Pragma("unroll") for (int _i = 0; _i < 2; ++_i) \
;         __builtin_amdgcn_global_load_lds((const unsigned*)((const char*)(gbase) + (voff)[_i]), (LAS unsigned*)(lds + (bufoff) + ldsw + _i * 8192), 16, 0, 0); } while (0)
; #define PG8_LDA(dst, b, h) do { _Pragma("unroll") for (int m = 0; m < 4; ++m) _Pragma("unroll") for (int k = 0; k < 2; ++k) dst[m][k] = *(const LAS bf16x8*)(lds + PG8_SA(b, h) + aoff + m * 2048 + k * 1024); } while (0)
; #define PG8_LDB(dst, b, h) do { _Pragma("unroll") for (int n = 0; n < 2; ++n) _Pragma("unroll") for (int k = 0; k < 2; ++k) dst[n][k] = *(const LAS bf16x8*)(lds + PG8_SB(b, h) + boff + n * 2048 + k * 1024); } while (0)
; #define PG8_MMA(ai, bj, At, Bt) do { __builtin_amdgcn_s_setprio(1); _Pragma("unroll") for (int m = 0; m < 4; ++m) _Pragma("unroll") for (int n = 0; n < 2; ++n) _Pragma("unroll") for (int k = 0; k < 2; ++k) \
;         acc[ai][bj][m][n] = __builtin_amdgcn_mfma_f32_16x16x32_bf16(Bt[n][k], At[m][k], acc[ai][bj][m][n], 0, 0, 0); __builtin_amdgcn_s_setprio(0); } while (0)
; #define PG8_WAIT_V(n) asm volatile("s_waitcnt vmcnt(" #n ")" ::: "memory")
; #define PG8_WAIT_L(n) asm volatile("s_waitcnt lgkmcnt(" #n ")" ::: "memory")
; #define PG8_BAR __builtin_amdgcn_s_barrier()
; #define PG8_SCHED __builtin_amdgcn_sched_barrier(0)
; template <class Epi, class Sched>
; __device__ __forceinline__ void gemm_phase(LAS unsigned char* lds, const Gemm g, const Sched& S, const Epi& E) {
;     ...
;             PG8_WAIT_V(8); PG8_WAIT_L(0); PG8_BAR; PG8_MMA(1, 0, At, B0); PG8_MMA(1, 1, At, B1); PG8_BAR; PG8_SCHED;
;             PG8_LDB(B0, 1, 0); PG8_LDB(B1, 1, 1); PG8_SCHED; PG8_LDA(At, 1, 0); PG8_STAGE(PG8_SA(0, 1), a2 + hstepA, voffA);
;             PG8_WAIT_V(8); PG8_WAIT_L(0); PG8_BAR; PG8_MMA(0, 0, At, B0); PG8_MMA(0, 1, At, B1); PG8_BAR; PG8_SCHED;
	s_setprio 1
	s_waitcnt lgkmcnt(0)
	v_mfma_f32_16x16x32_bf16 v[62:65], v[140:143], v[178:181], v[62:65]
	v_mfma_f32_16x16x32_bf16 v[58:61], v[148:151], v[178:181], v[58:61]
	v_mfma_f32_16x16x32_bf16 v[46:49], v[140:143], v[196:199], v[46:49]
	v_mfma_f32_16x16x32_bf16 v[42:45], v[148:151], v[196:199], v[42:45]
	v_mfma_f32_16x16x32_bf16 v[30:33], v[140:143], v[204:207], v[30:33]
	v_mfma_f32_16x16x32_bf16 v[26:29], v[148:151], v[204:207], v[26:29]
	v_mfma_f32_16x16x32_bf16 v[14:17], v[140:143], v[212:215], v[14:17]
	v_mfma_f32_16x16x32_bf16 v[10:13], v[148:151], v[212:215], v[10:13]
	v_mfma_f32_16x16x32_bf16 v[62:65], v[144:147], v[182:185], v[62:65]
	v_mfma_f32_16x16x32_bf16 v[58:61], v[152:155], v[182:185], v[58:61]
	v_mfma_f32_16x16x32_bf16 v[46:49], v[144:147], v[200:203], v[46:49]
	v_mfma_f32_16x16x32_bf16 v[42:45], v[152:155], v[200:203], v[42:45]
	v_mfma_f32_16x16x32_bf16 v[30:33], v[144:147], v[208:211], v[30:33]
	v_mfma_f32_16x16x32_bf16 v[26:29], v[152:155], v[208:211], v[26:29]
	v_mfma_f32_16x16x32_bf16 v[14:17], v[144:147], v[216:219], v[14:17]
	v_mfma_f32_16x16x32_bf16 v[10:13], v[152:155], v[216:219], v[10:13]
	v_mfma_f32_16x16x32_bf16 v[54:57], v[156:159], v[178:181], v[54:57]
	v_mfma_f32_16x16x32_bf16 v[50:53], v[164:167], v[178:181], v[50:53]
	v_mfma_f32_16x16x32_bf16 v[38:41], v[156:159], v[196:199], v[38:41]
	v_mfma_f32_16x16x32_bf16 v[34:37], v[164:167], v[196:199], v[34:37]
	v_mfma_f32_16x16x32_bf16 v[22:25], v[156:159], v[204:207], v[22:25]
	v_mfma_f32_16x16x32_bf16 v[18:21], v[164:167], v[204:207], v[18:21]
	v_mfma_f32_16x16x32_bf16 v[6:9], v[156:159], v[212:215], v[6:9]
	v_mfma_f32_16x16x32_bf16 v[2:5], v[164:167], v[212:215], v[2:5]
	v_mfma_f32_16x16x32_bf16 v[54:57], v[160:163], v[182:185], v[54:57]
	v_mfma_f32_16x16x32_bf16 v[50:53], v[168:171], v[182:185], v[50:53]
	v_mfma_f32_16x16x32_bf16 v[38:41], v[160:163], v[200:203], v[38:41]
	v_mfma_f32_16x16x32_bf16 v[34:37], v[168:171], v[200:203], v[34:37]
	v_mfma_f32_16x16x32_bf16 v[22:25], v[160:163], v[208:211], v[22:25]
	v_mfma_f32_16x16x32_bf16 v[18:21], v[168:171], v[208:211], v[18:21]
	v_mfma_f32_16x16x32_bf16 v[6:9], v[160:163], v[216:219], v[6:9]
	v_mfma_f32_16x16x32_bf16 v[2:5], v[168:171], v[216:219], v[2:5]
	s_setprio 0
	s_barrier
	s_add_i32 s76, 0, 0x18000
	s_add_i32 s80, 0, 0x1c000
	v_add_u32_e32 v152, s76, v176
	v_add_u32_e32 v168, s80, v176
	ds_read_b128 v[140:143], v152
	ds_read_b128 v[144:147], v152 offset:1024
	ds_read_b128 v[148:151], v152 offset:2048
	ds_read_b128 v[152:155], v152 offset:3072
	ds_read_b128 v[156:159], v168
	ds_read_b128 v[160:163], v168 offset:1024
	ds_read_b128 v[164:167], v168 offset:2048
	ds_read_b128 v[168:171], v168 offset:3072
	s_add_u32 s44, s44, 0x40000
	s_addc_u32 s45, s45, 0
	s_mov_b32 m0, s15
	v_lshl_add_u64 v[248:249], s[44:45], 0, v[130:131]
	ds_read_b128 v[178:181], v177 offset:32768
	ds_read_b128 v[182:185], v177 offset:33792
	ds_read_b128 v[196:199], v177 offset:34816
	ds_read_b128 v[200:203], v177 offset:35840
	ds_read_b128 v[204:207], v177 offset:36864
	ds_read_b128 v[208:211], v177 offset:37888
	ds_read_b128 v[212:215], v177 offset:38912
	ds_read_b128 v[216:219], v177 offset:39936
	global_load_lds_dwordx4 v[248:249], off
	v_lshl_add_u64 v[248:249], s[44:45], 0, v[132:133]
	s_mov_b32 m0, s16
	s_nop 0
	global_load_lds_dwordx4 v[248:249], off
	s_waitcnt vmcnt(8)
	s_waitcnt lgkmcnt(0)
	s_barrier
	s_setprio 1
	s_waitcnt lgkmcnt(0)
	v_mfma_f32_16x16x32_bf16 v[126:129], v[140:143], v[178:181], v[126:129]
	v_mfma_f32_16x16x32_bf16 v[122:125], v[148:151], v[178:181], v[122:125]
	v_mfma_f32_16x16x32_bf16 v[110:113], v[140:143], v[196:199], v[110:113]
	v_mfma_f32_16x16x32_bf16 v[106:109], v[148:151], v[196:199], v[106:109]
	v_mfma_f32_16x16x32_bf16 v[94:97], v[140:143], v[204:207], v[94:97]
	v_mfma_f32_16x16x32_bf16 v[90:93], v[148:151], v[204:207], v[90:93]
	v_mfma_f32_16x16x32_bf16 v[78:81], v[140:143], v[212:215], v[78:81]
	v_mfma_f32_16x16x32_bf16 v[74:77], v[148:151], v[212:215], v[74:77]
	v_mfma_f32_16x16x32_bf16 v[126:129], v[144:147], v[182:185], v[126:129]
	v_mfma_f32_16x16x32_bf16 v[122:125], v[152:155], v[182:185], v[122:125]
	v_mfma_f32_16x16x32_bf16 v[110:113], v[144:147], v[200:203], v[110:113]
	v_mfma_f32_16x16x32_bf16 v[106:109], v[152:155], v[200:203], v[106:109]
	v_mfma_f32_16x16x32_bf16 v[94:97], v[144:147], v[208:211], v[94:97]
	v_mfma_f32_16x16x32_bf16 v[90:93], v[152:155], v[208:211], v[90:93]
	v_mfma_f32_16x16x32_bf16 v[78:81], v[144:147], v[216:219], v[78:81]
	v_mfma_f32_16x16x32_bf16 v[74:77], v[152:155], v[216:219], v[74:77]
	v_mfma_f32_16x16x32_bf16 v[118:121], v[156:159], v[178:181], v[118:121]
	v_mfma_f32_16x16x32_bf16 v[114:117], v[164:167], v[178:181], v[114:117]
	v_mfma_f32_16x16x32_bf16 v[102:105], v[156:159], v[196:199], v[102:105]
	v_mfma_f32_16x16x32_bf16 v[98:101], v[164:167], v[196:199], v[98:101]
	v_mfma_f32_16x16x32_bf16 v[86:89], v[156:159], v[204:207], v[86:89]
	v_mfma_f32_16x16x32_bf16 v[82:85], v[164:167], v[204:207], v[82:85]
	v_mfma_f32_16x16x32_bf16 v[70:73], v[156:159], v[212:215], v[70:73]
	v_mfma_f32_16x16x32_bf16 v[66:69], v[164:167], v[212:215], v[66:69]
	v_mfma_f32_16x16x32_bf16 v[118:121], v[160:163], v[182:185], v[118:121]
	v_mfma_f32_16x16x32_bf16 v[114:117], v[168:171], v[182:185], v[114:117]
	v_mfma_f32_16x16x32_bf16 v[102:105], v[160:163], v[200:203], v[102:105]
	v_mfma_f32_16x16x32_bf16 v[98:101], v[168:171], v[200:203], v[98:101]
	v_mfma_f32_16x16x32_bf16 v[86:89], v[160:163], v[208:211], v[86:89]
	v_mfma_f32_16x16x32_bf16 v[82:85], v[168:171], v[208:211], v[82:85]
	v_mfma_f32_16x16x32_bf16 v[70:73], v[160:163], v[216:219], v[70:73]
	v_mfma_f32_16x16x32_bf16 v[66:69], v[168:171], v[216:219], v[66:69]
	s_setprio 0
	s_barrier
; #define PG8_STAGE(bufoff, gbase, voff) do { _Pragma("unroll") for (int _i = 0; _i < 2; ++_i) \
;         __builtin_amdgcn_global_load_lds((const unsigned*)((const char*)(gbase) + (voff)[_i]), (LAS unsigned*)(lds + (bufoff) + ldsw + _i * 8192), 16, 0, 0); } while (0)
; #define PG8_LDA(dst, b, h) do { _Pragma("unroll") for (int m = 0; m < 4; ++m) _Pragma("unroll") for (int k = 0; k < 2; ++k) dst[m][k] = *(const LAS bf16x8*)(lds + PG8_SA(b, h) + aoff + m * 2048 + k * 1024); } while (0)
; #define PG8_MMA(ai, bj, At, Bt) do { __builtin_amdgcn_s_setprio(1); _Pragma("unroll") for (int m = 0; m < 4; ++m) _Pragma("unroll") for (int n = 0; n < 2; ++n) _Pragma("unroll") for (int k = 0; k < 2; ++k) \
;         acc[ai][bj][m][n] = __builtin_amdgcn_mfma_f32_16x16x32_bf16(Bt[n][k], At[m][k], acc[ai][bj][m][n], 0, 0, 0); __builtin_amdgcn_s_setprio(0); } while (0)
; #define PG8_WAIT_V(n) asm volatile("s_waitcnt vmcnt(" #n ")" ::: "memory")
; #define PG8_WAIT_L(n) asm volatile("s_waitcnt lgkmcnt(" #n ")" ::: "memory")
; #define PG8_BAR __builtin_amdgcn_s_barrier()
; #define PG8_SCHED __builtin_amdgcn_sched_barrier(0)
; template <class Epi, class Sched>
; __device__ __forceinline__ void gemm_phase(LAS unsigned char* lds, const Gemm g, const Sched& S, const Epi& E) {
;     ...
;             PG8_LDA(At, 1, 1); PG8_STAGE(PG8_SB(1, 0), b3, voffB); PG8_STAGE(PG8_SB(1, 1), b3 + hstepB, voffB); PG8_STAGE(PG8_SA(1, 0), a3, voffA);
;             PG8_WAIT_V(8); PG8_WAIT_L(0); PG8_BAR; PG8_MMA(1, 0, At, B0); PG8_MMA(1, 1, At, B1); PG8_BAR; PG8_SCHED;
;         }
	s_add_i32 s44, s76, s12
	v_lshl_add_u64 v[172:173], v[172:173], 0, s[26:27]
	s_mov_b32 m0, s44
	ds_read_b128 v[178:181], v177 offset:49152
	ds_read_b128 v[182:185], v177 offset:50176
	ds_read_b128 v[196:199], v177 offset:51200
	ds_read_b128 v[200:203], v177 offset:52224
	ds_read_b128 v[204:207], v177 offset:53248
	ds_read_b128 v[208:211], v177 offset:54272
	ds_read_b128 v[212:215], v177 offset:55296
	ds_read_b128 v[216:219], v177 offset:56320
	global_load_lds_dwordx4 v[172:173], off
	s_add_i32 m0, s44, 0x2000
	s_add_u32 s0, s0, 0x40080
	v_lshl_add_u64 v[172:173], v[220:221], 0, s[26:27]
	s_addc_u32 s1, s1, 0
	s_add_i32 s44, s80, s12
	global_load_lds_dwordx4 v[172:173], off
	v_lshl_add_u64 v[172:173], s[0:1], 0, v[0:1]
	s_mov_b32 m0, s44
	s_nop 0
	global_load_lds_dwordx4 v[172:173], off
	v_lshl_add_u64 v[172:173], s[0:1], 0, v[134:135]
	s_add_i32 m0, s44, 0x2000
	s_nop 0
	global_load_lds_dwordx4 v[172:173], off
	v_lshl_add_u64 v[172:173], v[232:233], 0, s[26:27]
	s_mov_b32 m0, s65
	s_nop 0
	global_load_lds_dwordx4 v[172:173], off
	v_lshl_add_u64 v[172:173], v[234:235], 0, s[26:27]
	s_mov_b32 m0, s67
	s_nop 0
	global_load_lds_dwordx4 v[172:173], off
	s_waitcnt vmcnt(8)
	s_waitcnt lgkmcnt(0)
	s_barrier
	s_setprio 1
	s_waitcnt lgkmcnt(0)
	v_mfma_f32_16x16x32_bf16 v[62:65], v[140:143], v[178:181], v[62:65]
	v_mfma_f32_16x16x32_bf16 v[58:61], v[148:151], v[178:181], v[58:61]
	v_mfma_f32_16x16x32_bf16 v[46:49], v[140:143], v[196:199], v[46:49]
	v_mfma_f32_16x16x32_bf16 v[42:45], v[148:151], v[196:199], v[42:45]
	v_mfma_f32_16x16x32_bf16 v[30:33], v[140:143], v[204:207], v[30:33]
	v_mfma_f32_16x16x32_bf16 v[26:29], v[148:151], v[204:207], v[26:29]
	v_mfma_f32_16x16x32_bf16 v[14:17], v[140:143], v[212:215], v[14:17]
	v_mfma_f32_16x16x32_bf16 v[10:13], v[148:151], v[212:215], v[10:13]
	v_mfma_f32_16x16x32_bf16 v[62:65], v[144:147], v[182:185], v[62:65]
	v_mfma_f32_16x16x32_bf16 v[58:61], v[152:155], v[182:185], v[58:61]
	v_mfma_f32_16x16x32_bf16 v[46:49], v[144:147], v[200:203], v[46:49]
	v_mfma_f32_16x16x32_bf16 v[42:45], v[152:155], v[200:203], v[42:45]
	v_mfma_f32_16x16x32_bf16 v[30:33], v[144:147], v[208:211], v[30:33]
	v_mfma_f32_16x16x32_bf16 v[26:29], v[152:155], v[208:211], v[26:29]
	v_mfma_f32_16x16x32_bf16 v[14:17], v[144:147], v[216:219], v[14:17]
	v_mfma_f32_16x16x32_bf16 v[10:13], v[152:155], v[216:219], v[10:13]
	v_mfma_f32_16x16x32_bf16 v[54:57], v[156:159], v[178:181], v[54:57]
	v_mfma_f32_16x16x32_bf16 v[50:53], v[164:167], v[178:181], v[50:53]
	v_mfma_f32_16x16x32_bf16 v[38:41], v[156:159], v[196:199], v[38:41]
	v_mfma_f32_16x16x32_bf16 v[34:37], v[164:167], v[196:199], v[34:37]
	v_mfma_f32_16x16x32_bf16 v[22:25], v[156:159], v[204:207], v[22:25]
	v_mfma_f32_16x16x32_bf16 v[18:21], v[164:167], v[204:207], v[18:21]
	v_mfma_f32_16x16x32_bf16 v[6:9], v[156:159], v[212:215], v[6:9]
	v_mfma_f32_16x16x32_bf16 v[2:5], v[164:167], v[212:215], v[2:5]
	v_mfma_f32_16x16x32_bf16 v[54:57], v[160:163], v[182:185], v[54:57]
	v_mfma_f32_16x16x32_bf16 v[50:53], v[168:171], v[182:185], v[50:53]
	v_mfma_f32_16x16x32_bf16 v[38:41], v[160:163], v[200:203], v[38:41]
	v_mfma_f32_16x16x32_bf16 v[34:37], v[168:171], v[200:203], v[34:37]
	v_mfma_f32_16x16x32_bf16 v[22:25], v[160:163], v[208:211], v[22:25]
	v_mfma_f32_16x16x32_bf16 v[18:21], v[168:171], v[208:211], v[18:21]
	v_mfma_f32_16x16x32_bf16 v[6:9], v[160:163], v[216:219], v[6:9]
	v_mfma_f32_16x16x32_bf16 v[2:5], v[168:171], v[216:219], v[2:5]
	s_setprio 0
	s_barrier
	s_add_u32 s55, s55, 0x100
	s_addc_u32 s77, s77, 0
	s_add_u32 s20, s20, 0x100
	s_addc_u32 s21, s21, 0
	s_cmp_ge_i32 s68, s19
	s_mov_b32 s0, s68
	s_cbranch_scc0 .LBB0_742
